# all four scan passes and the neighbourhood attention hand-written: decay-factored state, f32 4x4x1 MFMA rank-1 updates, attention with windowed batched loads and bias preloaded as MFMA C
# speedup vs baseline: 1.1260x; 1.0689x over previous
; __device__ __forceinline__ void nat_phase(const Params& p, float* ldsf, int wave0, int nwaves) {
;     const int lane = threadIdx.x & 63, wid = __builtin_amdgcn_readfirstlane(threadIdx.x >> 6), l15 = lane & 15, lq = lane >> 4;
;     const u16* Qn = (const u16*)p.out; const u16* Kn = Qn + (size_t)NTOK * RW; const u16* VT = Kn + (size_t)NTOK * RW; const u16* Gn = VT + (size_t)NTOK * RW;
;     u16* MIX = (u16*)(p.ws + O_HN);
;     for (int item = wave0; item < 8192; item += nwaves) {
;         const int r = item & 255, h = (item >> 8) & 15, b = item >> 12;
;         const int rs = min(max(r - 4, 0), 248);
;         const u16* Qb = Qn + (size_t)(b * SEQ + r * 64) * RW + h * 64;
;         const u16* Kb = Kn + (size_t)(b * SEQ + rs * 64) * RW + h * 64;
;         const u16* Vb = VT + (size_t)((b * 16 + h) * 64) * SEQ + rs * 64;
;         float* tb = ldsf + wid * 256;
;         { const float* rpb = p.rpb + h * 465 + (rs - r + 7) * 31;
; #pragma unroll
;           for (int q = 0; q < 4; ++q) { const int e = lane + q * 64; if (e < 248) tb[e] = rpb[e]; } }
; #pragma unroll 1
;         for (int qt = 0; qt < 4; ++qt) {
;             const int c0 = qt * 16, cs0 = (qt == 0) ? 0 : (qt == 1 ? 8 : (qt == 2 ? 24 : 32));
;             const int c = c0 + l15, csq = min(max(c - 8, 0), 48);
;             const bf16x8 bq0 = *(const bf16x8*)(Qb + (size_t)c * RW + lq * 8), bq1 = *(const bf16x8*)(Qb + (size_t)c * RW + 32 + lq * 8);
;             f32x4 sc[8][2];
; #pragma unroll
;             for (int i = 0; i < 8; ++i)
; #pragma unroll
;                 for (int hf = 0; hf < 2; ++hf) { const u16* kp = Kb + (size_t)(i * 64 + cs0 + (l15 >> 2) * 8 + hf * 4 + (l15 & 3)) * RW + lq * 8;
;                     const bf16x8 a0 = *(const bf16x8*)kp, a1 = *(const bf16x8*)(kp + 32); f32x4 z = {0.f, 0.f, 0.f, 0.f};
;                     z = __builtin_amdgcn_mfma_f32_16x16x32_bf16(a0, bq0, z, 0, 0, 0); z = __builtin_amdgcn_mfma_f32_16x16x32_bf16(a1, bq1, z, 0, 0, 0); sc[i][hf] = z; }
;             float mx = -1e30f;
; #pragma unroll
;             for (int i = 0; i < 8; ++i)
; #pragma unroll
;                 for (int hf = 0; hf < 2; ++hf)
; #pragma unroll
;                     for (int j = 0; j < 4; ++j) { const int kc = cs0 + lq * 8 + hf * 4 + j; const bool valid = (kc >= csq) && (kc < csq + 16); const int bc = valid ? (kc - c + 15) : 0;
.LBB0_413:
	s_cmp_lt_i32 s58, 5
	s_cselect_b64 s[0:1], -1, 0
	s_cmp_gt_i32 s59, 4
	s_cselect_b64 s[4:5], -1, 0
	s_and_b64 s[0:1], s[0:1], s[4:5]
	s_andn2_b64 vcc, exec, s[0:1]
	s_cbranch_vccnz .LBB0_628
	v_readfirstlane_b32 s0, v254
	v_and_b32_e32 v96, 63, v254
	s_cmpk_lt_u32 s0, 0x100
	v_and_b32_e32 v65, 15, v254
	s_cbranch_scc1 .LBB0_555
	s_setprio 3
	s_lshr_b32 s1, s0, 6
	s_cmp_eq_u32 s96, 0x100
	s_cbranch_scc0 .Lmy_nat_generic
	s_and_b32 s84, s2, 7
	s_lshr_b32 s85, s2, 3
	s_lshl_b32 s84, s84, 10
	s_lshl_b32 s85, s85, 3
	s_add_u32 s0, s84, s85
	s_add_u32 s0, s0, s1
	s_add_i32 s0, s0, -4
	s_mov_b32 s81, 4
	s_movk_i32 s89, 256
	s_mov_b32 s88, 8
	s_branch .Lmy_nat_go
.Lmy_nat_generic:
	s_lshl_b32 s0, s2, 2
	s_add_i32 s0, s0, s1
	s_add_i32 s0, s0, -4
	s_lshl_b32 s81, s96, 2
	s_lshl_b32 s89, s96, 3
	s_brev_b32 s88, -2
	s_cmpk_gt_i32 s0, 0x1fff
	s_cbranch_scc1 .Lmy_nat_end
.Lmy_nat_go:
	s_mov_b32 s64, s56
	s_and_b32 s65, s57, 0xffff
	s_brev_b32 s66, -2
	s_mov_b32 s67, 0x27000
	s_mov_b32 s68, s54
	s_and_b32 s69, s55, 0xffff
	s_mov_b32 s70, s66
	s_mov_b32 s71, s67
	s_mov_b32 s72, s50
	s_and_b32 s73, s51, 0xffff
	s_movk_i32 s74, 0x7440
	s_mov_b32 s75, s67
	v_and_b32_e32 v237, 15, v254
	v_bfe_u32 v238, v254, 4, 2
	v_and_b32_e32 v242, 63, v254
	v_lshlrev_b32_e32 v243, 4, v238
	v_lshl_add_u32 v224, v237, 11, v243
	v_lshl_add_u32 v226, v237, 15, v243
	v_lshrrev_b32_e32 v244, 2, v237
	v_and_b32_e32 v245, 3, v237
	v_lshl_add_u32 v244, v244, 3, v245
	v_lshl_add_u32 v225, v244, 11, v243
	v_lshlrev_b32_e32 v243, 3, v238
	v_lshl_add_u32 v227, v237, 11, v243
	v_lshl_add_u32 v228, v237, 12, v243
	v_xor_b32_e32 v248, 16, v242
	v_lshlrev_b32_e32 v248, 2, v248
	v_xor_b32_e32 v249, 32, v242
	v_lshlrev_b32_e32 v249, 2, v249
	s_lshl_b32 s3, s1, 11
	s_add_u32 s3, s3, 0x6000
	v_lshl_add_u32 v250, v242, 2, s3
	v_mov_b32_e32 v243, 0xf2c9f2ca
	ds_write_b32 v250, v243 offset:1024
	ds_write_b32 v250, v243 offset:1280
	ds_write_b32 v250, v243 offset:1536
	ds_write_b32 v250, v243 offset:1792
	v_mov_b32_e32 v252, 0x3e38aa3b
	v_mov_b32_e32 v253, 0x3e38aa3b
.Lmy_nat_item:
	s_and_b32 s4, s0, 255
	s_bfe_u32 s5, s0, 0x40008
	s_lshr_b32 s6, s0, 12
	s_add_i32 s7, s4, -4
	s_max_i32 s7, s7, 0
	s_min_i32 s7, s7, 0xf8
	s_lshl_b32 s8, s6, 14
	s_lshl_b32 s9, s4, 6
	s_add_u32 s9, s9, s8
	s_lshl_b32 s84, s5, 7
	s_lshl_b32 s76, s9, 11
	s_add_u32 s76, s76, s84
	s_add_u32 s79, s76, 0xc000000
	s_lshl_b32 s80, s9, 12
	s_add_u32 s80, s80, s84
	s_add_u32 s80, s80, 0x3800800
	s_lshl_b32 s85, s7, 6
	s_add_u32 s85, s85, s8
	s_lshl_b32 s77, s85, 11
	s_add_u32 s77, s77, s84
	s_add_u32 s77, s77, 0x4000000
	s_lshl_b32 s85, s6, 4
	s_add_u32 s85, s85, s5
	s_lshl_b32 s78, s85, 21
	s_lshl_b32 s86, s7, 7
	s_add_u32 s78, s78, s86
	s_add_u32 s78, s78, 0x8000000
	s_sub_i32 s85, s7, s4
	s_add_i32 s85, s85, 7
	s_mul_i32 s85, s85, 31
	s_mul_i32 s86, s5, 465
	s_add_u32 s85, s85, s86
	s_lshl_b32 s85, s85, 2
	v_and_b32_e32 v242, 63, v254
	v_lshlrev_b32_e32 v244, 2, v242
	buffer_load_dword v0, v244, s[72:75], s85 offen offset:0
	buffer_load_dword v1, v244, s[72:75], s85 offen offset:256
	buffer_load_dword v2, v244, s[72:75], s85 offen offset:512
	buffer_load_dword v3, v244, s[72:75], s85 offen offset:768
	s_waitcnt vmcnt(0)
	v_mul_f32_e32 v0, 0x41000000, v0
	v_mul_f32_e32 v1, 0x41000000, v1
	v_mul_f32_e32 v2, 0x41000000, v2
	v_mul_f32_e32 v3, 0x41000000, v3
	ds_write_b32 v250, v0 offset:0
	ds_write_b32 v250, v1 offset:256
	ds_write_b32 v250, v2 offset:512
	ds_write_b32 v250, v3 offset:768
	s_mov_b32 s16, 0
.Lmy_nat_qt:
	s_lshl_b32 s82, s16, 4
	s_add_i32 s83, s82, -8
	s_max_i32 s83, s83, 0
	s_min_i32 s83, s83, 32
	s_lshl_b32 s84, s82, 11
	s_add_u32 s84, s84, s76
	buffer_load_dwordx4 v[192:195], v224, s[68:71], s84 offen
	buffer_load_dwordx4 v[196:199], v224, s[68:71], s84 offen offset:64
	s_lshl_b32 s84, s83, 11
	s_add_u32 s84, s84, s77
	s_add_u32 s85, s84, 0x0
	buffer_load_dwordx4 v[0:3], v225, s[68:71], s85 offen
	s_add_u32 s85, s84, 0x0
	buffer_load_dwordx4 v[4:7], v225, s[68:71], s85 offen offset:64
	s_add_u32 s85, s84, 0x2000
	buffer_load_dwordx4 v[8:11], v225, s[68:71], s85 offen
	s_add_u32 s85, s84, 0x2000
	buffer_load_dwordx4 v[12:15], v225, s[68:71], s85 offen offset:64
	s_add_u32 s85, s84, 0x20000
	buffer_load_dwordx4 v[16:19], v225, s[68:71], s85 offen
	s_add_u32 s85, s84, 0x20000
	buffer_load_dwordx4 v[20:23], v225, s[68:71], s85 offen offset:64
	s_add_u32 s85, s84, 0x22000
	buffer_load_dwordx4 v[24:27], v225, s[68:71], s85 offen
	s_add_u32 s85, s84, 0x22000
	buffer_load_dwordx4 v[28:31], v225, s[68:71], s85 offen offset:64
	v_add_u32_e32 v241, s82, v237
	v_add_u32_e32 v242, -8, v241
	v_med3_i32 v242, v242, 0, 48
	v_lshl_add_u32 v251, v238, 3, s83
	v_sub_u32_e32 v243, v251, v242
	v_sub_u32_e32 v244, v251, v241
	v_lshl_add_u32 v244, v244, 2, s3
	v_mov_b32_e32 v245, s3
	v_add_u32_e32 v245, 0x400, v245
	v_add_u32_e32 v246, 0, v243
	v_cmp_gt_u32_e32 vcc, 16, v246
	v_add_u32_e32 v247, 60, v244
	s_nop 0
	v_cndmask_b32_e32 v229, v245, v247, vcc
	v_add_u32_e32 v246, 1, v243
	v_cmp_gt_u32_e32 vcc, 16, v246
	v_add_u32_e32 v247, 64, v244
	s_nop 0
	v_cndmask_b32_e32 v230, v245, v247, vcc
	v_add_u32_e32 v246, 2, v243
	v_cmp_gt_u32_e32 vcc, 16, v246
	v_add_u32_e32 v247, 68, v244
	s_nop 0
	v_cndmask_b32_e32 v231, v245, v247, vcc
	v_add_u32_e32 v246, 3, v243
	v_cmp_gt_u32_e32 vcc, 16, v246
	v_add_u32_e32 v247, 72, v244
	s_nop 0
	v_cndmask_b32_e32 v232, v245, v247, vcc
	v_add_u32_e32 v246, 4, v243
	v_cmp_gt_u32_e32 vcc, 16, v246
	v_add_u32_e32 v247, 76, v244
	s_nop 0
	v_cndmask_b32_e32 v233, v245, v247, vcc
	v_add_u32_e32 v246, 5, v243
	v_cmp_gt_u32_e32 vcc, 16, v246
	v_add_u32_e32 v247, 80, v244
	s_nop 0
; __device__ __forceinline__ void nat_phase(const Params& p, float* ldsf, int wave0, int nwaves) {
;     ...
;             const bf16x8 bq0 = *(const bf16x8*)(Qb + (size_t)c * RW + lq * 8), bq1 = *(const bf16x8*)(Qb + (size_t)c * RW + 32 + lq * 8);
;             f32x4 sc[8][2];
; #pragma unroll
;             for (int i = 0; i < 8; ++i)
; #pragma unroll
;                 for (int hf = 0; hf < 2; ++hf) { const u16* kp = Kb + (size_t)(i * 64 + cs0 + (l15 >> 2) * 8 + hf * 4 + (l15 & 3)) * RW + lq * 8;
;                     const bf16x8 a0 = *(const bf16x8*)kp, a1 = *(const bf16x8*)(kp + 32); f32x4 z = {0.f, 0.f, 0.f, 0.f};
;                     z = __builtin_amdgcn_mfma_f32_16x16x32_bf16(a0, bq0, z, 0, 0, 0); z = __builtin_amdgcn_mfma_f32_16x16x32_bf16(a1, bq1, z, 0, 0, 0); sc[i][hf] = z; }
;             float mx = -1e30f;
; #pragma unroll
;             for (int i = 0; i < 8; ++i)
; #pragma unroll
;                 for (int hf = 0; hf < 2; ++hf)
; #pragma unroll
;                     for (int j = 0; j < 4; ++j) { const int kc = cs0 + lq * 8 + hf * 4 + j; const bool valid = (kc >= csq) && (kc < csq + 16); const int bc = valid ? (kc - c + 15) : 0;
;                         const float s = valid ? sc[i][hf][j] * 0.125f + tb[i * 31 + bc] : -1e30f; sc[i][hf][j] = s; mx = fmaxf(mx, s); }
	v_cndmask_b32_e32 v234, v245, v247, vcc
	v_add_u32_e32 v246, 6, v243
	v_cmp_gt_u32_e32 vcc, 16, v246
	v_add_u32_e32 v247, 84, v244
	s_nop 0
	v_cndmask_b32_e32 v235, v245, v247, vcc
	v_add_u32_e32 v246, 7, v243
	v_cmp_gt_u32_e32 vcc, 16, v246
	v_add_u32_e32 v247, 88, v244
	s_nop 0
	v_cndmask_b32_e32 v236, v245, v247, vcc
	ds_read_b32 v128, v229 offset:0
	ds_read_b32 v129, v230 offset:0
	ds_read_b32 v130, v231 offset:0
	ds_read_b32 v131, v232 offset:0
	ds_read_b32 v132, v233 offset:0
	ds_read_b32 v133, v234 offset:0
	ds_read_b32 v134, v235 offset:0
	ds_read_b32 v135, v236 offset:0
	ds_read_b32 v136, v229 offset:124
	ds_read_b32 v137, v230 offset:124
	ds_read_b32 v138, v231 offset:124
	ds_read_b32 v139, v232 offset:124
	ds_read_b32 v140, v233 offset:124
	ds_read_b32 v141, v234 offset:124
	ds_read_b32 v142, v235 offset:124
	ds_read_b32 v143, v236 offset:124
	ds_read_b32 v144, v229 offset:248
	ds_read_b32 v145, v230 offset:248
	ds_read_b32 v146, v231 offset:248
	ds_read_b32 v147, v232 offset:248
	ds_read_b32 v148, v233 offset:248
	ds_read_b32 v149, v234 offset:248
	ds_read_b32 v150, v235 offset:248
	ds_read_b32 v151, v236 offset:248
	ds_read_b32 v152, v229 offset:372
	ds_read_b32 v153, v230 offset:372
	ds_read_b32 v154, v231 offset:372
	ds_read_b32 v155, v232 offset:372
	ds_read_b32 v156, v233 offset:372
	ds_read_b32 v157, v234 offset:372
	ds_read_b32 v158, v235 offset:372
	ds_read_b32 v159, v236 offset:372
	ds_read_b32 v160, v229 offset:496
	ds_read_b32 v161, v230 offset:496
	ds_read_b32 v162, v231 offset:496
	ds_read_b32 v163, v232 offset:496
	ds_read_b32 v164, v233 offset:496
	ds_read_b32 v165, v234 offset:496
	ds_read_b32 v166, v235 offset:496
	ds_read_b32 v167, v236 offset:496
	ds_read_b32 v168, v229 offset:620
	ds_read_b32 v169, v230 offset:620
	ds_read_b32 v170, v231 offset:620
	ds_read_b32 v171, v232 offset:620
	ds_read_b32 v172, v233 offset:620
	ds_read_b32 v173, v234 offset:620
	ds_read_b32 v174, v235 offset:620
	ds_read_b32 v175, v236 offset:620
	ds_read_b32 v176, v229 offset:744
	ds_read_b32 v177, v230 offset:744
	ds_read_b32 v178, v231 offset:744
	ds_read_b32 v179, v232 offset:744
	ds_read_b32 v180, v233 offset:744
	ds_read_b32 v181, v234 offset:744
	ds_read_b32 v182, v235 offset:744
	ds_read_b32 v183, v236 offset:744
	ds_read_b32 v184, v229 offset:868
	ds_read_b32 v185, v230 offset:868
	ds_read_b32 v186, v231 offset:868
	ds_read_b32 v187, v232 offset:868
	ds_read_b32 v188, v233 offset:868
	ds_read_b32 v189, v234 offset:868
	ds_read_b32 v190, v235 offset:868
	ds_read_b32 v191, v236 offset:868
	s_waitcnt lgkmcnt(0)
	s_add_u32 s85, s84, 0x40000
	buffer_load_dwordx4 v[32:35], v225, s[68:71], s85 offen
	s_waitcnt vmcnt(8)
	v_mfma_f32_16x16x32_bf16 v[128:131], v[0:3], v[192:195], v[128:131]
	s_add_u32 s85, s84, 0x40000
	buffer_load_dwordx4 v[36:39], v225, s[68:71], s85 offen offset:64
	s_waitcnt vmcnt(8)
	v_mfma_f32_16x16x32_bf16 v[128:131], v[4:7], v[196:199], v[128:131]
	s_add_u32 s85, s84, 0x42000
	buffer_load_dwordx4 v[40:43], v225, s[68:71], s85 offen
	s_waitcnt vmcnt(8)
	v_mfma_f32_16x16x32_bf16 v[132:135], v[8:11], v[192:195], v[132:135]
	s_add_u32 s85, s84, 0x42000
	buffer_load_dwordx4 v[44:47], v225, s[68:71], s85 offen offset:64
	s_waitcnt vmcnt(8)
	v_mfma_f32_16x16x32_bf16 v[132:135], v[12:15], v[196:199], v[132:135]
	s_add_u32 s85, s84, 0x60000
	buffer_load_dwordx4 v[48:51], v225, s[68:71], s85 offen
	s_waitcnt vmcnt(8)
	v_mfma_f32_16x16x32_bf16 v[136:139], v[16:19], v[192:195], v[136:139]
	s_add_u32 s85, s84, 0x60000
	buffer_load_dwordx4 v[52:55], v225, s[68:71], s85 offen offset:64
	s_waitcnt vmcnt(8)
	v_mfma_f32_16x16x32_bf16 v[136:139], v[20:23], v[196:199], v[136:139]
	s_add_u32 s85, s84, 0x62000
	buffer_load_dwordx4 v[56:59], v225, s[68:71], s85 offen
	s_waitcnt vmcnt(8)
	v_mfma_f32_16x16x32_bf16 v[140:143], v[24:27], v[192:195], v[140:143]
	s_add_u32 s85, s84, 0x62000
	buffer_load_dwordx4 v[60:63], v225, s[68:71], s85 offen offset:64
	s_waitcnt vmcnt(8)
	v_mfma_f32_16x16x32_bf16 v[140:143], v[28:31], v[196:199], v[140:143]
	s_add_u32 s85, s84, 0x80000
	buffer_load_dwordx4 v[64:67], v225, s[68:71], s85 offen
	s_waitcnt vmcnt(8)
	v_mfma_f32_16x16x32_bf16 v[144:147], v[32:35], v[192:195], v[144:147]
	s_add_u32 s85, s84, 0x80000
	buffer_load_dwordx4 v[68:71], v225, s[68:71], s85 offen offset:64
	s_waitcnt vmcnt(8)
	v_mfma_f32_16x16x32_bf16 v[144:147], v[36:39], v[196:199], v[144:147]
	s_add_u32 s85, s84, 0x82000
	buffer_load_dwordx4 v[72:75], v225, s[68:71], s85 offen
	s_waitcnt vmcnt(8)
	v_mfma_f32_16x16x32_bf16 v[148:151], v[40:43], v[192:195], v[148:151]
	s_add_u32 s85, s84, 0x82000
	buffer_load_dwordx4 v[76:79], v225, s[68:71], s85 offen offset:64
	s_waitcnt vmcnt(8)
	v_mfma_f32_16x16x32_bf16 v[148:151], v[44:47], v[196:199], v[148:151]
	s_add_u32 s85, s84, 0xa0000
	buffer_load_dwordx4 v[80:83], v225, s[68:71], s85 offen
	s_waitcnt vmcnt(8)
	v_mfma_f32_16x16x32_bf16 v[152:155], v[48:51], v[192:195], v[152:155]
	s_add_u32 s85, s84, 0xa0000
	buffer_load_dwordx4 v[84:87], v225, s[68:71], s85 offen offset:64
	s_waitcnt vmcnt(8)
	v_mfma_f32_16x16x32_bf16 v[152:155], v[52:55], v[196:199], v[152:155]
	s_add_u32 s85, s84, 0xa2000
	buffer_load_dwordx4 v[88:91], v225, s[68:71], s85 offen
	s_waitcnt vmcnt(8)
	v_mfma_f32_16x16x32_bf16 v[156:159], v[56:59], v[192:195], v[156:159]
	s_add_u32 s85, s84, 0xa2000
	buffer_load_dwordx4 v[92:95], v225, s[68:71], s85 offen offset:64
	s_waitcnt vmcnt(8)
	v_mfma_f32_16x16x32_bf16 v[156:159], v[60:63], v[196:199], v[156:159]
	s_add_u32 s85, s84, 0xc0000
	buffer_load_dwordx4 v[96:99], v225, s[68:71], s85 offen
	s_waitcnt vmcnt(8)
; __device__ __forceinline__ void nat_phase(const Params& p, float* ldsf, int wave0, int nwaves) {
;     ...
;             const bf16x8 bq0 = *(const bf16x8*)(Qb + (size_t)c * RW + lq * 8), bq1 = *(const bf16x8*)(Qb + (size_t)c * RW + 32 + lq * 8);
;             f32x4 sc[8][2];
; #pragma unroll
;             for (int i = 0; i < 8; ++i)
; #pragma unroll
;                 for (int hf = 0; hf < 2; ++hf) { const u16* kp = Kb + (size_t)(i * 64 + cs0 + (l15 >> 2) * 8 + hf * 4 + (l15 & 3)) * RW + lq * 8;
;                     const bf16x8 a0 = *(const bf16x8*)kp, a1 = *(const bf16x8*)(kp + 32); f32x4 z = {0.f, 0.f, 0.f, 0.f};
;                     z = __builtin_amdgcn_mfma_f32_16x16x32_bf16(a0, bq0, z, 0, 0, 0); z = __builtin_amdgcn_mfma_f32_16x16x32_bf16(a1, bq1, z, 0, 0, 0); sc[i][hf] = z; }
;             float mx = -1e30f;
; #pragma unroll
;             for (int i = 0; i < 8; ++i)
; #pragma unroll
;                 for (int hf = 0; hf < 2; ++hf)
; #pragma unroll
;                     for (int j = 0; j < 4; ++j) { const int kc = cs0 + lq * 8 + hf * 4 + j; const bool valid = (kc >= csq) && (kc < csq + 16); const int bc = valid ? (kc - c + 15) : 0;
;                         const float s = valid ? sc[i][hf][j] * 0.125f + tb[i * 31 + bc] : -1e30f; sc[i][hf][j] = s; mx = fmaxf(mx, s); }
;             mx = fmaxf(mx, __shfl_xor(mx, 16)); mx = fmaxf(mx, __shfl_xor(mx, 32));
	v_mfma_f32_16x16x32_bf16 v[160:163], v[64:67], v[192:195], v[160:163]
	s_add_u32 s85, s84, 0xc0000
	buffer_load_dwordx4 v[100:103], v225, s[68:71], s85 offen offset:64
	s_waitcnt vmcnt(8)
	v_mfma_f32_16x16x32_bf16 v[160:163], v[68:71], v[196:199], v[160:163]
	s_add_u32 s85, s84, 0xc2000
	buffer_load_dwordx4 v[104:107], v225, s[68:71], s85 offen
	s_waitcnt vmcnt(8)
	v_mfma_f32_16x16x32_bf16 v[164:167], v[72:75], v[192:195], v[164:167]
	s_add_u32 s85, s84, 0xc2000
	buffer_load_dwordx4 v[108:111], v225, s[68:71], s85 offen offset:64
	s_waitcnt vmcnt(8)
	v_mfma_f32_16x16x32_bf16 v[164:167], v[76:79], v[196:199], v[164:167]
	s_add_u32 s85, s84, 0xe0000
	buffer_load_dwordx4 v[112:115], v225, s[68:71], s85 offen
	s_waitcnt vmcnt(8)
	v_mfma_f32_16x16x32_bf16 v[168:171], v[80:83], v[192:195], v[168:171]
	s_add_u32 s85, s84, 0xe0000
	buffer_load_dwordx4 v[116:119], v225, s[68:71], s85 offen offset:64
	s_waitcnt vmcnt(8)
	v_mfma_f32_16x16x32_bf16 v[168:171], v[84:87], v[196:199], v[168:171]
	s_add_u32 s85, s84, 0xe2000
	buffer_load_dwordx4 v[120:123], v225, s[68:71], s85 offen
	s_waitcnt vmcnt(8)
	v_mfma_f32_16x16x32_bf16 v[172:175], v[88:91], v[192:195], v[172:175]
	s_add_u32 s85, s84, 0xe2000
	buffer_load_dwordx4 v[124:127], v225, s[68:71], s85 offen offset:64
	s_waitcnt vmcnt(8)
	v_mfma_f32_16x16x32_bf16 v[172:175], v[92:95], v[196:199], v[172:175]
	s_waitcnt vmcnt(7)
	v_mfma_f32_16x16x32_bf16 v[176:179], v[96:99], v[192:195], v[176:179]
	s_waitcnt vmcnt(6)
	v_mfma_f32_16x16x32_bf16 v[176:179], v[100:103], v[196:199], v[176:179]
	s_waitcnt vmcnt(5)
	v_mfma_f32_16x16x32_bf16 v[180:183], v[104:107], v[192:195], v[180:183]
	s_waitcnt vmcnt(4)
	v_mfma_f32_16x16x32_bf16 v[180:183], v[108:111], v[196:199], v[180:183]
	s_waitcnt vmcnt(3)
	v_mfma_f32_16x16x32_bf16 v[184:187], v[112:115], v[192:195], v[184:187]
	s_waitcnt vmcnt(2)
	v_mfma_f32_16x16x32_bf16 v[184:187], v[116:119], v[196:199], v[184:187]
	s_waitcnt vmcnt(1)
	v_mfma_f32_16x16x32_bf16 v[188:191], v[120:123], v[192:195], v[188:191]
	s_waitcnt vmcnt(0)
	v_mfma_f32_16x16x32_bf16 v[188:191], v[124:127], v[196:199], v[188:191]
	s_lshl_b32 s84, s82, 11
	s_add_u32 s84, s84, s79
	buffer_load_dwordx2 v[216:217], v227, s[68:71], s84 offen offset:0
	buffer_load_dwordx2 v[218:219], v227, s[68:71], s84 offen offset:32
	buffer_load_dwordx2 v[220:221], v227, s[68:71], s84 offen offset:64
	buffer_load_dwordx2 v[222:223], v227, s[68:71], s84 offen offset:96
	s_lshl_b32 s84, s83, 1
	s_add_u32 s84, s84, s78
	s_add_u32 s85, s84, 0x80000
	s_add_u32 s86, s84, 0x100000
	s_add_u32 s87, s84, 0x180000
	buffer_load_dwordx4 v[0:3], v226, s[68:71], s84 offen offset:0
	buffer_load_dwordx4 v[4:7], v226, s[68:71], s85 offen offset:0
	buffer_load_dwordx4 v[8:11], v226, s[68:71], s86 offen offset:0
	buffer_load_dwordx4 v[12:15], v226, s[68:71], s87 offen offset:0
	buffer_load_dwordx4 v[16:19], v226, s[68:71], s84 offen offset:128
	buffer_load_dwordx4 v[20:23], v226, s[68:71], s85 offen offset:128
	buffer_load_dwordx4 v[24:27], v226, s[68:71], s86 offen offset:128
	buffer_load_dwordx4 v[28:31], v226, s[68:71], s87 offen offset:128
	v_max3_f32 v239, v128, v129, v130
	v_max3_f32 v239, v239, v131, v132
	v_max3_f32 v239, v239, v133, v134
	v_max3_f32 v239, v239, v135, v136
	v_max3_f32 v239, v239, v137, v138
	v_max3_f32 v239, v239, v139, v140
	v_max3_f32 v239, v239, v141, v142
	v_max3_f32 v239, v239, v143, v144
	v_max3_f32 v239, v239, v145, v146
	v_max3_f32 v239, v239, v147, v148
	v_max3_f32 v239, v239, v149, v150
	v_max3_f32 v239, v239, v151, v152
	v_max3_f32 v239, v239, v153, v154
	v_max3_f32 v239, v239, v155, v156
	v_max3_f32 v239, v239, v157, v158
	v_max3_f32 v239, v239, v159, v160
	v_max3_f32 v239, v239, v161, v162
	v_max3_f32 v239, v239, v163, v164
	v_max3_f32 v239, v239, v165, v166
	v_max3_f32 v239, v239, v167, v168
	v_max3_f32 v239, v239, v169, v170
	v_max3_f32 v239, v239, v171, v172
	v_max3_f32 v239, v239, v173, v174
	v_max3_f32 v239, v239, v175, v176
	v_max3_f32 v239, v239, v177, v178
	v_max3_f32 v239, v239, v179, v180
	v_max3_f32 v239, v239, v181, v182
	v_max3_f32 v239, v239, v183, v184
	v_max3_f32 v239, v239, v185, v186
	v_max3_f32 v239, v239, v187, v188
	v_max3_f32 v239, v239, v189, v190
	v_max_f32_e32 v239, v239, v191
	ds_bpermute_b32 v242, v248, v239
	s_waitcnt lgkmcnt(0)
	v_max_f32_e32 v239, v239, v242
	ds_bpermute_b32 v242, v249, v239
	s_waitcnt lgkmcnt(0)
; __device__ __forceinline__ void nat_phase(const Params& p, float* ldsf, int wave0, int nwaves) {
;     ...
;             mx = fmaxf(mx, __shfl_xor(mx, 16)); mx = fmaxf(mx, __shfl_xor(mx, 32));
;             float sum = 0.f;
; #pragma unroll
;             for (int i = 0; i < 8; ++i)
; #pragma unroll
;                 for (int hf = 0; hf < 2; ++hf)
; #pragma unroll
;                     for (int j = 0; j < 4; ++j) { const float e = __expf(sc[i][hf][j] - mx); sc[i][hf][j] = e; sum += e; }
;             sum += __shfl_xor(sum, 16); sum += __shfl_xor(sum, 32);
;             const float inv = 1.0f / sum;
	v_max_f32_e32 v239, v239, v242
	v_mul_f32_e64 v242, -v239, v252
	v_mov_b32_e32 v243, v242
	v_pk_fma_f32 v[128:129], v[128:129], v[252:253], v[242:243]
	v_pk_fma_f32 v[130:131], v[130:131], v[252:253], v[242:243]
	v_pk_fma_f32 v[132:133], v[132:133], v[252:253], v[242:243]
	v_pk_fma_f32 v[134:135], v[134:135], v[252:253], v[242:243]
	v_pk_fma_f32 v[136:137], v[136:137], v[252:253], v[242:243]
	v_pk_fma_f32 v[138:139], v[138:139], v[252:253], v[242:243]
	v_pk_fma_f32 v[140:141], v[140:141], v[252:253], v[242:243]
	v_pk_fma_f32 v[142:143], v[142:143], v[252:253], v[242:243]
	v_pk_fma_f32 v[144:145], v[144:145], v[252:253], v[242:243]
	v_pk_fma_f32 v[146:147], v[146:147], v[252:253], v[242:243]
	v_pk_fma_f32 v[148:149], v[148:149], v[252:253], v[242:243]
	v_pk_fma_f32 v[150:151], v[150:151], v[252:253], v[242:243]
	v_pk_fma_f32 v[152:153], v[152:153], v[252:253], v[242:243]
	v_pk_fma_f32 v[154:155], v[154:155], v[252:253], v[242:243]
	v_pk_fma_f32 v[156:157], v[156:157], v[252:253], v[242:243]
	v_pk_fma_f32 v[158:159], v[158:159], v[252:253], v[242:243]
	v_pk_fma_f32 v[160:161], v[160:161], v[252:253], v[242:243]
	v_pk_fma_f32 v[162:163], v[162:163], v[252:253], v[242:243]
	v_pk_fma_f32 v[164:165], v[164:165], v[252:253], v[242:243]
	v_pk_fma_f32 v[166:167], v[166:167], v[252:253], v[242:243]
	v_pk_fma_f32 v[168:169], v[168:169], v[252:253], v[242:243]
	v_pk_fma_f32 v[170:171], v[170:171], v[252:253], v[242:243]
	v_pk_fma_f32 v[172:173], v[172:173], v[252:253], v[242:243]
	v_pk_fma_f32 v[174:175], v[174:175], v[252:253], v[242:243]
	v_pk_fma_f32 v[176:177], v[176:177], v[252:253], v[242:243]
	v_pk_fma_f32 v[178:179], v[178:179], v[252:253], v[242:243]
	v_pk_fma_f32 v[180:181], v[180:181], v[252:253], v[242:243]
	v_pk_fma_f32 v[182:183], v[182:183], v[252:253], v[242:243]
	v_pk_fma_f32 v[184:185], v[184:185], v[252:253], v[242:243]
	v_pk_fma_f32 v[186:187], v[186:187], v[252:253], v[242:243]
	v_pk_fma_f32 v[188:189], v[188:189], v[252:253], v[242:243]
	v_pk_fma_f32 v[190:191], v[190:191], v[252:253], v[242:243]
	v_exp_f32_e32 v128, v128
	v_exp_f32_e32 v129, v129
	v_exp_f32_e32 v130, v130
	v_exp_f32_e32 v131, v131
	v_exp_f32_e32 v132, v132
	v_exp_f32_e32 v133, v133
	v_exp_f32_e32 v134, v134
	v_exp_f32_e32 v135, v135
	v_exp_f32_e32 v136, v136
	v_exp_f32_e32 v137, v137
	v_exp_f32_e32 v138, v138
	v_exp_f32_e32 v139, v139
	v_exp_f32_e32 v140, v140
	v_exp_f32_e32 v141, v141
	v_exp_f32_e32 v142, v142
	v_exp_f32_e32 v143, v143
	v_exp_f32_e32 v144, v144
	v_exp_f32_e32 v145, v145
	v_exp_f32_e32 v146, v146
	v_exp_f32_e32 v147, v147
	v_exp_f32_e32 v148, v148
	v_exp_f32_e32 v149, v149
	v_exp_f32_e32 v150, v150
	v_exp_f32_e32 v151, v151
	v_exp_f32_e32 v152, v152
	v_exp_f32_e32 v153, v153
	v_exp_f32_e32 v154, v154
	v_exp_f32_e32 v155, v155
	v_exp_f32_e32 v156, v156
	v_exp_f32_e32 v157, v157
	v_exp_f32_e32 v158, v158
	v_exp_f32_e32 v159, v159
	v_exp_f32_e32 v160, v160
	v_exp_f32_e32 v161, v161
	v_exp_f32_e32 v162, v162
	v_exp_f32_e32 v163, v163
	v_exp_f32_e32 v164, v164
	v_exp_f32_e32 v165, v165
	v_exp_f32_e32 v166, v166
	v_exp_f32_e32 v167, v167
	v_exp_f32_e32 v168, v168
	v_exp_f32_e32 v169, v169
	v_exp_f32_e32 v170, v170
	v_exp_f32_e32 v171, v171
	v_exp_f32_e32 v172, v172
	v_exp_f32_e32 v173, v173
	v_exp_f32_e32 v174, v174
	v_exp_f32_e32 v175, v175
	v_exp_f32_e32 v176, v176
	v_exp_f32_e32 v177, v177
	v_exp_f32_e32 v178, v178
	v_exp_f32_e32 v179, v179
	v_exp_f32_e32 v180, v180
	v_exp_f32_e32 v181, v181
	v_exp_f32_e32 v182, v182
	v_exp_f32_e32 v183, v183
	v_exp_f32_e32 v184, v184
	v_exp_f32_e32 v185, v185
	v_exp_f32_e32 v186, v186
	v_exp_f32_e32 v187, v187
	v_exp_f32_e32 v188, v188
	v_exp_f32_e32 v189, v189
	v_exp_f32_e32 v190, v190
	v_exp_f32_e32 v191, v191
	s_nop 0
	v_pk_add_f32 v[244:245], v[128:129], v[130:131]
	v_pk_add_f32 v[246:247], v[132:133], v[134:135]
	v_pk_add_f32 v[244:245], v[244:245], v[136:137]
	v_pk_add_f32 v[246:247], v[246:247], v[138:139]
	v_pk_add_f32 v[244:245], v[244:245], v[140:141]
	v_pk_add_f32 v[246:247], v[246:247], v[142:143]
	v_pk_add_f32 v[244:245], v[244:245], v[144:145]
	v_pk_add_f32 v[246:247], v[246:247], v[146:147]
	v_pk_add_f32 v[244:245], v[244:245], v[148:149]
	v_pk_add_f32 v[246:247], v[246:247], v[150:151]
	v_pk_add_f32 v[244:245], v[244:245], v[152:153]
	v_pk_add_f32 v[246:247], v[246:247], v[154:155]
	v_pk_add_f32 v[244:245], v[244:245], v[156:157]
	v_pk_add_f32 v[246:247], v[246:247], v[158:159]
	v_pk_add_f32 v[244:245], v[244:245], v[160:161]
	v_pk_add_f32 v[246:247], v[246:247], v[162:163]
	v_pk_add_f32 v[244:245], v[244:245], v[164:165]
	v_pk_add_f32 v[246:247], v[246:247], v[166:167]
	v_pk_add_f32 v[244:245], v[244:245], v[168:169]
	v_pk_add_f32 v[246:247], v[246:247], v[170:171]
	v_pk_add_f32 v[244:245], v[244:245], v[172:173]
	v_pk_add_f32 v[246:247], v[246:247], v[174:175]
	v_pk_add_f32 v[244:245], v[244:245], v[176:177]
	v_pk_add_f32 v[246:247], v[246:247], v[178:179]
	v_pk_add_f32 v[244:245], v[244:245], v[180:181]
	v_pk_add_f32 v[246:247], v[246:247], v[182:183]
	v_pk_add_f32 v[244:245], v[244:245], v[184:185]
	v_pk_add_f32 v[246:247], v[246:247], v[186:187]
	v_pk_add_f32 v[244:245], v[244:245], v[188:189]
	v_pk_add_f32 v[246:247], v[246:247], v[190:191]
	v_pk_add_f32 v[244:245], v[244:245], v[246:247]
	v_add_f32_e32 v240, v244, v245
	ds_bpermute_b32 v242, v248, v240
	s_waitcnt lgkmcnt(0)
	v_add_f32_e32 v240, v240, v242
	ds_bpermute_b32 v242, v249, v240
	s_waitcnt lgkmcnt(0)
; __device__ __forceinline__ unsigned cvt_pk_bf16(float lo, float hi) { unsigned r; asm volatile("v_cvt_pk_bf16_f32 %0, %1, %2" : "=v"(r) : "v"(lo), "v"(hi)); return r; }
; __device__ __forceinline__ void nat_phase(const Params& p, float* ldsf, int wave0, int nwaves) {
;     ...
;             const float inv = 1.0f / sum;
;             f32x4 o[4];
; #pragma unroll
;             for (int mt = 0; mt < 4; ++mt) o[mt] = (f32x4){0.f, 0.f, 0.f, 0.f};
; #pragma unroll
;             for (int i = 0; i < 8; ++i) {
;                 u32x4 pw; pw.x = cvt_pk_bf16(sc[i][0][0] * inv, sc[i][0][1] * inv); pw.y = cvt_pk_bf16(sc[i][0][2] * inv, sc[i][0][3] * inv);
;                 pw.z = cvt_pk_bf16(sc[i][1][0] * inv, sc[i][1][1] * inv); pw.w = cvt_pk_bf16(sc[i][1][2] * inv, sc[i][1][3] * inv);
;                 const bf16x8 bp = __builtin_bit_cast(bf16x8, pw);
; #pragma unroll
;                 for (int mt = 0; mt < 4; ++mt) { const u16* vp = Vb + (size_t)(mt * 16 + l15) * SEQ + i * 64 + cs0 + lq * 8;
;                     o[mt] = __builtin_amdgcn_mfma_f32_16x16x32_bf16(*(const bf16x8*)vp, bp, o[mt], 0, 0, 0); }
;             }
	v_add_f32_e32 v240, v240, v242
	v_rcp_f32_e32 v242, v240
	s_nop 0
	v_mov_b32_e32 v243, v242
	v_pk_mul_f32 v[128:129], v[128:129], v[242:243]
	v_pk_mul_f32 v[130:131], v[130:131], v[242:243]
	v_pk_mul_f32 v[132:133], v[132:133], v[242:243]
	v_pk_mul_f32 v[134:135], v[134:135], v[242:243]
	v_pk_mul_f32 v[136:137], v[136:137], v[242:243]
	v_pk_mul_f32 v[138:139], v[138:139], v[242:243]
	v_pk_mul_f32 v[140:141], v[140:141], v[242:243]
	v_pk_mul_f32 v[142:143], v[142:143], v[242:243]
	v_pk_mul_f32 v[144:145], v[144:145], v[242:243]
	v_pk_mul_f32 v[146:147], v[146:147], v[242:243]
	v_pk_mul_f32 v[148:149], v[148:149], v[242:243]
	v_pk_mul_f32 v[150:151], v[150:151], v[242:243]
	v_pk_mul_f32 v[152:153], v[152:153], v[242:243]
	v_pk_mul_f32 v[154:155], v[154:155], v[242:243]
	v_pk_mul_f32 v[156:157], v[156:157], v[242:243]
	v_pk_mul_f32 v[158:159], v[158:159], v[242:243]
	v_pk_mul_f32 v[160:161], v[160:161], v[242:243]
	v_pk_mul_f32 v[162:163], v[162:163], v[242:243]
	v_pk_mul_f32 v[164:165], v[164:165], v[242:243]
	v_pk_mul_f32 v[166:167], v[166:167], v[242:243]
	v_pk_mul_f32 v[168:169], v[168:169], v[242:243]
	v_pk_mul_f32 v[170:171], v[170:171], v[242:243]
	v_pk_mul_f32 v[172:173], v[172:173], v[242:243]
	v_pk_mul_f32 v[174:175], v[174:175], v[242:243]
	v_pk_mul_f32 v[176:177], v[176:177], v[242:243]
	v_pk_mul_f32 v[178:179], v[178:179], v[242:243]
	v_pk_mul_f32 v[180:181], v[180:181], v[242:243]
	v_pk_mul_f32 v[182:183], v[182:183], v[242:243]
	v_pk_mul_f32 v[184:185], v[184:185], v[242:243]
	v_pk_mul_f32 v[186:187], v[186:187], v[242:243]
	v_pk_mul_f32 v[188:189], v[188:189], v[242:243]
	v_pk_mul_f32 v[190:191], v[190:191], v[242:243]
	v_cvt_pk_bf16_f32 v128, v128, v129
	v_cvt_pk_bf16_f32 v129, v130, v131
	v_cvt_pk_bf16_f32 v130, v132, v133
	v_cvt_pk_bf16_f32 v131, v134, v135
	v_cvt_pk_bf16_f32 v136, v136, v137
	v_cvt_pk_bf16_f32 v137, v138, v139
	v_cvt_pk_bf16_f32 v138, v140, v141
	v_cvt_pk_bf16_f32 v139, v142, v143
	v_cvt_pk_bf16_f32 v144, v144, v145
	v_cvt_pk_bf16_f32 v145, v146, v147
	v_cvt_pk_bf16_f32 v146, v148, v149
	v_cvt_pk_bf16_f32 v147, v150, v151
	v_cvt_pk_bf16_f32 v152, v152, v153
	v_cvt_pk_bf16_f32 v153, v154, v155
	v_cvt_pk_bf16_f32 v154, v156, v157
	v_cvt_pk_bf16_f32 v155, v158, v159
	v_cvt_pk_bf16_f32 v160, v160, v161
	v_cvt_pk_bf16_f32 v161, v162, v163
	v_cvt_pk_bf16_f32 v162, v164, v165
	v_cvt_pk_bf16_f32 v163, v166, v167
	v_cvt_pk_bf16_f32 v168, v168, v169
	v_cvt_pk_bf16_f32 v169, v170, v171
	v_cvt_pk_bf16_f32 v170, v172, v173
	v_cvt_pk_bf16_f32 v171, v174, v175
	v_cvt_pk_bf16_f32 v176, v176, v177
	v_cvt_pk_bf16_f32 v177, v178, v179
	v_cvt_pk_bf16_f32 v178, v180, v181
	v_cvt_pk_bf16_f32 v179, v182, v183
	v_cvt_pk_bf16_f32 v184, v184, v185
	v_cvt_pk_bf16_f32 v185, v186, v187
	v_cvt_pk_bf16_f32 v186, v188, v189
	v_cvt_pk_bf16_f32 v187, v190, v191
	buffer_load_dwordx4 v[32:35], v226, s[68:71], s84 offen offset:256
	s_waitcnt vmcnt(8)
	v_mfma_f32_16x16x32_bf16 v[200:203], v[0:3], v[128:131], 0
	buffer_load_dwordx4 v[36:39], v226, s[68:71], s85 offen offset:256
	s_waitcnt vmcnt(8)
	v_mfma_f32_16x16x32_bf16 v[204:207], v[4:7], v[128:131], 0
	buffer_load_dwordx4 v[40:43], v226, s[68:71], s86 offen offset:256
	s_waitcnt vmcnt(8)
	v_mfma_f32_16x16x32_bf16 v[208:211], v[8:11], v[128:131], 0
	buffer_load_dwordx4 v[44:47], v226, s[68:71], s87 offen offset:256
	s_waitcnt vmcnt(8)
	v_mfma_f32_16x16x32_bf16 v[212:215], v[12:15], v[128:131], 0
	buffer_load_dwordx4 v[48:51], v226, s[68:71], s84 offen offset:384
	s_waitcnt vmcnt(8)
	v_mfma_f32_16x16x32_bf16 v[200:203], v[16:19], v[136:139], v[200:203]
	buffer_load_dwordx4 v[52:55], v226, s[68:71], s85 offen offset:384
	s_waitcnt vmcnt(8)
	v_mfma_f32_16x16x32_bf16 v[204:207], v[20:23], v[136:139], v[204:207]
	buffer_load_dwordx4 v[56:59], v226, s[68:71], s86 offen offset:384
	s_waitcnt vmcnt(8)
	v_mfma_f32_16x16x32_bf16 v[208:211], v[24:27], v[136:139], v[208:211]
	buffer_load_dwordx4 v[60:63], v226, s[68:71], s87 offen offset:384
	s_waitcnt vmcnt(8)
	v_mfma_f32_16x16x32_bf16 v[212:215], v[28:31], v[136:139], v[212:215]
	buffer_load_dwordx4 v[64:67], v226, s[68:71], s84 offen offset:512
	s_waitcnt vmcnt(8)
	v_mfma_f32_16x16x32_bf16 v[200:203], v[32:35], v[144:147], v[200:203]
	buffer_load_dwordx4 v[68:71], v226, s[68:71], s85 offen offset:512
	s_waitcnt vmcnt(8)
	v_mfma_f32_16x16x32_bf16 v[204:207], v[36:39], v[144:147], v[204:207]
	buffer_load_dwordx4 v[72:75], v226, s[68:71], s86 offen offset:512
	s_waitcnt vmcnt(8)
	v_mfma_f32_16x16x32_bf16 v[208:211], v[40:43], v[144:147], v[208:211]
	buffer_load_dwordx4 v[76:79], v226, s[68:71], s87 offen offset:512
	s_waitcnt vmcnt(8)
	v_mfma_f32_16x16x32_bf16 v[212:215], v[44:47], v[144:147], v[212:215]
	buffer_load_dwordx4 v[80:83], v226, s[68:71], s84 offen offset:640
	s_waitcnt vmcnt(8)
	v_mfma_f32_16x16x32_bf16 v[200:203], v[48:51], v[152:155], v[200:203]
	buffer_load_dwordx4 v[84:87], v226, s[68:71], s85 offen offset:640
	s_waitcnt vmcnt(8)
	v_mfma_f32_16x16x32_bf16 v[204:207], v[52:55], v[152:155], v[204:207]
	buffer_load_dwordx4 v[88:91], v226, s[68:71], s86 offen offset:640
	s_waitcnt vmcnt(8)
	v_mfma_f32_16x16x32_bf16 v[208:211], v[56:59], v[152:155], v[208:211]
	buffer_load_dwordx4 v[92:95], v226, s[68:71], s87 offen offset:640
	s_waitcnt vmcnt(8)
	v_mfma_f32_16x16x32_bf16 v[212:215], v[60:63], v[152:155], v[212:215]
	buffer_load_dwordx4 v[96:99], v226, s[68:71], s84 offen offset:768
	s_waitcnt vmcnt(8)
	v_mfma_f32_16x16x32_bf16 v[200:203], v[64:67], v[160:163], v[200:203]
	buffer_load_dwordx4 v[100:103], v226, s[68:71], s85 offen offset:768
	s_waitcnt vmcnt(8)
; __device__ __forceinline__ float bflo(unsigned w) { return __uint_as_float(w << 16); }
; __device__ __forceinline__ float bfhi(unsigned w) { return __uint_as_float(w & 0xffff0000u); }
; __device__ __forceinline__ unsigned cvt_pk_bf16(float lo, float hi) { unsigned r; asm volatile("v_cvt_pk_bf16_f32 %0, %1, %2" : "=v"(r) : "v"(lo), "v"(hi)); return r; }
; __device__ __forceinline__ float sigmoidf_(float x) { return __builtin_amdgcn_rcpf(1.0f + __expf(-x)); }
; __device__ __forceinline__ void nat_phase(const Params& p, float* ldsf, int wave0, int nwaves) {
;     ...
;             const size_t tok = (size_t)(b * SEQ + r * 64 + c);
; #pragma unroll
;             for (int mt = 0; mt < 4; ++mt) { const int ch = h * 64 + mt * 16 + lq * 4; const u32x2 gw = *(const u32x2*)(Gn + tok * RW + ch);
;                 const float g0 = bflo(gw.x), g1 = bfhi(gw.x), g2 = bflo(gw.y), g3 = bfhi(gw.y);
;                 u32x2 w; w.x = cvt_pk_bf16(o[mt][0] * g0 * sigmoidf_(g0), o[mt][1] * g1 * sigmoidf_(g1)); w.y = cvt_pk_bf16(o[mt][2] * g2 * sigmoidf_(g2), o[mt][3] * g3 * sigmoidf_(g3));
;                 *(u32x2*)(MIX + tok * DM + 1024 + ch) = w; }
;         }
;     }
	v_mfma_f32_16x16x32_bf16 v[204:207], v[68:71], v[160:163], v[204:207]
	buffer_load_dwordx4 v[104:107], v226, s[68:71], s86 offen offset:768
	s_waitcnt vmcnt(8)
	v_mfma_f32_16x16x32_bf16 v[208:211], v[72:75], v[160:163], v[208:211]
	buffer_load_dwordx4 v[108:111], v226, s[68:71], s87 offen offset:768
	s_waitcnt vmcnt(8)
	v_mfma_f32_16x16x32_bf16 v[212:215], v[76:79], v[160:163], v[212:215]
	buffer_load_dwordx4 v[112:115], v226, s[68:71], s84 offen offset:896
	s_waitcnt vmcnt(8)
	v_mfma_f32_16x16x32_bf16 v[200:203], v[80:83], v[168:171], v[200:203]
	buffer_load_dwordx4 v[116:119], v226, s[68:71], s85 offen offset:896
	s_waitcnt vmcnt(8)
	v_mfma_f32_16x16x32_bf16 v[204:207], v[84:87], v[168:171], v[204:207]
	buffer_load_dwordx4 v[120:123], v226, s[68:71], s86 offen offset:896
	s_waitcnt vmcnt(8)
	v_mfma_f32_16x16x32_bf16 v[208:211], v[88:91], v[168:171], v[208:211]
	buffer_load_dwordx4 v[124:127], v226, s[68:71], s87 offen offset:896
	s_waitcnt vmcnt(8)
	v_mfma_f32_16x16x32_bf16 v[212:215], v[92:95], v[168:171], v[212:215]
	s_waitcnt vmcnt(7)
	v_mfma_f32_16x16x32_bf16 v[200:203], v[96:99], v[176:179], v[200:203]
	s_waitcnt vmcnt(6)
	v_mfma_f32_16x16x32_bf16 v[204:207], v[100:103], v[176:179], v[204:207]
	s_waitcnt vmcnt(5)
	v_mfma_f32_16x16x32_bf16 v[208:211], v[104:107], v[176:179], v[208:211]
	s_waitcnt vmcnt(4)
	v_mfma_f32_16x16x32_bf16 v[212:215], v[108:111], v[176:179], v[212:215]
	s_waitcnt vmcnt(3)
	v_mfma_f32_16x16x32_bf16 v[200:203], v[112:115], v[184:187], v[200:203]
	s_waitcnt vmcnt(2)
	v_mfma_f32_16x16x32_bf16 v[204:207], v[116:119], v[184:187], v[204:207]
	s_waitcnt vmcnt(1)
	v_mfma_f32_16x16x32_bf16 v[208:211], v[120:123], v[184:187], v[208:211]
	s_waitcnt vmcnt(0)
	v_mfma_f32_16x16x32_bf16 v[212:215], v[124:127], v[184:187], v[212:215]
	s_waitcnt vmcnt(0)
	v_lshlrev_b32_e32 v132, 16, v216
	v_and_b32_e32 v133, 0xffff0000, v216
	v_lshlrev_b32_e32 v134, 16, v217
	v_and_b32_e32 v135, 0xffff0000, v217
	v_lshlrev_b32_e32 v140, 16, v218
	v_and_b32_e32 v141, 0xffff0000, v218
	v_lshlrev_b32_e32 v142, 16, v219
	v_and_b32_e32 v143, 0xffff0000, v219
	v_lshlrev_b32_e32 v148, 16, v220
	v_and_b32_e32 v149, 0xffff0000, v220
	v_lshlrev_b32_e32 v150, 16, v221
	v_and_b32_e32 v151, 0xffff0000, v221
	v_lshlrev_b32_e32 v156, 16, v222
	v_and_b32_e32 v157, 0xffff0000, v222
	v_lshlrev_b32_e32 v158, 16, v223
	v_and_b32_e32 v159, 0xffff0000, v223
	v_mul_f32_e32 v164, 0xbfb8aa3b, v132
	v_mul_f32_e32 v165, 0xbfb8aa3b, v133
	v_mul_f32_e32 v166, 0xbfb8aa3b, v134
	v_mul_f32_e32 v167, 0xbfb8aa3b, v135
	v_mul_f32_e32 v172, 0xbfb8aa3b, v140
	v_mul_f32_e32 v173, 0xbfb8aa3b, v141
	v_mul_f32_e32 v174, 0xbfb8aa3b, v142
	v_mul_f32_e32 v175, 0xbfb8aa3b, v143
	v_mul_f32_e32 v180, 0xbfb8aa3b, v148
	v_mul_f32_e32 v181, 0xbfb8aa3b, v149
	v_mul_f32_e32 v182, 0xbfb8aa3b, v150
	v_mul_f32_e32 v183, 0xbfb8aa3b, v151
	v_mul_f32_e32 v188, 0xbfb8aa3b, v156
	v_mul_f32_e32 v189, 0xbfb8aa3b, v157
	v_mul_f32_e32 v190, 0xbfb8aa3b, v158
	v_mul_f32_e32 v191, 0xbfb8aa3b, v159
	v_exp_f32_e32 v164, v164
	v_exp_f32_e32 v165, v165
	v_exp_f32_e32 v166, v166
	v_exp_f32_e32 v167, v167
	v_exp_f32_e32 v172, v172
	v_exp_f32_e32 v173, v173
	v_exp_f32_e32 v174, v174
	v_exp_f32_e32 v175, v175
	v_exp_f32_e32 v180, v180
	v_exp_f32_e32 v181, v181
	v_exp_f32_e32 v182, v182
	v_exp_f32_e32 v183, v183
	v_exp_f32_e32 v188, v188
	v_exp_f32_e32 v189, v189
	v_exp_f32_e32 v190, v190
	v_exp_f32_e32 v191, v191
	s_nop 0
	v_add_f32_e32 v164, 1.0, v164
	v_add_f32_e32 v165, 1.0, v165
	v_add_f32_e32 v166, 1.0, v166
	v_add_f32_e32 v167, 1.0, v167
	v_add_f32_e32 v172, 1.0, v172
	v_add_f32_e32 v173, 1.0, v173
	v_add_f32_e32 v174, 1.0, v174
	v_add_f32_e32 v175, 1.0, v175
	v_add_f32_e32 v180, 1.0, v180
	v_add_f32_e32 v181, 1.0, v181
	v_add_f32_e32 v182, 1.0, v182
	v_add_f32_e32 v183, 1.0, v183
	v_add_f32_e32 v188, 1.0, v188
	v_add_f32_e32 v189, 1.0, v189
	v_add_f32_e32 v190, 1.0, v190
	v_add_f32_e32 v191, 1.0, v191
	v_rcp_f32_e32 v164, v164
	v_rcp_f32_e32 v165, v165
	v_rcp_f32_e32 v166, v166
	v_rcp_f32_e32 v167, v167
	v_rcp_f32_e32 v172, v172
	v_rcp_f32_e32 v173, v173
	v_rcp_f32_e32 v174, v174
	v_rcp_f32_e32 v175, v175
	v_rcp_f32_e32 v180, v180
	v_rcp_f32_e32 v181, v181
	v_rcp_f32_e32 v182, v182
	v_rcp_f32_e32 v183, v183
	v_rcp_f32_e32 v188, v188
	v_rcp_f32_e32 v189, v189
	v_rcp_f32_e32 v190, v190
	v_rcp_f32_e32 v191, v191
	s_nop 0
	v_mul_f32_e32 v200, v200, v132
	v_mul_f32_e32 v201, v201, v133
	v_mul_f32_e32 v202, v202, v134
	v_mul_f32_e32 v203, v203, v135
	v_mul_f32_e32 v204, v204, v140
	v_mul_f32_e32 v205, v205, v141
	v_mul_f32_e32 v206, v206, v142
	v_mul_f32_e32 v207, v207, v143
	v_mul_f32_e32 v208, v208, v148
	v_mul_f32_e32 v209, v209, v149
	v_mul_f32_e32 v210, v210, v150
	v_mul_f32_e32 v211, v211, v151
	v_mul_f32_e32 v212, v212, v156
	v_mul_f32_e32 v213, v213, v157
	v_mul_f32_e32 v214, v214, v158
	v_mul_f32_e32 v215, v215, v159
	v_mul_f32_e32 v200, v200, v164
	v_mul_f32_e32 v201, v201, v165
	v_mul_f32_e32 v202, v202, v166
	v_mul_f32_e32 v203, v203, v167
	v_mul_f32_e32 v204, v204, v172
	v_mul_f32_e32 v205, v205, v173
	v_mul_f32_e32 v206, v206, v174
	v_mul_f32_e32 v207, v207, v175
	v_mul_f32_e32 v208, v208, v180
	v_mul_f32_e32 v209, v209, v181
	v_mul_f32_e32 v210, v210, v182
	v_mul_f32_e32 v211, v211, v183
	v_mul_f32_e32 v212, v212, v188
	v_mul_f32_e32 v213, v213, v189
	v_mul_f32_e32 v214, v214, v190
	v_mul_f32_e32 v215, v215, v191
	v_cvt_pk_bf16_f32 v200, v200, v201
	v_cvt_pk_bf16_f32 v201, v202, v203
	v_cvt_pk_bf16_f32 v204, v204, v205
	v_cvt_pk_bf16_f32 v205, v206, v207
	v_cvt_pk_bf16_f32 v208, v208, v209
	v_cvt_pk_bf16_f32 v209, v210, v211
	v_cvt_pk_bf16_f32 v212, v212, v213
	v_cvt_pk_bf16_f32 v213, v214, v215
	s_lshl_b32 s84, s82, 12
	s_add_u32 s84, s84, s80
	buffer_store_dwordx2 v[200:201], v228, s[64:67], s84 offen offset:0
	buffer_store_dwordx2 v[204:205], v228, s[64:67], s84 offen offset:32
	buffer_store_dwordx2 v[208:209], v228, s[64:67], s84 offen offset:64
	buffer_store_dwordx2 v[212:213], v228, s[64:67], s84 offen offset:96
	s_add_u32 s16, s16, 1
	s_cmp_lt_u32 s16, 4
	s_cbranch_scc1 .Lmy_nat_qt
	s_add_i32 s0, s0, s81
	s_sub_u32 s81, s89, s81
	s_sub_u32 s88, s88, 1
	s_cmp_eq_u32 s88, 0
	s_cbranch_scc1 .Lmy_nat_end
	s_cmpk_lt_i32 s0, 0x2000
	s_cbranch_scc1 .Lmy_nat_item
; #define NEXT_ITEM() (MIX ? (int)__builtin_amdgcn_readfirstlane(lane == 0 ? __hip_atomic_fetch_add(qctr, 1u, __ATOMIC_RELAXED, __HIP_MEMORY_SCOPE_AGENT) : 0u) : item + (int)gridDim.x * 8)
; #define SB __builtin_amdgcn_sched_barrier(0)
; #define MKR(ptr) __builtin_amdgcn_make_buffer_rsrc((void*)(ptr), 0, 0x7fffffff, 0x00027000)
; #define TOUCH1(set) asm volatile("" :: "v"(set.w), "v"(set.a), "v"(set.b), "v"(set.kw), "v"(set.v))
; #define TOUCH1(set) asm volatile("" :: "v"(set.w), "v"(set.a), "v"(set.b))
; template <bool MIX> __device__ __forceinline__ void scan_pass1(const Params& p, int d, float* ldsf) {
;     const int lane = threadIdx.x & 63, wid = __builtin_amdgcn_readfirstlane(threadIdx.x >> 6); const unsigned lo16 = (lane & 15) * 16, lo2 = lane * 2;
;     const float* Wd = (const float*)(p.ws + O_KD); const float* Bd = (const float*)(p.ws + O_Y); const u16* KB = (const u16*)(p.ws + O_K); const float* A = (const float*)(p.ws + O_A);
;     const u16* V = (const u16*)(p.ws + O_V); float* PT = (float*)(p.ws + O_PT); float* SLT = (float*)(p.ws + O_SLT); const unsigned lo8 = (lane & 15) * 8;
;     constexpr int NS = 32 * (NC - 1);
;     unsigned* qctr = (unsigned*)(p.ws + O_BAR);
;     if (MIX && wid >= 4) nat_phase(p, ldsf, blockIdx.x * 4 + (wid - 4), gridDim.x * 4);
;     ...
;     for (int item = MIX ? NEXT_ITEM() : (int)(blockIdx.x * 8 + wid); item < 2 * NS; item = NEXT_ITEM()) {
;         const bool isP = item >= NS; const int idx = isP ? item - NS : item;
;         const int bh = idx / (NC - 1), c = idx - bh * (NC - 1), b = bh >> 4, h = bh & 15;
;         const int t0 = d ? (SEQ - 1 - c * LC) : c * LC;
;         const size_t off0 = ((size_t)(b * SEQ + t0)) * RW + h * 64; const long stp = d ? -(long)RW : (long)RW;
;         const unsigned ob4 = (unsigned)(off0 * 4), ob2 = (unsigned)(off0 * 2);
;         const f32x4 ka4 = *(const f32x4*)(p.k_a + h * 64 + (lane & 15) * 4), c04 = 1.0f - ka4;
;         float S[64]; int ln = lane; asm volatile("" : "+v"(ln));
;     ...
;         const __amdgpu_buffer_rsrc_t rW = MKR(Wd), rA = MKR(A), rB = MKR(Bd), rK = MKR(KB), rV = MKR(V);
;         if (!isP) {
; #pragma unroll
;             for (int i = 0; i < 64; ++i) S[i] = 0.f;
;     ...
;             In1 i0, i1; LD1(i0, 0);
; #pragma unroll 1
;             for (int s = 0; s < LC; s += 2) { TOUCH1(i0); SB; LD1(i1, s + 1); SB; ST1(i0); TOUCH1(i1); SB; LD1(i0, s + 2); SB; ST1(i1); }
.Lmy_nat_end:
.LBB0_555:
	s_mov_b64 exec, -1
	s_setprio 0
	v_readfirstlane_b32 s0, v254
	s_nop 3
	s_lshr_b32 s1, s0, 6
	s_lshl_b32 s0, s2, 3
	s_add_i32 s0, s1, s0
	s_mov_b32 s64, s56
	s_and_b32 s65, s57, 0xffff
	s_brev_b32 s66, -2
	s_mov_b32 s67, 0x27000
	s_mov_b32 s68, s54
	s_and_b32 s69, s55, 0xffff
	s_mov_b32 s70, s66
	s_mov_b32 s71, s67
	v_and_b32_e32 v212, 63, v254
	v_and_b32_e32 v213, 15, v254
	v_lshlrev_b32_e32 v204, 4, v213
	v_lshlrev_b32_e32 v205, 3, v213
	v_lshlrev_b32_e32 v206, 1, v212
	v_lshlrev_b32_e32 v207, 2, v212
	v_lshlrev_b32_e32 v210, 8, v212
	s_lshl_b32 s3, s1, 10
	s_add_u32 s3, s3, 0x10000
	v_add_u32_e32 v208, s3, v204
	v_and_b32_e32 v209, 3, v254
	v_lshlrev_b32_e32 v209, 2, v209
	v_add_u32_e32 v209, s3, v209
	v_mov_b32_e32 v213, 1.0
	v_mov_b32_e32 v214, 0
	v_mov_b32_e32 v215, 1
	s_mov_b64 exec, 1
	global_atomic_add v214, v214, v215, s[34:35] sc0
	s_mov_b64 exec, -1
	s_waitcnt vmcnt(0)
	s_nop 0
	v_readfirstlane_b32 s0, v214
	s_nop 3
.Lmy_p1d0_item:
	s_cmpk_gt_i32 s0, 0xfbf
	s_cbranch_scc1 .Lmy_p1d0_end
	s_cmpk_gt_i32 s0, 0x7df
	s_cselect_b32 s88, 1, 0
	s_cselect_b32 s6, 0x7e0, 0
	s_sub_u32 s6, s0, s6
	s_mul_i32 s86, s6, 2081
	s_lshr_b32 s86, s86, 17
	s_mul_i32 s7, s86, 63
	s_sub_u32 s85, s6, s7
	s_and_b32 s87, s86, 15
	s_lshr_b32 s6, s86, 4
	s_lshl_b32 s6, s6, 14
	s_lshl_b32 s7, s85, 8
	s_add_u32 s6, s6, s7
	s_lshl_b32 s6, s6, 10
	s_lshl_b32 s7, s87, 6
	s_add_u32 s84, s6, s7
	s_lshl_b32 s6, s84, 2
	s_lshl_b32 s7, s84, 1
	s_add_u32 s72, s6, 0xb800000
	s_add_u32 s73, s6, 0x24800000
	s_add_u32 s74, s6, 0x35a00000
	s_add_u32 s76, s7, 0x30800000
	s_add_u32 s77, s7, 0x2c800000
	s_lshl_b32 s6, s86, 6
	s_add_u32 s6, s6, s85
	s_lshl_b32 s6, s6, 14
	s_mov_b32 s7, 0x15800000
	s_cmp_eq_u32 s88, 1
	s_cselect_b32 s7, 0x13800000, s7
	s_add_u32 s6, s6, s7
	s_add_u32 s90, s56, s6
	s_addc_u32 s91, s57, 0
	s_cmp_eq_u32 s88, 1
	s_cbranch_scc1 .Lmy_p1d0_pitem
	s_lshl_b32 s8, s87, 8
	s_add_u32 s4, s42, s8
	s_addc_u32 s5, s43, 0
	global_load_dwordx4 v[188:191], v204, s[4:5]
	buffer_load_dwordx4 v[96:99], v204, s[64:67], s72 offen
	buffer_load_dwordx4 v[100:103], v204, s[64:67], s73 offen
	buffer_load_dwordx4 v[104:107], v204, s[64:67], s74 offen
	buffer_load_dwordx2 v[112:113], v205, s[64:67], s76 offen
	buffer_load_ushort v114, v206, s[64:67], s77 offen
	s_add_u32 s72, s72, 0x1000
	s_add_u32 s73, s73, 0x1000
	s_add_u32 s74, s74, 0x1000
	s_add_u32 s76, s76, 0x800
	s_add_u32 s77, s77, 0x800
	buffer_load_dwordx4 v[116:119], v204, s[64:67], s72 offen
	buffer_load_dwordx4 v[120:123], v204, s[64:67], s73 offen
	buffer_load_dwordx4 v[124:127], v204, s[64:67], s74 offen
	buffer_load_dwordx2 v[132:133], v205, s[64:67], s76 offen
	buffer_load_ushort v134, v206, s[64:67], s77 offen
	s_add_u32 s72, s72, 0x1000
	s_add_u32 s73, s73, 0x1000
	s_add_u32 s74, s74, 0x1000
	s_add_u32 s76, s76, 0x800
	s_add_u32 s77, s77, 0x800
	buffer_load_dwordx4 v[136:139], v204, s[64:67], s72 offen
	buffer_load_dwordx4 v[140:143], v204, s[64:67], s73 offen
	buffer_load_dwordx4 v[144:147], v204, s[64:67], s74 offen
	buffer_load_dwordx2 v[152:153], v205, s[64:67], s76 offen
	buffer_load_ushort v154, v206, s[64:67], s77 offen
	s_add_u32 s72, s72, 0x1000
	s_add_u32 s73, s73, 0x1000
	s_add_u32 s74, s74, 0x1000
	s_add_u32 s76, s76, 0x800
	s_add_u32 s77, s77, 0x800
	s_mov_b32 s80, 3
	v_mov_b32_e32 v0, 0
	v_mov_b32_e32 v1, 0
	v_mov_b32_e32 v2, 0
	v_mov_b32_e32 v3, 0
	v_mov_b32_e32 v4, 0
	v_mov_b32_e32 v5, 0
	v_mov_b32_e32 v6, 0
	v_mov_b32_e32 v7, 0
	v_mov_b32_e32 v8, 0
	v_mov_b32_e32 v9, 0
	v_mov_b32_e32 v10, 0
	v_mov_b32_e32 v11, 0
	v_mov_b32_e32 v12, 0
	v_mov_b32_e32 v13, 0
	v_mov_b32_e32 v14, 0
	v_mov_b32_e32 v15, 0
	v_mov_b32_e32 v16, 0
	v_mov_b32_e32 v17, 0
	v_mov_b32_e32 v18, 0
	v_mov_b32_e32 v19, 0
	v_mov_b32_e32 v20, 0
	v_mov_b32_e32 v21, 0
	v_mov_b32_e32 v22, 0
	v_mov_b32_e32 v23, 0
	v_mov_b32_e32 v24, 0
	v_mov_b32_e32 v25, 0
	v_mov_b32_e32 v26, 0
	v_mov_b32_e32 v27, 0
	v_mov_b32_e32 v28, 0
	v_mov_b32_e32 v29, 0
	v_mov_b32_e32 v30, 0
	v_mov_b32_e32 v31, 0
	v_mov_b32_e32 v32, 0
	v_mov_b32_e32 v33, 0
	v_mov_b32_e32 v34, 0
	v_mov_b32_e32 v35, 0
	v_mov_b32_e32 v36, 0
	v_mov_b32_e32 v37, 0
	v_mov_b32_e32 v38, 0
	v_mov_b32_e32 v39, 0
	v_mov_b32_e32 v40, 0
	v_mov_b32_e32 v41, 0
	v_mov_b32_e32 v42, 0
	v_mov_b32_e32 v43, 0
	v_mov_b32_e32 v44, 0
	v_mov_b32_e32 v45, 0
	v_mov_b32_e32 v46, 0
	v_mov_b32_e32 v47, 0
	v_mov_b32_e32 v48, 0
	v_mov_b32_e32 v49, 0
	v_mov_b32_e32 v50, 0
	v_mov_b32_e32 v51, 0
	v_mov_b32_e32 v52, 0
	v_mov_b32_e32 v53, 0
	v_mov_b32_e32 v54, 0
	v_mov_b32_e32 v55, 0
	v_mov_b32_e32 v56, 0
	v_mov_b32_e32 v57, 0
	v_mov_b32_e32 v58, 0
	v_mov_b32_e32 v59, 0
	v_mov_b32_e32 v60, 0
	v_mov_b32_e32 v61, 0
	v_mov_b32_e32 v62, 0
	v_mov_b32_e32 v63, 0
	s_waitcnt vmcnt(0)
	v_sub_f32_e32 v192, 1.0, v188
	v_sub_f32_e32 v193, 1.0, v189
	v_sub_f32_e32 v194, 1.0, v190
	v_sub_f32_e32 v195, 1.0, v191
	v_mov_b32_e32 v216, 1.0
	v_mov_b32_e32 v217, 1.0
	v_mov_b32_e32 v218, 1.0
	v_mov_b32_e32 v219, 1.0
	s_movk_i32 s83, 64
	s_branch .Lmy_p1d0_loop_s

; #define SB __builtin_amdgcn_sched_barrier(0)
; #define TOUCH1(set) asm volatile("" :: "v"(set.w), "v"(set.a), "v"(set.b), "v"(set.kw), "v"(set.v))
; #define ST1(set) { DERIVE_BK(set); float sd[4]; ScanK<0>::dot(S, set.a, sd); ScanK<0>::updS(S, set, -((sd[0] + sd[1]) + (sd[2] + sd[3])), __uint_as_float(set.v << 16)); }
; #define TOUCH1(set) asm volatile("" :: "v"(set.w), "v"(set.a), "v"(set.b))
;     static __device__ __forceinline__ void dot(const float (&S)[64], const f32x4& a, float (&s)[4]) {
;         if constexpr (K == 0) {
;             asm volatile("v_mul_f32_dpp %0, %4, %8 row_newbcast:%16" DPPM "v_mul_f32_dpp %1, %5, %9 row_newbcast:%16" DPPM "v_mul_f32_dpp %2, %6, %10 row_newbcast:%16" DPPM "v_mul_f32_dpp %3, %7, %11 row_newbcast:%16" DPPM
;                          "v_fmac_f32_dpp %0, %4, %12 row_newbcast:%17" DPPM "v_fmac_f32_dpp %1, %5, %13 row_newbcast:%17" DPPM "v_fmac_f32_dpp %2, %6, %14 row_newbcast:%17" DPPM "v_fmac_f32_dpp %3, %7, %15 row_newbcast:%17" DPPM
;                          : "=&v"(s[0]), "=&v"(s[1]), "=&v"(s[2]), "=&v"(s[3])
;                          : "v"(a[0]), "v"(a[1]), "v"(a[2]), "v"(a[3]), "v"(S[K]), "v"(S[K + 1]), "v"(S[K + 2]), "v"(S[K + 3]), "v"(S[K + 4]), "v"(S[K + 5]), "v"(S[K + 6]), "v"(S[K + 7]), "n"(N0), "n"(N1));
;         } else
;         asm volatile("v_fmac_f32_dpp %0, %4, %8 row_newbcast:%16" DPPM "v_fmac_f32_dpp %1, %5, %9 row_newbcast:%16" DPPM "v_fmac_f32_dpp %2, %6, %10 row_newbcast:%16" DPPM "v_fmac_f32_dpp %3, %7, %11 row_newbcast:%16" DPPM
;                      "v_fmac_f32_dpp %0, %4, %12 row_newbcast:%17" DPPM "v_fmac_f32_dpp %1, %5, %13 row_newbcast:%17" DPPM "v_fmac_f32_dpp %2, %6, %14 row_newbcast:%17" DPPM "v_fmac_f32_dpp %3, %7, %15 row_newbcast:%17" DPPM
;                      : "+v"(s[0]), "+v"(s[1]), "+v"(s[2]), "+v"(s[3])
;                      : "v"(a[0]), "v"(a[1]), "v"(a[2]), "v"(a[3]), "v"(S[K]), "v"(S[K + 1]), "v"(S[K + 2]), "v"(S[K + 3]), "v"(S[K + 4]), "v"(S[K + 5]), "v"(S[K + 6]), "v"(S[K + 7]), "n"(N0), "n"(N1));
;         if constexpr (K + 8 < 64) ScanK<K + 8>::dot(S, a, s);
;     }
; template <bool MIX> __device__ __forceinline__ void scan_pass1(const Params& p, int d, float* ldsf) {
;     ...
;             In1 i0, i1; LD1(i0, 0);
; #pragma unroll 1
;             for (int s = 0; s < LC; s += 2) { TOUCH1(i0); SB; LD1(i1, s + 1); SB; ST1(i0); TOUCH1(i1); SB; LD1(i0, s + 2); SB; ST1(i1); }
.Lmy_p1d0_loop_s:
	s_waitcnt vmcnt(10)
	buffer_load_dwordx4 v[156:159], v204, s[64:67], s72 offen
	buffer_load_dwordx4 v[160:163], v204, s[64:67], s73 offen
	buffer_load_dwordx4 v[164:167], v204, s[64:67], s74 offen
	buffer_load_dwordx2 v[172:173], v205, s[64:67], s76 offen
	buffer_load_ushort v174, v206, s[64:67], s77 offen
	s_cmp_lt_u32 s80, 255
	s_cselect_b32 s81, 0x1000, 0
	s_cselect_b32 s82, 0x800, 0
	s_cselect_b32 s9, 1, 0
	s_add_u32 s80, s80, s9
	s_add_u32 s72, s72, s81
	s_add_u32 s73, s73, s81
	s_add_u32 s74, s74, s81
	s_add_u32 s76, s76, s82
	s_add_u32 s77, s77, s82
	v_pk_mul_f32 v[224:225], v[100:101], v[216:217]
	v_pk_mul_f32 v[226:227], v[102:103], v[218:219]
	v_pk_mul_f32 v[216:217], v[216:217], v[96:97]
	v_pk_mul_f32 v[218:219], v[218:219], v[98:99]
	v_pk_fma_f32 v[184:185], v[104:105], v[188:189], v[192:193]
	v_pk_fma_f32 v[186:187], v[106:107], v[190:191], v[194:195]
	v_pk_mul_f32 v[176:177], v[100:101], v[104:105]
	v_pk_mul_f32 v[178:179], v[102:103], v[106:107]
	v_rcp_f32_e32 v220, v216
	v_rcp_f32_e32 v221, v217
	v_rcp_f32_e32 v222, v218
	v_rcp_f32_e32 v223, v219
	v_lshlrev_b32_e32 v180, 16, v112
	v_and_b32_e32 v181, 0xffff0000, v112
	v_lshlrev_b32_e32 v182, 16, v113
	v_and_b32_e32 v183, 0xffff0000, v113
	v_pk_mul_f32 v[180:181], v[180:181], v[184:185]
	v_pk_mul_f32 v[182:183], v[182:183], v[186:187]
	v_lshlrev_b32_e32 v203, 16, v114
	v_pk_mul_f32 v[176:177], v[176:177], v[220:221]
	v_pk_mul_f32 v[178:179], v[178:179], v[222:223]
	v_pk_mul_f32 v[180:181], v[180:181], v[220:221]
	v_pk_mul_f32 v[182:183], v[182:183], v[222:223]
	ds_write_b128 v208, v[176:179]
	ds_write_b128 v208, v[180:183] offset:256
	ds_read2_b32 v[64:65], v209 offset0:0 offset1:4
	ds_read2_b32 v[66:67], v209 offset0:8 offset1:12
	ds_read2_b32 v[68:69], v209 offset0:16 offset1:20
	ds_read2_b32 v[70:71], v209 offset0:24 offset1:28
	ds_read2_b32 v[72:73], v209 offset0:32 offset1:36
	ds_read2_b32 v[74:75], v209 offset0:40 offset1:44
	ds_read2_b32 v[76:77], v209 offset0:48 offset1:52
	ds_read2_b32 v[78:79], v209 offset0:56 offset1:60
	ds_read2_b32 v[80:81], v209 offset0:64 offset1:68
	ds_read2_b32 v[82:83], v209 offset0:72 offset1:76
	ds_read2_b32 v[84:85], v209 offset0:80 offset1:84
	ds_read2_b32 v[86:87], v209 offset0:88 offset1:92
	ds_read2_b32 v[88:89], v209 offset0:96 offset1:100
	ds_read2_b32 v[90:91], v209 offset0:104 offset1:108
	ds_read2_b32 v[92:93], v209 offset0:112 offset1:116
	ds_read2_b32 v[94:95], v209 offset0:120 offset1:124
	v_mul_f32_dpp v196, v224, v0 row_newbcast:0 row_mask:0xf bank_mask:0xf
	v_mul_f32_dpp v197, v225, v1 row_newbcast:0 row_mask:0xf bank_mask:0xf
	v_mul_f32_dpp v198, v226, v2 row_newbcast:0 row_mask:0xf bank_mask:0xf
	v_mul_f32_dpp v199, v227, v3 row_newbcast:0 row_mask:0xf bank_mask:0xf
	v_fmac_f32_dpp v196, v224, v4 row_newbcast:1 row_mask:0xf bank_mask:0xf
	v_fmac_f32_dpp v197, v225, v5 row_newbcast:1 row_mask:0xf bank_mask:0xf
	v_fmac_f32_dpp v198, v226, v6 row_newbcast:1 row_mask:0xf bank_mask:0xf
	v_fmac_f32_dpp v199, v227, v7 row_newbcast:1 row_mask:0xf bank_mask:0xf
	v_fmac_f32_dpp v196, v224, v8 row_newbcast:2 row_mask:0xf bank_mask:0xf
	v_fmac_f32_dpp v197, v225, v9 row_newbcast:2 row_mask:0xf bank_mask:0xf
	v_fmac_f32_dpp v198, v226, v10 row_newbcast:2 row_mask:0xf bank_mask:0xf
	v_fmac_f32_dpp v199, v227, v11 row_newbcast:2 row_mask:0xf bank_mask:0xf
	v_fmac_f32_dpp v196, v224, v12 row_newbcast:3 row_mask:0xf bank_mask:0xf
	v_fmac_f32_dpp v197, v225, v13 row_newbcast:3 row_mask:0xf bank_mask:0xf
	v_fmac_f32_dpp v198, v226, v14 row_newbcast:3 row_mask:0xf bank_mask:0xf
	v_fmac_f32_dpp v199, v227, v15 row_newbcast:3 row_mask:0xf bank_mask:0xf
	v_fmac_f32_dpp v196, v224, v16 row_newbcast:4 row_mask:0xf bank_mask:0xf
	v_fmac_f32_dpp v197, v225, v17 row_newbcast:4 row_mask:0xf bank_mask:0xf
	v_fmac_f32_dpp v198, v226, v18 row_newbcast:4 row_mask:0xf bank_mask:0xf
	v_fmac_f32_dpp v199, v227, v19 row_newbcast:4 row_mask:0xf bank_mask:0xf
	v_fmac_f32_dpp v196, v224, v20 row_newbcast:5 row_mask:0xf bank_mask:0xf
	v_fmac_f32_dpp v197, v225, v21 row_newbcast:5 row_mask:0xf bank_mask:0xf
	v_fmac_f32_dpp v198, v226, v22 row_newbcast:5 row_mask:0xf bank_mask:0xf
	v_fmac_f32_dpp v199, v227, v23 row_newbcast:5 row_mask:0xf bank_mask:0xf
	v_fmac_f32_dpp v196, v224, v24 row_newbcast:6 row_mask:0xf bank_mask:0xf
	v_fmac_f32_dpp v197, v225, v25 row_newbcast:6 row_mask:0xf bank_mask:0xf
	v_fmac_f32_dpp v198, v226, v26 row_newbcast:6 row_mask:0xf bank_mask:0xf
	v_fmac_f32_dpp v199, v227, v27 row_newbcast:6 row_mask:0xf bank_mask:0xf
	v_fmac_f32_dpp v196, v224, v28 row_newbcast:7 row_mask:0xf bank_mask:0xf
	v_fmac_f32_dpp v197, v225, v29 row_newbcast:7 row_mask:0xf bank_mask:0xf
	v_fmac_f32_dpp v198, v226, v30 row_newbcast:7 row_mask:0xf bank_mask:0xf
	v_fmac_f32_dpp v199, v227, v31 row_newbcast:7 row_mask:0xf bank_mask:0xf
	v_fmac_f32_dpp v196, v224, v32 row_newbcast:8 row_mask:0xf bank_mask:0xf
	v_fmac_f32_dpp v197, v225, v33 row_newbcast:8 row_mask:0xf bank_mask:0xf
	v_fmac_f32_dpp v198, v226, v34 row_newbcast:8 row_mask:0xf bank_mask:0xf
	v_fmac_f32_dpp v199, v227, v35 row_newbcast:8 row_mask:0xf bank_mask:0xf
	v_fmac_f32_dpp v196, v224, v36 row_newbcast:9 row_mask:0xf bank_mask:0xf
	v_fmac_f32_dpp v197, v225, v37 row_newbcast:9 row_mask:0xf bank_mask:0xf
	v_fmac_f32_dpp v198, v226, v38 row_newbcast:9 row_mask:0xf bank_mask:0xf
	v_fmac_f32_dpp v199, v227, v39 row_newbcast:9 row_mask:0xf bank_mask:0xf
	v_fmac_f32_dpp v196, v224, v40 row_newbcast:10 row_mask:0xf bank_mask:0xf
	v_fmac_f32_dpp v197, v225, v41 row_newbcast:10 row_mask:0xf bank_mask:0xf
	v_fmac_f32_dpp v198, v226, v42 row_newbcast:10 row_mask:0xf bank_mask:0xf
;     static __device__ __forceinline__ void dot(const float (&S)[64], const f32x4& a, float (&s)[4]) {
;         if constexpr (K == 0) {
;             asm volatile("v_mul_f32_dpp %0, %4, %8 row_newbcast:%16" DPPM "v_mul_f32_dpp %1, %5, %9 row_newbcast:%16" DPPM "v_mul_f32_dpp %2, %6, %10 row_newbcast:%16" DPPM "v_mul_f32_dpp %3, %7, %11 row_newbcast:%16" DPPM
;                          "v_fmac_f32_dpp %0, %4, %12 row_newbcast:%17" DPPM "v_fmac_f32_dpp %1, %5, %13 row_newbcast:%17" DPPM "v_fmac_f32_dpp %2, %6, %14 row_newbcast:%17" DPPM "v_fmac_f32_dpp %3, %7, %15 row_newbcast:%17" DPPM
;                          : "=&v"(s[0]), "=&v"(s[1]), "=&v"(s[2]), "=&v"(s[3])
;                          : "v"(a[0]), "v"(a[1]), "v"(a[2]), "v"(a[3]), "v"(S[K]), "v"(S[K + 1]), "v"(S[K + 2]), "v"(S[K + 3]), "v"(S[K + 4]), "v"(S[K + 5]), "v"(S[K + 6]), "v"(S[K + 7]), "n"(N0), "n"(N1));
;         } else
;         asm volatile("v_fmac_f32_dpp %0, %4, %8 row_newbcast:%16" DPPM "v_fmac_f32_dpp %1, %5, %9 row_newbcast:%16" DPPM "v_fmac_f32_dpp %2, %6, %10 row_newbcast:%16" DPPM "v_fmac_f32_dpp %3, %7, %11 row_newbcast:%16" DPPM
;                      "v_fmac_f32_dpp %0, %4, %12 row_newbcast:%17" DPPM "v_fmac_f32_dpp %1, %5, %13 row_newbcast:%17" DPPM "v_fmac_f32_dpp %2, %6, %14 row_newbcast:%17" DPPM "v_fmac_f32_dpp %3, %7, %15 row_newbcast:%17" DPPM
;                      : "+v"(s[0]), "+v"(s[1]), "+v"(s[2]), "+v"(s[3])
;                      : "v"(a[0]), "v"(a[1]), "v"(a[2]), "v"(a[3]), "v"(S[K]), "v"(S[K + 1]), "v"(S[K + 2]), "v"(S[K + 3]), "v"(S[K + 4]), "v"(S[K + 5]), "v"(S[K + 6]), "v"(S[K + 7]), "n"(N0), "n"(N1));
;         if constexpr (K + 8 < 64) ScanK<K + 8>::dot(S, a, s);
;     }
;     static __device__ __forceinline__ void upd(float (&S)[64], const In2& in, float sa, float vv, float& y0, float& y1) {
;         float t0, t1, t2, t3;
;         asm volatile("v_mul_f32_dpp %0, %10, %27 row_newbcast:%28" DPPM "v_mul_f32_dpp %1, %11, %27 row_newbcast:%28" DPPM "v_mul_f32_dpp %2, %12, %27 row_newbcast:%28" DPPM "v_mul_f32_dpp %3, %13, %27 row_newbcast:%28" DPPM
;                      "v_fmac_f32_dpp %0, %14, %6 row_newbcast:%28" DPPM "v_fmac_f32_dpp %1, %15, %7 row_newbcast:%28" DPPM "v_fmac_f32_dpp %2, %16, %8 row_newbcast:%28" DPPM "v_fmac_f32_dpp %3, %17, %9 row_newbcast:%28" DPPM
	v_fmac_f32_dpp v199, v227, v43 row_newbcast:10 row_mask:0xf bank_mask:0xf
	v_fmac_f32_dpp v196, v224, v44 row_newbcast:11 row_mask:0xf bank_mask:0xf
	v_fmac_f32_dpp v197, v225, v45 row_newbcast:11 row_mask:0xf bank_mask:0xf
	v_fmac_f32_dpp v198, v226, v46 row_newbcast:11 row_mask:0xf bank_mask:0xf
	v_fmac_f32_dpp v199, v227, v47 row_newbcast:11 row_mask:0xf bank_mask:0xf
	v_fmac_f32_dpp v196, v224, v48 row_newbcast:12 row_mask:0xf bank_mask:0xf
	v_fmac_f32_dpp v197, v225, v49 row_newbcast:12 row_mask:0xf bank_mask:0xf
	v_fmac_f32_dpp v198, v226, v50 row_newbcast:12 row_mask:0xf bank_mask:0xf
	v_fmac_f32_dpp v199, v227, v51 row_newbcast:12 row_mask:0xf bank_mask:0xf
	v_fmac_f32_dpp v196, v224, v52 row_newbcast:13 row_mask:0xf bank_mask:0xf
	v_fmac_f32_dpp v197, v225, v53 row_newbcast:13 row_mask:0xf bank_mask:0xf
	v_fmac_f32_dpp v198, v226, v54 row_newbcast:13 row_mask:0xf bank_mask:0xf
	v_fmac_f32_dpp v199, v227, v55 row_newbcast:13 row_mask:0xf bank_mask:0xf
	v_fmac_f32_dpp v196, v224, v56 row_newbcast:14 row_mask:0xf bank_mask:0xf
	v_fmac_f32_dpp v197, v225, v57 row_newbcast:14 row_mask:0xf bank_mask:0xf
	v_fmac_f32_dpp v198, v226, v58 row_newbcast:14 row_mask:0xf bank_mask:0xf
	v_fmac_f32_dpp v199, v227, v59 row_newbcast:14 row_mask:0xf bank_mask:0xf
	v_fmac_f32_dpp v196, v224, v60 row_newbcast:15 row_mask:0xf bank_mask:0xf
	v_fmac_f32_dpp v197, v225, v61 row_newbcast:15 row_mask:0xf bank_mask:0xf
	v_fmac_f32_dpp v198, v226, v62 row_newbcast:15 row_mask:0xf bank_mask:0xf
	v_fmac_f32_dpp v199, v227, v63 row_newbcast:15 row_mask:0xf bank_mask:0xf
	v_add_f32_e32 v196, v196, v197
	v_add_f32_e32 v198, v198, v199
	v_add_f32_e32 v196, v196, v198
	v_xor_b32_e32 v202, 0x80000000, v196
	s_waitcnt lgkmcnt(0)
	s_nop 1
	v_mfma_f32_4x4x1_16b_f32 v[0:3], v64, v202, v[0:3]
	v_mfma_f32_4x4x1_16b_f32 v[4:7], v65, v202, v[4:7]
	v_mfma_f32_4x4x1_16b_f32 v[8:11], v66, v202, v[8:11]
	v_mfma_f32_4x4x1_16b_f32 v[12:15], v67, v202, v[12:15]
	v_mfma_f32_4x4x1_16b_f32 v[16:19], v68, v202, v[16:19]
	v_mfma_f32_4x4x1_16b_f32 v[20:23], v69, v202, v[20:23]
	v_mfma_f32_4x4x1_16b_f32 v[24:27], v70, v202, v[24:27]
	v_mfma_f32_4x4x1_16b_f32 v[28:31], v71, v202, v[28:31]
	v_mfma_f32_4x4x1_16b_f32 v[32:35], v72, v202, v[32:35]
	v_mfma_f32_4x4x1_16b_f32 v[36:39], v73, v202, v[36:39]
	v_mfma_f32_4x4x1_16b_f32 v[40:43], v74, v202, v[40:43]
	v_mfma_f32_4x4x1_16b_f32 v[44:47], v75, v202, v[44:47]
	v_mfma_f32_4x4x1_16b_f32 v[48:51], v76, v202, v[48:51]
	v_mfma_f32_4x4x1_16b_f32 v[52:55], v77, v202, v[52:55]
	v_mfma_f32_4x4x1_16b_f32 v[56:59], v78, v202, v[56:59]
	v_mfma_f32_4x4x1_16b_f32 v[60:63], v79, v202, v[60:63]
	v_mfma_f32_4x4x1_16b_f32 v[0:3], v80, v203, v[0:3]
	v_mfma_f32_4x4x1_16b_f32 v[4:7], v81, v203, v[4:7]
	v_mfma_f32_4x4x1_16b_f32 v[8:11], v82, v203, v[8:11]
	v_mfma_f32_4x4x1_16b_f32 v[12:15], v83, v203, v[12:15]
	v_mfma_f32_4x4x1_16b_f32 v[16:19], v84, v203, v[16:19]
	v_mfma_f32_4x4x1_16b_f32 v[20:23], v85, v203, v[20:23]
	v_mfma_f32_4x4x1_16b_f32 v[24:27], v86, v203, v[24:27]
	v_mfma_f32_4x4x1_16b_f32 v[28:31], v87, v203, v[28:31]
	v_mfma_f32_4x4x1_16b_f32 v[32:35], v88, v203, v[32:35]
	v_mfma_f32_4x4x1_16b_f32 v[36:39], v89, v203, v[36:39]
	v_mfma_f32_4x4x1_16b_f32 v[40:43], v90, v203, v[40:43]
	v_mfma_f32_4x4x1_16b_f32 v[44:47], v91, v203, v[44:47]
	v_mfma_f32_4x4x1_16b_f32 v[48:51], v92, v203, v[48:51]
	v_mfma_f32_4x4x1_16b_f32 v[52:55], v93, v203, v[52:55]
	v_mfma_f32_4x4x1_16b_f32 v[56:59], v94, v203, v[56:59]
	v_mfma_f32_4x4x1_16b_f32 v[60:63], v95, v203, v[60:63]
	s_waitcnt vmcnt(10)
	buffer_load_dwordx4 v[96:99], v204, s[64:67], s72 offen
	buffer_load_dwordx4 v[100:103], v204, s[64:67], s73 offen
	buffer_load_dwordx4 v[104:107], v204, s[64:67], s74 offen
	buffer_load_dwordx2 v[112:113], v205, s[64:67], s76 offen
	buffer_load_ushort v114, v206, s[64:67], s77 offen
	s_cmp_lt_u32 s80, 255
	s_cselect_b32 s81, 0x1000, 0
	s_cselect_b32 s82, 0x800, 0
	s_cselect_b32 s9, 1, 0
	s_add_u32 s80, s80, s9
	s_add_u32 s72, s72, s81
	s_add_u32 s73, s73, s81
	s_add_u32 s74, s74, s81
	s_add_u32 s76, s76, s82
	s_add_u32 s77, s77, s82
	v_pk_mul_f32 v[224:225], v[120:121], v[216:217]
	v_pk_mul_f32 v[226:227], v[122:123], v[218:219]
	v_pk_mul_f32 v[216:217], v[216:217], v[116:117]
	v_pk_mul_f32 v[218:219], v[218:219], v[118:119]
	v_pk_fma_f32 v[184:185], v[124:125], v[188:189], v[192:193]
	v_pk_fma_f32 v[186:187], v[126:127], v[190:191], v[194:195]
	v_pk_mul_f32 v[176:177], v[120:121], v[124:125]
	v_pk_mul_f32 v[178:179], v[122:123], v[126:127]
	v_rcp_f32_e32 v220, v216
	v_rcp_f32_e32 v221, v217
	v_rcp_f32_e32 v222, v218
	v_rcp_f32_e32 v223, v219
	v_lshlrev_b32_e32 v180, 16, v132
	v_and_b32_e32 v181, 0xffff0000, v132
	v_lshlrev_b32_e32 v182, 16, v133
	v_and_b32_e32 v183, 0xffff0000, v133
	v_pk_mul_f32 v[180:181], v[180:181], v[184:185]
	v_pk_mul_f32 v[182:183], v[182:183], v[186:187]
	v_lshlrev_b32_e32 v203, 16, v134
	v_pk_mul_f32 v[176:177], v[176:177], v[220:221]
	v_pk_mul_f32 v[178:179], v[178:179], v[222:223]
	v_pk_mul_f32 v[180:181], v[180:181], v[220:221]
	v_pk_mul_f32 v[182:183], v[182:183], v[222:223]
	ds_write_b128 v208, v[176:179]
	ds_write_b128 v208, v[180:183] offset:256
	ds_read2_b32 v[64:65], v209 offset0:0 offset1:4
	ds_read2_b32 v[66:67], v209 offset0:8 offset1:12
	ds_read2_b32 v[68:69], v209 offset0:16 offset1:20
	ds_read2_b32 v[70:71], v209 offset0:24 offset1:28
	ds_read2_b32 v[72:73], v209 offset0:32 offset1:36
	ds_read2_b32 v[74:75], v209 offset0:40 offset1:44
	ds_read2_b32 v[76:77], v209 offset0:48 offset1:52
	ds_read2_b32 v[78:79], v209 offset0:56 offset1:60
	ds_read2_b32 v[80:81], v209 offset0:64 offset1:68
	ds_read2_b32 v[82:83], v209 offset0:72 offset1:76
;     static __device__ __forceinline__ void dot(const float (&S)[64], const f32x4& a, float (&s)[4]) {
;         if constexpr (K == 0) {
;             asm volatile("v_mul_f32_dpp %0, %4, %8 row_newbcast:%16" DPPM "v_mul_f32_dpp %1, %5, %9 row_newbcast:%16" DPPM "v_mul_f32_dpp %2, %6, %10 row_newbcast:%16" DPPM "v_mul_f32_dpp %3, %7, %11 row_newbcast:%16" DPPM
;                          "v_fmac_f32_dpp %0, %4, %12 row_newbcast:%17" DPPM "v_fmac_f32_dpp %1, %5, %13 row_newbcast:%17" DPPM "v_fmac_f32_dpp %2, %6, %14 row_newbcast:%17" DPPM "v_fmac_f32_dpp %3, %7, %15 row_newbcast:%17" DPPM
;                          : "=&v"(s[0]), "=&v"(s[1]), "=&v"(s[2]), "=&v"(s[3])
;                          : "v"(a[0]), "v"(a[1]), "v"(a[2]), "v"(a[3]), "v"(S[K]), "v"(S[K + 1]), "v"(S[K + 2]), "v"(S[K + 3]), "v"(S[K + 4]), "v"(S[K + 5]), "v"(S[K + 6]), "v"(S[K + 7]), "n"(N0), "n"(N1));
;         } else
;         asm volatile("v_fmac_f32_dpp %0, %4, %8 row_newbcast:%16" DPPM "v_fmac_f32_dpp %1, %5, %9 row_newbcast:%16" DPPM "v_fmac_f32_dpp %2, %6, %10 row_newbcast:%16" DPPM "v_fmac_f32_dpp %3, %7, %11 row_newbcast:%16" DPPM
;                      "v_fmac_f32_dpp %0, %4, %12 row_newbcast:%17" DPPM "v_fmac_f32_dpp %1, %5, %13 row_newbcast:%17" DPPM "v_fmac_f32_dpp %2, %6, %14 row_newbcast:%17" DPPM "v_fmac_f32_dpp %3, %7, %15 row_newbcast:%17" DPPM
;                      : "+v"(s[0]), "+v"(s[1]), "+v"(s[2]), "+v"(s[3])
;                      : "v"(a[0]), "v"(a[1]), "v"(a[2]), "v"(a[3]), "v"(S[K]), "v"(S[K + 1]), "v"(S[K + 2]), "v"(S[K + 3]), "v"(S[K + 4]), "v"(S[K + 5]), "v"(S[K + 6]), "v"(S[K + 7]), "n"(N0), "n"(N1));
;         if constexpr (K + 8 < 64) ScanK<K + 8>::dot(S, a, s);
;     }
	ds_read2_b32 v[84:85], v209 offset0:80 offset1:84
	ds_read2_b32 v[86:87], v209 offset0:88 offset1:92
	ds_read2_b32 v[88:89], v209 offset0:96 offset1:100
	ds_read2_b32 v[90:91], v209 offset0:104 offset1:108
	ds_read2_b32 v[92:93], v209 offset0:112 offset1:116
	ds_read2_b32 v[94:95], v209 offset0:120 offset1:124
	v_mul_f32_dpp v196, v224, v0 row_newbcast:0 row_mask:0xf bank_mask:0xf
	v_mul_f32_dpp v197, v225, v1 row_newbcast:0 row_mask:0xf bank_mask:0xf
	v_mul_f32_dpp v198, v226, v2 row_newbcast:0 row_mask:0xf bank_mask:0xf
	v_mul_f32_dpp v199, v227, v3 row_newbcast:0 row_mask:0xf bank_mask:0xf
	v_fmac_f32_dpp v196, v224, v4 row_newbcast:1 row_mask:0xf bank_mask:0xf
	v_fmac_f32_dpp v197, v225, v5 row_newbcast:1 row_mask:0xf bank_mask:0xf
	v_fmac_f32_dpp v198, v226, v6 row_newbcast:1 row_mask:0xf bank_mask:0xf
	v_fmac_f32_dpp v199, v227, v7 row_newbcast:1 row_mask:0xf bank_mask:0xf
	v_fmac_f32_dpp v196, v224, v8 row_newbcast:2 row_mask:0xf bank_mask:0xf
	v_fmac_f32_dpp v197, v225, v9 row_newbcast:2 row_mask:0xf bank_mask:0xf
	v_fmac_f32_dpp v198, v226, v10 row_newbcast:2 row_mask:0xf bank_mask:0xf
	v_fmac_f32_dpp v199, v227, v11 row_newbcast:2 row_mask:0xf bank_mask:0xf
	v_fmac_f32_dpp v196, v224, v12 row_newbcast:3 row_mask:0xf bank_mask:0xf
	v_fmac_f32_dpp v197, v225, v13 row_newbcast:3 row_mask:0xf bank_mask:0xf
	v_fmac_f32_dpp v198, v226, v14 row_newbcast:3 row_mask:0xf bank_mask:0xf
	v_fmac_f32_dpp v199, v227, v15 row_newbcast:3 row_mask:0xf bank_mask:0xf
	v_fmac_f32_dpp v196, v224, v16 row_newbcast:4 row_mask:0xf bank_mask:0xf
	v_fmac_f32_dpp v197, v225, v17 row_newbcast:4 row_mask:0xf bank_mask:0xf
	v_fmac_f32_dpp v198, v226, v18 row_newbcast:4 row_mask:0xf bank_mask:0xf
	v_fmac_f32_dpp v199, v227, v19 row_newbcast:4 row_mask:0xf bank_mask:0xf
	v_fmac_f32_dpp v196, v224, v20 row_newbcast:5 row_mask:0xf bank_mask:0xf
	v_fmac_f32_dpp v197, v225, v21 row_newbcast:5 row_mask:0xf bank_mask:0xf
	v_fmac_f32_dpp v198, v226, v22 row_newbcast:5 row_mask:0xf bank_mask:0xf
	v_fmac_f32_dpp v199, v227, v23 row_newbcast:5 row_mask:0xf bank_mask:0xf
	v_fmac_f32_dpp v196, v224, v24 row_newbcast:6 row_mask:0xf bank_mask:0xf
	v_fmac_f32_dpp v197, v225, v25 row_newbcast:6 row_mask:0xf bank_mask:0xf
	v_fmac_f32_dpp v198, v226, v26 row_newbcast:6 row_mask:0xf bank_mask:0xf
	v_fmac_f32_dpp v199, v227, v27 row_newbcast:6 row_mask:0xf bank_mask:0xf
	v_fmac_f32_dpp v196, v224, v28 row_newbcast:7 row_mask:0xf bank_mask:0xf
	v_fmac_f32_dpp v197, v225, v29 row_newbcast:7 row_mask:0xf bank_mask:0xf
	v_fmac_f32_dpp v198, v226, v30 row_newbcast:7 row_mask:0xf bank_mask:0xf
	v_fmac_f32_dpp v199, v227, v31 row_newbcast:7 row_mask:0xf bank_mask:0xf
	v_fmac_f32_dpp v196, v224, v32 row_newbcast:8 row_mask:0xf bank_mask:0xf
	v_fmac_f32_dpp v197, v225, v33 row_newbcast:8 row_mask:0xf bank_mask:0xf
	v_fmac_f32_dpp v198, v226, v34 row_newbcast:8 row_mask:0xf bank_mask:0xf
	v_fmac_f32_dpp v199, v227, v35 row_newbcast:8 row_mask:0xf bank_mask:0xf
	v_fmac_f32_dpp v196, v224, v36 row_newbcast:9 row_mask:0xf bank_mask:0xf
	v_fmac_f32_dpp v197, v225, v37 row_newbcast:9 row_mask:0xf bank_mask:0xf
	v_fmac_f32_dpp v198, v226, v38 row_newbcast:9 row_mask:0xf bank_mask:0xf
	v_fmac_f32_dpp v199, v227, v39 row_newbcast:9 row_mask:0xf bank_mask:0xf
	v_fmac_f32_dpp v196, v224, v40 row_newbcast:10 row_mask:0xf bank_mask:0xf
	v_fmac_f32_dpp v197, v225, v41 row_newbcast:10 row_mask:0xf bank_mask:0xf
	v_fmac_f32_dpp v198, v226, v42 row_newbcast:10 row_mask:0xf bank_mask:0xf
	v_fmac_f32_dpp v199, v227, v43 row_newbcast:10 row_mask:0xf bank_mask:0xf
	v_fmac_f32_dpp v196, v224, v44 row_newbcast:11 row_mask:0xf bank_mask:0xf
	v_fmac_f32_dpp v197, v225, v45 row_newbcast:11 row_mask:0xf bank_mask:0xf
	v_fmac_f32_dpp v198, v226, v46 row_newbcast:11 row_mask:0xf bank_mask:0xf
	v_fmac_f32_dpp v199, v227, v47 row_newbcast:11 row_mask:0xf bank_mask:0xf
	v_fmac_f32_dpp v196, v224, v48 row_newbcast:12 row_mask:0xf bank_mask:0xf
	v_fmac_f32_dpp v197, v225, v49 row_newbcast:12 row_mask:0xf bank_mask:0xf
	v_fmac_f32_dpp v198, v226, v50 row_newbcast:12 row_mask:0xf bank_mask:0xf
	v_fmac_f32_dpp v199, v227, v51 row_newbcast:12 row_mask:0xf bank_mask:0xf
	v_fmac_f32_dpp v196, v224, v52 row_newbcast:13 row_mask:0xf bank_mask:0xf
	v_fmac_f32_dpp v197, v225, v53 row_newbcast:13 row_mask:0xf bank_mask:0xf
	v_fmac_f32_dpp v198, v226, v54 row_newbcast:13 row_mask:0xf bank_mask:0xf
	v_fmac_f32_dpp v199, v227, v55 row_newbcast:13 row_mask:0xf bank_mask:0xf
	v_fmac_f32_dpp v196, v224, v56 row_newbcast:14 row_mask:0xf bank_mask:0xf
	v_fmac_f32_dpp v197, v225, v57 row_newbcast:14 row_mask:0xf bank_mask:0xf
	v_fmac_f32_dpp v198, v226, v58 row_newbcast:14 row_mask:0xf bank_mask:0xf
	v_fmac_f32_dpp v199, v227, v59 row_newbcast:14 row_mask:0xf bank_mask:0xf
	v_fmac_f32_dpp v196, v224, v60 row_newbcast:15 row_mask:0xf bank_mask:0xf
	v_fmac_f32_dpp v197, v225, v61 row_newbcast:15 row_mask:0xf bank_mask:0xf
	v_fmac_f32_dpp v198, v226, v62 row_newbcast:15 row_mask:0xf bank_mask:0xf
	v_fmac_f32_dpp v199, v227, v63 row_newbcast:15 row_mask:0xf bank_mask:0xf
	v_add_f32_e32 v196, v196, v197
	v_add_f32_e32 v198, v198, v199
	v_add_f32_e32 v196, v196, v198
	v_xor_b32_e32 v202, 0x80000000, v196
	s_waitcnt lgkmcnt(0)
;     static __device__ __forceinline__ void dot(const float (&S)[64], const f32x4& a, float (&s)[4]) {
;         if constexpr (K == 0) {
;             asm volatile("v_mul_f32_dpp %0, %4, %8 row_newbcast:%16" DPPM "v_mul_f32_dpp %1, %5, %9 row_newbcast:%16" DPPM "v_mul_f32_dpp %2, %6, %10 row_newbcast:%16" DPPM "v_mul_f32_dpp %3, %7, %11 row_newbcast:%16" DPPM
;                          "v_fmac_f32_dpp %0, %4, %12 row_newbcast:%17" DPPM "v_fmac_f32_dpp %1, %5, %13 row_newbcast:%17" DPPM "v_fmac_f32_dpp %2, %6, %14 row_newbcast:%17" DPPM "v_fmac_f32_dpp %3, %7, %15 row_newbcast:%17" DPPM
;                          : "=&v"(s[0]), "=&v"(s[1]), "=&v"(s[2]), "=&v"(s[3])
;                          : "v"(a[0]), "v"(a[1]), "v"(a[2]), "v"(a[3]), "v"(S[K]), "v"(S[K + 1]), "v"(S[K + 2]), "v"(S[K + 3]), "v"(S[K + 4]), "v"(S[K + 5]), "v"(S[K + 6]), "v"(S[K + 7]), "n"(N0), "n"(N1));
;         } else
;         asm volatile("v_fmac_f32_dpp %0, %4, %8 row_newbcast:%16" DPPM "v_fmac_f32_dpp %1, %5, %9 row_newbcast:%16" DPPM "v_fmac_f32_dpp %2, %6, %10 row_newbcast:%16" DPPM "v_fmac_f32_dpp %3, %7, %11 row_newbcast:%16" DPPM
;                      "v_fmac_f32_dpp %0, %4, %12 row_newbcast:%17" DPPM "v_fmac_f32_dpp %1, %5, %13 row_newbcast:%17" DPPM "v_fmac_f32_dpp %2, %6, %14 row_newbcast:%17" DPPM "v_fmac_f32_dpp %3, %7, %15 row_newbcast:%17" DPPM
;                      : "+v"(s[0]), "+v"(s[1]), "+v"(s[2]), "+v"(s[3])
;                      : "v"(a[0]), "v"(a[1]), "v"(a[2]), "v"(a[3]), "v"(S[K]), "v"(S[K + 1]), "v"(S[K + 2]), "v"(S[K + 3]), "v"(S[K + 4]), "v"(S[K + 5]), "v"(S[K + 6]), "v"(S[K + 7]), "n"(N0), "n"(N1));
;         if constexpr (K + 8 < 64) ScanK<K + 8>::dot(S, a, s);
;     }
;     static __device__ __forceinline__ void upd(float (&S)[64], const In2& in, float sa, float vv, float& y0, float& y1) {
;         float t0, t1, t2, t3;
;         asm volatile("v_mul_f32_dpp %0, %10, %27 row_newbcast:%28" DPPM "v_mul_f32_dpp %1, %11, %27 row_newbcast:%28" DPPM "v_mul_f32_dpp %2, %12, %27 row_newbcast:%28" DPPM "v_mul_f32_dpp %3, %13, %27 row_newbcast:%28" DPPM
;                      "v_fmac_f32_dpp %0, %14, %6 row_newbcast:%28" DPPM "v_fmac_f32_dpp %1, %15, %7 row_newbcast:%28" DPPM "v_fmac_f32_dpp %2, %16, %8 row_newbcast:%28" DPPM "v_fmac_f32_dpp %3, %17, %9 row_newbcast:%28" DPPM
	s_nop 1
	v_mfma_f32_4x4x1_16b_f32 v[0:3], v64, v202, v[0:3]
	v_mfma_f32_4x4x1_16b_f32 v[4:7], v65, v202, v[4:7]
	v_mfma_f32_4x4x1_16b_f32 v[8:11], v66, v202, v[8:11]
	v_mfma_f32_4x4x1_16b_f32 v[12:15], v67, v202, v[12:15]
	v_mfma_f32_4x4x1_16b_f32 v[16:19], v68, v202, v[16:19]
	v_mfma_f32_4x4x1_16b_f32 v[20:23], v69, v202, v[20:23]
	v_mfma_f32_4x4x1_16b_f32 v[24:27], v70, v202, v[24:27]
	v_mfma_f32_4x4x1_16b_f32 v[28:31], v71, v202, v[28:31]
	v_mfma_f32_4x4x1_16b_f32 v[32:35], v72, v202, v[32:35]
	v_mfma_f32_4x4x1_16b_f32 v[36:39], v73, v202, v[36:39]
	v_mfma_f32_4x4x1_16b_f32 v[40:43], v74, v202, v[40:43]
	v_mfma_f32_4x4x1_16b_f32 v[44:47], v75, v202, v[44:47]
	v_mfma_f32_4x4x1_16b_f32 v[48:51], v76, v202, v[48:51]
	v_mfma_f32_4x4x1_16b_f32 v[52:55], v77, v202, v[52:55]
	v_mfma_f32_4x4x1_16b_f32 v[56:59], v78, v202, v[56:59]
	v_mfma_f32_4x4x1_16b_f32 v[60:63], v79, v202, v[60:63]
	v_mfma_f32_4x4x1_16b_f32 v[0:3], v80, v203, v[0:3]
	v_mfma_f32_4x4x1_16b_f32 v[4:7], v81, v203, v[4:7]
	v_mfma_f32_4x4x1_16b_f32 v[8:11], v82, v203, v[8:11]
	v_mfma_f32_4x4x1_16b_f32 v[12:15], v83, v203, v[12:15]
	v_mfma_f32_4x4x1_16b_f32 v[16:19], v84, v203, v[16:19]
	v_mfma_f32_4x4x1_16b_f32 v[20:23], v85, v203, v[20:23]
	v_mfma_f32_4x4x1_16b_f32 v[24:27], v86, v203, v[24:27]
	v_mfma_f32_4x4x1_16b_f32 v[28:31], v87, v203, v[28:31]
	v_mfma_f32_4x4x1_16b_f32 v[32:35], v88, v203, v[32:35]
	v_mfma_f32_4x4x1_16b_f32 v[36:39], v89, v203, v[36:39]
	v_mfma_f32_4x4x1_16b_f32 v[40:43], v90, v203, v[40:43]
	v_mfma_f32_4x4x1_16b_f32 v[44:47], v91, v203, v[44:47]
	v_mfma_f32_4x4x1_16b_f32 v[48:51], v92, v203, v[48:51]
	v_mfma_f32_4x4x1_16b_f32 v[52:55], v93, v203, v[52:55]
	v_mfma_f32_4x4x1_16b_f32 v[56:59], v94, v203, v[56:59]
	v_mfma_f32_4x4x1_16b_f32 v[60:63], v95, v203, v[60:63]
	s_waitcnt vmcnt(10)
	buffer_load_dwordx4 v[116:119], v204, s[64:67], s72 offen
	buffer_load_dwordx4 v[120:123], v204, s[64:67], s73 offen
	buffer_load_dwordx4 v[124:127], v204, s[64:67], s74 offen
	buffer_load_dwordx2 v[132:133], v205, s[64:67], s76 offen
	buffer_load_ushort v134, v206, s[64:67], s77 offen
	s_cmp_lt_u32 s80, 255
	s_cselect_b32 s81, 0x1000, 0
	s_cselect_b32 s82, 0x800, 0
	s_cselect_b32 s9, 1, 0
	s_add_u32 s80, s80, s9
	s_add_u32 s72, s72, s81
	s_add_u32 s73, s73, s81
	s_add_u32 s74, s74, s81
	s_add_u32 s76, s76, s82
	s_add_u32 s77, s77, s82
	v_pk_mul_f32 v[224:225], v[140:141], v[216:217]
	v_pk_mul_f32 v[226:227], v[142:143], v[218:219]
	v_pk_mul_f32 v[216:217], v[216:217], v[136:137]
	v_pk_mul_f32 v[218:219], v[218:219], v[138:139]
	v_pk_fma_f32 v[184:185], v[144:145], v[188:189], v[192:193]
	v_pk_fma_f32 v[186:187], v[146:147], v[190:191], v[194:195]
	v_pk_mul_f32 v[176:177], v[140:141], v[144:145]
	v_pk_mul_f32 v[178:179], v[142:143], v[146:147]
	v_rcp_f32_e32 v220, v216
	v_rcp_f32_e32 v221, v217
	v_rcp_f32_e32 v222, v218
	v_rcp_f32_e32 v223, v219
	v_lshlrev_b32_e32 v180, 16, v152
	v_and_b32_e32 v181, 0xffff0000, v152
	v_lshlrev_b32_e32 v182, 16, v153
	v_and_b32_e32 v183, 0xffff0000, v153
	v_pk_mul_f32 v[180:181], v[180:181], v[184:185]
	v_pk_mul_f32 v[182:183], v[182:183], v[186:187]
	v_lshlrev_b32_e32 v203, 16, v154
	v_pk_mul_f32 v[176:177], v[176:177], v[220:221]
	v_pk_mul_f32 v[178:179], v[178:179], v[222:223]
	v_pk_mul_f32 v[180:181], v[180:181], v[220:221]
	v_pk_mul_f32 v[182:183], v[182:183], v[222:223]
	ds_write_b128 v208, v[176:179]
	ds_write_b128 v208, v[180:183] offset:256
	ds_read2_b32 v[64:65], v209 offset0:0 offset1:4
	ds_read2_b32 v[66:67], v209 offset0:8 offset1:12
	ds_read2_b32 v[68:69], v209 offset0:16 offset1:20
	ds_read2_b32 v[70:71], v209 offset0:24 offset1:28
	ds_read2_b32 v[72:73], v209 offset0:32 offset1:36
	ds_read2_b32 v[74:75], v209 offset0:40 offset1:44
	ds_read2_b32 v[76:77], v209 offset0:48 offset1:52
	ds_read2_b32 v[78:79], v209 offset0:56 offset1:60
	ds_read2_b32 v[80:81], v209 offset0:64 offset1:68
	ds_read2_b32 v[82:83], v209 offset0:72 offset1:76
	ds_read2_b32 v[84:85], v209 offset0:80 offset1:84
	ds_read2_b32 v[86:87], v209 offset0:88 offset1:92
	ds_read2_b32 v[88:89], v209 offset0:96 offset1:100
	ds_read2_b32 v[90:91], v209 offset0:104 offset1:108
	ds_read2_b32 v[92:93], v209 offset0:112 offset1:116
	ds_read2_b32 v[94:95], v209 offset0:120 offset1:124
	v_mul_f32_dpp v196, v224, v0 row_newbcast:0 row_mask:0xf bank_mask:0xf
	v_mul_f32_dpp v197, v225, v1 row_newbcast:0 row_mask:0xf bank_mask:0xf
	v_mul_f32_dpp v198, v226, v2 row_newbcast:0 row_mask:0xf bank_mask:0xf
	v_mul_f32_dpp v199, v227, v3 row_newbcast:0 row_mask:0xf bank_mask:0xf
	v_fmac_f32_dpp v196, v224, v4 row_newbcast:1 row_mask:0xf bank_mask:0xf
	v_fmac_f32_dpp v197, v225, v5 row_newbcast:1 row_mask:0xf bank_mask:0xf
	v_fmac_f32_dpp v198, v226, v6 row_newbcast:1 row_mask:0xf bank_mask:0xf
	v_fmac_f32_dpp v199, v227, v7 row_newbcast:1 row_mask:0xf bank_mask:0xf
	v_fmac_f32_dpp v196, v224, v8 row_newbcast:2 row_mask:0xf bank_mask:0xf
	v_fmac_f32_dpp v197, v225, v9 row_newbcast:2 row_mask:0xf bank_mask:0xf
	v_fmac_f32_dpp v198, v226, v10 row_newbcast:2 row_mask:0xf bank_mask:0xf
	v_fmac_f32_dpp v199, v227, v11 row_newbcast:2 row_mask:0xf bank_mask:0xf
	v_fmac_f32_dpp v196, v224, v12 row_newbcast:3 row_mask:0xf bank_mask:0xf
	v_fmac_f32_dpp v197, v225, v13 row_newbcast:3 row_mask:0xf bank_mask:0xf
	v_fmac_f32_dpp v198, v226, v14 row_newbcast:3 row_mask:0xf bank_mask:0xf
	v_fmac_f32_dpp v199, v227, v15 row_newbcast:3 row_mask:0xf bank_mask:0xf
	v_fmac_f32_dpp v196, v224, v16 row_newbcast:4 row_mask:0xf bank_mask:0xf
	v_fmac_f32_dpp v197, v225, v17 row_newbcast:4 row_mask:0xf bank_mask:0xf
	v_fmac_f32_dpp v198, v226, v18 row_newbcast:4 row_mask:0xf bank_mask:0xf
;     static __device__ __forceinline__ void dot(const float (&S)[64], const f32x4& a, float (&s)[4]) {
;         if constexpr (K == 0) {
;             asm volatile("v_mul_f32_dpp %0, %4, %8 row_newbcast:%16" DPPM "v_mul_f32_dpp %1, %5, %9 row_newbcast:%16" DPPM "v_mul_f32_dpp %2, %6, %10 row_newbcast:%16" DPPM "v_mul_f32_dpp %3, %7, %11 row_newbcast:%16" DPPM
;                          "v_fmac_f32_dpp %0, %4, %12 row_newbcast:%17" DPPM "v_fmac_f32_dpp %1, %5, %13 row_newbcast:%17" DPPM "v_fmac_f32_dpp %2, %6, %14 row_newbcast:%17" DPPM "v_fmac_f32_dpp %3, %7, %15 row_newbcast:%17" DPPM
;                          : "=&v"(s[0]), "=&v"(s[1]), "=&v"(s[2]), "=&v"(s[3])
;                          : "v"(a[0]), "v"(a[1]), "v"(a[2]), "v"(a[3]), "v"(S[K]), "v"(S[K + 1]), "v"(S[K + 2]), "v"(S[K + 3]), "v"(S[K + 4]), "v"(S[K + 5]), "v"(S[K + 6]), "v"(S[K + 7]), "n"(N0), "n"(N1));
;         } else
;         asm volatile("v_fmac_f32_dpp %0, %4, %8 row_newbcast:%16" DPPM "v_fmac_f32_dpp %1, %5, %9 row_newbcast:%16" DPPM "v_fmac_f32_dpp %2, %6, %10 row_newbcast:%16" DPPM "v_fmac_f32_dpp %3, %7, %11 row_newbcast:%16" DPPM
;                      "v_fmac_f32_dpp %0, %4, %12 row_newbcast:%17" DPPM "v_fmac_f32_dpp %1, %5, %13 row_newbcast:%17" DPPM "v_fmac_f32_dpp %2, %6, %14 row_newbcast:%17" DPPM "v_fmac_f32_dpp %3, %7, %15 row_newbcast:%17" DPPM
;                      : "+v"(s[0]), "+v"(s[1]), "+v"(s[2]), "+v"(s[3])
;                      : "v"(a[0]), "v"(a[1]), "v"(a[2]), "v"(a[3]), "v"(S[K]), "v"(S[K + 1]), "v"(S[K + 2]), "v"(S[K + 3]), "v"(S[K + 4]), "v"(S[K + 5]), "v"(S[K + 6]), "v"(S[K + 7]), "n"(N0), "n"(N1));
;         if constexpr (K + 8 < 64) ScanK<K + 8>::dot(S, a, s);
;     }
;     static __device__ __forceinline__ void upd(float (&S)[64], const In2& in, float sa, float vv, float& y0, float& y1) {
;         float t0, t1, t2, t3;
;         asm volatile("v_mul_f32_dpp %0, %10, %27 row_newbcast:%28" DPPM "v_mul_f32_dpp %1, %11, %27 row_newbcast:%28" DPPM "v_mul_f32_dpp %2, %12, %27 row_newbcast:%28" DPPM "v_mul_f32_dpp %3, %13, %27 row_newbcast:%28" DPPM
;                      "v_fmac_f32_dpp %0, %14, %6 row_newbcast:%28" DPPM "v_fmac_f32_dpp %1, %15, %7 row_newbcast:%28" DPPM "v_fmac_f32_dpp %2, %16, %8 row_newbcast:%28" DPPM "v_fmac_f32_dpp %3, %17, %9 row_newbcast:%28" DPPM
	v_fmac_f32_dpp v199, v227, v19 row_newbcast:4 row_mask:0xf bank_mask:0xf
	v_fmac_f32_dpp v196, v224, v20 row_newbcast:5 row_mask:0xf bank_mask:0xf
	v_fmac_f32_dpp v197, v225, v21 row_newbcast:5 row_mask:0xf bank_mask:0xf
	v_fmac_f32_dpp v198, v226, v22 row_newbcast:5 row_mask:0xf bank_mask:0xf
	v_fmac_f32_dpp v199, v227, v23 row_newbcast:5 row_mask:0xf bank_mask:0xf
	v_fmac_f32_dpp v196, v224, v24 row_newbcast:6 row_mask:0xf bank_mask:0xf
	v_fmac_f32_dpp v197, v225, v25 row_newbcast:6 row_mask:0xf bank_mask:0xf
	v_fmac_f32_dpp v198, v226, v26 row_newbcast:6 row_mask:0xf bank_mask:0xf
	v_fmac_f32_dpp v199, v227, v27 row_newbcast:6 row_mask:0xf bank_mask:0xf
	v_fmac_f32_dpp v196, v224, v28 row_newbcast:7 row_mask:0xf bank_mask:0xf
	v_fmac_f32_dpp v197, v225, v29 row_newbcast:7 row_mask:0xf bank_mask:0xf
	v_fmac_f32_dpp v198, v226, v30 row_newbcast:7 row_mask:0xf bank_mask:0xf
	v_fmac_f32_dpp v199, v227, v31 row_newbcast:7 row_mask:0xf bank_mask:0xf
	v_fmac_f32_dpp v196, v224, v32 row_newbcast:8 row_mask:0xf bank_mask:0xf
	v_fmac_f32_dpp v197, v225, v33 row_newbcast:8 row_mask:0xf bank_mask:0xf
	v_fmac_f32_dpp v198, v226, v34 row_newbcast:8 row_mask:0xf bank_mask:0xf
	v_fmac_f32_dpp v199, v227, v35 row_newbcast:8 row_mask:0xf bank_mask:0xf
	v_fmac_f32_dpp v196, v224, v36 row_newbcast:9 row_mask:0xf bank_mask:0xf
	v_fmac_f32_dpp v197, v225, v37 row_newbcast:9 row_mask:0xf bank_mask:0xf
	v_fmac_f32_dpp v198, v226, v38 row_newbcast:9 row_mask:0xf bank_mask:0xf
	v_fmac_f32_dpp v199, v227, v39 row_newbcast:9 row_mask:0xf bank_mask:0xf
	v_fmac_f32_dpp v196, v224, v40 row_newbcast:10 row_mask:0xf bank_mask:0xf
	v_fmac_f32_dpp v197, v225, v41 row_newbcast:10 row_mask:0xf bank_mask:0xf
	v_fmac_f32_dpp v198, v226, v42 row_newbcast:10 row_mask:0xf bank_mask:0xf
	v_fmac_f32_dpp v199, v227, v43 row_newbcast:10 row_mask:0xf bank_mask:0xf
	v_fmac_f32_dpp v196, v224, v44 row_newbcast:11 row_mask:0xf bank_mask:0xf
	v_fmac_f32_dpp v197, v225, v45 row_newbcast:11 row_mask:0xf bank_mask:0xf
	v_fmac_f32_dpp v198, v226, v46 row_newbcast:11 row_mask:0xf bank_mask:0xf
	v_fmac_f32_dpp v199, v227, v47 row_newbcast:11 row_mask:0xf bank_mask:0xf
	v_fmac_f32_dpp v196, v224, v48 row_newbcast:12 row_mask:0xf bank_mask:0xf
	v_fmac_f32_dpp v197, v225, v49 row_newbcast:12 row_mask:0xf bank_mask:0xf
	v_fmac_f32_dpp v198, v226, v50 row_newbcast:12 row_mask:0xf bank_mask:0xf
	v_fmac_f32_dpp v199, v227, v51 row_newbcast:12 row_mask:0xf bank_mask:0xf
	v_fmac_f32_dpp v196, v224, v52 row_newbcast:13 row_mask:0xf bank_mask:0xf
	v_fmac_f32_dpp v197, v225, v53 row_newbcast:13 row_mask:0xf bank_mask:0xf
	v_fmac_f32_dpp v198, v226, v54 row_newbcast:13 row_mask:0xf bank_mask:0xf
	v_fmac_f32_dpp v199, v227, v55 row_newbcast:13 row_mask:0xf bank_mask:0xf
	v_fmac_f32_dpp v196, v224, v56 row_newbcast:14 row_mask:0xf bank_mask:0xf
	v_fmac_f32_dpp v197, v225, v57 row_newbcast:14 row_mask:0xf bank_mask:0xf
	v_fmac_f32_dpp v198, v226, v58 row_newbcast:14 row_mask:0xf bank_mask:0xf
	v_fmac_f32_dpp v199, v227, v59 row_newbcast:14 row_mask:0xf bank_mask:0xf
	v_fmac_f32_dpp v196, v224, v60 row_newbcast:15 row_mask:0xf bank_mask:0xf
	v_fmac_f32_dpp v197, v225, v61 row_newbcast:15 row_mask:0xf bank_mask:0xf
	v_fmac_f32_dpp v198, v226, v62 row_newbcast:15 row_mask:0xf bank_mask:0xf
	v_fmac_f32_dpp v199, v227, v63 row_newbcast:15 row_mask:0xf bank_mask:0xf
	v_add_f32_e32 v196, v196, v197
	v_add_f32_e32 v198, v198, v199
	v_add_f32_e32 v196, v196, v198
	v_xor_b32_e32 v202, 0x80000000, v196
	s_waitcnt lgkmcnt(0)
	s_nop 1
	v_mfma_f32_4x4x1_16b_f32 v[0:3], v64, v202, v[0:3]
	v_mfma_f32_4x4x1_16b_f32 v[4:7], v65, v202, v[4:7]
	v_mfma_f32_4x4x1_16b_f32 v[8:11], v66, v202, v[8:11]
	v_mfma_f32_4x4x1_16b_f32 v[12:15], v67, v202, v[12:15]
	v_mfma_f32_4x4x1_16b_f32 v[16:19], v68, v202, v[16:19]
	v_mfma_f32_4x4x1_16b_f32 v[20:23], v69, v202, v[20:23]
	v_mfma_f32_4x4x1_16b_f32 v[24:27], v70, v202, v[24:27]
	v_mfma_f32_4x4x1_16b_f32 v[28:31], v71, v202, v[28:31]
	v_mfma_f32_4x4x1_16b_f32 v[32:35], v72, v202, v[32:35]
	v_mfma_f32_4x4x1_16b_f32 v[36:39], v73, v202, v[36:39]
	v_mfma_f32_4x4x1_16b_f32 v[40:43], v74, v202, v[40:43]
	v_mfma_f32_4x4x1_16b_f32 v[44:47], v75, v202, v[44:47]
	v_mfma_f32_4x4x1_16b_f32 v[48:51], v76, v202, v[48:51]
	v_mfma_f32_4x4x1_16b_f32 v[52:55], v77, v202, v[52:55]
	v_mfma_f32_4x4x1_16b_f32 v[56:59], v78, v202, v[56:59]
	v_mfma_f32_4x4x1_16b_f32 v[60:63], v79, v202, v[60:63]
	v_mfma_f32_4x4x1_16b_f32 v[0:3], v80, v203, v[0:3]
	v_mfma_f32_4x4x1_16b_f32 v[4:7], v81, v203, v[4:7]
	v_mfma_f32_4x4x1_16b_f32 v[8:11], v82, v203, v[8:11]
	v_mfma_f32_4x4x1_16b_f32 v[12:15], v83, v203, v[12:15]
	v_mfma_f32_4x4x1_16b_f32 v[16:19], v84, v203, v[16:19]
	v_mfma_f32_4x4x1_16b_f32 v[20:23], v85, v203, v[20:23]
	v_mfma_f32_4x4x1_16b_f32 v[24:27], v86, v203, v[24:27]
	v_mfma_f32_4x4x1_16b_f32 v[28:31], v87, v203, v[28:31]
	v_mfma_f32_4x4x1_16b_f32 v[32:35], v88, v203, v[32:35]
	v_mfma_f32_4x4x1_16b_f32 v[36:39], v89, v203, v[36:39]
	v_mfma_f32_4x4x1_16b_f32 v[40:43], v90, v203, v[40:43]
	v_mfma_f32_4x4x1_16b_f32 v[44:47], v91, v203, v[44:47]
	v_mfma_f32_4x4x1_16b_f32 v[48:51], v92, v203, v[48:51]
	v_mfma_f32_4x4x1_16b_f32 v[52:55], v93, v203, v[52:55]
	v_mfma_f32_4x4x1_16b_f32 v[56:59], v94, v203, v[56:59]
	v_mfma_f32_4x4x1_16b_f32 v[60:63], v95, v203, v[60:63]
	s_waitcnt vmcnt(10)
;     static __device__ __forceinline__ void dot(const float (&S)[64], const f32x4& a, float (&s)[4]) {
;         if constexpr (K == 0) {
;             asm volatile("v_mul_f32_dpp %0, %4, %8 row_newbcast:%16" DPPM "v_mul_f32_dpp %1, %5, %9 row_newbcast:%16" DPPM "v_mul_f32_dpp %2, %6, %10 row_newbcast:%16" DPPM "v_mul_f32_dpp %3, %7, %11 row_newbcast:%16" DPPM
;                          "v_fmac_f32_dpp %0, %4, %12 row_newbcast:%17" DPPM "v_fmac_f32_dpp %1, %5, %13 row_newbcast:%17" DPPM "v_fmac_f32_dpp %2, %6, %14 row_newbcast:%17" DPPM "v_fmac_f32_dpp %3, %7, %15 row_newbcast:%17" DPPM
;                          : "=&v"(s[0]), "=&v"(s[1]), "=&v"(s[2]), "=&v"(s[3])
;                          : "v"(a[0]), "v"(a[1]), "v"(a[2]), "v"(a[3]), "v"(S[K]), "v"(S[K + 1]), "v"(S[K + 2]), "v"(S[K + 3]), "v"(S[K + 4]), "v"(S[K + 5]), "v"(S[K + 6]), "v"(S[K + 7]), "n"(N0), "n"(N1));
;         } else
;         asm volatile("v_fmac_f32_dpp %0, %4, %8 row_newbcast:%16" DPPM "v_fmac_f32_dpp %1, %5, %9 row_newbcast:%16" DPPM "v_fmac_f32_dpp %2, %6, %10 row_newbcast:%16" DPPM "v_fmac_f32_dpp %3, %7, %11 row_newbcast:%16" DPPM
;                      "v_fmac_f32_dpp %0, %4, %12 row_newbcast:%17" DPPM "v_fmac_f32_dpp %1, %5, %13 row_newbcast:%17" DPPM "v_fmac_f32_dpp %2, %6, %14 row_newbcast:%17" DPPM "v_fmac_f32_dpp %3, %7, %15 row_newbcast:%17" DPPM
;                      : "+v"(s[0]), "+v"(s[1]), "+v"(s[2]), "+v"(s[3])
;                      : "v"(a[0]), "v"(a[1]), "v"(a[2]), "v"(a[3]), "v"(S[K]), "v"(S[K + 1]), "v"(S[K + 2]), "v"(S[K + 3]), "v"(S[K + 4]), "v"(S[K + 5]), "v"(S[K + 6]), "v"(S[K + 7]), "n"(N0), "n"(N1));
;         if constexpr (K + 8 < 64) ScanK<K + 8>::dot(S, a, s);
;     }
;     static __device__ __forceinline__ void upd(float (&S)[64], const In2& in, float sa, float vv, float& y0, float& y1) {
;         float t0, t1, t2, t3;
;         asm volatile("v_mul_f32_dpp %0, %10, %27 row_newbcast:%28" DPPM "v_mul_f32_dpp %1, %11, %27 row_newbcast:%28" DPPM "v_mul_f32_dpp %2, %12, %27 row_newbcast:%28" DPPM "v_mul_f32_dpp %3, %13, %27 row_newbcast:%28" DPPM
;                      "v_fmac_f32_dpp %0, %14, %6 row_newbcast:%28" DPPM "v_fmac_f32_dpp %1, %15, %7 row_newbcast:%28" DPPM "v_fmac_f32_dpp %2, %16, %8 row_newbcast:%28" DPPM "v_fmac_f32_dpp %3, %17, %9 row_newbcast:%28" DPPM
	buffer_load_dwordx4 v[136:139], v204, s[64:67], s72 offen
	buffer_load_dwordx4 v[140:143], v204, s[64:67], s73 offen
	buffer_load_dwordx4 v[144:147], v204, s[64:67], s74 offen
	buffer_load_dwordx2 v[152:153], v205, s[64:67], s76 offen
	buffer_load_ushort v154, v206, s[64:67], s77 offen
	s_cmp_lt_u32 s80, 255
	s_cselect_b32 s81, 0x1000, 0
	s_cselect_b32 s82, 0x800, 0
	s_cselect_b32 s9, 1, 0
	s_add_u32 s80, s80, s9
	s_add_u32 s72, s72, s81
	s_add_u32 s73, s73, s81
	s_add_u32 s74, s74, s81
	s_add_u32 s76, s76, s82
	s_add_u32 s77, s77, s82
	v_pk_mul_f32 v[224:225], v[160:161], v[216:217]
	v_pk_mul_f32 v[226:227], v[162:163], v[218:219]
	v_pk_mul_f32 v[216:217], v[216:217], v[156:157]
	v_pk_mul_f32 v[218:219], v[218:219], v[158:159]
	v_pk_fma_f32 v[184:185], v[164:165], v[188:189], v[192:193]
	v_pk_fma_f32 v[186:187], v[166:167], v[190:191], v[194:195]
	v_pk_mul_f32 v[176:177], v[160:161], v[164:165]
	v_pk_mul_f32 v[178:179], v[162:163], v[166:167]
	v_rcp_f32_e32 v220, v216
	v_rcp_f32_e32 v221, v217
	v_rcp_f32_e32 v222, v218
	v_rcp_f32_e32 v223, v219
	v_lshlrev_b32_e32 v180, 16, v172
	v_and_b32_e32 v181, 0xffff0000, v172
	v_lshlrev_b32_e32 v182, 16, v173
	v_and_b32_e32 v183, 0xffff0000, v173
	v_pk_mul_f32 v[180:181], v[180:181], v[184:185]
	v_pk_mul_f32 v[182:183], v[182:183], v[186:187]
	v_lshlrev_b32_e32 v203, 16, v174
	v_pk_mul_f32 v[176:177], v[176:177], v[220:221]
	v_pk_mul_f32 v[178:179], v[178:179], v[222:223]
	v_pk_mul_f32 v[180:181], v[180:181], v[220:221]
	v_pk_mul_f32 v[182:183], v[182:183], v[222:223]
	ds_write_b128 v208, v[176:179]
	ds_write_b128 v208, v[180:183] offset:256
	ds_read2_b32 v[64:65], v209 offset0:0 offset1:4
	ds_read2_b32 v[66:67], v209 offset0:8 offset1:12
	ds_read2_b32 v[68:69], v209 offset0:16 offset1:20
	ds_read2_b32 v[70:71], v209 offset0:24 offset1:28
	ds_read2_b32 v[72:73], v209 offset0:32 offset1:36
	ds_read2_b32 v[74:75], v209 offset0:40 offset1:44
	ds_read2_b32 v[76:77], v209 offset0:48 offset1:52
	ds_read2_b32 v[78:79], v209 offset0:56 offset1:60
	ds_read2_b32 v[80:81], v209 offset0:64 offset1:68
	ds_read2_b32 v[82:83], v209 offset0:72 offset1:76
	ds_read2_b32 v[84:85], v209 offset0:80 offset1:84
	ds_read2_b32 v[86:87], v209 offset0:88 offset1:92
	ds_read2_b32 v[88:89], v209 offset0:96 offset1:100
	ds_read2_b32 v[90:91], v209 offset0:104 offset1:108
	ds_read2_b32 v[92:93], v209 offset0:112 offset1:116
	ds_read2_b32 v[94:95], v209 offset0:120 offset1:124
	v_mul_f32_dpp v196, v224, v0 row_newbcast:0 row_mask:0xf bank_mask:0xf
	v_mul_f32_dpp v197, v225, v1 row_newbcast:0 row_mask:0xf bank_mask:0xf
	v_mul_f32_dpp v198, v226, v2 row_newbcast:0 row_mask:0xf bank_mask:0xf
	v_mul_f32_dpp v199, v227, v3 row_newbcast:0 row_mask:0xf bank_mask:0xf
	v_fmac_f32_dpp v196, v224, v4 row_newbcast:1 row_mask:0xf bank_mask:0xf
	v_fmac_f32_dpp v197, v225, v5 row_newbcast:1 row_mask:0xf bank_mask:0xf
	v_fmac_f32_dpp v198, v226, v6 row_newbcast:1 row_mask:0xf bank_mask:0xf
	v_fmac_f32_dpp v199, v227, v7 row_newbcast:1 row_mask:0xf bank_mask:0xf
	v_fmac_f32_dpp v196, v224, v8 row_newbcast:2 row_mask:0xf bank_mask:0xf
	v_fmac_f32_dpp v197, v225, v9 row_newbcast:2 row_mask:0xf bank_mask:0xf
	v_fmac_f32_dpp v198, v226, v10 row_newbcast:2 row_mask:0xf bank_mask:0xf
	v_fmac_f32_dpp v199, v227, v11 row_newbcast:2 row_mask:0xf bank_mask:0xf
	v_fmac_f32_dpp v196, v224, v12 row_newbcast:3 row_mask:0xf bank_mask:0xf
	v_fmac_f32_dpp v197, v225, v13 row_newbcast:3 row_mask:0xf bank_mask:0xf
	v_fmac_f32_dpp v198, v226, v14 row_newbcast:3 row_mask:0xf bank_mask:0xf
	v_fmac_f32_dpp v199, v227, v15 row_newbcast:3 row_mask:0xf bank_mask:0xf
	v_fmac_f32_dpp v196, v224, v16 row_newbcast:4 row_mask:0xf bank_mask:0xf
	v_fmac_f32_dpp v197, v225, v17 row_newbcast:4 row_mask:0xf bank_mask:0xf
	v_fmac_f32_dpp v198, v226, v18 row_newbcast:4 row_mask:0xf bank_mask:0xf
	v_fmac_f32_dpp v199, v227, v19 row_newbcast:4 row_mask:0xf bank_mask:0xf
	v_fmac_f32_dpp v196, v224, v20 row_newbcast:5 row_mask:0xf bank_mask:0xf
	v_fmac_f32_dpp v197, v225, v21 row_newbcast:5 row_mask:0xf bank_mask:0xf
	v_fmac_f32_dpp v198, v226, v22 row_newbcast:5 row_mask:0xf bank_mask:0xf
	v_fmac_f32_dpp v199, v227, v23 row_newbcast:5 row_mask:0xf bank_mask:0xf
	v_fmac_f32_dpp v196, v224, v24 row_newbcast:6 row_mask:0xf bank_mask:0xf
	v_fmac_f32_dpp v197, v225, v25 row_newbcast:6 row_mask:0xf bank_mask:0xf
	v_fmac_f32_dpp v198, v226, v26 row_newbcast:6 row_mask:0xf bank_mask:0xf
	v_fmac_f32_dpp v199, v227, v27 row_newbcast:6 row_mask:0xf bank_mask:0xf
	v_fmac_f32_dpp v196, v224, v28 row_newbcast:7 row_mask:0xf bank_mask:0xf
	v_fmac_f32_dpp v197, v225, v29 row_newbcast:7 row_mask:0xf bank_mask:0xf
	v_fmac_f32_dpp v198, v226, v30 row_newbcast:7 row_mask:0xf bank_mask:0xf
	v_fmac_f32_dpp v199, v227, v31 row_newbcast:7 row_mask:0xf bank_mask:0xf
	v_fmac_f32_dpp v196, v224, v32 row_newbcast:8 row_mask:0xf bank_mask:0xf
	v_fmac_f32_dpp v197, v225, v33 row_newbcast:8 row_mask:0xf bank_mask:0xf
	v_fmac_f32_dpp v198, v226, v34 row_newbcast:8 row_mask:0xf bank_mask:0xf
	v_fmac_f32_dpp v199, v227, v35 row_newbcast:8 row_mask:0xf bank_mask:0xf
	v_fmac_f32_dpp v196, v224, v36 row_newbcast:9 row_mask:0xf bank_mask:0xf
	v_fmac_f32_dpp v197, v225, v37 row_newbcast:9 row_mask:0xf bank_mask:0xf
	v_fmac_f32_dpp v198, v226, v38 row_newbcast:9 row_mask:0xf bank_mask:0xf
	v_fmac_f32_dpp v199, v227, v39 row_newbcast:9 row_mask:0xf bank_mask:0xf
	v_fmac_f32_dpp v196, v224, v40 row_newbcast:10 row_mask:0xf bank_mask:0xf
	v_fmac_f32_dpp v197, v225, v41 row_newbcast:10 row_mask:0xf bank_mask:0xf
	v_fmac_f32_dpp v198, v226, v42 row_newbcast:10 row_mask:0xf bank_mask:0xf
	v_fmac_f32_dpp v199, v227, v43 row_newbcast:10 row_mask:0xf bank_mask:0xf
;     static __device__ __forceinline__ void dot(const float (&S)[64], const f32x4& a, float (&s)[4]) {
;         if constexpr (K == 0) {
;             asm volatile("v_mul_f32_dpp %0, %4, %8 row_newbcast:%16" DPPM "v_mul_f32_dpp %1, %5, %9 row_newbcast:%16" DPPM "v_mul_f32_dpp %2, %6, %10 row_newbcast:%16" DPPM "v_mul_f32_dpp %3, %7, %11 row_newbcast:%16" DPPM
;                          "v_fmac_f32_dpp %0, %4, %12 row_newbcast:%17" DPPM "v_fmac_f32_dpp %1, %5, %13 row_newbcast:%17" DPPM "v_fmac_f32_dpp %2, %6, %14 row_newbcast:%17" DPPM "v_fmac_f32_dpp %3, %7, %15 row_newbcast:%17" DPPM
;                          : "=&v"(s[0]), "=&v"(s[1]), "=&v"(s[2]), "=&v"(s[3])
;                          : "v"(a[0]), "v"(a[1]), "v"(a[2]), "v"(a[3]), "v"(S[K]), "v"(S[K + 1]), "v"(S[K + 2]), "v"(S[K + 3]), "v"(S[K + 4]), "v"(S[K + 5]), "v"(S[K + 6]), "v"(S[K + 7]), "n"(N0), "n"(N1));
;         } else
;         asm volatile("v_fmac_f32_dpp %0, %4, %8 row_newbcast:%16" DPPM "v_fmac_f32_dpp %1, %5, %9 row_newbcast:%16" DPPM "v_fmac_f32_dpp %2, %6, %10 row_newbcast:%16" DPPM "v_fmac_f32_dpp %3, %7, %11 row_newbcast:%16" DPPM
;                      "v_fmac_f32_dpp %0, %4, %12 row_newbcast:%17" DPPM "v_fmac_f32_dpp %1, %5, %13 row_newbcast:%17" DPPM "v_fmac_f32_dpp %2, %6, %14 row_newbcast:%17" DPPM "v_fmac_f32_dpp %3, %7, %15 row_newbcast:%17" DPPM
;                      : "+v"(s[0]), "+v"(s[1]), "+v"(s[2]), "+v"(s[3])
;                      : "v"(a[0]), "v"(a[1]), "v"(a[2]), "v"(a[3]), "v"(S[K]), "v"(S[K + 1]), "v"(S[K + 2]), "v"(S[K + 3]), "v"(S[K + 4]), "v"(S[K + 5]), "v"(S[K + 6]), "v"(S[K + 7]), "n"(N0), "n"(N1));
;         if constexpr (K + 8 < 64) ScanK<K + 8>::dot(S, a, s);
;     }
;     static __device__ __forceinline__ void upd(float (&S)[64], const In2& in, float sa, float vv, float& y0, float& y1) {
;         float t0, t1, t2, t3;
;         asm volatile("v_mul_f32_dpp %0, %10, %27 row_newbcast:%28" DPPM "v_mul_f32_dpp %1, %11, %27 row_newbcast:%28" DPPM "v_mul_f32_dpp %2, %12, %27 row_newbcast:%28" DPPM "v_mul_f32_dpp %3, %13, %27 row_newbcast:%28" DPPM
;                      "v_fmac_f32_dpp %0, %14, %6 row_newbcast:%28" DPPM "v_fmac_f32_dpp %1, %15, %7 row_newbcast:%28" DPPM "v_fmac_f32_dpp %2, %16, %8 row_newbcast:%28" DPPM "v_fmac_f32_dpp %3, %17, %9 row_newbcast:%28" DPPM
	v_fmac_f32_dpp v196, v224, v44 row_newbcast:11 row_mask:0xf bank_mask:0xf
	v_fmac_f32_dpp v197, v225, v45 row_newbcast:11 row_mask:0xf bank_mask:0xf
	v_fmac_f32_dpp v198, v226, v46 row_newbcast:11 row_mask:0xf bank_mask:0xf
	v_fmac_f32_dpp v199, v227, v47 row_newbcast:11 row_mask:0xf bank_mask:0xf
	v_fmac_f32_dpp v196, v224, v48 row_newbcast:12 row_mask:0xf bank_mask:0xf
	v_fmac_f32_dpp v197, v225, v49 row_newbcast:12 row_mask:0xf bank_mask:0xf
	v_fmac_f32_dpp v198, v226, v50 row_newbcast:12 row_mask:0xf bank_mask:0xf
	v_fmac_f32_dpp v199, v227, v51 row_newbcast:12 row_mask:0xf bank_mask:0xf
	v_fmac_f32_dpp v196, v224, v52 row_newbcast:13 row_mask:0xf bank_mask:0xf
	v_fmac_f32_dpp v197, v225, v53 row_newbcast:13 row_mask:0xf bank_mask:0xf
	v_fmac_f32_dpp v198, v226, v54 row_newbcast:13 row_mask:0xf bank_mask:0xf
	v_fmac_f32_dpp v199, v227, v55 row_newbcast:13 row_mask:0xf bank_mask:0xf
	v_fmac_f32_dpp v196, v224, v56 row_newbcast:14 row_mask:0xf bank_mask:0xf
	v_fmac_f32_dpp v197, v225, v57 row_newbcast:14 row_mask:0xf bank_mask:0xf
	v_fmac_f32_dpp v198, v226, v58 row_newbcast:14 row_mask:0xf bank_mask:0xf
	v_fmac_f32_dpp v199, v227, v59 row_newbcast:14 row_mask:0xf bank_mask:0xf
	v_fmac_f32_dpp v196, v224, v60 row_newbcast:15 row_mask:0xf bank_mask:0xf
	v_fmac_f32_dpp v197, v225, v61 row_newbcast:15 row_mask:0xf bank_mask:0xf
	v_fmac_f32_dpp v198, v226, v62 row_newbcast:15 row_mask:0xf bank_mask:0xf
	v_fmac_f32_dpp v199, v227, v63 row_newbcast:15 row_mask:0xf bank_mask:0xf
	v_add_f32_e32 v196, v196, v197
	v_add_f32_e32 v198, v198, v199
	v_add_f32_e32 v196, v196, v198
	v_xor_b32_e32 v202, 0x80000000, v196
	s_waitcnt lgkmcnt(0)
	s_nop 1
	v_mfma_f32_4x4x1_16b_f32 v[0:3], v64, v202, v[0:3]
	v_mfma_f32_4x4x1_16b_f32 v[4:7], v65, v202, v[4:7]
	v_mfma_f32_4x4x1_16b_f32 v[8:11], v66, v202, v[8:11]
	v_mfma_f32_4x4x1_16b_f32 v[12:15], v67, v202, v[12:15]
	v_mfma_f32_4x4x1_16b_f32 v[16:19], v68, v202, v[16:19]
	v_mfma_f32_4x4x1_16b_f32 v[20:23], v69, v202, v[20:23]
	v_mfma_f32_4x4x1_16b_f32 v[24:27], v70, v202, v[24:27]
	v_mfma_f32_4x4x1_16b_f32 v[28:31], v71, v202, v[28:31]
	v_mfma_f32_4x4x1_16b_f32 v[32:35], v72, v202, v[32:35]
	v_mfma_f32_4x4x1_16b_f32 v[36:39], v73, v202, v[36:39]
	v_mfma_f32_4x4x1_16b_f32 v[40:43], v74, v202, v[40:43]
	v_mfma_f32_4x4x1_16b_f32 v[44:47], v75, v202, v[44:47]
	v_mfma_f32_4x4x1_16b_f32 v[48:51], v76, v202, v[48:51]
	v_mfma_f32_4x4x1_16b_f32 v[52:55], v77, v202, v[52:55]
	v_mfma_f32_4x4x1_16b_f32 v[56:59], v78, v202, v[56:59]
	v_mfma_f32_4x4x1_16b_f32 v[60:63], v79, v202, v[60:63]
	v_mfma_f32_4x4x1_16b_f32 v[0:3], v80, v203, v[0:3]
	v_mfma_f32_4x4x1_16b_f32 v[4:7], v81, v203, v[4:7]
	v_mfma_f32_4x4x1_16b_f32 v[8:11], v82, v203, v[8:11]
	v_mfma_f32_4x4x1_16b_f32 v[12:15], v83, v203, v[12:15]
	v_mfma_f32_4x4x1_16b_f32 v[16:19], v84, v203, v[16:19]
	v_mfma_f32_4x4x1_16b_f32 v[20:23], v85, v203, v[20:23]
	v_mfma_f32_4x4x1_16b_f32 v[24:27], v86, v203, v[24:27]
	v_mfma_f32_4x4x1_16b_f32 v[28:31], v87, v203, v[28:31]
	v_mfma_f32_4x4x1_16b_f32 v[32:35], v88, v203, v[32:35]
	v_mfma_f32_4x4x1_16b_f32 v[36:39], v89, v203, v[36:39]
	v_mfma_f32_4x4x1_16b_f32 v[40:43], v90, v203, v[40:43]
	v_mfma_f32_4x4x1_16b_f32 v[44:47], v91, v203, v[44:47]
	v_mfma_f32_4x4x1_16b_f32 v[48:51], v92, v203, v[48:51]
	v_mfma_f32_4x4x1_16b_f32 v[52:55], v93, v203, v[52:55]
	v_mfma_f32_4x4x1_16b_f32 v[56:59], v94, v203, v[56:59]
	v_mfma_f32_4x4x1_16b_f32 v[60:63], v95, v203, v[60:63]
	s_sub_u32 s83, s83, 1
	s_cmp_eq_u32 s83, 0
	s_cbranch_scc1 .Lmy_p1d0_ldone_s
	s_and_b32 s9, s83, 7
	s_cmp_eq_u32 s9, 0
	s_cbranch_scc1 .Lmy_p1d0_renorm_s
	s_branch .Lmy_p1d0_loop_s
.Lmy_p1d0_ldone_s:
	v_mul_f32_dpp v0, v216, v0 row_newbcast:0 row_mask:0xf bank_mask:0xf
	v_mul_f32_dpp v1, v217, v1 row_newbcast:0 row_mask:0xf bank_mask:0xf
	v_mul_f32_dpp v2, v218, v2 row_newbcast:0 row_mask:0xf bank_mask:0xf
	v_mul_f32_dpp v3, v219, v3 row_newbcast:0 row_mask:0xf bank_mask:0xf
	v_mul_f32_dpp v4, v216, v4 row_newbcast:1 row_mask:0xf bank_mask:0xf
	v_mul_f32_dpp v5, v217, v5 row_newbcast:1 row_mask:0xf bank_mask:0xf
	v_mul_f32_dpp v6, v218, v6 row_newbcast:1 row_mask:0xf bank_mask:0xf
	v_mul_f32_dpp v7, v219, v7 row_newbcast:1 row_mask:0xf bank_mask:0xf
	v_mul_f32_dpp v8, v216, v8 row_newbcast:2 row_mask:0xf bank_mask:0xf
	v_mul_f32_dpp v9, v217, v9 row_newbcast:2 row_mask:0xf bank_mask:0xf
	v_mul_f32_dpp v10, v218, v10 row_newbcast:2 row_mask:0xf bank_mask:0xf
	v_mul_f32_dpp v11, v219, v11 row_newbcast:2 row_mask:0xf bank_mask:0xf
	v_mul_f32_dpp v12, v216, v12 row_newbcast:3 row_mask:0xf bank_mask:0xf
	v_mul_f32_dpp v13, v217, v13 row_newbcast:3 row_mask:0xf bank_mask:0xf
	v_mul_f32_dpp v14, v218, v14 row_newbcast:3 row_mask:0xf bank_mask:0xf
	v_mul_f32_dpp v15, v219, v15 row_newbcast:3 row_mask:0xf bank_mask:0xf
	v_mul_f32_dpp v16, v216, v16 row_newbcast:4 row_mask:0xf bank_mask:0xf
	v_mul_f32_dpp v17, v217, v17 row_newbcast:4 row_mask:0xf bank_mask:0xf
	v_mul_f32_dpp v18, v218, v18 row_newbcast:4 row_mask:0xf bank_mask:0xf
	v_mul_f32_dpp v19, v219, v19 row_newbcast:4 row_mask:0xf bank_mask:0xf
	v_mul_f32_dpp v20, v216, v20 row_newbcast:5 row_mask:0xf bank_mask:0xf
	v_mul_f32_dpp v21, v217, v21 row_newbcast:5 row_mask:0xf bank_mask:0xf
	v_mul_f32_dpp v22, v218, v22 row_newbcast:5 row_mask:0xf bank_mask:0xf
	v_mul_f32_dpp v23, v219, v23 row_newbcast:5 row_mask:0xf bank_mask:0xf
	v_mul_f32_dpp v24, v216, v24 row_newbcast:6 row_mask:0xf bank_mask:0xf
	v_mul_f32_dpp v25, v217, v25 row_newbcast:6 row_mask:0xf bank_mask:0xf
	v_mul_f32_dpp v26, v218, v26 row_newbcast:6 row_mask:0xf bank_mask:0xf
	v_mul_f32_dpp v27, v219, v27 row_newbcast:6 row_mask:0xf bank_mask:0xf
; template <bool MIX> __device__ __forceinline__ void scan_pass1(const Params& p, int d, float* ldsf) {
;     ...
;         float* po = (isP ? PT : SLT) + ((size_t)(bh * NC + c)) * 4096 + lane * 64;
; #pragma unroll
;         for (int i = 0; i < 16; ++i) *(f32x4*)(po + 4 * i) = (f32x4){S[4 * i], S[4 * i + 1], S[4 * i + 2], S[4 * i + 3]};
	v_mul_f32_dpp v28, v216, v28 row_newbcast:7 row_mask:0xf bank_mask:0xf
	v_mul_f32_dpp v29, v217, v29 row_newbcast:7 row_mask:0xf bank_mask:0xf
	v_mul_f32_dpp v30, v218, v30 row_newbcast:7 row_mask:0xf bank_mask:0xf
	v_mul_f32_dpp v31, v219, v31 row_newbcast:7 row_mask:0xf bank_mask:0xf
	v_mul_f32_dpp v32, v216, v32 row_newbcast:8 row_mask:0xf bank_mask:0xf
	v_mul_f32_dpp v33, v217, v33 row_newbcast:8 row_mask:0xf bank_mask:0xf
	v_mul_f32_dpp v34, v218, v34 row_newbcast:8 row_mask:0xf bank_mask:0xf
	v_mul_f32_dpp v35, v219, v35 row_newbcast:8 row_mask:0xf bank_mask:0xf
	v_mul_f32_dpp v36, v216, v36 row_newbcast:9 row_mask:0xf bank_mask:0xf
	v_mul_f32_dpp v37, v217, v37 row_newbcast:9 row_mask:0xf bank_mask:0xf
	v_mul_f32_dpp v38, v218, v38 row_newbcast:9 row_mask:0xf bank_mask:0xf
	v_mul_f32_dpp v39, v219, v39 row_newbcast:9 row_mask:0xf bank_mask:0xf
	v_mul_f32_dpp v40, v216, v40 row_newbcast:10 row_mask:0xf bank_mask:0xf
	v_mul_f32_dpp v41, v217, v41 row_newbcast:10 row_mask:0xf bank_mask:0xf
	v_mul_f32_dpp v42, v218, v42 row_newbcast:10 row_mask:0xf bank_mask:0xf
	v_mul_f32_dpp v43, v219, v43 row_newbcast:10 row_mask:0xf bank_mask:0xf
	v_mul_f32_dpp v44, v216, v44 row_newbcast:11 row_mask:0xf bank_mask:0xf
	v_mul_f32_dpp v45, v217, v45 row_newbcast:11 row_mask:0xf bank_mask:0xf
	v_mul_f32_dpp v46, v218, v46 row_newbcast:11 row_mask:0xf bank_mask:0xf
	v_mul_f32_dpp v47, v219, v47 row_newbcast:11 row_mask:0xf bank_mask:0xf
	v_mul_f32_dpp v48, v216, v48 row_newbcast:12 row_mask:0xf bank_mask:0xf
	v_mul_f32_dpp v49, v217, v49 row_newbcast:12 row_mask:0xf bank_mask:0xf
	v_mul_f32_dpp v50, v218, v50 row_newbcast:12 row_mask:0xf bank_mask:0xf
	v_mul_f32_dpp v51, v219, v51 row_newbcast:12 row_mask:0xf bank_mask:0xf
	v_mul_f32_dpp v52, v216, v52 row_newbcast:13 row_mask:0xf bank_mask:0xf
	v_mul_f32_dpp v53, v217, v53 row_newbcast:13 row_mask:0xf bank_mask:0xf
	v_mul_f32_dpp v54, v218, v54 row_newbcast:13 row_mask:0xf bank_mask:0xf
	v_mul_f32_dpp v55, v219, v55 row_newbcast:13 row_mask:0xf bank_mask:0xf
	v_mul_f32_dpp v56, v216, v56 row_newbcast:14 row_mask:0xf bank_mask:0xf
	v_mul_f32_dpp v57, v217, v57 row_newbcast:14 row_mask:0xf bank_mask:0xf
	v_mul_f32_dpp v58, v218, v58 row_newbcast:14 row_mask:0xf bank_mask:0xf
	v_mul_f32_dpp v59, v219, v59 row_newbcast:14 row_mask:0xf bank_mask:0xf
	v_mul_f32_dpp v60, v216, v60 row_newbcast:15 row_mask:0xf bank_mask:0xf
	v_mul_f32_dpp v61, v217, v61 row_newbcast:15 row_mask:0xf bank_mask:0xf
	v_mul_f32_dpp v62, v218, v62 row_newbcast:15 row_mask:0xf bank_mask:0xf
	v_mul_f32_dpp v63, v219, v63 row_newbcast:15 row_mask:0xf bank_mask:0xf
	v_mov_b32_e32 v216, 1.0
	v_mov_b32_e32 v217, 1.0
	v_mov_b32_e32 v218, 1.0
	v_mov_b32_e32 v219, 1.0
	s_branch .Lmy_p1d0_store
; #define LD1(set, s) { const int e_ = min((int)(s), LC - 1) * (int)stp; const unsigned s4_ = ob4 + (unsigned)(e_ * 4), s2_ = ob2 + (unsigned)(e_ * 2); set.w = LDX(rW, s4_); set.a = LDX(rA, s4_); set.b = LDX(rB, s4_); \
;             set.kw = __builtin_amdgcn_raw_buffer_load_b64(rK, lo8, s2_, 0); set.v = __builtin_amdgcn_raw_buffer_load_b16(rV, lo2, s2_, 0); }
; #define LD1(set, s) { const int e_ = min((int)(s), LC - 1) * (int)stp; const unsigned s4_ = ob4 + (unsigned)(e_ * 4); set.w = LDX(rW, s4_); set.a = LDX(rA, s4_); set.b = LDX(rB, s4_); }
; template <bool MIX> __device__ __forceinline__ void scan_pass1(const Params& p, int d, float* ldsf) {
;     ...
;             for (int i = 0; i < 64; ++i) S[i] = (ln == i) ? 1.f : 0.f;
;     ...
;             In1 i0, i1; LD1(i0, 0);
.Lmy_p1d0_pitem:
	buffer_load_dwordx4 v[96:99], v204, s[64:67], s72 offen
	buffer_load_dwordx4 v[100:103], v204, s[64:67], s73 offen
	buffer_load_dwordx4 v[104:107], v204, s[64:67], s74 offen
	s_add_u32 s72, s72, 0x1000
	s_add_u32 s73, s73, 0x1000
	s_add_u32 s74, s74, 0x1000
	buffer_load_dwordx4 v[116:119], v204, s[64:67], s72 offen
	buffer_load_dwordx4 v[120:123], v204, s[64:67], s73 offen
	buffer_load_dwordx4 v[124:127], v204, s[64:67], s74 offen
	s_add_u32 s72, s72, 0x1000
	s_add_u32 s73, s73, 0x1000
	s_add_u32 s74, s74, 0x1000
	buffer_load_dwordx4 v[136:139], v204, s[64:67], s72 offen
	buffer_load_dwordx4 v[140:143], v204, s[64:67], s73 offen
	buffer_load_dwordx4 v[144:147], v204, s[64:67], s74 offen
	s_add_u32 s72, s72, 0x1000
	s_add_u32 s73, s73, 0x1000
	s_add_u32 s74, s74, 0x1000
	s_mov_b32 s80, 3
	v_cmp_eq_u32_e32 vcc, 0, v212
	s_nop 1
	v_cndmask_b32_e32 v0, 0, v213, vcc
	v_cmp_eq_u32_e32 vcc, 1, v212
	s_nop 1
	v_cndmask_b32_e32 v1, 0, v213, vcc
	v_cmp_eq_u32_e32 vcc, 2, v212
	s_nop 1
	v_cndmask_b32_e32 v2, 0, v213, vcc
	v_cmp_eq_u32_e32 vcc, 3, v212
	s_nop 1
	v_cndmask_b32_e32 v3, 0, v213, vcc
	v_cmp_eq_u32_e32 vcc, 4, v212
	s_nop 1
	v_cndmask_b32_e32 v4, 0, v213, vcc
	v_cmp_eq_u32_e32 vcc, 5, v212
	s_nop 1
	v_cndmask_b32_e32 v5, 0, v213, vcc
	v_cmp_eq_u32_e32 vcc, 6, v212
	s_nop 1
	v_cndmask_b32_e32 v6, 0, v213, vcc
	v_cmp_eq_u32_e32 vcc, 7, v212
	s_nop 1
	v_cndmask_b32_e32 v7, 0, v213, vcc
	v_cmp_eq_u32_e32 vcc, 8, v212
	s_nop 1
	v_cndmask_b32_e32 v8, 0, v213, vcc
	v_cmp_eq_u32_e32 vcc, 9, v212
	s_nop 1
	v_cndmask_b32_e32 v9, 0, v213, vcc
	v_cmp_eq_u32_e32 vcc, 10, v212
	s_nop 1
	v_cndmask_b32_e32 v10, 0, v213, vcc
	v_cmp_eq_u32_e32 vcc, 11, v212
	s_nop 1
	v_cndmask_b32_e32 v11, 0, v213, vcc
	v_cmp_eq_u32_e32 vcc, 12, v212
	s_nop 1
	v_cndmask_b32_e32 v12, 0, v213, vcc
	v_cmp_eq_u32_e32 vcc, 13, v212
	s_nop 1
	v_cndmask_b32_e32 v13, 0, v213, vcc
	v_cmp_eq_u32_e32 vcc, 14, v212
	s_nop 1
	v_cndmask_b32_e32 v14, 0, v213, vcc
	v_cmp_eq_u32_e32 vcc, 15, v212
	s_nop 1
	v_cndmask_b32_e32 v15, 0, v213, vcc
	v_cmp_eq_u32_e32 vcc, 16, v212
	s_nop 1
	v_cndmask_b32_e32 v16, 0, v213, vcc
	v_cmp_eq_u32_e32 vcc, 17, v212
	s_nop 1
	v_cndmask_b32_e32 v17, 0, v213, vcc
	v_cmp_eq_u32_e32 vcc, 18, v212
	s_nop 1
	v_cndmask_b32_e32 v18, 0, v213, vcc
	v_cmp_eq_u32_e32 vcc, 19, v212
	s_nop 1
	v_cndmask_b32_e32 v19, 0, v213, vcc
	v_cmp_eq_u32_e32 vcc, 20, v212
	s_nop 1
	v_cndmask_b32_e32 v20, 0, v213, vcc
	v_cmp_eq_u32_e32 vcc, 21, v212
	s_nop 1
	v_cndmask_b32_e32 v21, 0, v213, vcc
	v_cmp_eq_u32_e32 vcc, 22, v212
	s_nop 1
	v_cndmask_b32_e32 v22, 0, v213, vcc
	v_cmp_eq_u32_e32 vcc, 23, v212
	s_nop 1
	v_cndmask_b32_e32 v23, 0, v213, vcc
	v_cmp_eq_u32_e32 vcc, 24, v212
	s_nop 1
	v_cndmask_b32_e32 v24, 0, v213, vcc
	v_cmp_eq_u32_e32 vcc, 25, v212
	s_nop 1
	v_cndmask_b32_e32 v25, 0, v213, vcc
	v_cmp_eq_u32_e32 vcc, 26, v212
	s_nop 1
	v_cndmask_b32_e32 v26, 0, v213, vcc
	v_cmp_eq_u32_e32 vcc, 27, v212
	s_nop 1
	v_cndmask_b32_e32 v27, 0, v213, vcc
	v_cmp_eq_u32_e32 vcc, 28, v212
	s_nop 1
	v_cndmask_b32_e32 v28, 0, v213, vcc
	v_cmp_eq_u32_e32 vcc, 29, v212
	s_nop 1
	v_cndmask_b32_e32 v29, 0, v213, vcc
	v_cmp_eq_u32_e32 vcc, 30, v212
	s_nop 1
	v_cndmask_b32_e32 v30, 0, v213, vcc
	v_cmp_eq_u32_e32 vcc, 31, v212
	s_nop 1
	v_cndmask_b32_e32 v31, 0, v213, vcc
	v_cmp_eq_u32_e32 vcc, 32, v212
	s_nop 1
	v_cndmask_b32_e32 v32, 0, v213, vcc
	v_cmp_eq_u32_e32 vcc, 33, v212
	s_nop 1
	v_cndmask_b32_e32 v33, 0, v213, vcc
	v_cmp_eq_u32_e32 vcc, 34, v212
	s_nop 1
	v_cndmask_b32_e32 v34, 0, v213, vcc
	v_cmp_eq_u32_e32 vcc, 35, v212
	s_nop 1
	v_cndmask_b32_e32 v35, 0, v213, vcc
	v_cmp_eq_u32_e32 vcc, 36, v212
	s_nop 1
	v_cndmask_b32_e32 v36, 0, v213, vcc
	v_cmp_eq_u32_e32 vcc, 37, v212
	s_nop 1
	v_cndmask_b32_e32 v37, 0, v213, vcc
	v_cmp_eq_u32_e32 vcc, 38, v212
	s_nop 1
	v_cndmask_b32_e32 v38, 0, v213, vcc
	v_cmp_eq_u32_e32 vcc, 39, v212
	s_nop 1
	v_cndmask_b32_e32 v39, 0, v213, vcc
	v_cmp_eq_u32_e32 vcc, 40, v212
	s_nop 1
	v_cndmask_b32_e32 v40, 0, v213, vcc
	v_cmp_eq_u32_e32 vcc, 41, v212
	s_nop 1
	v_cndmask_b32_e32 v41, 0, v213, vcc
	v_cmp_eq_u32_e32 vcc, 42, v212
	s_nop 1
	v_cndmask_b32_e32 v42, 0, v213, vcc
	v_cmp_eq_u32_e32 vcc, 43, v212
	s_nop 1
	v_cndmask_b32_e32 v43, 0, v213, vcc
	v_cmp_eq_u32_e32 vcc, 44, v212
	s_nop 1
	v_cndmask_b32_e32 v44, 0, v213, vcc
	v_cmp_eq_u32_e32 vcc, 45, v212
	s_nop 1
	v_cndmask_b32_e32 v45, 0, v213, vcc
	v_cmp_eq_u32_e32 vcc, 46, v212
	s_nop 1
	v_cndmask_b32_e32 v46, 0, v213, vcc
	v_cmp_eq_u32_e32 vcc, 47, v212
	s_nop 1
	v_cndmask_b32_e32 v47, 0, v213, vcc
	v_cmp_eq_u32_e32 vcc, 48, v212
	s_nop 1
	v_cndmask_b32_e32 v48, 0, v213, vcc
	v_cmp_eq_u32_e32 vcc, 49, v212
	s_nop 1
	v_cndmask_b32_e32 v49, 0, v213, vcc
	v_cmp_eq_u32_e32 vcc, 50, v212
	s_nop 1
	v_cndmask_b32_e32 v50, 0, v213, vcc
	v_cmp_eq_u32_e32 vcc, 51, v212
	s_nop 1
	v_cndmask_b32_e32 v51, 0, v213, vcc
	v_cmp_eq_u32_e32 vcc, 52, v212
	s_nop 1
	v_cndmask_b32_e32 v52, 0, v213, vcc
	v_cmp_eq_u32_e32 vcc, 53, v212
	s_nop 1
	v_cndmask_b32_e32 v53, 0, v213, vcc
	v_cmp_eq_u32_e32 vcc, 54, v212
	s_nop 1
	v_cndmask_b32_e32 v54, 0, v213, vcc
	v_cmp_eq_u32_e32 vcc, 55, v212
	s_nop 1
	v_cndmask_b32_e32 v55, 0, v213, vcc
	v_cmp_eq_u32_e32 vcc, 56, v212
	s_nop 1
	v_cndmask_b32_e32 v56, 0, v213, vcc
	v_cmp_eq_u32_e32 vcc, 57, v212
	s_nop 1
	v_cndmask_b32_e32 v57, 0, v213, vcc
	v_cmp_eq_u32_e32 vcc, 58, v212
	s_nop 1
	v_cndmask_b32_e32 v58, 0, v213, vcc
	v_cmp_eq_u32_e32 vcc, 59, v212
	s_nop 1
	v_cndmask_b32_e32 v59, 0, v213, vcc
	v_cmp_eq_u32_e32 vcc, 60, v212
	s_nop 1
	v_cndmask_b32_e32 v60, 0, v213, vcc
	v_cmp_eq_u32_e32 vcc, 61, v212
	s_nop 1
	v_cndmask_b32_e32 v61, 0, v213, vcc
	v_cmp_eq_u32_e32 vcc, 62, v212
	s_nop 1
	v_cndmask_b32_e32 v62, 0, v213, vcc
	v_cmp_eq_u32_e32 vcc, 63, v212
	s_nop 1
	v_cndmask_b32_e32 v63, 0, v213, vcc
	s_waitcnt vmcnt(0)
	v_mov_b32_e32 v216, 1.0
	v_mov_b32_e32 v217, 1.0
	v_mov_b32_e32 v218, 1.0
	v_mov_b32_e32 v219, 1.0
	s_movk_i32 s83, 64
	s_branch .Lmy_p1d0_loop_p

;     static __device__ __forceinline__ void dot(const float (&S)[64], const f32x4& a, float (&s)[4]) {
;         if constexpr (K == 0) {
;             asm volatile("v_mul_f32_dpp %0, %4, %8 row_newbcast:%16" DPPM "v_mul_f32_dpp %1, %5, %9 row_newbcast:%16" DPPM "v_mul_f32_dpp %2, %6, %10 row_newbcast:%16" DPPM "v_mul_f32_dpp %3, %7, %11 row_newbcast:%16" DPPM
;                          "v_fmac_f32_dpp %0, %4, %12 row_newbcast:%17" DPPM "v_fmac_f32_dpp %1, %5, %13 row_newbcast:%17" DPPM "v_fmac_f32_dpp %2, %6, %14 row_newbcast:%17" DPPM "v_fmac_f32_dpp %3, %7, %15 row_newbcast:%17" DPPM
;                          : "=&v"(s[0]), "=&v"(s[1]), "=&v"(s[2]), "=&v"(s[3])
;                          : "v"(a[0]), "v"(a[1]), "v"(a[2]), "v"(a[3]), "v"(S[K]), "v"(S[K + 1]), "v"(S[K + 2]), "v"(S[K + 3]), "v"(S[K + 4]), "v"(S[K + 5]), "v"(S[K + 6]), "v"(S[K + 7]), "n"(N0), "n"(N1));
;         } else
;         asm volatile("v_fmac_f32_dpp %0, %4, %8 row_newbcast:%16" DPPM "v_fmac_f32_dpp %1, %5, %9 row_newbcast:%16" DPPM "v_fmac_f32_dpp %2, %6, %10 row_newbcast:%16" DPPM "v_fmac_f32_dpp %3, %7, %11 row_newbcast:%16" DPPM
;                      "v_fmac_f32_dpp %0, %4, %12 row_newbcast:%17" DPPM "v_fmac_f32_dpp %1, %5, %13 row_newbcast:%17" DPPM "v_fmac_f32_dpp %2, %6, %14 row_newbcast:%17" DPPM "v_fmac_f32_dpp %3, %7, %15 row_newbcast:%17" DPPM
;                      : "+v"(s[0]), "+v"(s[1]), "+v"(s[2]), "+v"(s[3])
;                      : "v"(a[0]), "v"(a[1]), "v"(a[2]), "v"(a[3]), "v"(S[K]), "v"(S[K + 1]), "v"(S[K + 2]), "v"(S[K + 3]), "v"(S[K + 4]), "v"(S[K + 5]), "v"(S[K + 6]), "v"(S[K + 7]), "n"(N0), "n"(N1));
;         if constexpr (K + 8 < 64) ScanK<K + 8>::dot(S, a, s);
;     static __device__ __forceinline__ void updP(float (&P)[64], const In1& in, float sa) {
;         float u0, u1, u2, u3;
;         asm volatile("v_mul_f32_dpp %0, %8, %4 row_newbcast:%17" DPPM "v_mul_f32_dpp %1, %9, %5 row_newbcast:%17" DPPM "v_mul_f32_dpp %2, %10, %6 row_newbcast:%17" DPPM "v_mul_f32_dpp %3, %11, %7 row_newbcast:%17" DPPM
;                      "v_fmac_f32_dpp %0, %12, %16 row_newbcast:%17" DPPM "v_fmac_f32_dpp %1, %13, %16 row_newbcast:%17" DPPM "v_fmac_f32_dpp %2, %14, %16 row_newbcast:%17" DPPM "v_fmac_f32_dpp %3, %15, %16 row_newbcast:%17" DPPM
;                      : "=&v"(u0), "=&v"(u1), "=&v"(u2), "=&v"(u3)
.Lmy_p1d0_loop_p:
	s_waitcnt vmcnt(6)
	buffer_load_dwordx4 v[156:159], v204, s[64:67], s72 offen
	buffer_load_dwordx4 v[160:163], v204, s[64:67], s73 offen
	buffer_load_dwordx4 v[164:167], v204, s[64:67], s74 offen
	s_cmp_lt_u32 s80, 255
	s_cselect_b32 s81, 0x1000, 0
	s_cselect_b32 s82, 0x800, 0
	s_cselect_b32 s9, 1, 0
	s_add_u32 s80, s80, s9
	s_add_u32 s72, s72, s81
	s_add_u32 s73, s73, s81
	s_add_u32 s74, s74, s81
	v_pk_mul_f32 v[224:225], v[100:101], v[216:217]
	v_pk_mul_f32 v[226:227], v[102:103], v[218:219]
	v_pk_mul_f32 v[216:217], v[216:217], v[96:97]
	v_pk_mul_f32 v[218:219], v[218:219], v[98:99]
	v_pk_mul_f32 v[176:177], v[100:101], v[104:105]
	v_pk_mul_f32 v[178:179], v[102:103], v[106:107]
	v_rcp_f32_e32 v220, v216
	v_rcp_f32_e32 v221, v217
	v_rcp_f32_e32 v222, v218
	v_rcp_f32_e32 v223, v219
	s_nop 0
	v_pk_mul_f32 v[176:177], v[176:177], v[220:221]
	v_pk_mul_f32 v[178:179], v[178:179], v[222:223]
	ds_write_b128 v208, v[176:179]
	ds_read2_b32 v[64:65], v209 offset0:0 offset1:4
	ds_read2_b32 v[66:67], v209 offset0:8 offset1:12
	ds_read2_b32 v[68:69], v209 offset0:16 offset1:20
	ds_read2_b32 v[70:71], v209 offset0:24 offset1:28
	ds_read2_b32 v[72:73], v209 offset0:32 offset1:36
	ds_read2_b32 v[74:75], v209 offset0:40 offset1:44
	ds_read2_b32 v[76:77], v209 offset0:48 offset1:52
	ds_read2_b32 v[78:79], v209 offset0:56 offset1:60
	v_mul_f32_dpp v196, v224, v0 row_newbcast:0 row_mask:0xf bank_mask:0xf
	v_mul_f32_dpp v197, v225, v1 row_newbcast:0 row_mask:0xf bank_mask:0xf
	v_mul_f32_dpp v198, v226, v2 row_newbcast:0 row_mask:0xf bank_mask:0xf
	v_mul_f32_dpp v199, v227, v3 row_newbcast:0 row_mask:0xf bank_mask:0xf
	v_fmac_f32_dpp v196, v224, v4 row_newbcast:1 row_mask:0xf bank_mask:0xf
	v_fmac_f32_dpp v197, v225, v5 row_newbcast:1 row_mask:0xf bank_mask:0xf
	v_fmac_f32_dpp v198, v226, v6 row_newbcast:1 row_mask:0xf bank_mask:0xf
	v_fmac_f32_dpp v199, v227, v7 row_newbcast:1 row_mask:0xf bank_mask:0xf
	v_fmac_f32_dpp v196, v224, v8 row_newbcast:2 row_mask:0xf bank_mask:0xf
	v_fmac_f32_dpp v197, v225, v9 row_newbcast:2 row_mask:0xf bank_mask:0xf
	v_fmac_f32_dpp v198, v226, v10 row_newbcast:2 row_mask:0xf bank_mask:0xf
	v_fmac_f32_dpp v199, v227, v11 row_newbcast:2 row_mask:0xf bank_mask:0xf
	v_fmac_f32_dpp v196, v224, v12 row_newbcast:3 row_mask:0xf bank_mask:0xf
	v_fmac_f32_dpp v197, v225, v13 row_newbcast:3 row_mask:0xf bank_mask:0xf
	v_fmac_f32_dpp v198, v226, v14 row_newbcast:3 row_mask:0xf bank_mask:0xf
	v_fmac_f32_dpp v199, v227, v15 row_newbcast:3 row_mask:0xf bank_mask:0xf
	v_fmac_f32_dpp v196, v224, v16 row_newbcast:4 row_mask:0xf bank_mask:0xf
	v_fmac_f32_dpp v197, v225, v17 row_newbcast:4 row_mask:0xf bank_mask:0xf
	v_fmac_f32_dpp v198, v226, v18 row_newbcast:4 row_mask:0xf bank_mask:0xf
	v_fmac_f32_dpp v199, v227, v19 row_newbcast:4 row_mask:0xf bank_mask:0xf
	v_fmac_f32_dpp v196, v224, v20 row_newbcast:5 row_mask:0xf bank_mask:0xf
	v_fmac_f32_dpp v197, v225, v21 row_newbcast:5 row_mask:0xf bank_mask:0xf
	v_fmac_f32_dpp v198, v226, v22 row_newbcast:5 row_mask:0xf bank_mask:0xf
	v_fmac_f32_dpp v199, v227, v23 row_newbcast:5 row_mask:0xf bank_mask:0xf
	v_fmac_f32_dpp v196, v224, v24 row_newbcast:6 row_mask:0xf bank_mask:0xf
	v_fmac_f32_dpp v197, v225, v25 row_newbcast:6 row_mask:0xf bank_mask:0xf
	v_fmac_f32_dpp v198, v226, v26 row_newbcast:6 row_mask:0xf bank_mask:0xf
	v_fmac_f32_dpp v199, v227, v27 row_newbcast:6 row_mask:0xf bank_mask:0xf
	v_fmac_f32_dpp v196, v224, v28 row_newbcast:7 row_mask:0xf bank_mask:0xf
	v_fmac_f32_dpp v197, v225, v29 row_newbcast:7 row_mask:0xf bank_mask:0xf
	v_fmac_f32_dpp v198, v226, v30 row_newbcast:7 row_mask:0xf bank_mask:0xf
	v_fmac_f32_dpp v199, v227, v31 row_newbcast:7 row_mask:0xf bank_mask:0xf
	v_fmac_f32_dpp v196, v224, v32 row_newbcast:8 row_mask:0xf bank_mask:0xf
	v_fmac_f32_dpp v197, v225, v33 row_newbcast:8 row_mask:0xf bank_mask:0xf
	v_fmac_f32_dpp v198, v226, v34 row_newbcast:8 row_mask:0xf bank_mask:0xf
	v_fmac_f32_dpp v199, v227, v35 row_newbcast:8 row_mask:0xf bank_mask:0xf
	v_fmac_f32_dpp v196, v224, v36 row_newbcast:9 row_mask:0xf bank_mask:0xf
	v_fmac_f32_dpp v197, v225, v37 row_newbcast:9 row_mask:0xf bank_mask:0xf
	v_fmac_f32_dpp v198, v226, v38 row_newbcast:9 row_mask:0xf bank_mask:0xf
	v_fmac_f32_dpp v199, v227, v39 row_newbcast:9 row_mask:0xf bank_mask:0xf
	v_fmac_f32_dpp v196, v224, v40 row_newbcast:10 row_mask:0xf bank_mask:0xf
	v_fmac_f32_dpp v197, v225, v41 row_newbcast:10 row_mask:0xf bank_mask:0xf
	v_fmac_f32_dpp v198, v226, v42 row_newbcast:10 row_mask:0xf bank_mask:0xf
	v_fmac_f32_dpp v199, v227, v43 row_newbcast:10 row_mask:0xf bank_mask:0xf
	v_fmac_f32_dpp v196, v224, v44 row_newbcast:11 row_mask:0xf bank_mask:0xf
	v_fmac_f32_dpp v197, v225, v45 row_newbcast:11 row_mask:0xf bank_mask:0xf
	v_fmac_f32_dpp v198, v226, v46 row_newbcast:11 row_mask:0xf bank_mask:0xf
	v_fmac_f32_dpp v199, v227, v47 row_newbcast:11 row_mask:0xf bank_mask:0xf
	v_fmac_f32_dpp v196, v224, v48 row_newbcast:12 row_mask:0xf bank_mask:0xf
	v_fmac_f32_dpp v197, v225, v49 row_newbcast:12 row_mask:0xf bank_mask:0xf
	v_fmac_f32_dpp v198, v226, v50 row_newbcast:12 row_mask:0xf bank_mask:0xf
	v_fmac_f32_dpp v199, v227, v51 row_newbcast:12 row_mask:0xf bank_mask:0xf
	v_fmac_f32_dpp v196, v224, v52 row_newbcast:13 row_mask:0xf bank_mask:0xf
	v_fmac_f32_dpp v197, v225, v53 row_newbcast:13 row_mask:0xf bank_mask:0xf
	v_fmac_f32_dpp v198, v226, v54 row_newbcast:13 row_mask:0xf bank_mask:0xf
	v_fmac_f32_dpp v199, v227, v55 row_newbcast:13 row_mask:0xf bank_mask:0xf
	v_fmac_f32_dpp v196, v224, v56 row_newbcast:14 row_mask:0xf bank_mask:0xf
	v_fmac_f32_dpp v197, v225, v57 row_newbcast:14 row_mask:0xf bank_mask:0xf
	v_fmac_f32_dpp v198, v226, v58 row_newbcast:14 row_mask:0xf bank_mask:0xf
	v_fmac_f32_dpp v199, v227, v59 row_newbcast:14 row_mask:0xf bank_mask:0xf
	v_fmac_f32_dpp v196, v224, v60 row_newbcast:15 row_mask:0xf bank_mask:0xf
	v_fmac_f32_dpp v197, v225, v61 row_newbcast:15 row_mask:0xf bank_mask:0xf
	v_fmac_f32_dpp v198, v226, v62 row_newbcast:15 row_mask:0xf bank_mask:0xf
	v_fmac_f32_dpp v199, v227, v63 row_newbcast:15 row_mask:0xf bank_mask:0xf
	v_add_f32_e32 v196, v196, v197
	v_add_f32_e32 v198, v198, v199
	v_add_f32_e32 v196, v196, v198
	v_xor_b32_e32 v202, 0x80000000, v196
	s_waitcnt lgkmcnt(0)
;     static __device__ __forceinline__ void dot(const float (&S)[64], const f32x4& a, float (&s)[4]) {
;         if constexpr (K == 0) {
;             asm volatile("v_mul_f32_dpp %0, %4, %8 row_newbcast:%16" DPPM "v_mul_f32_dpp %1, %5, %9 row_newbcast:%16" DPPM "v_mul_f32_dpp %2, %6, %10 row_newbcast:%16" DPPM "v_mul_f32_dpp %3, %7, %11 row_newbcast:%16" DPPM
;                          "v_fmac_f32_dpp %0, %4, %12 row_newbcast:%17" DPPM "v_fmac_f32_dpp %1, %5, %13 row_newbcast:%17" DPPM "v_fmac_f32_dpp %2, %6, %14 row_newbcast:%17" DPPM "v_fmac_f32_dpp %3, %7, %15 row_newbcast:%17" DPPM
;                          : "=&v"(s[0]), "=&v"(s[1]), "=&v"(s[2]), "=&v"(s[3])
;                          : "v"(a[0]), "v"(a[1]), "v"(a[2]), "v"(a[3]), "v"(S[K]), "v"(S[K + 1]), "v"(S[K + 2]), "v"(S[K + 3]), "v"(S[K + 4]), "v"(S[K + 5]), "v"(S[K + 6]), "v"(S[K + 7]), "n"(N0), "n"(N1));
;         } else
;         asm volatile("v_fmac_f32_dpp %0, %4, %8 row_newbcast:%16" DPPM "v_fmac_f32_dpp %1, %5, %9 row_newbcast:%16" DPPM "v_fmac_f32_dpp %2, %6, %10 row_newbcast:%16" DPPM "v_fmac_f32_dpp %3, %7, %11 row_newbcast:%16" DPPM
;                      "v_fmac_f32_dpp %0, %4, %12 row_newbcast:%17" DPPM "v_fmac_f32_dpp %1, %5, %13 row_newbcast:%17" DPPM "v_fmac_f32_dpp %2, %6, %14 row_newbcast:%17" DPPM "v_fmac_f32_dpp %3, %7, %15 row_newbcast:%17" DPPM
;                      : "+v"(s[0]), "+v"(s[1]), "+v"(s[2]), "+v"(s[3])
;                      : "v"(a[0]), "v"(a[1]), "v"(a[2]), "v"(a[3]), "v"(S[K]), "v"(S[K + 1]), "v"(S[K + 2]), "v"(S[K + 3]), "v"(S[K + 4]), "v"(S[K + 5]), "v"(S[K + 6]), "v"(S[K + 7]), "n"(N0), "n"(N1));
;         if constexpr (K + 8 < 64) ScanK<K + 8>::dot(S, a, s);
;     static __device__ __forceinline__ void updP(float (&P)[64], const In1& in, float sa) {
;         float u0, u1, u2, u3;
;         asm volatile("v_mul_f32_dpp %0, %8, %4 row_newbcast:%17" DPPM "v_mul_f32_dpp %1, %9, %5 row_newbcast:%17" DPPM "v_mul_f32_dpp %2, %10, %6 row_newbcast:%17" DPPM "v_mul_f32_dpp %3, %11, %7 row_newbcast:%17" DPPM
;                      "v_fmac_f32_dpp %0, %12, %16 row_newbcast:%17" DPPM "v_fmac_f32_dpp %1, %13, %16 row_newbcast:%17" DPPM "v_fmac_f32_dpp %2, %14, %16 row_newbcast:%17" DPPM "v_fmac_f32_dpp %3, %15, %16 row_newbcast:%17" DPPM
;                      : "=&v"(u0), "=&v"(u1), "=&v"(u2), "=&v"(u3)
	s_nop 1
	v_mfma_f32_4x4x1_16b_f32 v[0:3], v64, v202, v[0:3]
	v_mfma_f32_4x4x1_16b_f32 v[4:7], v65, v202, v[4:7]
	v_mfma_f32_4x4x1_16b_f32 v[8:11], v66, v202, v[8:11]
	v_mfma_f32_4x4x1_16b_f32 v[12:15], v67, v202, v[12:15]
	v_mfma_f32_4x4x1_16b_f32 v[16:19], v68, v202, v[16:19]
	v_mfma_f32_4x4x1_16b_f32 v[20:23], v69, v202, v[20:23]
	v_mfma_f32_4x4x1_16b_f32 v[24:27], v70, v202, v[24:27]
	v_mfma_f32_4x4x1_16b_f32 v[28:31], v71, v202, v[28:31]
	v_mfma_f32_4x4x1_16b_f32 v[32:35], v72, v202, v[32:35]
	v_mfma_f32_4x4x1_16b_f32 v[36:39], v73, v202, v[36:39]
	v_mfma_f32_4x4x1_16b_f32 v[40:43], v74, v202, v[40:43]
	v_mfma_f32_4x4x1_16b_f32 v[44:47], v75, v202, v[44:47]
	v_mfma_f32_4x4x1_16b_f32 v[48:51], v76, v202, v[48:51]
	v_mfma_f32_4x4x1_16b_f32 v[52:55], v77, v202, v[52:55]
	v_mfma_f32_4x4x1_16b_f32 v[56:59], v78, v202, v[56:59]
	v_mfma_f32_4x4x1_16b_f32 v[60:63], v79, v202, v[60:63]
	s_waitcnt vmcnt(6)
	buffer_load_dwordx4 v[96:99], v204, s[64:67], s72 offen
	buffer_load_dwordx4 v[100:103], v204, s[64:67], s73 offen
	buffer_load_dwordx4 v[104:107], v204, s[64:67], s74 offen
	s_cmp_lt_u32 s80, 255
	s_cselect_b32 s81, 0x1000, 0
	s_cselect_b32 s82, 0x800, 0
	s_cselect_b32 s9, 1, 0
	s_add_u32 s80, s80, s9
	s_add_u32 s72, s72, s81
	s_add_u32 s73, s73, s81
	s_add_u32 s74, s74, s81
	v_pk_mul_f32 v[224:225], v[120:121], v[216:217]
	v_pk_mul_f32 v[226:227], v[122:123], v[218:219]
	v_pk_mul_f32 v[216:217], v[216:217], v[116:117]
	v_pk_mul_f32 v[218:219], v[218:219], v[118:119]
	v_pk_mul_f32 v[176:177], v[120:121], v[124:125]
	v_pk_mul_f32 v[178:179], v[122:123], v[126:127]
	v_rcp_f32_e32 v220, v216
	v_rcp_f32_e32 v221, v217
	v_rcp_f32_e32 v222, v218
	v_rcp_f32_e32 v223, v219
	s_nop 0
	v_pk_mul_f32 v[176:177], v[176:177], v[220:221]
	v_pk_mul_f32 v[178:179], v[178:179], v[222:223]
	ds_write_b128 v208, v[176:179]
	ds_read2_b32 v[64:65], v209 offset0:0 offset1:4
	ds_read2_b32 v[66:67], v209 offset0:8 offset1:12
	ds_read2_b32 v[68:69], v209 offset0:16 offset1:20
	ds_read2_b32 v[70:71], v209 offset0:24 offset1:28
	ds_read2_b32 v[72:73], v209 offset0:32 offset1:36
	ds_read2_b32 v[74:75], v209 offset0:40 offset1:44
	ds_read2_b32 v[76:77], v209 offset0:48 offset1:52
	ds_read2_b32 v[78:79], v209 offset0:56 offset1:60
	v_mul_f32_dpp v196, v224, v0 row_newbcast:0 row_mask:0xf bank_mask:0xf
	v_mul_f32_dpp v197, v225, v1 row_newbcast:0 row_mask:0xf bank_mask:0xf
	v_mul_f32_dpp v198, v226, v2 row_newbcast:0 row_mask:0xf bank_mask:0xf
	v_mul_f32_dpp v199, v227, v3 row_newbcast:0 row_mask:0xf bank_mask:0xf
	v_fmac_f32_dpp v196, v224, v4 row_newbcast:1 row_mask:0xf bank_mask:0xf
	v_fmac_f32_dpp v197, v225, v5 row_newbcast:1 row_mask:0xf bank_mask:0xf
	v_fmac_f32_dpp v198, v226, v6 row_newbcast:1 row_mask:0xf bank_mask:0xf
	v_fmac_f32_dpp v199, v227, v7 row_newbcast:1 row_mask:0xf bank_mask:0xf
	v_fmac_f32_dpp v196, v224, v8 row_newbcast:2 row_mask:0xf bank_mask:0xf
	v_fmac_f32_dpp v197, v225, v9 row_newbcast:2 row_mask:0xf bank_mask:0xf
	v_fmac_f32_dpp v198, v226, v10 row_newbcast:2 row_mask:0xf bank_mask:0xf
	v_fmac_f32_dpp v199, v227, v11 row_newbcast:2 row_mask:0xf bank_mask:0xf
	v_fmac_f32_dpp v196, v224, v12 row_newbcast:3 row_mask:0xf bank_mask:0xf
	v_fmac_f32_dpp v197, v225, v13 row_newbcast:3 row_mask:0xf bank_mask:0xf
	v_fmac_f32_dpp v198, v226, v14 row_newbcast:3 row_mask:0xf bank_mask:0xf
	v_fmac_f32_dpp v199, v227, v15 row_newbcast:3 row_mask:0xf bank_mask:0xf
	v_fmac_f32_dpp v196, v224, v16 row_newbcast:4 row_mask:0xf bank_mask:0xf
	v_fmac_f32_dpp v197, v225, v17 row_newbcast:4 row_mask:0xf bank_mask:0xf
	v_fmac_f32_dpp v198, v226, v18 row_newbcast:4 row_mask:0xf bank_mask:0xf
	v_fmac_f32_dpp v199, v227, v19 row_newbcast:4 row_mask:0xf bank_mask:0xf
	v_fmac_f32_dpp v196, v224, v20 row_newbcast:5 row_mask:0xf bank_mask:0xf
	v_fmac_f32_dpp v197, v225, v21 row_newbcast:5 row_mask:0xf bank_mask:0xf
	v_fmac_f32_dpp v198, v226, v22 row_newbcast:5 row_mask:0xf bank_mask:0xf
	v_fmac_f32_dpp v199, v227, v23 row_newbcast:5 row_mask:0xf bank_mask:0xf
	v_fmac_f32_dpp v196, v224, v24 row_newbcast:6 row_mask:0xf bank_mask:0xf
	v_fmac_f32_dpp v197, v225, v25 row_newbcast:6 row_mask:0xf bank_mask:0xf
	v_fmac_f32_dpp v198, v226, v26 row_newbcast:6 row_mask:0xf bank_mask:0xf
	v_fmac_f32_dpp v199, v227, v27 row_newbcast:6 row_mask:0xf bank_mask:0xf
	v_fmac_f32_dpp v196, v224, v28 row_newbcast:7 row_mask:0xf bank_mask:0xf
	v_fmac_f32_dpp v197, v225, v29 row_newbcast:7 row_mask:0xf bank_mask:0xf
	v_fmac_f32_dpp v198, v226, v30 row_newbcast:7 row_mask:0xf bank_mask:0xf
	v_fmac_f32_dpp v199, v227, v31 row_newbcast:7 row_mask:0xf bank_mask:0xf
	v_fmac_f32_dpp v196, v224, v32 row_newbcast:8 row_mask:0xf bank_mask:0xf
	v_fmac_f32_dpp v197, v225, v33 row_newbcast:8 row_mask:0xf bank_mask:0xf
	v_fmac_f32_dpp v198, v226, v34 row_newbcast:8 row_mask:0xf bank_mask:0xf
	v_fmac_f32_dpp v199, v227, v35 row_newbcast:8 row_mask:0xf bank_mask:0xf
	v_fmac_f32_dpp v196, v224, v36 row_newbcast:9 row_mask:0xf bank_mask:0xf
	v_fmac_f32_dpp v197, v225, v37 row_newbcast:9 row_mask:0xf bank_mask:0xf
	v_fmac_f32_dpp v198, v226, v38 row_newbcast:9 row_mask:0xf bank_mask:0xf
	v_fmac_f32_dpp v199, v227, v39 row_newbcast:9 row_mask:0xf bank_mask:0xf
	v_fmac_f32_dpp v196, v224, v40 row_newbcast:10 row_mask:0xf bank_mask:0xf
	v_fmac_f32_dpp v197, v225, v41 row_newbcast:10 row_mask:0xf bank_mask:0xf
	v_fmac_f32_dpp v198, v226, v42 row_newbcast:10 row_mask:0xf bank_mask:0xf
	v_fmac_f32_dpp v199, v227, v43 row_newbcast:10 row_mask:0xf bank_mask:0xf
	v_fmac_f32_dpp v196, v224, v44 row_newbcast:11 row_mask:0xf bank_mask:0xf
	v_fmac_f32_dpp v197, v225, v45 row_newbcast:11 row_mask:0xf bank_mask:0xf
;     static __device__ __forceinline__ void dot(const float (&S)[64], const f32x4& a, float (&s)[4]) {
;         if constexpr (K == 0) {
;             asm volatile("v_mul_f32_dpp %0, %4, %8 row_newbcast:%16" DPPM "v_mul_f32_dpp %1, %5, %9 row_newbcast:%16" DPPM "v_mul_f32_dpp %2, %6, %10 row_newbcast:%16" DPPM "v_mul_f32_dpp %3, %7, %11 row_newbcast:%16" DPPM
;                          "v_fmac_f32_dpp %0, %4, %12 row_newbcast:%17" DPPM "v_fmac_f32_dpp %1, %5, %13 row_newbcast:%17" DPPM "v_fmac_f32_dpp %2, %6, %14 row_newbcast:%17" DPPM "v_fmac_f32_dpp %3, %7, %15 row_newbcast:%17" DPPM
;                          : "=&v"(s[0]), "=&v"(s[1]), "=&v"(s[2]), "=&v"(s[3])
;                          : "v"(a[0]), "v"(a[1]), "v"(a[2]), "v"(a[3]), "v"(S[K]), "v"(S[K + 1]), "v"(S[K + 2]), "v"(S[K + 3]), "v"(S[K + 4]), "v"(S[K + 5]), "v"(S[K + 6]), "v"(S[K + 7]), "n"(N0), "n"(N1));
;         } else
;         asm volatile("v_fmac_f32_dpp %0, %4, %8 row_newbcast:%16" DPPM "v_fmac_f32_dpp %1, %5, %9 row_newbcast:%16" DPPM "v_fmac_f32_dpp %2, %6, %10 row_newbcast:%16" DPPM "v_fmac_f32_dpp %3, %7, %11 row_newbcast:%16" DPPM
;                      "v_fmac_f32_dpp %0, %4, %12 row_newbcast:%17" DPPM "v_fmac_f32_dpp %1, %5, %13 row_newbcast:%17" DPPM "v_fmac_f32_dpp %2, %6, %14 row_newbcast:%17" DPPM "v_fmac_f32_dpp %3, %7, %15 row_newbcast:%17" DPPM
;                      : "+v"(s[0]), "+v"(s[1]), "+v"(s[2]), "+v"(s[3])
;                      : "v"(a[0]), "v"(a[1]), "v"(a[2]), "v"(a[3]), "v"(S[K]), "v"(S[K + 1]), "v"(S[K + 2]), "v"(S[K + 3]), "v"(S[K + 4]), "v"(S[K + 5]), "v"(S[K + 6]), "v"(S[K + 7]), "n"(N0), "n"(N1));
;         if constexpr (K + 8 < 64) ScanK<K + 8>::dot(S, a, s);
;     static __device__ __forceinline__ void updP(float (&P)[64], const In1& in, float sa) {
;         float u0, u1, u2, u3;
;         asm volatile("v_mul_f32_dpp %0, %8, %4 row_newbcast:%17" DPPM "v_mul_f32_dpp %1, %9, %5 row_newbcast:%17" DPPM "v_mul_f32_dpp %2, %10, %6 row_newbcast:%17" DPPM "v_mul_f32_dpp %3, %11, %7 row_newbcast:%17" DPPM
;                      "v_fmac_f32_dpp %0, %12, %16 row_newbcast:%17" DPPM "v_fmac_f32_dpp %1, %13, %16 row_newbcast:%17" DPPM "v_fmac_f32_dpp %2, %14, %16 row_newbcast:%17" DPPM "v_fmac_f32_dpp %3, %15, %16 row_newbcast:%17" DPPM
;                      : "=&v"(u0), "=&v"(u1), "=&v"(u2), "=&v"(u3)
	v_fmac_f32_dpp v198, v226, v46 row_newbcast:11 row_mask:0xf bank_mask:0xf
	v_fmac_f32_dpp v199, v227, v47 row_newbcast:11 row_mask:0xf bank_mask:0xf
	v_fmac_f32_dpp v196, v224, v48 row_newbcast:12 row_mask:0xf bank_mask:0xf
	v_fmac_f32_dpp v197, v225, v49 row_newbcast:12 row_mask:0xf bank_mask:0xf
	v_fmac_f32_dpp v198, v226, v50 row_newbcast:12 row_mask:0xf bank_mask:0xf
	v_fmac_f32_dpp v199, v227, v51 row_newbcast:12 row_mask:0xf bank_mask:0xf
	v_fmac_f32_dpp v196, v224, v52 row_newbcast:13 row_mask:0xf bank_mask:0xf
	v_fmac_f32_dpp v197, v225, v53 row_newbcast:13 row_mask:0xf bank_mask:0xf
	v_fmac_f32_dpp v198, v226, v54 row_newbcast:13 row_mask:0xf bank_mask:0xf
	v_fmac_f32_dpp v199, v227, v55 row_newbcast:13 row_mask:0xf bank_mask:0xf
	v_fmac_f32_dpp v196, v224, v56 row_newbcast:14 row_mask:0xf bank_mask:0xf
	v_fmac_f32_dpp v197, v225, v57 row_newbcast:14 row_mask:0xf bank_mask:0xf
	v_fmac_f32_dpp v198, v226, v58 row_newbcast:14 row_mask:0xf bank_mask:0xf
	v_fmac_f32_dpp v199, v227, v59 row_newbcast:14 row_mask:0xf bank_mask:0xf
	v_fmac_f32_dpp v196, v224, v60 row_newbcast:15 row_mask:0xf bank_mask:0xf
	v_fmac_f32_dpp v197, v225, v61 row_newbcast:15 row_mask:0xf bank_mask:0xf
	v_fmac_f32_dpp v198, v226, v62 row_newbcast:15 row_mask:0xf bank_mask:0xf
	v_fmac_f32_dpp v199, v227, v63 row_newbcast:15 row_mask:0xf bank_mask:0xf
	v_add_f32_e32 v196, v196, v197
	v_add_f32_e32 v198, v198, v199
	v_add_f32_e32 v196, v196, v198
	v_xor_b32_e32 v202, 0x80000000, v196
	s_waitcnt lgkmcnt(0)
	s_nop 1
	v_mfma_f32_4x4x1_16b_f32 v[0:3], v64, v202, v[0:3]
	v_mfma_f32_4x4x1_16b_f32 v[4:7], v65, v202, v[4:7]
	v_mfma_f32_4x4x1_16b_f32 v[8:11], v66, v202, v[8:11]
	v_mfma_f32_4x4x1_16b_f32 v[12:15], v67, v202, v[12:15]
	v_mfma_f32_4x4x1_16b_f32 v[16:19], v68, v202, v[16:19]
	v_mfma_f32_4x4x1_16b_f32 v[20:23], v69, v202, v[20:23]
	v_mfma_f32_4x4x1_16b_f32 v[24:27], v70, v202, v[24:27]
	v_mfma_f32_4x4x1_16b_f32 v[28:31], v71, v202, v[28:31]
	v_mfma_f32_4x4x1_16b_f32 v[32:35], v72, v202, v[32:35]
	v_mfma_f32_4x4x1_16b_f32 v[36:39], v73, v202, v[36:39]
	v_mfma_f32_4x4x1_16b_f32 v[40:43], v74, v202, v[40:43]
	v_mfma_f32_4x4x1_16b_f32 v[44:47], v75, v202, v[44:47]
	v_mfma_f32_4x4x1_16b_f32 v[48:51], v76, v202, v[48:51]
	v_mfma_f32_4x4x1_16b_f32 v[52:55], v77, v202, v[52:55]
	v_mfma_f32_4x4x1_16b_f32 v[56:59], v78, v202, v[56:59]
	v_mfma_f32_4x4x1_16b_f32 v[60:63], v79, v202, v[60:63]
	s_waitcnt vmcnt(6)
	buffer_load_dwordx4 v[116:119], v204, s[64:67], s72 offen
	buffer_load_dwordx4 v[120:123], v204, s[64:67], s73 offen
	buffer_load_dwordx4 v[124:127], v204, s[64:67], s74 offen
	s_cmp_lt_u32 s80, 255
	s_cselect_b32 s81, 0x1000, 0
	s_cselect_b32 s82, 0x800, 0
	s_cselect_b32 s9, 1, 0
	s_add_u32 s80, s80, s9
	s_add_u32 s72, s72, s81
	s_add_u32 s73, s73, s81
	s_add_u32 s74, s74, s81
	v_pk_mul_f32 v[224:225], v[140:141], v[216:217]
	v_pk_mul_f32 v[226:227], v[142:143], v[218:219]
	v_pk_mul_f32 v[216:217], v[216:217], v[136:137]
	v_pk_mul_f32 v[218:219], v[218:219], v[138:139]
	v_pk_mul_f32 v[176:177], v[140:141], v[144:145]
	v_pk_mul_f32 v[178:179], v[142:143], v[146:147]
	v_rcp_f32_e32 v220, v216
	v_rcp_f32_e32 v221, v217
	v_rcp_f32_e32 v222, v218
	v_rcp_f32_e32 v223, v219
	s_nop 0
	v_pk_mul_f32 v[176:177], v[176:177], v[220:221]
	v_pk_mul_f32 v[178:179], v[178:179], v[222:223]
	ds_write_b128 v208, v[176:179]
	ds_read2_b32 v[64:65], v209 offset0:0 offset1:4
	ds_read2_b32 v[66:67], v209 offset0:8 offset1:12
	ds_read2_b32 v[68:69], v209 offset0:16 offset1:20
	ds_read2_b32 v[70:71], v209 offset0:24 offset1:28
	ds_read2_b32 v[72:73], v209 offset0:32 offset1:36
	ds_read2_b32 v[74:75], v209 offset0:40 offset1:44
	ds_read2_b32 v[76:77], v209 offset0:48 offset1:52
	ds_read2_b32 v[78:79], v209 offset0:56 offset1:60
	v_mul_f32_dpp v196, v224, v0 row_newbcast:0 row_mask:0xf bank_mask:0xf
	v_mul_f32_dpp v197, v225, v1 row_newbcast:0 row_mask:0xf bank_mask:0xf
	v_mul_f32_dpp v198, v226, v2 row_newbcast:0 row_mask:0xf bank_mask:0xf
	v_mul_f32_dpp v199, v227, v3 row_newbcast:0 row_mask:0xf bank_mask:0xf
	v_fmac_f32_dpp v196, v224, v4 row_newbcast:1 row_mask:0xf bank_mask:0xf
	v_fmac_f32_dpp v197, v225, v5 row_newbcast:1 row_mask:0xf bank_mask:0xf
	v_fmac_f32_dpp v198, v226, v6 row_newbcast:1 row_mask:0xf bank_mask:0xf
	v_fmac_f32_dpp v199, v227, v7 row_newbcast:1 row_mask:0xf bank_mask:0xf
	v_fmac_f32_dpp v196, v224, v8 row_newbcast:2 row_mask:0xf bank_mask:0xf
	v_fmac_f32_dpp v197, v225, v9 row_newbcast:2 row_mask:0xf bank_mask:0xf
	v_fmac_f32_dpp v198, v226, v10 row_newbcast:2 row_mask:0xf bank_mask:0xf
	v_fmac_f32_dpp v199, v227, v11 row_newbcast:2 row_mask:0xf bank_mask:0xf
	v_fmac_f32_dpp v196, v224, v12 row_newbcast:3 row_mask:0xf bank_mask:0xf
	v_fmac_f32_dpp v197, v225, v13 row_newbcast:3 row_mask:0xf bank_mask:0xf
	v_fmac_f32_dpp v198, v226, v14 row_newbcast:3 row_mask:0xf bank_mask:0xf
	v_fmac_f32_dpp v199, v227, v15 row_newbcast:3 row_mask:0xf bank_mask:0xf
	v_fmac_f32_dpp v196, v224, v16 row_newbcast:4 row_mask:0xf bank_mask:0xf
	v_fmac_f32_dpp v197, v225, v17 row_newbcast:4 row_mask:0xf bank_mask:0xf
	v_fmac_f32_dpp v198, v226, v18 row_newbcast:4 row_mask:0xf bank_mask:0xf
	v_fmac_f32_dpp v199, v227, v19 row_newbcast:4 row_mask:0xf bank_mask:0xf
	v_fmac_f32_dpp v196, v224, v20 row_newbcast:5 row_mask:0xf bank_mask:0xf
	v_fmac_f32_dpp v197, v225, v21 row_newbcast:5 row_mask:0xf bank_mask:0xf
	v_fmac_f32_dpp v198, v226, v22 row_newbcast:5 row_mask:0xf bank_mask:0xf
	v_fmac_f32_dpp v199, v227, v23 row_newbcast:5 row_mask:0xf bank_mask:0xf
	v_fmac_f32_dpp v196, v224, v24 row_newbcast:6 row_mask:0xf bank_mask:0xf
	v_fmac_f32_dpp v197, v225, v25 row_newbcast:6 row_mask:0xf bank_mask:0xf
;     static __device__ __forceinline__ void dot(const float (&S)[64], const f32x4& a, float (&s)[4]) {
;         if constexpr (K == 0) {
;             asm volatile("v_mul_f32_dpp %0, %4, %8 row_newbcast:%16" DPPM "v_mul_f32_dpp %1, %5, %9 row_newbcast:%16" DPPM "v_mul_f32_dpp %2, %6, %10 row_newbcast:%16" DPPM "v_mul_f32_dpp %3, %7, %11 row_newbcast:%16" DPPM
;                          "v_fmac_f32_dpp %0, %4, %12 row_newbcast:%17" DPPM "v_fmac_f32_dpp %1, %5, %13 row_newbcast:%17" DPPM "v_fmac_f32_dpp %2, %6, %14 row_newbcast:%17" DPPM "v_fmac_f32_dpp %3, %7, %15 row_newbcast:%17" DPPM
;                          : "=&v"(s[0]), "=&v"(s[1]), "=&v"(s[2]), "=&v"(s[3])
;                          : "v"(a[0]), "v"(a[1]), "v"(a[2]), "v"(a[3]), "v"(S[K]), "v"(S[K + 1]), "v"(S[K + 2]), "v"(S[K + 3]), "v"(S[K + 4]), "v"(S[K + 5]), "v"(S[K + 6]), "v"(S[K + 7]), "n"(N0), "n"(N1));
;         } else
;         asm volatile("v_fmac_f32_dpp %0, %4, %8 row_newbcast:%16" DPPM "v_fmac_f32_dpp %1, %5, %9 row_newbcast:%16" DPPM "v_fmac_f32_dpp %2, %6, %10 row_newbcast:%16" DPPM "v_fmac_f32_dpp %3, %7, %11 row_newbcast:%16" DPPM
;                      "v_fmac_f32_dpp %0, %4, %12 row_newbcast:%17" DPPM "v_fmac_f32_dpp %1, %5, %13 row_newbcast:%17" DPPM "v_fmac_f32_dpp %2, %6, %14 row_newbcast:%17" DPPM "v_fmac_f32_dpp %3, %7, %15 row_newbcast:%17" DPPM
;                      : "+v"(s[0]), "+v"(s[1]), "+v"(s[2]), "+v"(s[3])
;                      : "v"(a[0]), "v"(a[1]), "v"(a[2]), "v"(a[3]), "v"(S[K]), "v"(S[K + 1]), "v"(S[K + 2]), "v"(S[K + 3]), "v"(S[K + 4]), "v"(S[K + 5]), "v"(S[K + 6]), "v"(S[K + 7]), "n"(N0), "n"(N1));
;         if constexpr (K + 8 < 64) ScanK<K + 8>::dot(S, a, s);
;     static __device__ __forceinline__ void updP(float (&P)[64], const In1& in, float sa) {
;         float u0, u1, u2, u3;
;         asm volatile("v_mul_f32_dpp %0, %8, %4 row_newbcast:%17" DPPM "v_mul_f32_dpp %1, %9, %5 row_newbcast:%17" DPPM "v_mul_f32_dpp %2, %10, %6 row_newbcast:%17" DPPM "v_mul_f32_dpp %3, %11, %7 row_newbcast:%17" DPPM
;                      "v_fmac_f32_dpp %0, %12, %16 row_newbcast:%17" DPPM "v_fmac_f32_dpp %1, %13, %16 row_newbcast:%17" DPPM "v_fmac_f32_dpp %2, %14, %16 row_newbcast:%17" DPPM "v_fmac_f32_dpp %3, %15, %16 row_newbcast:%17" DPPM
;                      : "=&v"(u0), "=&v"(u1), "=&v"(u2), "=&v"(u3)
	v_fmac_f32_dpp v198, v226, v26 row_newbcast:6 row_mask:0xf bank_mask:0xf
	v_fmac_f32_dpp v199, v227, v27 row_newbcast:6 row_mask:0xf bank_mask:0xf
	v_fmac_f32_dpp v196, v224, v28 row_newbcast:7 row_mask:0xf bank_mask:0xf
	v_fmac_f32_dpp v197, v225, v29 row_newbcast:7 row_mask:0xf bank_mask:0xf
	v_fmac_f32_dpp v198, v226, v30 row_newbcast:7 row_mask:0xf bank_mask:0xf
	v_fmac_f32_dpp v199, v227, v31 row_newbcast:7 row_mask:0xf bank_mask:0xf
	v_fmac_f32_dpp v196, v224, v32 row_newbcast:8 row_mask:0xf bank_mask:0xf
	v_fmac_f32_dpp v197, v225, v33 row_newbcast:8 row_mask:0xf bank_mask:0xf
	v_fmac_f32_dpp v198, v226, v34 row_newbcast:8 row_mask:0xf bank_mask:0xf
	v_fmac_f32_dpp v199, v227, v35 row_newbcast:8 row_mask:0xf bank_mask:0xf
	v_fmac_f32_dpp v196, v224, v36 row_newbcast:9 row_mask:0xf bank_mask:0xf
	v_fmac_f32_dpp v197, v225, v37 row_newbcast:9 row_mask:0xf bank_mask:0xf
	v_fmac_f32_dpp v198, v226, v38 row_newbcast:9 row_mask:0xf bank_mask:0xf
	v_fmac_f32_dpp v199, v227, v39 row_newbcast:9 row_mask:0xf bank_mask:0xf
	v_fmac_f32_dpp v196, v224, v40 row_newbcast:10 row_mask:0xf bank_mask:0xf
	v_fmac_f32_dpp v197, v225, v41 row_newbcast:10 row_mask:0xf bank_mask:0xf
	v_fmac_f32_dpp v198, v226, v42 row_newbcast:10 row_mask:0xf bank_mask:0xf
	v_fmac_f32_dpp v199, v227, v43 row_newbcast:10 row_mask:0xf bank_mask:0xf
	v_fmac_f32_dpp v196, v224, v44 row_newbcast:11 row_mask:0xf bank_mask:0xf
	v_fmac_f32_dpp v197, v225, v45 row_newbcast:11 row_mask:0xf bank_mask:0xf
	v_fmac_f32_dpp v198, v226, v46 row_newbcast:11 row_mask:0xf bank_mask:0xf
	v_fmac_f32_dpp v199, v227, v47 row_newbcast:11 row_mask:0xf bank_mask:0xf
	v_fmac_f32_dpp v196, v224, v48 row_newbcast:12 row_mask:0xf bank_mask:0xf
	v_fmac_f32_dpp v197, v225, v49 row_newbcast:12 row_mask:0xf bank_mask:0xf
	v_fmac_f32_dpp v198, v226, v50 row_newbcast:12 row_mask:0xf bank_mask:0xf
	v_fmac_f32_dpp v199, v227, v51 row_newbcast:12 row_mask:0xf bank_mask:0xf
	v_fmac_f32_dpp v196, v224, v52 row_newbcast:13 row_mask:0xf bank_mask:0xf
	v_fmac_f32_dpp v197, v225, v53 row_newbcast:13 row_mask:0xf bank_mask:0xf
	v_fmac_f32_dpp v198, v226, v54 row_newbcast:13 row_mask:0xf bank_mask:0xf
	v_fmac_f32_dpp v199, v227, v55 row_newbcast:13 row_mask:0xf bank_mask:0xf
	v_fmac_f32_dpp v196, v224, v56 row_newbcast:14 row_mask:0xf bank_mask:0xf
	v_fmac_f32_dpp v197, v225, v57 row_newbcast:14 row_mask:0xf bank_mask:0xf
	v_fmac_f32_dpp v198, v226, v58 row_newbcast:14 row_mask:0xf bank_mask:0xf
	v_fmac_f32_dpp v199, v227, v59 row_newbcast:14 row_mask:0xf bank_mask:0xf
	v_fmac_f32_dpp v196, v224, v60 row_newbcast:15 row_mask:0xf bank_mask:0xf
	v_fmac_f32_dpp v197, v225, v61 row_newbcast:15 row_mask:0xf bank_mask:0xf
	v_fmac_f32_dpp v198, v226, v62 row_newbcast:15 row_mask:0xf bank_mask:0xf
	v_fmac_f32_dpp v199, v227, v63 row_newbcast:15 row_mask:0xf bank_mask:0xf
	v_add_f32_e32 v196, v196, v197
	v_add_f32_e32 v198, v198, v199
	v_add_f32_e32 v196, v196, v198
	v_xor_b32_e32 v202, 0x80000000, v196
	s_waitcnt lgkmcnt(0)
	s_nop 1
	v_mfma_f32_4x4x1_16b_f32 v[0:3], v64, v202, v[0:3]
	v_mfma_f32_4x4x1_16b_f32 v[4:7], v65, v202, v[4:7]
	v_mfma_f32_4x4x1_16b_f32 v[8:11], v66, v202, v[8:11]
	v_mfma_f32_4x4x1_16b_f32 v[12:15], v67, v202, v[12:15]
	v_mfma_f32_4x4x1_16b_f32 v[16:19], v68, v202, v[16:19]
	v_mfma_f32_4x4x1_16b_f32 v[20:23], v69, v202, v[20:23]
	v_mfma_f32_4x4x1_16b_f32 v[24:27], v70, v202, v[24:27]
	v_mfma_f32_4x4x1_16b_f32 v[28:31], v71, v202, v[28:31]
	v_mfma_f32_4x4x1_16b_f32 v[32:35], v72, v202, v[32:35]
	v_mfma_f32_4x4x1_16b_f32 v[36:39], v73, v202, v[36:39]
	v_mfma_f32_4x4x1_16b_f32 v[40:43], v74, v202, v[40:43]
	v_mfma_f32_4x4x1_16b_f32 v[44:47], v75, v202, v[44:47]
	v_mfma_f32_4x4x1_16b_f32 v[48:51], v76, v202, v[48:51]
	v_mfma_f32_4x4x1_16b_f32 v[52:55], v77, v202, v[52:55]
	v_mfma_f32_4x4x1_16b_f32 v[56:59], v78, v202, v[56:59]
	v_mfma_f32_4x4x1_16b_f32 v[60:63], v79, v202, v[60:63]
	s_waitcnt vmcnt(6)
	buffer_load_dwordx4 v[136:139], v204, s[64:67], s72 offen
	buffer_load_dwordx4 v[140:143], v204, s[64:67], s73 offen
	buffer_load_dwordx4 v[144:147], v204, s[64:67], s74 offen
	s_cmp_lt_u32 s80, 255
	s_cselect_b32 s81, 0x1000, 0
	s_cselect_b32 s82, 0x800, 0
	s_cselect_b32 s9, 1, 0
	s_add_u32 s80, s80, s9
	s_add_u32 s72, s72, s81
	s_add_u32 s73, s73, s81
	s_add_u32 s74, s74, s81
	v_pk_mul_f32 v[224:225], v[160:161], v[216:217]
	v_pk_mul_f32 v[226:227], v[162:163], v[218:219]
	v_pk_mul_f32 v[216:217], v[216:217], v[156:157]
	v_pk_mul_f32 v[218:219], v[218:219], v[158:159]
	v_pk_mul_f32 v[176:177], v[160:161], v[164:165]
	v_pk_mul_f32 v[178:179], v[162:163], v[166:167]
	v_rcp_f32_e32 v220, v216
	v_rcp_f32_e32 v221, v217
	v_rcp_f32_e32 v222, v218
	v_rcp_f32_e32 v223, v219
	s_nop 0
	v_pk_mul_f32 v[176:177], v[176:177], v[220:221]
	v_pk_mul_f32 v[178:179], v[178:179], v[222:223]
	ds_write_b128 v208, v[176:179]
	ds_read2_b32 v[64:65], v209 offset0:0 offset1:4
	ds_read2_b32 v[66:67], v209 offset0:8 offset1:12
	ds_read2_b32 v[68:69], v209 offset0:16 offset1:20
	ds_read2_b32 v[70:71], v209 offset0:24 offset1:28
	ds_read2_b32 v[72:73], v209 offset0:32 offset1:36
	ds_read2_b32 v[74:75], v209 offset0:40 offset1:44
	ds_read2_b32 v[76:77], v209 offset0:48 offset1:52
	ds_read2_b32 v[78:79], v209 offset0:56 offset1:60
	v_mul_f32_dpp v196, v224, v0 row_newbcast:0 row_mask:0xf bank_mask:0xf
	v_mul_f32_dpp v197, v225, v1 row_newbcast:0 row_mask:0xf bank_mask:0xf
	v_mul_f32_dpp v198, v226, v2 row_newbcast:0 row_mask:0xf bank_mask:0xf
	v_mul_f32_dpp v199, v227, v3 row_newbcast:0 row_mask:0xf bank_mask:0xf
	v_fmac_f32_dpp v196, v224, v4 row_newbcast:1 row_mask:0xf bank_mask:0xf
;     static __device__ __forceinline__ void dot(const float (&S)[64], const f32x4& a, float (&s)[4]) {
;         if constexpr (K == 0) {
;             asm volatile("v_mul_f32_dpp %0, %4, %8 row_newbcast:%16" DPPM "v_mul_f32_dpp %1, %5, %9 row_newbcast:%16" DPPM "v_mul_f32_dpp %2, %6, %10 row_newbcast:%16" DPPM "v_mul_f32_dpp %3, %7, %11 row_newbcast:%16" DPPM
;                          "v_fmac_f32_dpp %0, %4, %12 row_newbcast:%17" DPPM "v_fmac_f32_dpp %1, %5, %13 row_newbcast:%17" DPPM "v_fmac_f32_dpp %2, %6, %14 row_newbcast:%17" DPPM "v_fmac_f32_dpp %3, %7, %15 row_newbcast:%17" DPPM
;                          : "=&v"(s[0]), "=&v"(s[1]), "=&v"(s[2]), "=&v"(s[3])
;                          : "v"(a[0]), "v"(a[1]), "v"(a[2]), "v"(a[3]), "v"(S[K]), "v"(S[K + 1]), "v"(S[K + 2]), "v"(S[K + 3]), "v"(S[K + 4]), "v"(S[K + 5]), "v"(S[K + 6]), "v"(S[K + 7]), "n"(N0), "n"(N1));
;         } else
;         asm volatile("v_fmac_f32_dpp %0, %4, %8 row_newbcast:%16" DPPM "v_fmac_f32_dpp %1, %5, %9 row_newbcast:%16" DPPM "v_fmac_f32_dpp %2, %6, %10 row_newbcast:%16" DPPM "v_fmac_f32_dpp %3, %7, %11 row_newbcast:%16" DPPM
;                      "v_fmac_f32_dpp %0, %4, %12 row_newbcast:%17" DPPM "v_fmac_f32_dpp %1, %5, %13 row_newbcast:%17" DPPM "v_fmac_f32_dpp %2, %6, %14 row_newbcast:%17" DPPM "v_fmac_f32_dpp %3, %7, %15 row_newbcast:%17" DPPM
;                      : "+v"(s[0]), "+v"(s[1]), "+v"(s[2]), "+v"(s[3])
;                      : "v"(a[0]), "v"(a[1]), "v"(a[2]), "v"(a[3]), "v"(S[K]), "v"(S[K + 1]), "v"(S[K + 2]), "v"(S[K + 3]), "v"(S[K + 4]), "v"(S[K + 5]), "v"(S[K + 6]), "v"(S[K + 7]), "n"(N0), "n"(N1));
;         if constexpr (K + 8 < 64) ScanK<K + 8>::dot(S, a, s);
;     static __device__ __forceinline__ void updP(float (&P)[64], const In1& in, float sa) {
;         float u0, u1, u2, u3;
;         asm volatile("v_mul_f32_dpp %0, %8, %4 row_newbcast:%17" DPPM "v_mul_f32_dpp %1, %9, %5 row_newbcast:%17" DPPM "v_mul_f32_dpp %2, %10, %6 row_newbcast:%17" DPPM "v_mul_f32_dpp %3, %11, %7 row_newbcast:%17" DPPM
;                      "v_fmac_f32_dpp %0, %12, %16 row_newbcast:%17" DPPM "v_fmac_f32_dpp %1, %13, %16 row_newbcast:%17" DPPM "v_fmac_f32_dpp %2, %14, %16 row_newbcast:%17" DPPM "v_fmac_f32_dpp %3, %15, %16 row_newbcast:%17" DPPM
;                      : "=&v"(u0), "=&v"(u1), "=&v"(u2), "=&v"(u3)
	v_fmac_f32_dpp v197, v225, v5 row_newbcast:1 row_mask:0xf bank_mask:0xf
	v_fmac_f32_dpp v198, v226, v6 row_newbcast:1 row_mask:0xf bank_mask:0xf
	v_fmac_f32_dpp v199, v227, v7 row_newbcast:1 row_mask:0xf bank_mask:0xf
	v_fmac_f32_dpp v196, v224, v8 row_newbcast:2 row_mask:0xf bank_mask:0xf
	v_fmac_f32_dpp v197, v225, v9 row_newbcast:2 row_mask:0xf bank_mask:0xf
	v_fmac_f32_dpp v198, v226, v10 row_newbcast:2 row_mask:0xf bank_mask:0xf
	v_fmac_f32_dpp v199, v227, v11 row_newbcast:2 row_mask:0xf bank_mask:0xf
	v_fmac_f32_dpp v196, v224, v12 row_newbcast:3 row_mask:0xf bank_mask:0xf
	v_fmac_f32_dpp v197, v225, v13 row_newbcast:3 row_mask:0xf bank_mask:0xf
	v_fmac_f32_dpp v198, v226, v14 row_newbcast:3 row_mask:0xf bank_mask:0xf
	v_fmac_f32_dpp v199, v227, v15 row_newbcast:3 row_mask:0xf bank_mask:0xf
	v_fmac_f32_dpp v196, v224, v16 row_newbcast:4 row_mask:0xf bank_mask:0xf
	v_fmac_f32_dpp v197, v225, v17 row_newbcast:4 row_mask:0xf bank_mask:0xf
	v_fmac_f32_dpp v198, v226, v18 row_newbcast:4 row_mask:0xf bank_mask:0xf
	v_fmac_f32_dpp v199, v227, v19 row_newbcast:4 row_mask:0xf bank_mask:0xf
	v_fmac_f32_dpp v196, v224, v20 row_newbcast:5 row_mask:0xf bank_mask:0xf
	v_fmac_f32_dpp v197, v225, v21 row_newbcast:5 row_mask:0xf bank_mask:0xf
	v_fmac_f32_dpp v198, v226, v22 row_newbcast:5 row_mask:0xf bank_mask:0xf
	v_fmac_f32_dpp v199, v227, v23 row_newbcast:5 row_mask:0xf bank_mask:0xf
	v_fmac_f32_dpp v196, v224, v24 row_newbcast:6 row_mask:0xf bank_mask:0xf
	v_fmac_f32_dpp v197, v225, v25 row_newbcast:6 row_mask:0xf bank_mask:0xf
	v_fmac_f32_dpp v198, v226, v26 row_newbcast:6 row_mask:0xf bank_mask:0xf
	v_fmac_f32_dpp v199, v227, v27 row_newbcast:6 row_mask:0xf bank_mask:0xf
	v_fmac_f32_dpp v196, v224, v28 row_newbcast:7 row_mask:0xf bank_mask:0xf
	v_fmac_f32_dpp v197, v225, v29 row_newbcast:7 row_mask:0xf bank_mask:0xf
	v_fmac_f32_dpp v198, v226, v30 row_newbcast:7 row_mask:0xf bank_mask:0xf
	v_fmac_f32_dpp v199, v227, v31 row_newbcast:7 row_mask:0xf bank_mask:0xf
	v_fmac_f32_dpp v196, v224, v32 row_newbcast:8 row_mask:0xf bank_mask:0xf
	v_fmac_f32_dpp v197, v225, v33 row_newbcast:8 row_mask:0xf bank_mask:0xf
	v_fmac_f32_dpp v198, v226, v34 row_newbcast:8 row_mask:0xf bank_mask:0xf
	v_fmac_f32_dpp v199, v227, v35 row_newbcast:8 row_mask:0xf bank_mask:0xf
	v_fmac_f32_dpp v196, v224, v36 row_newbcast:9 row_mask:0xf bank_mask:0xf
	v_fmac_f32_dpp v197, v225, v37 row_newbcast:9 row_mask:0xf bank_mask:0xf
	v_fmac_f32_dpp v198, v226, v38 row_newbcast:9 row_mask:0xf bank_mask:0xf
	v_fmac_f32_dpp v199, v227, v39 row_newbcast:9 row_mask:0xf bank_mask:0xf
	v_fmac_f32_dpp v196, v224, v40 row_newbcast:10 row_mask:0xf bank_mask:0xf
	v_fmac_f32_dpp v197, v225, v41 row_newbcast:10 row_mask:0xf bank_mask:0xf
	v_fmac_f32_dpp v198, v226, v42 row_newbcast:10 row_mask:0xf bank_mask:0xf
	v_fmac_f32_dpp v199, v227, v43 row_newbcast:10 row_mask:0xf bank_mask:0xf
	v_fmac_f32_dpp v196, v224, v44 row_newbcast:11 row_mask:0xf bank_mask:0xf
	v_fmac_f32_dpp v197, v225, v45 row_newbcast:11 row_mask:0xf bank_mask:0xf
	v_fmac_f32_dpp v198, v226, v46 row_newbcast:11 row_mask:0xf bank_mask:0xf
	v_fmac_f32_dpp v199, v227, v47 row_newbcast:11 row_mask:0xf bank_mask:0xf
	v_fmac_f32_dpp v196, v224, v48 row_newbcast:12 row_mask:0xf bank_mask:0xf
	v_fmac_f32_dpp v197, v225, v49 row_newbcast:12 row_mask:0xf bank_mask:0xf
	v_fmac_f32_dpp v198, v226, v50 row_newbcast:12 row_mask:0xf bank_mask:0xf
	v_fmac_f32_dpp v199, v227, v51 row_newbcast:12 row_mask:0xf bank_mask:0xf
	v_fmac_f32_dpp v196, v224, v52 row_newbcast:13 row_mask:0xf bank_mask:0xf
	v_fmac_f32_dpp v197, v225, v53 row_newbcast:13 row_mask:0xf bank_mask:0xf
	v_fmac_f32_dpp v198, v226, v54 row_newbcast:13 row_mask:0xf bank_mask:0xf
	v_fmac_f32_dpp v199, v227, v55 row_newbcast:13 row_mask:0xf bank_mask:0xf
	v_fmac_f32_dpp v196, v224, v56 row_newbcast:14 row_mask:0xf bank_mask:0xf
	v_fmac_f32_dpp v197, v225, v57 row_newbcast:14 row_mask:0xf bank_mask:0xf
	v_fmac_f32_dpp v198, v226, v58 row_newbcast:14 row_mask:0xf bank_mask:0xf
	v_fmac_f32_dpp v199, v227, v59 row_newbcast:14 row_mask:0xf bank_mask:0xf
	v_fmac_f32_dpp v196, v224, v60 row_newbcast:15 row_mask:0xf bank_mask:0xf
	v_fmac_f32_dpp v197, v225, v61 row_newbcast:15 row_mask:0xf bank_mask:0xf
	v_fmac_f32_dpp v198, v226, v62 row_newbcast:15 row_mask:0xf bank_mask:0xf
	v_fmac_f32_dpp v199, v227, v63 row_newbcast:15 row_mask:0xf bank_mask:0xf
	v_add_f32_e32 v196, v196, v197
	v_add_f32_e32 v198, v198, v199
	v_add_f32_e32 v196, v196, v198
	v_xor_b32_e32 v202, 0x80000000, v196
	s_waitcnt lgkmcnt(0)
	s_nop 1
	v_mfma_f32_4x4x1_16b_f32 v[0:3], v64, v202, v[0:3]
	v_mfma_f32_4x4x1_16b_f32 v[4:7], v65, v202, v[4:7]
	v_mfma_f32_4x4x1_16b_f32 v[8:11], v66, v202, v[8:11]
	v_mfma_f32_4x4x1_16b_f32 v[12:15], v67, v202, v[12:15]
	v_mfma_f32_4x4x1_16b_f32 v[16:19], v68, v202, v[16:19]
	v_mfma_f32_4x4x1_16b_f32 v[20:23], v69, v202, v[20:23]
	v_mfma_f32_4x4x1_16b_f32 v[24:27], v70, v202, v[24:27]
	v_mfma_f32_4x4x1_16b_f32 v[28:31], v71, v202, v[28:31]
	v_mfma_f32_4x4x1_16b_f32 v[32:35], v72, v202, v[32:35]
	v_mfma_f32_4x4x1_16b_f32 v[36:39], v73, v202, v[36:39]
	v_mfma_f32_4x4x1_16b_f32 v[40:43], v74, v202, v[40:43]
	v_mfma_f32_4x4x1_16b_f32 v[44:47], v75, v202, v[44:47]
	v_mfma_f32_4x4x1_16b_f32 v[48:51], v76, v202, v[48:51]
	v_mfma_f32_4x4x1_16b_f32 v[52:55], v77, v202, v[52:55]
	v_mfma_f32_4x4x1_16b_f32 v[56:59], v78, v202, v[56:59]
	v_mfma_f32_4x4x1_16b_f32 v[60:63], v79, v202, v[60:63]
	s_sub_u32 s83, s83, 1
	s_cmp_eq_u32 s83, 0
	s_cbranch_scc1 .Lmy_p1d0_ldone_p
	s_and_b32 s9, s83, 7
	s_cmp_eq_u32 s9, 0
	s_cbranch_scc1 .Lmy_p1d0_renorm_p
	s_branch .Lmy_p1d0_loop_p

; #define NEXT_ITEM() (MIX ? (int)__builtin_amdgcn_readfirstlane(lane == 0 ? __hip_atomic_fetch_add(qctr, 1u, __ATOMIC_RELAXED, __HIP_MEMORY_SCOPE_AGENT) : 0u) : item + (int)gridDim.x * 8)
; template <bool MIX> __device__ __forceinline__ void scan_pass1(const Params& p, int d, float* ldsf) {
;     ...
;     for (int item = MIX ? NEXT_ITEM() : (int)(blockIdx.x * 8 + wid); item < 2 * NS; item = NEXT_ITEM()) {
;     ...
;         float* po = (isP ? PT : SLT) + ((size_t)(bh * NC + c)) * 4096 + lane * 64;
; #pragma unroll
;         for (int i = 0; i < 16; ++i) *(f32x4*)(po + 4 * i) = (f32x4){S[4 * i], S[4 * i + 1], S[4 * i + 2], S[4 * i + 3]};
.Lmy_p1d0_store:
	s_nop 1
	global_store_dwordx4 v210, v[0:3], s[90:91] offset:0
	global_store_dwordx4 v210, v[4:7], s[90:91] offset:16
	global_store_dwordx4 v210, v[8:11], s[90:91] offset:32
	global_store_dwordx4 v210, v[12:15], s[90:91] offset:48
	global_store_dwordx4 v210, v[16:19], s[90:91] offset:64
	global_store_dwordx4 v210, v[20:23], s[90:91] offset:80
	global_store_dwordx4 v210, v[24:27], s[90:91] offset:96
	global_store_dwordx4 v210, v[28:31], s[90:91] offset:112
	global_store_dwordx4 v210, v[32:35], s[90:91] offset:128
	global_store_dwordx4 v210, v[36:39], s[90:91] offset:144
	global_store_dwordx4 v210, v[40:43], s[90:91] offset:160
	global_store_dwordx4 v210, v[44:47], s[90:91] offset:176
	global_store_dwordx4 v210, v[48:51], s[90:91] offset:192
	global_store_dwordx4 v210, v[52:55], s[90:91] offset:208
	global_store_dwordx4 v210, v[56:59], s[90:91] offset:224
	global_store_dwordx4 v210, v[60:63], s[90:91] offset:240
	s_nop 1
	v_mov_b32_e32 v214, 0
	v_mov_b32_e32 v215, 1
	s_mov_b64 exec, 1
	global_atomic_add v214, v214, v215, s[34:35] sc0
	s_mov_b64 exec, -1
	s_waitcnt vmcnt(0)
	s_nop 0
	v_readfirstlane_b32 s0, v214
	s_nop 3
	s_branch .Lmy_p1d0_item

; #define NEXT_ITEM() (MIX ? (int)__builtin_amdgcn_readfirstlane(lane == 0 ? __hip_atomic_fetch_add(qctr, 1u, __ATOMIC_RELAXED, __HIP_MEMORY_SCOPE_AGENT) : 0u) : item + (int)gridDim.x * 8)
; #define MKR(ptr) __builtin_amdgcn_make_buffer_rsrc((void*)(ptr), 0, 0x7fffffff, 0x00027000)
; #define LD1(set, s) { const int e_ = min((int)(s), LC - 1) * (int)stp; const unsigned s4_ = ob4 + (unsigned)(e_ * 4), s2_ = ob2 + (unsigned)(e_ * 2); set.w = LDX(rW, s4_); set.a = LDX(rA, s4_); set.b = LDX(rB, s4_); \
;             set.kw = __builtin_amdgcn_raw_buffer_load_b64(rK, lo8, s2_, 0); set.v = __builtin_amdgcn_raw_buffer_load_b16(rV, lo2, s2_, 0); }
; template <bool MIX> __device__ __forceinline__ void scan_pass1(const Params& p, int d, float* ldsf) {
;     const int lane = threadIdx.x & 63, wid = __builtin_amdgcn_readfirstlane(threadIdx.x >> 6); const unsigned lo16 = (lane & 15) * 16, lo2 = lane * 2;
;     const float* Wd = (const float*)(p.ws + O_KD); const float* Bd = (const float*)(p.ws + O_Y); const u16* KB = (const u16*)(p.ws + O_K); const float* A = (const float*)(p.ws + O_A);
;     const u16* V = (const u16*)(p.ws + O_V); float* PT = (float*)(p.ws + O_PT); float* SLT = (float*)(p.ws + O_SLT); const unsigned lo8 = (lane & 15) * 8;
;     constexpr int NS = 32 * (NC - 1);
;     unsigned* qctr = (unsigned*)(p.ws + O_BAR);
;     if (MIX && wid >= 4) nat_phase(p, ldsf, blockIdx.x * 4 + (wid - 4), gridDim.x * 4);
;     ...
;     for (int item = MIX ? NEXT_ITEM() : (int)(blockIdx.x * 8 + wid); item < 2 * NS; item = NEXT_ITEM()) {
;         const bool isP = item >= NS; const int idx = isP ? item - NS : item;
;         const int bh = idx / (NC - 1), c = idx - bh * (NC - 1), b = bh >> 4, h = bh & 15;
;         const int t0 = d ? (SEQ - 1 - c * LC) : c * LC;
;         const size_t off0 = ((size_t)(b * SEQ + t0)) * RW + h * 64; const long stp = d ? -(long)RW : (long)RW;
;         const unsigned ob4 = (unsigned)(off0 * 4), ob2 = (unsigned)(off0 * 2);
;         const f32x4 ka4 = *(const f32x4*)(p.k_a + h * 64 + (lane & 15) * 4), c04 = 1.0f - ka4;
;         float S[64]; int ln = lane; asm volatile("" : "+v"(ln));
;     ...
;         const __amdgpu_buffer_rsrc_t rW = MKR(Wd), rA = MKR(A), rB = MKR(Bd), rK = MKR(KB), rV = MKR(V);
;         if (!isP) {
; #pragma unroll
;             for (int i = 0; i < 64; ++i) S[i] = 0.f;
;     ...
;             In1 i0, i1; LD1(i0, 0);
.LBB0_827:
	s_cmp_lt_i32 s58, 9
	s_cselect_b64 s[0:1], -1, 0
	s_cmp_gt_i32 s59, 8
	s_cselect_b64 s[4:5], -1, 0
	s_and_b64 s[0:1], s[0:1], s[4:5]
	s_andn2_b64 vcc, exec, s[0:1]
	s_cbranch_vccnz .LBB0_893
	s_mov_b64 exec, -1
	v_readfirstlane_b32 s0, v254
	s_nop 3
	s_lshr_b32 s1, s0, 6
	s_lshl_b32 s0, s2, 3
	s_add_i32 s0, s1, s0
	s_mov_b32 s64, s56
	s_and_b32 s65, s57, 0xffff
	s_brev_b32 s66, -2
	s_mov_b32 s67, 0x27000
	s_mov_b32 s68, s54
	s_and_b32 s69, s55, 0xffff
	s_mov_b32 s70, s66
	s_mov_b32 s71, s67
	v_and_b32_e32 v212, 63, v254
	v_and_b32_e32 v213, 15, v254
	v_lshlrev_b32_e32 v204, 4, v213
	v_lshlrev_b32_e32 v205, 3, v213
	v_lshlrev_b32_e32 v206, 1, v212
	v_lshlrev_b32_e32 v207, 2, v212
	v_lshlrev_b32_e32 v210, 8, v212
	s_lshl_b32 s3, s1, 10
	s_add_u32 s3, s3, 0x10000
	v_add_u32_e32 v208, s3, v204
	v_and_b32_e32 v209, 3, v254
	v_lshlrev_b32_e32 v209, 2, v209
	v_add_u32_e32 v209, s3, v209
	v_mov_b32_e32 v213, 1.0
.Lmy_p1d1_item:
	s_cmpk_gt_i32 s0, 0xfbf
	s_cbranch_scc1 .Lmy_p1d1_end
	s_cmpk_gt_i32 s0, 0x7df
	s_cselect_b32 s88, 1, 0
	s_cselect_b32 s6, 0x7e0, 0
	s_sub_u32 s6, s0, s6
	s_mul_i32 s86, s6, 2081
	s_lshr_b32 s86, s86, 17
	s_mul_i32 s7, s86, 63
	s_sub_u32 s85, s6, s7
	s_and_b32 s87, s86, 15
	s_lshr_b32 s6, s86, 4
	s_lshl_b32 s6, s6, 14
	s_lshl_b32 s7, s85, 8
	s_sub_u32 s7, 0x3fff, s7
	s_add_u32 s6, s6, s7
	s_lshl_b32 s6, s6, 10
	s_lshl_b32 s7, s87, 6
	s_add_u32 s84, s6, s7
	s_lshl_b32 s6, s84, 2
	s_lshl_b32 s7, s84, 1
	s_add_u32 s72, s6, 0xb800000
	s_add_u32 s73, s6, 0x24800000
	s_add_u32 s74, s6, 0x35a00000
	s_add_u32 s76, s7, 0x30800000
	s_add_u32 s77, s7, 0x2c800000
	s_lshl_b32 s6, s86, 6
	s_add_u32 s6, s6, s85
	s_lshl_b32 s6, s6, 14
	s_mov_b32 s7, 0x15800000
	s_cmp_eq_u32 s88, 1
	s_cselect_b32 s7, 0x13800000, s7
	s_add_u32 s6, s6, s7
	s_add_u32 s90, s56, s6
	s_addc_u32 s91, s57, 0
	s_cmp_eq_u32 s88, 1
	s_cbranch_scc1 .Lmy_p1d1_pitem
	s_lshl_b32 s8, s87, 8
	s_add_u32 s4, s42, s8
	s_addc_u32 s5, s43, 0
	global_load_dwordx4 v[188:191], v204, s[4:5]
	buffer_load_dwordx4 v[96:99], v204, s[64:67], s72 offen
	buffer_load_dwordx4 v[100:103], v204, s[64:67], s73 offen
	buffer_load_dwordx4 v[104:107], v204, s[64:67], s74 offen
	buffer_load_dwordx2 v[112:113], v205, s[64:67], s76 offen
	buffer_load_ushort v114, v206, s[64:67], s77 offen
	s_add_u32 s72, s72, 0xfffff000
	s_add_u32 s73, s73, 0xfffff000
	s_add_u32 s74, s74, 0xfffff000
	s_add_u32 s76, s76, 0xfffff800
	s_add_u32 s77, s77, 0xfffff800
	buffer_load_dwordx4 v[116:119], v204, s[64:67], s72 offen
	buffer_load_dwordx4 v[120:123], v204, s[64:67], s73 offen
	buffer_load_dwordx4 v[124:127], v204, s[64:67], s74 offen
	buffer_load_dwordx2 v[132:133], v205, s[64:67], s76 offen
	buffer_load_ushort v134, v206, s[64:67], s77 offen
	s_add_u32 s72, s72, 0xfffff000
	s_add_u32 s73, s73, 0xfffff000
	s_add_u32 s74, s74, 0xfffff000
	s_add_u32 s76, s76, 0xfffff800
	s_add_u32 s77, s77, 0xfffff800
	buffer_load_dwordx4 v[136:139], v204, s[64:67], s72 offen
	buffer_load_dwordx4 v[140:143], v204, s[64:67], s73 offen
	buffer_load_dwordx4 v[144:147], v204, s[64:67], s74 offen
	buffer_load_dwordx2 v[152:153], v205, s[64:67], s76 offen
	buffer_load_ushort v154, v206, s[64:67], s77 offen
	s_add_u32 s72, s72, 0xfffff000
	s_add_u32 s73, s73, 0xfffff000
	s_add_u32 s74, s74, 0xfffff000
	s_add_u32 s76, s76, 0xfffff800
	s_add_u32 s77, s77, 0xfffff800
	s_mov_b32 s80, 3
	v_mov_b32_e32 v0, 0
	v_mov_b32_e32 v1, 0
	v_mov_b32_e32 v2, 0
	v_mov_b32_e32 v3, 0
	v_mov_b32_e32 v4, 0
	v_mov_b32_e32 v5, 0
	v_mov_b32_e32 v6, 0
	v_mov_b32_e32 v7, 0
	v_mov_b32_e32 v8, 0
	v_mov_b32_e32 v9, 0
	v_mov_b32_e32 v10, 0
	v_mov_b32_e32 v11, 0
	v_mov_b32_e32 v12, 0
	v_mov_b32_e32 v13, 0
	v_mov_b32_e32 v14, 0
	v_mov_b32_e32 v15, 0
	v_mov_b32_e32 v16, 0
	v_mov_b32_e32 v17, 0
	v_mov_b32_e32 v18, 0
	v_mov_b32_e32 v19, 0
	v_mov_b32_e32 v20, 0
	v_mov_b32_e32 v21, 0
	v_mov_b32_e32 v22, 0
	v_mov_b32_e32 v23, 0
	v_mov_b32_e32 v24, 0
	v_mov_b32_e32 v25, 0
	v_mov_b32_e32 v26, 0
	v_mov_b32_e32 v27, 0
	v_mov_b32_e32 v28, 0
	v_mov_b32_e32 v29, 0
	v_mov_b32_e32 v30, 0
	v_mov_b32_e32 v31, 0
	v_mov_b32_e32 v32, 0
	v_mov_b32_e32 v33, 0
	v_mov_b32_e32 v34, 0
	v_mov_b32_e32 v35, 0
	v_mov_b32_e32 v36, 0
	v_mov_b32_e32 v37, 0
	v_mov_b32_e32 v38, 0
	v_mov_b32_e32 v39, 0
	v_mov_b32_e32 v40, 0
	v_mov_b32_e32 v41, 0
	v_mov_b32_e32 v42, 0
	v_mov_b32_e32 v43, 0
	v_mov_b32_e32 v44, 0
	v_mov_b32_e32 v45, 0
	v_mov_b32_e32 v46, 0
	v_mov_b32_e32 v47, 0
	v_mov_b32_e32 v48, 0
	v_mov_b32_e32 v49, 0
	v_mov_b32_e32 v50, 0
	v_mov_b32_e32 v51, 0
	v_mov_b32_e32 v52, 0
	v_mov_b32_e32 v53, 0
	v_mov_b32_e32 v54, 0
	v_mov_b32_e32 v55, 0
	v_mov_b32_e32 v56, 0
	v_mov_b32_e32 v57, 0
	v_mov_b32_e32 v58, 0
	v_mov_b32_e32 v59, 0
	v_mov_b32_e32 v60, 0
	v_mov_b32_e32 v61, 0
	v_mov_b32_e32 v62, 0
	v_mov_b32_e32 v63, 0
	s_waitcnt vmcnt(0)
	v_sub_f32_e32 v192, 1.0, v188
	v_sub_f32_e32 v193, 1.0, v189
	v_sub_f32_e32 v194, 1.0, v190
	v_sub_f32_e32 v195, 1.0, v191
	v_mov_b32_e32 v216, 1.0
	v_mov_b32_e32 v217, 1.0
	v_mov_b32_e32 v218, 1.0
	v_mov_b32_e32 v219, 1.0
	s_movk_i32 s83, 64
	s_branch .Lmy_p1d1_loop_s

;     static __device__ __forceinline__ void dot(const float (&S)[64], const f32x4& a, float (&s)[4]) {
;         if constexpr (K == 0) {
;             asm volatile("v_mul_f32_dpp %0, %4, %8 row_newbcast:%16" DPPM "v_mul_f32_dpp %1, %5, %9 row_newbcast:%16" DPPM "v_mul_f32_dpp %2, %6, %10 row_newbcast:%16" DPPM "v_mul_f32_dpp %3, %7, %11 row_newbcast:%16" DPPM
;                          "v_fmac_f32_dpp %0, %4, %12 row_newbcast:%17" DPPM "v_fmac_f32_dpp %1, %5, %13 row_newbcast:%17" DPPM "v_fmac_f32_dpp %2, %6, %14 row_newbcast:%17" DPPM "v_fmac_f32_dpp %3, %7, %15 row_newbcast:%17" DPPM
;                          : "=&v"(s[0]), "=&v"(s[1]), "=&v"(s[2]), "=&v"(s[3])
;                          : "v"(a[0]), "v"(a[1]), "v"(a[2]), "v"(a[3]), "v"(S[K]), "v"(S[K + 1]), "v"(S[K + 2]), "v"(S[K + 3]), "v"(S[K + 4]), "v"(S[K + 5]), "v"(S[K + 6]), "v"(S[K + 7]), "n"(N0), "n"(N1));
;         } else
;         asm volatile("v_fmac_f32_dpp %0, %4, %8 row_newbcast:%16" DPPM "v_fmac_f32_dpp %1, %5, %9 row_newbcast:%16" DPPM "v_fmac_f32_dpp %2, %6, %10 row_newbcast:%16" DPPM "v_fmac_f32_dpp %3, %7, %11 row_newbcast:%16" DPPM
;                      "v_fmac_f32_dpp %0, %4, %12 row_newbcast:%17" DPPM "v_fmac_f32_dpp %1, %5, %13 row_newbcast:%17" DPPM "v_fmac_f32_dpp %2, %6, %14 row_newbcast:%17" DPPM "v_fmac_f32_dpp %3, %7, %15 row_newbcast:%17" DPPM
;                      : "+v"(s[0]), "+v"(s[1]), "+v"(s[2]), "+v"(s[3])
;                      : "v"(a[0]), "v"(a[1]), "v"(a[2]), "v"(a[3]), "v"(S[K]), "v"(S[K + 1]), "v"(S[K + 2]), "v"(S[K + 3]), "v"(S[K + 4]), "v"(S[K + 5]), "v"(S[K + 6]), "v"(S[K + 7]), "n"(N0), "n"(N1));
;         if constexpr (K + 8 < 64) ScanK<K + 8>::dot(S, a, s);
;     }
;     static __device__ __forceinline__ void upd(float (&S)[64], const In2& in, float sa, float vv, float& y0, float& y1) {
;         float t0, t1, t2, t3;
;         asm volatile("v_mul_f32_dpp %0, %10, %27 row_newbcast:%28" DPPM "v_mul_f32_dpp %1, %11, %27 row_newbcast:%28" DPPM "v_mul_f32_dpp %2, %12, %27 row_newbcast:%28" DPPM "v_mul_f32_dpp %3, %13, %27 row_newbcast:%28" DPPM
;                      "v_fmac_f32_dpp %0, %14, %6 row_newbcast:%28" DPPM "v_fmac_f32_dpp %1, %15, %7 row_newbcast:%28" DPPM "v_fmac_f32_dpp %2, %16, %8 row_newbcast:%28" DPPM "v_fmac_f32_dpp %3, %17, %9 row_newbcast:%28" DPPM
.Lmy_p1d1_loop_s:
	s_waitcnt vmcnt(10)
	buffer_load_dwordx4 v[156:159], v204, s[64:67], s72 offen
	buffer_load_dwordx4 v[160:163], v204, s[64:67], s73 offen
	buffer_load_dwordx4 v[164:167], v204, s[64:67], s74 offen
	buffer_load_dwordx2 v[172:173], v205, s[64:67], s76 offen
	buffer_load_ushort v174, v206, s[64:67], s77 offen
	s_cmp_lt_u32 s80, 255
	s_cselect_b32 s81, 0xfffff000, 0
	s_cselect_b32 s82, 0xfffff800, 0
	s_cselect_b32 s9, 1, 0
	s_add_u32 s80, s80, s9
	s_add_u32 s72, s72, s81
	s_add_u32 s73, s73, s81
	s_add_u32 s74, s74, s81
	s_add_u32 s76, s76, s82
	s_add_u32 s77, s77, s82
	v_pk_mul_f32 v[224:225], v[100:101], v[216:217]
	v_pk_mul_f32 v[226:227], v[102:103], v[218:219]
	v_pk_mul_f32 v[216:217], v[216:217], v[96:97]
	v_pk_mul_f32 v[218:219], v[218:219], v[98:99]
	v_pk_fma_f32 v[184:185], v[104:105], v[188:189], v[192:193]
	v_pk_fma_f32 v[186:187], v[106:107], v[190:191], v[194:195]
	v_pk_mul_f32 v[176:177], v[100:101], v[104:105]
	v_pk_mul_f32 v[178:179], v[102:103], v[106:107]
	v_rcp_f32_e32 v220, v216
	v_rcp_f32_e32 v221, v217
	v_rcp_f32_e32 v222, v218
	v_rcp_f32_e32 v223, v219
	v_lshlrev_b32_e32 v180, 16, v112
	v_and_b32_e32 v181, 0xffff0000, v112
	v_lshlrev_b32_e32 v182, 16, v113
	v_and_b32_e32 v183, 0xffff0000, v113
	v_pk_mul_f32 v[180:181], v[180:181], v[184:185]
	v_pk_mul_f32 v[182:183], v[182:183], v[186:187]
	v_lshlrev_b32_e32 v203, 16, v114
	v_pk_mul_f32 v[176:177], v[176:177], v[220:221]
	v_pk_mul_f32 v[178:179], v[178:179], v[222:223]
	v_pk_mul_f32 v[180:181], v[180:181], v[220:221]
	v_pk_mul_f32 v[182:183], v[182:183], v[222:223]
	ds_write_b128 v208, v[176:179]
	ds_write_b128 v208, v[180:183] offset:256
	ds_read2_b32 v[64:65], v209 offset0:0 offset1:4
	ds_read2_b32 v[66:67], v209 offset0:8 offset1:12
	ds_read2_b32 v[68:69], v209 offset0:16 offset1:20
	ds_read2_b32 v[70:71], v209 offset0:24 offset1:28
	ds_read2_b32 v[72:73], v209 offset0:32 offset1:36
	ds_read2_b32 v[74:75], v209 offset0:40 offset1:44
	ds_read2_b32 v[76:77], v209 offset0:48 offset1:52
	ds_read2_b32 v[78:79], v209 offset0:56 offset1:60
	ds_read2_b32 v[80:81], v209 offset0:64 offset1:68
	ds_read2_b32 v[82:83], v209 offset0:72 offset1:76
	ds_read2_b32 v[84:85], v209 offset0:80 offset1:84
	ds_read2_b32 v[86:87], v209 offset0:88 offset1:92
	ds_read2_b32 v[88:89], v209 offset0:96 offset1:100
	ds_read2_b32 v[90:91], v209 offset0:104 offset1:108
	ds_read2_b32 v[92:93], v209 offset0:112 offset1:116
	ds_read2_b32 v[94:95], v209 offset0:120 offset1:124
	v_mul_f32_dpp v196, v224, v0 row_newbcast:0 row_mask:0xf bank_mask:0xf
	v_mul_f32_dpp v197, v225, v1 row_newbcast:0 row_mask:0xf bank_mask:0xf
	v_mul_f32_dpp v198, v226, v2 row_newbcast:0 row_mask:0xf bank_mask:0xf
	v_mul_f32_dpp v199, v227, v3 row_newbcast:0 row_mask:0xf bank_mask:0xf
	v_fmac_f32_dpp v196, v224, v4 row_newbcast:1 row_mask:0xf bank_mask:0xf
	v_fmac_f32_dpp v197, v225, v5 row_newbcast:1 row_mask:0xf bank_mask:0xf
	v_fmac_f32_dpp v198, v226, v6 row_newbcast:1 row_mask:0xf bank_mask:0xf
	v_fmac_f32_dpp v199, v227, v7 row_newbcast:1 row_mask:0xf bank_mask:0xf
	v_fmac_f32_dpp v196, v224, v8 row_newbcast:2 row_mask:0xf bank_mask:0xf
	v_fmac_f32_dpp v197, v225, v9 row_newbcast:2 row_mask:0xf bank_mask:0xf
	v_fmac_f32_dpp v198, v226, v10 row_newbcast:2 row_mask:0xf bank_mask:0xf
	v_fmac_f32_dpp v199, v227, v11 row_newbcast:2 row_mask:0xf bank_mask:0xf
	v_fmac_f32_dpp v196, v224, v12 row_newbcast:3 row_mask:0xf bank_mask:0xf
	v_fmac_f32_dpp v197, v225, v13 row_newbcast:3 row_mask:0xf bank_mask:0xf
	v_fmac_f32_dpp v198, v226, v14 row_newbcast:3 row_mask:0xf bank_mask:0xf
	v_fmac_f32_dpp v199, v227, v15 row_newbcast:3 row_mask:0xf bank_mask:0xf
	v_fmac_f32_dpp v196, v224, v16 row_newbcast:4 row_mask:0xf bank_mask:0xf
	v_fmac_f32_dpp v197, v225, v17 row_newbcast:4 row_mask:0xf bank_mask:0xf
	v_fmac_f32_dpp v198, v226, v18 row_newbcast:4 row_mask:0xf bank_mask:0xf
	v_fmac_f32_dpp v199, v227, v19 row_newbcast:4 row_mask:0xf bank_mask:0xf
	v_fmac_f32_dpp v196, v224, v20 row_newbcast:5 row_mask:0xf bank_mask:0xf
	v_fmac_f32_dpp v197, v225, v21 row_newbcast:5 row_mask:0xf bank_mask:0xf
	v_fmac_f32_dpp v198, v226, v22 row_newbcast:5 row_mask:0xf bank_mask:0xf
	v_fmac_f32_dpp v199, v227, v23 row_newbcast:5 row_mask:0xf bank_mask:0xf
	v_fmac_f32_dpp v196, v224, v24 row_newbcast:6 row_mask:0xf bank_mask:0xf
	v_fmac_f32_dpp v197, v225, v25 row_newbcast:6 row_mask:0xf bank_mask:0xf
	v_fmac_f32_dpp v198, v226, v26 row_newbcast:6 row_mask:0xf bank_mask:0xf
	v_fmac_f32_dpp v199, v227, v27 row_newbcast:6 row_mask:0xf bank_mask:0xf
	v_fmac_f32_dpp v196, v224, v28 row_newbcast:7 row_mask:0xf bank_mask:0xf
	v_fmac_f32_dpp v197, v225, v29 row_newbcast:7 row_mask:0xf bank_mask:0xf
	v_fmac_f32_dpp v198, v226, v30 row_newbcast:7 row_mask:0xf bank_mask:0xf
	v_fmac_f32_dpp v199, v227, v31 row_newbcast:7 row_mask:0xf bank_mask:0xf
	v_fmac_f32_dpp v196, v224, v32 row_newbcast:8 row_mask:0xf bank_mask:0xf
	v_fmac_f32_dpp v197, v225, v33 row_newbcast:8 row_mask:0xf bank_mask:0xf
	v_fmac_f32_dpp v198, v226, v34 row_newbcast:8 row_mask:0xf bank_mask:0xf
	v_fmac_f32_dpp v199, v227, v35 row_newbcast:8 row_mask:0xf bank_mask:0xf
	v_fmac_f32_dpp v196, v224, v36 row_newbcast:9 row_mask:0xf bank_mask:0xf
	v_fmac_f32_dpp v197, v225, v37 row_newbcast:9 row_mask:0xf bank_mask:0xf
	v_fmac_f32_dpp v198, v226, v38 row_newbcast:9 row_mask:0xf bank_mask:0xf
	v_fmac_f32_dpp v199, v227, v39 row_newbcast:9 row_mask:0xf bank_mask:0xf
	v_fmac_f32_dpp v196, v224, v40 row_newbcast:10 row_mask:0xf bank_mask:0xf
	v_fmac_f32_dpp v197, v225, v41 row_newbcast:10 row_mask:0xf bank_mask:0xf
	v_fmac_f32_dpp v198, v226, v42 row_newbcast:10 row_mask:0xf bank_mask:0xf
;     static __device__ __forceinline__ void dot(const float (&S)[64], const f32x4& a, float (&s)[4]) {
;         if constexpr (K == 0) {
;             asm volatile("v_mul_f32_dpp %0, %4, %8 row_newbcast:%16" DPPM "v_mul_f32_dpp %1, %5, %9 row_newbcast:%16" DPPM "v_mul_f32_dpp %2, %6, %10 row_newbcast:%16" DPPM "v_mul_f32_dpp %3, %7, %11 row_newbcast:%16" DPPM
;                          "v_fmac_f32_dpp %0, %4, %12 row_newbcast:%17" DPPM "v_fmac_f32_dpp %1, %5, %13 row_newbcast:%17" DPPM "v_fmac_f32_dpp %2, %6, %14 row_newbcast:%17" DPPM "v_fmac_f32_dpp %3, %7, %15 row_newbcast:%17" DPPM
;                          : "=&v"(s[0]), "=&v"(s[1]), "=&v"(s[2]), "=&v"(s[3])
;                          : "v"(a[0]), "v"(a[1]), "v"(a[2]), "v"(a[3]), "v"(S[K]), "v"(S[K + 1]), "v"(S[K + 2]), "v"(S[K + 3]), "v"(S[K + 4]), "v"(S[K + 5]), "v"(S[K + 6]), "v"(S[K + 7]), "n"(N0), "n"(N1));
;         } else
;         asm volatile("v_fmac_f32_dpp %0, %4, %8 row_newbcast:%16" DPPM "v_fmac_f32_dpp %1, %5, %9 row_newbcast:%16" DPPM "v_fmac_f32_dpp %2, %6, %10 row_newbcast:%16" DPPM "v_fmac_f32_dpp %3, %7, %11 row_newbcast:%16" DPPM
;                      "v_fmac_f32_dpp %0, %4, %12 row_newbcast:%17" DPPM "v_fmac_f32_dpp %1, %5, %13 row_newbcast:%17" DPPM "v_fmac_f32_dpp %2, %6, %14 row_newbcast:%17" DPPM "v_fmac_f32_dpp %3, %7, %15 row_newbcast:%17" DPPM
;                      : "+v"(s[0]), "+v"(s[1]), "+v"(s[2]), "+v"(s[3])
;                      : "v"(a[0]), "v"(a[1]), "v"(a[2]), "v"(a[3]), "v"(S[K]), "v"(S[K + 1]), "v"(S[K + 2]), "v"(S[K + 3]), "v"(S[K + 4]), "v"(S[K + 5]), "v"(S[K + 6]), "v"(S[K + 7]), "n"(N0), "n"(N1));
;         if constexpr (K + 8 < 64) ScanK<K + 8>::dot(S, a, s);
;     }
;     static __device__ __forceinline__ void upd(float (&S)[64], const In2& in, float sa, float vv, float& y0, float& y1) {
;         float t0, t1, t2, t3;
;         asm volatile("v_mul_f32_dpp %0, %10, %27 row_newbcast:%28" DPPM "v_mul_f32_dpp %1, %11, %27 row_newbcast:%28" DPPM "v_mul_f32_dpp %2, %12, %27 row_newbcast:%28" DPPM "v_mul_f32_dpp %3, %13, %27 row_newbcast:%28" DPPM
;                      "v_fmac_f32_dpp %0, %14, %6 row_newbcast:%28" DPPM "v_fmac_f32_dpp %1, %15, %7 row_newbcast:%28" DPPM "v_fmac_f32_dpp %2, %16, %8 row_newbcast:%28" DPPM "v_fmac_f32_dpp %3, %17, %9 row_newbcast:%28" DPPM
	v_fmac_f32_dpp v199, v227, v43 row_newbcast:10 row_mask:0xf bank_mask:0xf
	v_fmac_f32_dpp v196, v224, v44 row_newbcast:11 row_mask:0xf bank_mask:0xf
	v_fmac_f32_dpp v197, v225, v45 row_newbcast:11 row_mask:0xf bank_mask:0xf
	v_fmac_f32_dpp v198, v226, v46 row_newbcast:11 row_mask:0xf bank_mask:0xf
	v_fmac_f32_dpp v199, v227, v47 row_newbcast:11 row_mask:0xf bank_mask:0xf
	v_fmac_f32_dpp v196, v224, v48 row_newbcast:12 row_mask:0xf bank_mask:0xf
	v_fmac_f32_dpp v197, v225, v49 row_newbcast:12 row_mask:0xf bank_mask:0xf
	v_fmac_f32_dpp v198, v226, v50 row_newbcast:12 row_mask:0xf bank_mask:0xf
	v_fmac_f32_dpp v199, v227, v51 row_newbcast:12 row_mask:0xf bank_mask:0xf
	v_fmac_f32_dpp v196, v224, v52 row_newbcast:13 row_mask:0xf bank_mask:0xf
	v_fmac_f32_dpp v197, v225, v53 row_newbcast:13 row_mask:0xf bank_mask:0xf
	v_fmac_f32_dpp v198, v226, v54 row_newbcast:13 row_mask:0xf bank_mask:0xf
	v_fmac_f32_dpp v199, v227, v55 row_newbcast:13 row_mask:0xf bank_mask:0xf
	v_fmac_f32_dpp v196, v224, v56 row_newbcast:14 row_mask:0xf bank_mask:0xf
	v_fmac_f32_dpp v197, v225, v57 row_newbcast:14 row_mask:0xf bank_mask:0xf
	v_fmac_f32_dpp v198, v226, v58 row_newbcast:14 row_mask:0xf bank_mask:0xf
	v_fmac_f32_dpp v199, v227, v59 row_newbcast:14 row_mask:0xf bank_mask:0xf
	v_fmac_f32_dpp v196, v224, v60 row_newbcast:15 row_mask:0xf bank_mask:0xf
	v_fmac_f32_dpp v197, v225, v61 row_newbcast:15 row_mask:0xf bank_mask:0xf
	v_fmac_f32_dpp v198, v226, v62 row_newbcast:15 row_mask:0xf bank_mask:0xf
	v_fmac_f32_dpp v199, v227, v63 row_newbcast:15 row_mask:0xf bank_mask:0xf
	v_add_f32_e32 v196, v196, v197
	v_add_f32_e32 v198, v198, v199
	v_add_f32_e32 v196, v196, v198
	v_xor_b32_e32 v202, 0x80000000, v196
	s_waitcnt lgkmcnt(0)
	s_nop 1
	v_mfma_f32_4x4x1_16b_f32 v[0:3], v64, v202, v[0:3]
	v_mfma_f32_4x4x1_16b_f32 v[4:7], v65, v202, v[4:7]
	v_mfma_f32_4x4x1_16b_f32 v[8:11], v66, v202, v[8:11]
	v_mfma_f32_4x4x1_16b_f32 v[12:15], v67, v202, v[12:15]
	v_mfma_f32_4x4x1_16b_f32 v[16:19], v68, v202, v[16:19]
	v_mfma_f32_4x4x1_16b_f32 v[20:23], v69, v202, v[20:23]
	v_mfma_f32_4x4x1_16b_f32 v[24:27], v70, v202, v[24:27]
	v_mfma_f32_4x4x1_16b_f32 v[28:31], v71, v202, v[28:31]
	v_mfma_f32_4x4x1_16b_f32 v[32:35], v72, v202, v[32:35]
	v_mfma_f32_4x4x1_16b_f32 v[36:39], v73, v202, v[36:39]
	v_mfma_f32_4x4x1_16b_f32 v[40:43], v74, v202, v[40:43]
	v_mfma_f32_4x4x1_16b_f32 v[44:47], v75, v202, v[44:47]
	v_mfma_f32_4x4x1_16b_f32 v[48:51], v76, v202, v[48:51]
	v_mfma_f32_4x4x1_16b_f32 v[52:55], v77, v202, v[52:55]
	v_mfma_f32_4x4x1_16b_f32 v[56:59], v78, v202, v[56:59]
	v_mfma_f32_4x4x1_16b_f32 v[60:63], v79, v202, v[60:63]
	v_mfma_f32_4x4x1_16b_f32 v[0:3], v80, v203, v[0:3]
	v_mfma_f32_4x4x1_16b_f32 v[4:7], v81, v203, v[4:7]
	v_mfma_f32_4x4x1_16b_f32 v[8:11], v82, v203, v[8:11]
	v_mfma_f32_4x4x1_16b_f32 v[12:15], v83, v203, v[12:15]
	v_mfma_f32_4x4x1_16b_f32 v[16:19], v84, v203, v[16:19]
	v_mfma_f32_4x4x1_16b_f32 v[20:23], v85, v203, v[20:23]
	v_mfma_f32_4x4x1_16b_f32 v[24:27], v86, v203, v[24:27]
	v_mfma_f32_4x4x1_16b_f32 v[28:31], v87, v203, v[28:31]
	v_mfma_f32_4x4x1_16b_f32 v[32:35], v88, v203, v[32:35]
	v_mfma_f32_4x4x1_16b_f32 v[36:39], v89, v203, v[36:39]
	v_mfma_f32_4x4x1_16b_f32 v[40:43], v90, v203, v[40:43]
	v_mfma_f32_4x4x1_16b_f32 v[44:47], v91, v203, v[44:47]
	v_mfma_f32_4x4x1_16b_f32 v[48:51], v92, v203, v[48:51]
	v_mfma_f32_4x4x1_16b_f32 v[52:55], v93, v203, v[52:55]
	v_mfma_f32_4x4x1_16b_f32 v[56:59], v94, v203, v[56:59]
	v_mfma_f32_4x4x1_16b_f32 v[60:63], v95, v203, v[60:63]
	s_waitcnt vmcnt(10)
	buffer_load_dwordx4 v[96:99], v204, s[64:67], s72 offen
	buffer_load_dwordx4 v[100:103], v204, s[64:67], s73 offen
	buffer_load_dwordx4 v[104:107], v204, s[64:67], s74 offen
	buffer_load_dwordx2 v[112:113], v205, s[64:67], s76 offen
	buffer_load_ushort v114, v206, s[64:67], s77 offen
	s_cmp_lt_u32 s80, 255
	s_cselect_b32 s81, 0xfffff000, 0
	s_cselect_b32 s82, 0xfffff800, 0
	s_cselect_b32 s9, 1, 0
	s_add_u32 s80, s80, s9
	s_add_u32 s72, s72, s81
	s_add_u32 s73, s73, s81
	s_add_u32 s74, s74, s81
	s_add_u32 s76, s76, s82
	s_add_u32 s77, s77, s82
	v_pk_mul_f32 v[224:225], v[120:121], v[216:217]
	v_pk_mul_f32 v[226:227], v[122:123], v[218:219]
	v_pk_mul_f32 v[216:217], v[216:217], v[116:117]
	v_pk_mul_f32 v[218:219], v[218:219], v[118:119]
	v_pk_fma_f32 v[184:185], v[124:125], v[188:189], v[192:193]
	v_pk_fma_f32 v[186:187], v[126:127], v[190:191], v[194:195]
	v_pk_mul_f32 v[176:177], v[120:121], v[124:125]
	v_pk_mul_f32 v[178:179], v[122:123], v[126:127]
	v_rcp_f32_e32 v220, v216
	v_rcp_f32_e32 v221, v217
	v_rcp_f32_e32 v222, v218
	v_rcp_f32_e32 v223, v219
	v_lshlrev_b32_e32 v180, 16, v132
	v_and_b32_e32 v181, 0xffff0000, v132
	v_lshlrev_b32_e32 v182, 16, v133
	v_and_b32_e32 v183, 0xffff0000, v133
	v_pk_mul_f32 v[180:181], v[180:181], v[184:185]
	v_pk_mul_f32 v[182:183], v[182:183], v[186:187]
	v_lshlrev_b32_e32 v203, 16, v134
	v_pk_mul_f32 v[176:177], v[176:177], v[220:221]
	v_pk_mul_f32 v[178:179], v[178:179], v[222:223]
	v_pk_mul_f32 v[180:181], v[180:181], v[220:221]
	v_pk_mul_f32 v[182:183], v[182:183], v[222:223]
	ds_write_b128 v208, v[176:179]
	ds_write_b128 v208, v[180:183] offset:256
	ds_read2_b32 v[64:65], v209 offset0:0 offset1:4
	ds_read2_b32 v[66:67], v209 offset0:8 offset1:12
	ds_read2_b32 v[68:69], v209 offset0:16 offset1:20
	ds_read2_b32 v[70:71], v209 offset0:24 offset1:28
	ds_read2_b32 v[72:73], v209 offset0:32 offset1:36
	ds_read2_b32 v[74:75], v209 offset0:40 offset1:44
	ds_read2_b32 v[76:77], v209 offset0:48 offset1:52
	ds_read2_b32 v[78:79], v209 offset0:56 offset1:60
	ds_read2_b32 v[80:81], v209 offset0:64 offset1:68
	ds_read2_b32 v[82:83], v209 offset0:72 offset1:76
;     static __device__ __forceinline__ void dot(const float (&S)[64], const f32x4& a, float (&s)[4]) {
;         if constexpr (K == 0) {
;             asm volatile("v_mul_f32_dpp %0, %4, %8 row_newbcast:%16" DPPM "v_mul_f32_dpp %1, %5, %9 row_newbcast:%16" DPPM "v_mul_f32_dpp %2, %6, %10 row_newbcast:%16" DPPM "v_mul_f32_dpp %3, %7, %11 row_newbcast:%16" DPPM
;                          "v_fmac_f32_dpp %0, %4, %12 row_newbcast:%17" DPPM "v_fmac_f32_dpp %1, %5, %13 row_newbcast:%17" DPPM "v_fmac_f32_dpp %2, %6, %14 row_newbcast:%17" DPPM "v_fmac_f32_dpp %3, %7, %15 row_newbcast:%17" DPPM
;                          : "=&v"(s[0]), "=&v"(s[1]), "=&v"(s[2]), "=&v"(s[3])
;                          : "v"(a[0]), "v"(a[1]), "v"(a[2]), "v"(a[3]), "v"(S[K]), "v"(S[K + 1]), "v"(S[K + 2]), "v"(S[K + 3]), "v"(S[K + 4]), "v"(S[K + 5]), "v"(S[K + 6]), "v"(S[K + 7]), "n"(N0), "n"(N1));
;         } else
;         asm volatile("v_fmac_f32_dpp %0, %4, %8 row_newbcast:%16" DPPM "v_fmac_f32_dpp %1, %5, %9 row_newbcast:%16" DPPM "v_fmac_f32_dpp %2, %6, %10 row_newbcast:%16" DPPM "v_fmac_f32_dpp %3, %7, %11 row_newbcast:%16" DPPM
;                      "v_fmac_f32_dpp %0, %4, %12 row_newbcast:%17" DPPM "v_fmac_f32_dpp %1, %5, %13 row_newbcast:%17" DPPM "v_fmac_f32_dpp %2, %6, %14 row_newbcast:%17" DPPM "v_fmac_f32_dpp %3, %7, %15 row_newbcast:%17" DPPM
;                      : "+v"(s[0]), "+v"(s[1]), "+v"(s[2]), "+v"(s[3])
;                      : "v"(a[0]), "v"(a[1]), "v"(a[2]), "v"(a[3]), "v"(S[K]), "v"(S[K + 1]), "v"(S[K + 2]), "v"(S[K + 3]), "v"(S[K + 4]), "v"(S[K + 5]), "v"(S[K + 6]), "v"(S[K + 7]), "n"(N0), "n"(N1));
;         if constexpr (K + 8 < 64) ScanK<K + 8>::dot(S, a, s);
;     }
;     static __device__ __forceinline__ void upd(float (&S)[64], const In2& in, float sa, float vv, float& y0, float& y1) {
;         float t0, t1, t2, t3;
;         asm volatile("v_mul_f32_dpp %0, %10, %27 row_newbcast:%28" DPPM "v_mul_f32_dpp %1, %11, %27 row_newbcast:%28" DPPM "v_mul_f32_dpp %2, %12, %27 row_newbcast:%28" DPPM "v_mul_f32_dpp %3, %13, %27 row_newbcast:%28" DPPM
;                      "v_fmac_f32_dpp %0, %14, %6 row_newbcast:%28" DPPM "v_fmac_f32_dpp %1, %15, %7 row_newbcast:%28" DPPM "v_fmac_f32_dpp %2, %16, %8 row_newbcast:%28" DPPM "v_fmac_f32_dpp %3, %17, %9 row_newbcast:%28" DPPM
	ds_read2_b32 v[84:85], v209 offset0:80 offset1:84
	ds_read2_b32 v[86:87], v209 offset0:88 offset1:92
	ds_read2_b32 v[88:89], v209 offset0:96 offset1:100
	ds_read2_b32 v[90:91], v209 offset0:104 offset1:108
	ds_read2_b32 v[92:93], v209 offset0:112 offset1:116
	ds_read2_b32 v[94:95], v209 offset0:120 offset1:124
	v_mul_f32_dpp v196, v224, v0 row_newbcast:0 row_mask:0xf bank_mask:0xf
	v_mul_f32_dpp v197, v225, v1 row_newbcast:0 row_mask:0xf bank_mask:0xf
	v_mul_f32_dpp v198, v226, v2 row_newbcast:0 row_mask:0xf bank_mask:0xf
	v_mul_f32_dpp v199, v227, v3 row_newbcast:0 row_mask:0xf bank_mask:0xf
	v_fmac_f32_dpp v196, v224, v4 row_newbcast:1 row_mask:0xf bank_mask:0xf
	v_fmac_f32_dpp v197, v225, v5 row_newbcast:1 row_mask:0xf bank_mask:0xf
	v_fmac_f32_dpp v198, v226, v6 row_newbcast:1 row_mask:0xf bank_mask:0xf
	v_fmac_f32_dpp v199, v227, v7 row_newbcast:1 row_mask:0xf bank_mask:0xf
	v_fmac_f32_dpp v196, v224, v8 row_newbcast:2 row_mask:0xf bank_mask:0xf
	v_fmac_f32_dpp v197, v225, v9 row_newbcast:2 row_mask:0xf bank_mask:0xf
	v_fmac_f32_dpp v198, v226, v10 row_newbcast:2 row_mask:0xf bank_mask:0xf
	v_fmac_f32_dpp v199, v227, v11 row_newbcast:2 row_mask:0xf bank_mask:0xf
	v_fmac_f32_dpp v196, v224, v12 row_newbcast:3 row_mask:0xf bank_mask:0xf
	v_fmac_f32_dpp v197, v225, v13 row_newbcast:3 row_mask:0xf bank_mask:0xf
	v_fmac_f32_dpp v198, v226, v14 row_newbcast:3 row_mask:0xf bank_mask:0xf
	v_fmac_f32_dpp v199, v227, v15 row_newbcast:3 row_mask:0xf bank_mask:0xf
	v_fmac_f32_dpp v196, v224, v16 row_newbcast:4 row_mask:0xf bank_mask:0xf
	v_fmac_f32_dpp v197, v225, v17 row_newbcast:4 row_mask:0xf bank_mask:0xf
	v_fmac_f32_dpp v198, v226, v18 row_newbcast:4 row_mask:0xf bank_mask:0xf
	v_fmac_f32_dpp v199, v227, v19 row_newbcast:4 row_mask:0xf bank_mask:0xf
	v_fmac_f32_dpp v196, v224, v20 row_newbcast:5 row_mask:0xf bank_mask:0xf
	v_fmac_f32_dpp v197, v225, v21 row_newbcast:5 row_mask:0xf bank_mask:0xf
	v_fmac_f32_dpp v198, v226, v22 row_newbcast:5 row_mask:0xf bank_mask:0xf
	v_fmac_f32_dpp v199, v227, v23 row_newbcast:5 row_mask:0xf bank_mask:0xf
	v_fmac_f32_dpp v196, v224, v24 row_newbcast:6 row_mask:0xf bank_mask:0xf
	v_fmac_f32_dpp v197, v225, v25 row_newbcast:6 row_mask:0xf bank_mask:0xf
	v_fmac_f32_dpp v198, v226, v26 row_newbcast:6 row_mask:0xf bank_mask:0xf
	v_fmac_f32_dpp v199, v227, v27 row_newbcast:6 row_mask:0xf bank_mask:0xf
	v_fmac_f32_dpp v196, v224, v28 row_newbcast:7 row_mask:0xf bank_mask:0xf
	v_fmac_f32_dpp v197, v225, v29 row_newbcast:7 row_mask:0xf bank_mask:0xf
	v_fmac_f32_dpp v198, v226, v30 row_newbcast:7 row_mask:0xf bank_mask:0xf
	v_fmac_f32_dpp v199, v227, v31 row_newbcast:7 row_mask:0xf bank_mask:0xf
	v_fmac_f32_dpp v196, v224, v32 row_newbcast:8 row_mask:0xf bank_mask:0xf
	v_fmac_f32_dpp v197, v225, v33 row_newbcast:8 row_mask:0xf bank_mask:0xf
	v_fmac_f32_dpp v198, v226, v34 row_newbcast:8 row_mask:0xf bank_mask:0xf
	v_fmac_f32_dpp v199, v227, v35 row_newbcast:8 row_mask:0xf bank_mask:0xf
	v_fmac_f32_dpp v196, v224, v36 row_newbcast:9 row_mask:0xf bank_mask:0xf
	v_fmac_f32_dpp v197, v225, v37 row_newbcast:9 row_mask:0xf bank_mask:0xf
	v_fmac_f32_dpp v198, v226, v38 row_newbcast:9 row_mask:0xf bank_mask:0xf
	v_fmac_f32_dpp v199, v227, v39 row_newbcast:9 row_mask:0xf bank_mask:0xf
	v_fmac_f32_dpp v196, v224, v40 row_newbcast:10 row_mask:0xf bank_mask:0xf
	v_fmac_f32_dpp v197, v225, v41 row_newbcast:10 row_mask:0xf bank_mask:0xf
	v_fmac_f32_dpp v198, v226, v42 row_newbcast:10 row_mask:0xf bank_mask:0xf
	v_fmac_f32_dpp v199, v227, v43 row_newbcast:10 row_mask:0xf bank_mask:0xf
	v_fmac_f32_dpp v196, v224, v44 row_newbcast:11 row_mask:0xf bank_mask:0xf
	v_fmac_f32_dpp v197, v225, v45 row_newbcast:11 row_mask:0xf bank_mask:0xf
	v_fmac_f32_dpp v198, v226, v46 row_newbcast:11 row_mask:0xf bank_mask:0xf
	v_fmac_f32_dpp v199, v227, v47 row_newbcast:11 row_mask:0xf bank_mask:0xf
	v_fmac_f32_dpp v196, v224, v48 row_newbcast:12 row_mask:0xf bank_mask:0xf
	v_fmac_f32_dpp v197, v225, v49 row_newbcast:12 row_mask:0xf bank_mask:0xf
	v_fmac_f32_dpp v198, v226, v50 row_newbcast:12 row_mask:0xf bank_mask:0xf
	v_fmac_f32_dpp v199, v227, v51 row_newbcast:12 row_mask:0xf bank_mask:0xf
	v_fmac_f32_dpp v196, v224, v52 row_newbcast:13 row_mask:0xf bank_mask:0xf
	v_fmac_f32_dpp v197, v225, v53 row_newbcast:13 row_mask:0xf bank_mask:0xf
	v_fmac_f32_dpp v198, v226, v54 row_newbcast:13 row_mask:0xf bank_mask:0xf
	v_fmac_f32_dpp v199, v227, v55 row_newbcast:13 row_mask:0xf bank_mask:0xf
	v_fmac_f32_dpp v196, v224, v56 row_newbcast:14 row_mask:0xf bank_mask:0xf
	v_fmac_f32_dpp v197, v225, v57 row_newbcast:14 row_mask:0xf bank_mask:0xf
	v_fmac_f32_dpp v198, v226, v58 row_newbcast:14 row_mask:0xf bank_mask:0xf
	v_fmac_f32_dpp v199, v227, v59 row_newbcast:14 row_mask:0xf bank_mask:0xf
	v_fmac_f32_dpp v196, v224, v60 row_newbcast:15 row_mask:0xf bank_mask:0xf
	v_fmac_f32_dpp v197, v225, v61 row_newbcast:15 row_mask:0xf bank_mask:0xf
	v_fmac_f32_dpp v198, v226, v62 row_newbcast:15 row_mask:0xf bank_mask:0xf
	v_fmac_f32_dpp v199, v227, v63 row_newbcast:15 row_mask:0xf bank_mask:0xf
	v_add_f32_e32 v196, v196, v197
	v_add_f32_e32 v198, v198, v199
	v_add_f32_e32 v196, v196, v198
	v_xor_b32_e32 v202, 0x80000000, v196
	s_waitcnt lgkmcnt(0)
;     static __device__ __forceinline__ void dot(const float (&S)[64], const f32x4& a, float (&s)[4]) {
;         if constexpr (K == 0) {
;             asm volatile("v_mul_f32_dpp %0, %4, %8 row_newbcast:%16" DPPM "v_mul_f32_dpp %1, %5, %9 row_newbcast:%16" DPPM "v_mul_f32_dpp %2, %6, %10 row_newbcast:%16" DPPM "v_mul_f32_dpp %3, %7, %11 row_newbcast:%16" DPPM
;                          "v_fmac_f32_dpp %0, %4, %12 row_newbcast:%17" DPPM "v_fmac_f32_dpp %1, %5, %13 row_newbcast:%17" DPPM "v_fmac_f32_dpp %2, %6, %14 row_newbcast:%17" DPPM "v_fmac_f32_dpp %3, %7, %15 row_newbcast:%17" DPPM
;                          : "=&v"(s[0]), "=&v"(s[1]), "=&v"(s[2]), "=&v"(s[3])
;                          : "v"(a[0]), "v"(a[1]), "v"(a[2]), "v"(a[3]), "v"(S[K]), "v"(S[K + 1]), "v"(S[K + 2]), "v"(S[K + 3]), "v"(S[K + 4]), "v"(S[K + 5]), "v"(S[K + 6]), "v"(S[K + 7]), "n"(N0), "n"(N1));
;         } else
;         asm volatile("v_fmac_f32_dpp %0, %4, %8 row_newbcast:%16" DPPM "v_fmac_f32_dpp %1, %5, %9 row_newbcast:%16" DPPM "v_fmac_f32_dpp %2, %6, %10 row_newbcast:%16" DPPM "v_fmac_f32_dpp %3, %7, %11 row_newbcast:%16" DPPM
;                      "v_fmac_f32_dpp %0, %4, %12 row_newbcast:%17" DPPM "v_fmac_f32_dpp %1, %5, %13 row_newbcast:%17" DPPM "v_fmac_f32_dpp %2, %6, %14 row_newbcast:%17" DPPM "v_fmac_f32_dpp %3, %7, %15 row_newbcast:%17" DPPM
;                      : "+v"(s[0]), "+v"(s[1]), "+v"(s[2]), "+v"(s[3])
;                      : "v"(a[0]), "v"(a[1]), "v"(a[2]), "v"(a[3]), "v"(S[K]), "v"(S[K + 1]), "v"(S[K + 2]), "v"(S[K + 3]), "v"(S[K + 4]), "v"(S[K + 5]), "v"(S[K + 6]), "v"(S[K + 7]), "n"(N0), "n"(N1));
;         if constexpr (K + 8 < 64) ScanK<K + 8>::dot(S, a, s);
;     }
;     static __device__ __forceinline__ void upd(float (&S)[64], const In2& in, float sa, float vv, float& y0, float& y1) {
;         float t0, t1, t2, t3;
;         asm volatile("v_mul_f32_dpp %0, %10, %27 row_newbcast:%28" DPPM "v_mul_f32_dpp %1, %11, %27 row_newbcast:%28" DPPM "v_mul_f32_dpp %2, %12, %27 row_newbcast:%28" DPPM "v_mul_f32_dpp %3, %13, %27 row_newbcast:%28" DPPM
;                      "v_fmac_f32_dpp %0, %14, %6 row_newbcast:%28" DPPM "v_fmac_f32_dpp %1, %15, %7 row_newbcast:%28" DPPM "v_fmac_f32_dpp %2, %16, %8 row_newbcast:%28" DPPM "v_fmac_f32_dpp %3, %17, %9 row_newbcast:%28" DPPM
	s_nop 1
	v_mfma_f32_4x4x1_16b_f32 v[0:3], v64, v202, v[0:3]
	v_mfma_f32_4x4x1_16b_f32 v[4:7], v65, v202, v[4:7]
	v_mfma_f32_4x4x1_16b_f32 v[8:11], v66, v202, v[8:11]
	v_mfma_f32_4x4x1_16b_f32 v[12:15], v67, v202, v[12:15]
	v_mfma_f32_4x4x1_16b_f32 v[16:19], v68, v202, v[16:19]
	v_mfma_f32_4x4x1_16b_f32 v[20:23], v69, v202, v[20:23]
	v_mfma_f32_4x4x1_16b_f32 v[24:27], v70, v202, v[24:27]
	v_mfma_f32_4x4x1_16b_f32 v[28:31], v71, v202, v[28:31]
	v_mfma_f32_4x4x1_16b_f32 v[32:35], v72, v202, v[32:35]
	v_mfma_f32_4x4x1_16b_f32 v[36:39], v73, v202, v[36:39]
	v_mfma_f32_4x4x1_16b_f32 v[40:43], v74, v202, v[40:43]
	v_mfma_f32_4x4x1_16b_f32 v[44:47], v75, v202, v[44:47]
	v_mfma_f32_4x4x1_16b_f32 v[48:51], v76, v202, v[48:51]
	v_mfma_f32_4x4x1_16b_f32 v[52:55], v77, v202, v[52:55]
	v_mfma_f32_4x4x1_16b_f32 v[56:59], v78, v202, v[56:59]
	v_mfma_f32_4x4x1_16b_f32 v[60:63], v79, v202, v[60:63]
	v_mfma_f32_4x4x1_16b_f32 v[0:3], v80, v203, v[0:3]
	v_mfma_f32_4x4x1_16b_f32 v[4:7], v81, v203, v[4:7]
	v_mfma_f32_4x4x1_16b_f32 v[8:11], v82, v203, v[8:11]
	v_mfma_f32_4x4x1_16b_f32 v[12:15], v83, v203, v[12:15]
	v_mfma_f32_4x4x1_16b_f32 v[16:19], v84, v203, v[16:19]
	v_mfma_f32_4x4x1_16b_f32 v[20:23], v85, v203, v[20:23]
	v_mfma_f32_4x4x1_16b_f32 v[24:27], v86, v203, v[24:27]
	v_mfma_f32_4x4x1_16b_f32 v[28:31], v87, v203, v[28:31]
	v_mfma_f32_4x4x1_16b_f32 v[32:35], v88, v203, v[32:35]
	v_mfma_f32_4x4x1_16b_f32 v[36:39], v89, v203, v[36:39]
	v_mfma_f32_4x4x1_16b_f32 v[40:43], v90, v203, v[40:43]
	v_mfma_f32_4x4x1_16b_f32 v[44:47], v91, v203, v[44:47]
	v_mfma_f32_4x4x1_16b_f32 v[48:51], v92, v203, v[48:51]
	v_mfma_f32_4x4x1_16b_f32 v[52:55], v93, v203, v[52:55]
	v_mfma_f32_4x4x1_16b_f32 v[56:59], v94, v203, v[56:59]
	v_mfma_f32_4x4x1_16b_f32 v[60:63], v95, v203, v[60:63]
	s_waitcnt vmcnt(10)
	buffer_load_dwordx4 v[116:119], v204, s[64:67], s72 offen
	buffer_load_dwordx4 v[120:123], v204, s[64:67], s73 offen
	buffer_load_dwordx4 v[124:127], v204, s[64:67], s74 offen
	buffer_load_dwordx2 v[132:133], v205, s[64:67], s76 offen
	buffer_load_ushort v134, v206, s[64:67], s77 offen
	s_cmp_lt_u32 s80, 255
	s_cselect_b32 s81, 0xfffff000, 0
	s_cselect_b32 s82, 0xfffff800, 0
	s_cselect_b32 s9, 1, 0
	s_add_u32 s80, s80, s9
	s_add_u32 s72, s72, s81
	s_add_u32 s73, s73, s81
	s_add_u32 s74, s74, s81
	s_add_u32 s76, s76, s82
	s_add_u32 s77, s77, s82
	v_pk_mul_f32 v[224:225], v[140:141], v[216:217]
	v_pk_mul_f32 v[226:227], v[142:143], v[218:219]
	v_pk_mul_f32 v[216:217], v[216:217], v[136:137]
	v_pk_mul_f32 v[218:219], v[218:219], v[138:139]
	v_pk_fma_f32 v[184:185], v[144:145], v[188:189], v[192:193]
	v_pk_fma_f32 v[186:187], v[146:147], v[190:191], v[194:195]
	v_pk_mul_f32 v[176:177], v[140:141], v[144:145]
	v_pk_mul_f32 v[178:179], v[142:143], v[146:147]
	v_rcp_f32_e32 v220, v216
	v_rcp_f32_e32 v221, v217
	v_rcp_f32_e32 v222, v218
	v_rcp_f32_e32 v223, v219
	v_lshlrev_b32_e32 v180, 16, v152
	v_and_b32_e32 v181, 0xffff0000, v152
	v_lshlrev_b32_e32 v182, 16, v153
	v_and_b32_e32 v183, 0xffff0000, v153
	v_pk_mul_f32 v[180:181], v[180:181], v[184:185]
	v_pk_mul_f32 v[182:183], v[182:183], v[186:187]
	v_lshlrev_b32_e32 v203, 16, v154
	v_pk_mul_f32 v[176:177], v[176:177], v[220:221]
	v_pk_mul_f32 v[178:179], v[178:179], v[222:223]
	v_pk_mul_f32 v[180:181], v[180:181], v[220:221]
	v_pk_mul_f32 v[182:183], v[182:183], v[222:223]
	ds_write_b128 v208, v[176:179]
	ds_write_b128 v208, v[180:183] offset:256
	ds_read2_b32 v[64:65], v209 offset0:0 offset1:4
	ds_read2_b32 v[66:67], v209 offset0:8 offset1:12
	ds_read2_b32 v[68:69], v209 offset0:16 offset1:20
	ds_read2_b32 v[70:71], v209 offset0:24 offset1:28
	ds_read2_b32 v[72:73], v209 offset0:32 offset1:36
	ds_read2_b32 v[74:75], v209 offset0:40 offset1:44
	ds_read2_b32 v[76:77], v209 offset0:48 offset1:52
	ds_read2_b32 v[78:79], v209 offset0:56 offset1:60
	ds_read2_b32 v[80:81], v209 offset0:64 offset1:68
	ds_read2_b32 v[82:83], v209 offset0:72 offset1:76
	ds_read2_b32 v[84:85], v209 offset0:80 offset1:84
	ds_read2_b32 v[86:87], v209 offset0:88 offset1:92
	ds_read2_b32 v[88:89], v209 offset0:96 offset1:100
	ds_read2_b32 v[90:91], v209 offset0:104 offset1:108
	ds_read2_b32 v[92:93], v209 offset0:112 offset1:116
	ds_read2_b32 v[94:95], v209 offset0:120 offset1:124
	v_mul_f32_dpp v196, v224, v0 row_newbcast:0 row_mask:0xf bank_mask:0xf
	v_mul_f32_dpp v197, v225, v1 row_newbcast:0 row_mask:0xf bank_mask:0xf
	v_mul_f32_dpp v198, v226, v2 row_newbcast:0 row_mask:0xf bank_mask:0xf
	v_mul_f32_dpp v199, v227, v3 row_newbcast:0 row_mask:0xf bank_mask:0xf
	v_fmac_f32_dpp v196, v224, v4 row_newbcast:1 row_mask:0xf bank_mask:0xf
	v_fmac_f32_dpp v197, v225, v5 row_newbcast:1 row_mask:0xf bank_mask:0xf
	v_fmac_f32_dpp v198, v226, v6 row_newbcast:1 row_mask:0xf bank_mask:0xf
	v_fmac_f32_dpp v199, v227, v7 row_newbcast:1 row_mask:0xf bank_mask:0xf
	v_fmac_f32_dpp v196, v224, v8 row_newbcast:2 row_mask:0xf bank_mask:0xf
	v_fmac_f32_dpp v197, v225, v9 row_newbcast:2 row_mask:0xf bank_mask:0xf
	v_fmac_f32_dpp v198, v226, v10 row_newbcast:2 row_mask:0xf bank_mask:0xf
	v_fmac_f32_dpp v199, v227, v11 row_newbcast:2 row_mask:0xf bank_mask:0xf
	v_fmac_f32_dpp v196, v224, v12 row_newbcast:3 row_mask:0xf bank_mask:0xf
	v_fmac_f32_dpp v197, v225, v13 row_newbcast:3 row_mask:0xf bank_mask:0xf
	v_fmac_f32_dpp v198, v226, v14 row_newbcast:3 row_mask:0xf bank_mask:0xf
	v_fmac_f32_dpp v199, v227, v15 row_newbcast:3 row_mask:0xf bank_mask:0xf
	v_fmac_f32_dpp v196, v224, v16 row_newbcast:4 row_mask:0xf bank_mask:0xf
	v_fmac_f32_dpp v197, v225, v17 row_newbcast:4 row_mask:0xf bank_mask:0xf
	v_fmac_f32_dpp v198, v226, v18 row_newbcast:4 row_mask:0xf bank_mask:0xf
;     static __device__ __forceinline__ void dot(const float (&S)[64], const f32x4& a, float (&s)[4]) {
;         if constexpr (K == 0) {
;             asm volatile("v_mul_f32_dpp %0, %4, %8 row_newbcast:%16" DPPM "v_mul_f32_dpp %1, %5, %9 row_newbcast:%16" DPPM "v_mul_f32_dpp %2, %6, %10 row_newbcast:%16" DPPM "v_mul_f32_dpp %3, %7, %11 row_newbcast:%16" DPPM
;                          "v_fmac_f32_dpp %0, %4, %12 row_newbcast:%17" DPPM "v_fmac_f32_dpp %1, %5, %13 row_newbcast:%17" DPPM "v_fmac_f32_dpp %2, %6, %14 row_newbcast:%17" DPPM "v_fmac_f32_dpp %3, %7, %15 row_newbcast:%17" DPPM
;                          : "=&v"(s[0]), "=&v"(s[1]), "=&v"(s[2]), "=&v"(s[3])
;                          : "v"(a[0]), "v"(a[1]), "v"(a[2]), "v"(a[3]), "v"(S[K]), "v"(S[K + 1]), "v"(S[K + 2]), "v"(S[K + 3]), "v"(S[K + 4]), "v"(S[K + 5]), "v"(S[K + 6]), "v"(S[K + 7]), "n"(N0), "n"(N1));
;         } else
;         asm volatile("v_fmac_f32_dpp %0, %4, %8 row_newbcast:%16" DPPM "v_fmac_f32_dpp %1, %5, %9 row_newbcast:%16" DPPM "v_fmac_f32_dpp %2, %6, %10 row_newbcast:%16" DPPM "v_fmac_f32_dpp %3, %7, %11 row_newbcast:%16" DPPM
;                      "v_fmac_f32_dpp %0, %4, %12 row_newbcast:%17" DPPM "v_fmac_f32_dpp %1, %5, %13 row_newbcast:%17" DPPM "v_fmac_f32_dpp %2, %6, %14 row_newbcast:%17" DPPM "v_fmac_f32_dpp %3, %7, %15 row_newbcast:%17" DPPM
;                      : "+v"(s[0]), "+v"(s[1]), "+v"(s[2]), "+v"(s[3])
;                      : "v"(a[0]), "v"(a[1]), "v"(a[2]), "v"(a[3]), "v"(S[K]), "v"(S[K + 1]), "v"(S[K + 2]), "v"(S[K + 3]), "v"(S[K + 4]), "v"(S[K + 5]), "v"(S[K + 6]), "v"(S[K + 7]), "n"(N0), "n"(N1));
;         if constexpr (K + 8 < 64) ScanK<K + 8>::dot(S, a, s);
;     }
;     static __device__ __forceinline__ void upd(float (&S)[64], const In2& in, float sa, float vv, float& y0, float& y1) {
;         float t0, t1, t2, t3;
;         asm volatile("v_mul_f32_dpp %0, %10, %27 row_newbcast:%28" DPPM "v_mul_f32_dpp %1, %11, %27 row_newbcast:%28" DPPM "v_mul_f32_dpp %2, %12, %27 row_newbcast:%28" DPPM "v_mul_f32_dpp %3, %13, %27 row_newbcast:%28" DPPM
;                      "v_fmac_f32_dpp %0, %14, %6 row_newbcast:%28" DPPM "v_fmac_f32_dpp %1, %15, %7 row_newbcast:%28" DPPM "v_fmac_f32_dpp %2, %16, %8 row_newbcast:%28" DPPM "v_fmac_f32_dpp %3, %17, %9 row_newbcast:%28" DPPM
	v_fmac_f32_dpp v199, v227, v19 row_newbcast:4 row_mask:0xf bank_mask:0xf
	v_fmac_f32_dpp v196, v224, v20 row_newbcast:5 row_mask:0xf bank_mask:0xf
	v_fmac_f32_dpp v197, v225, v21 row_newbcast:5 row_mask:0xf bank_mask:0xf
	v_fmac_f32_dpp v198, v226, v22 row_newbcast:5 row_mask:0xf bank_mask:0xf
	v_fmac_f32_dpp v199, v227, v23 row_newbcast:5 row_mask:0xf bank_mask:0xf
	v_fmac_f32_dpp v196, v224, v24 row_newbcast:6 row_mask:0xf bank_mask:0xf
	v_fmac_f32_dpp v197, v225, v25 row_newbcast:6 row_mask:0xf bank_mask:0xf
	v_fmac_f32_dpp v198, v226, v26 row_newbcast:6 row_mask:0xf bank_mask:0xf
	v_fmac_f32_dpp v199, v227, v27 row_newbcast:6 row_mask:0xf bank_mask:0xf
	v_fmac_f32_dpp v196, v224, v28 row_newbcast:7 row_mask:0xf bank_mask:0xf
	v_fmac_f32_dpp v197, v225, v29 row_newbcast:7 row_mask:0xf bank_mask:0xf
	v_fmac_f32_dpp v198, v226, v30 row_newbcast:7 row_mask:0xf bank_mask:0xf
	v_fmac_f32_dpp v199, v227, v31 row_newbcast:7 row_mask:0xf bank_mask:0xf
	v_fmac_f32_dpp v196, v224, v32 row_newbcast:8 row_mask:0xf bank_mask:0xf
	v_fmac_f32_dpp v197, v225, v33 row_newbcast:8 row_mask:0xf bank_mask:0xf
	v_fmac_f32_dpp v198, v226, v34 row_newbcast:8 row_mask:0xf bank_mask:0xf
	v_fmac_f32_dpp v199, v227, v35 row_newbcast:8 row_mask:0xf bank_mask:0xf
	v_fmac_f32_dpp v196, v224, v36 row_newbcast:9 row_mask:0xf bank_mask:0xf
	v_fmac_f32_dpp v197, v225, v37 row_newbcast:9 row_mask:0xf bank_mask:0xf
	v_fmac_f32_dpp v198, v226, v38 row_newbcast:9 row_mask:0xf bank_mask:0xf
	v_fmac_f32_dpp v199, v227, v39 row_newbcast:9 row_mask:0xf bank_mask:0xf
	v_fmac_f32_dpp v196, v224, v40 row_newbcast:10 row_mask:0xf bank_mask:0xf
	v_fmac_f32_dpp v197, v225, v41 row_newbcast:10 row_mask:0xf bank_mask:0xf
	v_fmac_f32_dpp v198, v226, v42 row_newbcast:10 row_mask:0xf bank_mask:0xf
	v_fmac_f32_dpp v199, v227, v43 row_newbcast:10 row_mask:0xf bank_mask:0xf
	v_fmac_f32_dpp v196, v224, v44 row_newbcast:11 row_mask:0xf bank_mask:0xf
	v_fmac_f32_dpp v197, v225, v45 row_newbcast:11 row_mask:0xf bank_mask:0xf
	v_fmac_f32_dpp v198, v226, v46 row_newbcast:11 row_mask:0xf bank_mask:0xf
	v_fmac_f32_dpp v199, v227, v47 row_newbcast:11 row_mask:0xf bank_mask:0xf
	v_fmac_f32_dpp v196, v224, v48 row_newbcast:12 row_mask:0xf bank_mask:0xf
	v_fmac_f32_dpp v197, v225, v49 row_newbcast:12 row_mask:0xf bank_mask:0xf
	v_fmac_f32_dpp v198, v226, v50 row_newbcast:12 row_mask:0xf bank_mask:0xf
	v_fmac_f32_dpp v199, v227, v51 row_newbcast:12 row_mask:0xf bank_mask:0xf
	v_fmac_f32_dpp v196, v224, v52 row_newbcast:13 row_mask:0xf bank_mask:0xf
	v_fmac_f32_dpp v197, v225, v53 row_newbcast:13 row_mask:0xf bank_mask:0xf
	v_fmac_f32_dpp v198, v226, v54 row_newbcast:13 row_mask:0xf bank_mask:0xf
	v_fmac_f32_dpp v199, v227, v55 row_newbcast:13 row_mask:0xf bank_mask:0xf
	v_fmac_f32_dpp v196, v224, v56 row_newbcast:14 row_mask:0xf bank_mask:0xf
	v_fmac_f32_dpp v197, v225, v57 row_newbcast:14 row_mask:0xf bank_mask:0xf
	v_fmac_f32_dpp v198, v226, v58 row_newbcast:14 row_mask:0xf bank_mask:0xf
	v_fmac_f32_dpp v199, v227, v59 row_newbcast:14 row_mask:0xf bank_mask:0xf
	v_fmac_f32_dpp v196, v224, v60 row_newbcast:15 row_mask:0xf bank_mask:0xf
	v_fmac_f32_dpp v197, v225, v61 row_newbcast:15 row_mask:0xf bank_mask:0xf
	v_fmac_f32_dpp v198, v226, v62 row_newbcast:15 row_mask:0xf bank_mask:0xf
	v_fmac_f32_dpp v199, v227, v63 row_newbcast:15 row_mask:0xf bank_mask:0xf
	v_add_f32_e32 v196, v196, v197
	v_add_f32_e32 v198, v198, v199
	v_add_f32_e32 v196, v196, v198
	v_xor_b32_e32 v202, 0x80000000, v196
	s_waitcnt lgkmcnt(0)
	s_nop 1
	v_mfma_f32_4x4x1_16b_f32 v[0:3], v64, v202, v[0:3]
	v_mfma_f32_4x4x1_16b_f32 v[4:7], v65, v202, v[4:7]
	v_mfma_f32_4x4x1_16b_f32 v[8:11], v66, v202, v[8:11]
	v_mfma_f32_4x4x1_16b_f32 v[12:15], v67, v202, v[12:15]
	v_mfma_f32_4x4x1_16b_f32 v[16:19], v68, v202, v[16:19]
	v_mfma_f32_4x4x1_16b_f32 v[20:23], v69, v202, v[20:23]
	v_mfma_f32_4x4x1_16b_f32 v[24:27], v70, v202, v[24:27]
	v_mfma_f32_4x4x1_16b_f32 v[28:31], v71, v202, v[28:31]
	v_mfma_f32_4x4x1_16b_f32 v[32:35], v72, v202, v[32:35]
	v_mfma_f32_4x4x1_16b_f32 v[36:39], v73, v202, v[36:39]
	v_mfma_f32_4x4x1_16b_f32 v[40:43], v74, v202, v[40:43]
	v_mfma_f32_4x4x1_16b_f32 v[44:47], v75, v202, v[44:47]
	v_mfma_f32_4x4x1_16b_f32 v[48:51], v76, v202, v[48:51]
	v_mfma_f32_4x4x1_16b_f32 v[52:55], v77, v202, v[52:55]
	v_mfma_f32_4x4x1_16b_f32 v[56:59], v78, v202, v[56:59]
	v_mfma_f32_4x4x1_16b_f32 v[60:63], v79, v202, v[60:63]
	v_mfma_f32_4x4x1_16b_f32 v[0:3], v80, v203, v[0:3]
	v_mfma_f32_4x4x1_16b_f32 v[4:7], v81, v203, v[4:7]
	v_mfma_f32_4x4x1_16b_f32 v[8:11], v82, v203, v[8:11]
	v_mfma_f32_4x4x1_16b_f32 v[12:15], v83, v203, v[12:15]
	v_mfma_f32_4x4x1_16b_f32 v[16:19], v84, v203, v[16:19]
	v_mfma_f32_4x4x1_16b_f32 v[20:23], v85, v203, v[20:23]
	v_mfma_f32_4x4x1_16b_f32 v[24:27], v86, v203, v[24:27]
	v_mfma_f32_4x4x1_16b_f32 v[28:31], v87, v203, v[28:31]
	v_mfma_f32_4x4x1_16b_f32 v[32:35], v88, v203, v[32:35]
	v_mfma_f32_4x4x1_16b_f32 v[36:39], v89, v203, v[36:39]
	v_mfma_f32_4x4x1_16b_f32 v[40:43], v90, v203, v[40:43]
	v_mfma_f32_4x4x1_16b_f32 v[44:47], v91, v203, v[44:47]
	v_mfma_f32_4x4x1_16b_f32 v[48:51], v92, v203, v[48:51]
	v_mfma_f32_4x4x1_16b_f32 v[52:55], v93, v203, v[52:55]
	v_mfma_f32_4x4x1_16b_f32 v[56:59], v94, v203, v[56:59]
	v_mfma_f32_4x4x1_16b_f32 v[60:63], v95, v203, v[60:63]
	s_waitcnt vmcnt(10)
;     static __device__ __forceinline__ void dot(const float (&S)[64], const f32x4& a, float (&s)[4]) {
;         if constexpr (K == 0) {
;             asm volatile("v_mul_f32_dpp %0, %4, %8 row_newbcast:%16" DPPM "v_mul_f32_dpp %1, %5, %9 row_newbcast:%16" DPPM "v_mul_f32_dpp %2, %6, %10 row_newbcast:%16" DPPM "v_mul_f32_dpp %3, %7, %11 row_newbcast:%16" DPPM
;                          "v_fmac_f32_dpp %0, %4, %12 row_newbcast:%17" DPPM "v_fmac_f32_dpp %1, %5, %13 row_newbcast:%17" DPPM "v_fmac_f32_dpp %2, %6, %14 row_newbcast:%17" DPPM "v_fmac_f32_dpp %3, %7, %15 row_newbcast:%17" DPPM
;                          : "=&v"(s[0]), "=&v"(s[1]), "=&v"(s[2]), "=&v"(s[3])
;                          : "v"(a[0]), "v"(a[1]), "v"(a[2]), "v"(a[3]), "v"(S[K]), "v"(S[K + 1]), "v"(S[K + 2]), "v"(S[K + 3]), "v"(S[K + 4]), "v"(S[K + 5]), "v"(S[K + 6]), "v"(S[K + 7]), "n"(N0), "n"(N1));
;         } else
;         asm volatile("v_fmac_f32_dpp %0, %4, %8 row_newbcast:%16" DPPM "v_fmac_f32_dpp %1, %5, %9 row_newbcast:%16" DPPM "v_fmac_f32_dpp %2, %6, %10 row_newbcast:%16" DPPM "v_fmac_f32_dpp %3, %7, %11 row_newbcast:%16" DPPM
;                      "v_fmac_f32_dpp %0, %4, %12 row_newbcast:%17" DPPM "v_fmac_f32_dpp %1, %5, %13 row_newbcast:%17" DPPM "v_fmac_f32_dpp %2, %6, %14 row_newbcast:%17" DPPM "v_fmac_f32_dpp %3, %7, %15 row_newbcast:%17" DPPM
;                      : "+v"(s[0]), "+v"(s[1]), "+v"(s[2]), "+v"(s[3])
;                      : "v"(a[0]), "v"(a[1]), "v"(a[2]), "v"(a[3]), "v"(S[K]), "v"(S[K + 1]), "v"(S[K + 2]), "v"(S[K + 3]), "v"(S[K + 4]), "v"(S[K + 5]), "v"(S[K + 6]), "v"(S[K + 7]), "n"(N0), "n"(N1));
;         if constexpr (K + 8 < 64) ScanK<K + 8>::dot(S, a, s);
;     }
;     static __device__ __forceinline__ void upd(float (&S)[64], const In2& in, float sa, float vv, float& y0, float& y1) {
;         float t0, t1, t2, t3;
;         asm volatile("v_mul_f32_dpp %0, %10, %27 row_newbcast:%28" DPPM "v_mul_f32_dpp %1, %11, %27 row_newbcast:%28" DPPM "v_mul_f32_dpp %2, %12, %27 row_newbcast:%28" DPPM "v_mul_f32_dpp %3, %13, %27 row_newbcast:%28" DPPM
;                      "v_fmac_f32_dpp %0, %14, %6 row_newbcast:%28" DPPM "v_fmac_f32_dpp %1, %15, %7 row_newbcast:%28" DPPM "v_fmac_f32_dpp %2, %16, %8 row_newbcast:%28" DPPM "v_fmac_f32_dpp %3, %17, %9 row_newbcast:%28" DPPM
	buffer_load_dwordx4 v[136:139], v204, s[64:67], s72 offen
	buffer_load_dwordx4 v[140:143], v204, s[64:67], s73 offen
	buffer_load_dwordx4 v[144:147], v204, s[64:67], s74 offen
	buffer_load_dwordx2 v[152:153], v205, s[64:67], s76 offen
	buffer_load_ushort v154, v206, s[64:67], s77 offen
	s_cmp_lt_u32 s80, 255
	s_cselect_b32 s81, 0xfffff000, 0
	s_cselect_b32 s82, 0xfffff800, 0
	s_cselect_b32 s9, 1, 0
	s_add_u32 s80, s80, s9
	s_add_u32 s72, s72, s81
	s_add_u32 s73, s73, s81
	s_add_u32 s74, s74, s81
	s_add_u32 s76, s76, s82
	s_add_u32 s77, s77, s82
	v_pk_mul_f32 v[224:225], v[160:161], v[216:217]
	v_pk_mul_f32 v[226:227], v[162:163], v[218:219]
	v_pk_mul_f32 v[216:217], v[216:217], v[156:157]
	v_pk_mul_f32 v[218:219], v[218:219], v[158:159]
	v_pk_fma_f32 v[184:185], v[164:165], v[188:189], v[192:193]
	v_pk_fma_f32 v[186:187], v[166:167], v[190:191], v[194:195]
	v_pk_mul_f32 v[176:177], v[160:161], v[164:165]
	v_pk_mul_f32 v[178:179], v[162:163], v[166:167]
	v_rcp_f32_e32 v220, v216
	v_rcp_f32_e32 v221, v217
	v_rcp_f32_e32 v222, v218
	v_rcp_f32_e32 v223, v219
	v_lshlrev_b32_e32 v180, 16, v172
	v_and_b32_e32 v181, 0xffff0000, v172
	v_lshlrev_b32_e32 v182, 16, v173
	v_and_b32_e32 v183, 0xffff0000, v173
	v_pk_mul_f32 v[180:181], v[180:181], v[184:185]
	v_pk_mul_f32 v[182:183], v[182:183], v[186:187]
	v_lshlrev_b32_e32 v203, 16, v174
	v_pk_mul_f32 v[176:177], v[176:177], v[220:221]
	v_pk_mul_f32 v[178:179], v[178:179], v[222:223]
	v_pk_mul_f32 v[180:181], v[180:181], v[220:221]
	v_pk_mul_f32 v[182:183], v[182:183], v[222:223]
	ds_write_b128 v208, v[176:179]
	ds_write_b128 v208, v[180:183] offset:256
	ds_read2_b32 v[64:65], v209 offset0:0 offset1:4
	ds_read2_b32 v[66:67], v209 offset0:8 offset1:12
	ds_read2_b32 v[68:69], v209 offset0:16 offset1:20
	ds_read2_b32 v[70:71], v209 offset0:24 offset1:28
	ds_read2_b32 v[72:73], v209 offset0:32 offset1:36
	ds_read2_b32 v[74:75], v209 offset0:40 offset1:44
	ds_read2_b32 v[76:77], v209 offset0:48 offset1:52
	ds_read2_b32 v[78:79], v209 offset0:56 offset1:60
	ds_read2_b32 v[80:81], v209 offset0:64 offset1:68
	ds_read2_b32 v[82:83], v209 offset0:72 offset1:76
	ds_read2_b32 v[84:85], v209 offset0:80 offset1:84
	ds_read2_b32 v[86:87], v209 offset0:88 offset1:92
	ds_read2_b32 v[88:89], v209 offset0:96 offset1:100
	ds_read2_b32 v[90:91], v209 offset0:104 offset1:108
	ds_read2_b32 v[92:93], v209 offset0:112 offset1:116
	ds_read2_b32 v[94:95], v209 offset0:120 offset1:124
	v_mul_f32_dpp v196, v224, v0 row_newbcast:0 row_mask:0xf bank_mask:0xf
	v_mul_f32_dpp v197, v225, v1 row_newbcast:0 row_mask:0xf bank_mask:0xf
	v_mul_f32_dpp v198, v226, v2 row_newbcast:0 row_mask:0xf bank_mask:0xf
	v_mul_f32_dpp v199, v227, v3 row_newbcast:0 row_mask:0xf bank_mask:0xf
	v_fmac_f32_dpp v196, v224, v4 row_newbcast:1 row_mask:0xf bank_mask:0xf
	v_fmac_f32_dpp v197, v225, v5 row_newbcast:1 row_mask:0xf bank_mask:0xf
	v_fmac_f32_dpp v198, v226, v6 row_newbcast:1 row_mask:0xf bank_mask:0xf
	v_fmac_f32_dpp v199, v227, v7 row_newbcast:1 row_mask:0xf bank_mask:0xf
	v_fmac_f32_dpp v196, v224, v8 row_newbcast:2 row_mask:0xf bank_mask:0xf
	v_fmac_f32_dpp v197, v225, v9 row_newbcast:2 row_mask:0xf bank_mask:0xf
	v_fmac_f32_dpp v198, v226, v10 row_newbcast:2 row_mask:0xf bank_mask:0xf
	v_fmac_f32_dpp v199, v227, v11 row_newbcast:2 row_mask:0xf bank_mask:0xf
	v_fmac_f32_dpp v196, v224, v12 row_newbcast:3 row_mask:0xf bank_mask:0xf
	v_fmac_f32_dpp v197, v225, v13 row_newbcast:3 row_mask:0xf bank_mask:0xf
	v_fmac_f32_dpp v198, v226, v14 row_newbcast:3 row_mask:0xf bank_mask:0xf
	v_fmac_f32_dpp v199, v227, v15 row_newbcast:3 row_mask:0xf bank_mask:0xf
	v_fmac_f32_dpp v196, v224, v16 row_newbcast:4 row_mask:0xf bank_mask:0xf
	v_fmac_f32_dpp v197, v225, v17 row_newbcast:4 row_mask:0xf bank_mask:0xf
	v_fmac_f32_dpp v198, v226, v18 row_newbcast:4 row_mask:0xf bank_mask:0xf
	v_fmac_f32_dpp v199, v227, v19 row_newbcast:4 row_mask:0xf bank_mask:0xf
	v_fmac_f32_dpp v196, v224, v20 row_newbcast:5 row_mask:0xf bank_mask:0xf
	v_fmac_f32_dpp v197, v225, v21 row_newbcast:5 row_mask:0xf bank_mask:0xf
	v_fmac_f32_dpp v198, v226, v22 row_newbcast:5 row_mask:0xf bank_mask:0xf
	v_fmac_f32_dpp v199, v227, v23 row_newbcast:5 row_mask:0xf bank_mask:0xf
	v_fmac_f32_dpp v196, v224, v24 row_newbcast:6 row_mask:0xf bank_mask:0xf
	v_fmac_f32_dpp v197, v225, v25 row_newbcast:6 row_mask:0xf bank_mask:0xf
	v_fmac_f32_dpp v198, v226, v26 row_newbcast:6 row_mask:0xf bank_mask:0xf
	v_fmac_f32_dpp v199, v227, v27 row_newbcast:6 row_mask:0xf bank_mask:0xf
	v_fmac_f32_dpp v196, v224, v28 row_newbcast:7 row_mask:0xf bank_mask:0xf
	v_fmac_f32_dpp v197, v225, v29 row_newbcast:7 row_mask:0xf bank_mask:0xf
;     static __device__ __forceinline__ void dot(const float (&S)[64], const f32x4& a, float (&s)[4]) {
;         if constexpr (K == 0) {
;             asm volatile("v_mul_f32_dpp %0, %4, %8 row_newbcast:%16" DPPM "v_mul_f32_dpp %1, %5, %9 row_newbcast:%16" DPPM "v_mul_f32_dpp %2, %6, %10 row_newbcast:%16" DPPM "v_mul_f32_dpp %3, %7, %11 row_newbcast:%16" DPPM
;                          "v_fmac_f32_dpp %0, %4, %12 row_newbcast:%17" DPPM "v_fmac_f32_dpp %1, %5, %13 row_newbcast:%17" DPPM "v_fmac_f32_dpp %2, %6, %14 row_newbcast:%17" DPPM "v_fmac_f32_dpp %3, %7, %15 row_newbcast:%17" DPPM
;                          : "=&v"(s[0]), "=&v"(s[1]), "=&v"(s[2]), "=&v"(s[3])
;                          : "v"(a[0]), "v"(a[1]), "v"(a[2]), "v"(a[3]), "v"(S[K]), "v"(S[K + 1]), "v"(S[K + 2]), "v"(S[K + 3]), "v"(S[K + 4]), "v"(S[K + 5]), "v"(S[K + 6]), "v"(S[K + 7]), "n"(N0), "n"(N1));
;         } else
;         asm volatile("v_fmac_f32_dpp %0, %4, %8 row_newbcast:%16" DPPM "v_fmac_f32_dpp %1, %5, %9 row_newbcast:%16" DPPM "v_fmac_f32_dpp %2, %6, %10 row_newbcast:%16" DPPM "v_fmac_f32_dpp %3, %7, %11 row_newbcast:%16" DPPM
;                      "v_fmac_f32_dpp %0, %4, %12 row_newbcast:%17" DPPM "v_fmac_f32_dpp %1, %5, %13 row_newbcast:%17" DPPM "v_fmac_f32_dpp %2, %6, %14 row_newbcast:%17" DPPM "v_fmac_f32_dpp %3, %7, %15 row_newbcast:%17" DPPM
;                      : "+v"(s[0]), "+v"(s[1]), "+v"(s[2]), "+v"(s[3])
;                      : "v"(a[0]), "v"(a[1]), "v"(a[2]), "v"(a[3]), "v"(S[K]), "v"(S[K + 1]), "v"(S[K + 2]), "v"(S[K + 3]), "v"(S[K + 4]), "v"(S[K + 5]), "v"(S[K + 6]), "v"(S[K + 7]), "n"(N0), "n"(N1));
;         if constexpr (K + 8 < 64) ScanK<K + 8>::dot(S, a, s);
;     }
;     static __device__ __forceinline__ void upd(float (&S)[64], const In2& in, float sa, float vv, float& y0, float& y1) {
;         float t0, t1, t2, t3;
;         asm volatile("v_mul_f32_dpp %0, %10, %27 row_newbcast:%28" DPPM "v_mul_f32_dpp %1, %11, %27 row_newbcast:%28" DPPM "v_mul_f32_dpp %2, %12, %27 row_newbcast:%28" DPPM "v_mul_f32_dpp %3, %13, %27 row_newbcast:%28" DPPM
;                      "v_fmac_f32_dpp %0, %14, %6 row_newbcast:%28" DPPM "v_fmac_f32_dpp %1, %15, %7 row_newbcast:%28" DPPM "v_fmac_f32_dpp %2, %16, %8 row_newbcast:%28" DPPM "v_fmac_f32_dpp %3, %17, %9 row_newbcast:%28" DPPM
	v_fmac_f32_dpp v198, v226, v30 row_newbcast:7 row_mask:0xf bank_mask:0xf
	v_fmac_f32_dpp v199, v227, v31 row_newbcast:7 row_mask:0xf bank_mask:0xf
	v_fmac_f32_dpp v196, v224, v32 row_newbcast:8 row_mask:0xf bank_mask:0xf
	v_fmac_f32_dpp v197, v225, v33 row_newbcast:8 row_mask:0xf bank_mask:0xf
	v_fmac_f32_dpp v198, v226, v34 row_newbcast:8 row_mask:0xf bank_mask:0xf
	v_fmac_f32_dpp v199, v227, v35 row_newbcast:8 row_mask:0xf bank_mask:0xf
	v_fmac_f32_dpp v196, v224, v36 row_newbcast:9 row_mask:0xf bank_mask:0xf
	v_fmac_f32_dpp v197, v225, v37 row_newbcast:9 row_mask:0xf bank_mask:0xf
	v_fmac_f32_dpp v198, v226, v38 row_newbcast:9 row_mask:0xf bank_mask:0xf
	v_fmac_f32_dpp v199, v227, v39 row_newbcast:9 row_mask:0xf bank_mask:0xf
	v_fmac_f32_dpp v196, v224, v40 row_newbcast:10 row_mask:0xf bank_mask:0xf
	v_fmac_f32_dpp v197, v225, v41 row_newbcast:10 row_mask:0xf bank_mask:0xf
	v_fmac_f32_dpp v198, v226, v42 row_newbcast:10 row_mask:0xf bank_mask:0xf
	v_fmac_f32_dpp v199, v227, v43 row_newbcast:10 row_mask:0xf bank_mask:0xf
	v_fmac_f32_dpp v196, v224, v44 row_newbcast:11 row_mask:0xf bank_mask:0xf
	v_fmac_f32_dpp v197, v225, v45 row_newbcast:11 row_mask:0xf bank_mask:0xf
	v_fmac_f32_dpp v198, v226, v46 row_newbcast:11 row_mask:0xf bank_mask:0xf
	v_fmac_f32_dpp v199, v227, v47 row_newbcast:11 row_mask:0xf bank_mask:0xf
	v_fmac_f32_dpp v196, v224, v48 row_newbcast:12 row_mask:0xf bank_mask:0xf
	v_fmac_f32_dpp v197, v225, v49 row_newbcast:12 row_mask:0xf bank_mask:0xf
	v_fmac_f32_dpp v198, v226, v50 row_newbcast:12 row_mask:0xf bank_mask:0xf
	v_fmac_f32_dpp v199, v227, v51 row_newbcast:12 row_mask:0xf bank_mask:0xf
	v_fmac_f32_dpp v196, v224, v52 row_newbcast:13 row_mask:0xf bank_mask:0xf
	v_fmac_f32_dpp v197, v225, v53 row_newbcast:13 row_mask:0xf bank_mask:0xf
	v_fmac_f32_dpp v198, v226, v54 row_newbcast:13 row_mask:0xf bank_mask:0xf
	v_fmac_f32_dpp v199, v227, v55 row_newbcast:13 row_mask:0xf bank_mask:0xf
	v_fmac_f32_dpp v196, v224, v56 row_newbcast:14 row_mask:0xf bank_mask:0xf
	v_fmac_f32_dpp v197, v225, v57 row_newbcast:14 row_mask:0xf bank_mask:0xf
	v_fmac_f32_dpp v198, v226, v58 row_newbcast:14 row_mask:0xf bank_mask:0xf
	v_fmac_f32_dpp v199, v227, v59 row_newbcast:14 row_mask:0xf bank_mask:0xf
	v_fmac_f32_dpp v196, v224, v60 row_newbcast:15 row_mask:0xf bank_mask:0xf
	v_fmac_f32_dpp v197, v225, v61 row_newbcast:15 row_mask:0xf bank_mask:0xf
	v_fmac_f32_dpp v198, v226, v62 row_newbcast:15 row_mask:0xf bank_mask:0xf
	v_fmac_f32_dpp v199, v227, v63 row_newbcast:15 row_mask:0xf bank_mask:0xf
	v_add_f32_e32 v196, v196, v197
	v_add_f32_e32 v198, v198, v199
	v_add_f32_e32 v196, v196, v198
	v_xor_b32_e32 v202, 0x80000000, v196
	s_waitcnt lgkmcnt(0)
	s_nop 1
	v_mfma_f32_4x4x1_16b_f32 v[0:3], v64, v202, v[0:3]
	v_mfma_f32_4x4x1_16b_f32 v[4:7], v65, v202, v[4:7]
	v_mfma_f32_4x4x1_16b_f32 v[8:11], v66, v202, v[8:11]
	v_mfma_f32_4x4x1_16b_f32 v[12:15], v67, v202, v[12:15]
	v_mfma_f32_4x4x1_16b_f32 v[16:19], v68, v202, v[16:19]
	v_mfma_f32_4x4x1_16b_f32 v[20:23], v69, v202, v[20:23]
	v_mfma_f32_4x4x1_16b_f32 v[24:27], v70, v202, v[24:27]
	v_mfma_f32_4x4x1_16b_f32 v[28:31], v71, v202, v[28:31]
	v_mfma_f32_4x4x1_16b_f32 v[32:35], v72, v202, v[32:35]
	v_mfma_f32_4x4x1_16b_f32 v[36:39], v73, v202, v[36:39]
	v_mfma_f32_4x4x1_16b_f32 v[40:43], v74, v202, v[40:43]
	v_mfma_f32_4x4x1_16b_f32 v[44:47], v75, v202, v[44:47]
	v_mfma_f32_4x4x1_16b_f32 v[48:51], v76, v202, v[48:51]
	v_mfma_f32_4x4x1_16b_f32 v[52:55], v77, v202, v[52:55]
	v_mfma_f32_4x4x1_16b_f32 v[56:59], v78, v202, v[56:59]
	v_mfma_f32_4x4x1_16b_f32 v[60:63], v79, v202, v[60:63]
	v_mfma_f32_4x4x1_16b_f32 v[0:3], v80, v203, v[0:3]
	v_mfma_f32_4x4x1_16b_f32 v[4:7], v81, v203, v[4:7]
	v_mfma_f32_4x4x1_16b_f32 v[8:11], v82, v203, v[8:11]
	v_mfma_f32_4x4x1_16b_f32 v[12:15], v83, v203, v[12:15]
	v_mfma_f32_4x4x1_16b_f32 v[16:19], v84, v203, v[16:19]
	v_mfma_f32_4x4x1_16b_f32 v[20:23], v85, v203, v[20:23]
	v_mfma_f32_4x4x1_16b_f32 v[24:27], v86, v203, v[24:27]
	v_mfma_f32_4x4x1_16b_f32 v[28:31], v87, v203, v[28:31]
	v_mfma_f32_4x4x1_16b_f32 v[32:35], v88, v203, v[32:35]
	v_mfma_f32_4x4x1_16b_f32 v[36:39], v89, v203, v[36:39]
	v_mfma_f32_4x4x1_16b_f32 v[40:43], v90, v203, v[40:43]
	v_mfma_f32_4x4x1_16b_f32 v[44:47], v91, v203, v[44:47]
	v_mfma_f32_4x4x1_16b_f32 v[48:51], v92, v203, v[48:51]
	v_mfma_f32_4x4x1_16b_f32 v[52:55], v93, v203, v[52:55]
	v_mfma_f32_4x4x1_16b_f32 v[56:59], v94, v203, v[56:59]
	v_mfma_f32_4x4x1_16b_f32 v[60:63], v95, v203, v[60:63]
	s_sub_u32 s83, s83, 1
	s_cmp_eq_u32 s83, 0
	s_cbranch_scc1 .Lmy_p1d1_ldone_s
	s_and_b32 s9, s83, 7
	s_cmp_eq_u32 s9, 0
	s_cbranch_scc1 .Lmy_p1d1_renorm_s
	s_branch .Lmy_p1d1_loop_s

; #define LD1(set, s) { const int e_ = min((int)(s), LC - 1) * (int)stp; const unsigned s4_ = ob4 + (unsigned)(e_ * 4), s2_ = ob2 + (unsigned)(e_ * 2); set.w = LDX(rW, s4_); set.a = LDX(rA, s4_); set.b = LDX(rB, s4_); \
;             set.kw = __builtin_amdgcn_raw_buffer_load_b64(rK, lo8, s2_, 0); set.v = __builtin_amdgcn_raw_buffer_load_b16(rV, lo2, s2_, 0); }
; #define LD1(set, s) { const int e_ = min((int)(s), LC - 1) * (int)stp; const unsigned s4_ = ob4 + (unsigned)(e_ * 4); set.w = LDX(rW, s4_); set.a = LDX(rA, s4_); set.b = LDX(rB, s4_); }
; template <bool MIX> __device__ __forceinline__ void scan_pass1(const Params& p, int d, float* ldsf) {
;     ...
;             for (int i = 0; i < 64; ++i) S[i] = (ln == i) ? 1.f : 0.f;
;     ...
;             In1 i0, i1; LD1(i0, 0);
.Lmy_p1d1_pitem:
	buffer_load_dwordx4 v[96:99], v204, s[64:67], s72 offen
	buffer_load_dwordx4 v[100:103], v204, s[64:67], s73 offen
	buffer_load_dwordx4 v[104:107], v204, s[64:67], s74 offen
	s_add_u32 s72, s72, 0xfffff000
	s_add_u32 s73, s73, 0xfffff000
	s_add_u32 s74, s74, 0xfffff000
	buffer_load_dwordx4 v[116:119], v204, s[64:67], s72 offen
	buffer_load_dwordx4 v[120:123], v204, s[64:67], s73 offen
	buffer_load_dwordx4 v[124:127], v204, s[64:67], s74 offen
	s_add_u32 s72, s72, 0xfffff000
	s_add_u32 s73, s73, 0xfffff000
	s_add_u32 s74, s74, 0xfffff000
	buffer_load_dwordx4 v[136:139], v204, s[64:67], s72 offen
	buffer_load_dwordx4 v[140:143], v204, s[64:67], s73 offen
	buffer_load_dwordx4 v[144:147], v204, s[64:67], s74 offen
	s_add_u32 s72, s72, 0xfffff000
	s_add_u32 s73, s73, 0xfffff000
	s_add_u32 s74, s74, 0xfffff000
	s_mov_b32 s80, 3
	v_cmp_eq_u32_e32 vcc, 0, v212
	s_nop 1
	v_cndmask_b32_e32 v0, 0, v213, vcc
	v_cmp_eq_u32_e32 vcc, 1, v212
	s_nop 1
	v_cndmask_b32_e32 v1, 0, v213, vcc
	v_cmp_eq_u32_e32 vcc, 2, v212
	s_nop 1
	v_cndmask_b32_e32 v2, 0, v213, vcc
	v_cmp_eq_u32_e32 vcc, 3, v212
	s_nop 1
	v_cndmask_b32_e32 v3, 0, v213, vcc
	v_cmp_eq_u32_e32 vcc, 4, v212
	s_nop 1
	v_cndmask_b32_e32 v4, 0, v213, vcc
	v_cmp_eq_u32_e32 vcc, 5, v212
	s_nop 1
	v_cndmask_b32_e32 v5, 0, v213, vcc
	v_cmp_eq_u32_e32 vcc, 6, v212
	s_nop 1
	v_cndmask_b32_e32 v6, 0, v213, vcc
	v_cmp_eq_u32_e32 vcc, 7, v212
	s_nop 1
	v_cndmask_b32_e32 v7, 0, v213, vcc
	v_cmp_eq_u32_e32 vcc, 8, v212
	s_nop 1
	v_cndmask_b32_e32 v8, 0, v213, vcc
	v_cmp_eq_u32_e32 vcc, 9, v212
	s_nop 1
	v_cndmask_b32_e32 v9, 0, v213, vcc
	v_cmp_eq_u32_e32 vcc, 10, v212
	s_nop 1
	v_cndmask_b32_e32 v10, 0, v213, vcc
	v_cmp_eq_u32_e32 vcc, 11, v212
	s_nop 1
	v_cndmask_b32_e32 v11, 0, v213, vcc
	v_cmp_eq_u32_e32 vcc, 12, v212
	s_nop 1
	v_cndmask_b32_e32 v12, 0, v213, vcc
	v_cmp_eq_u32_e32 vcc, 13, v212
	s_nop 1
	v_cndmask_b32_e32 v13, 0, v213, vcc
	v_cmp_eq_u32_e32 vcc, 14, v212
	s_nop 1
	v_cndmask_b32_e32 v14, 0, v213, vcc
	v_cmp_eq_u32_e32 vcc, 15, v212
	s_nop 1
	v_cndmask_b32_e32 v15, 0, v213, vcc
	v_cmp_eq_u32_e32 vcc, 16, v212
	s_nop 1
	v_cndmask_b32_e32 v16, 0, v213, vcc
	v_cmp_eq_u32_e32 vcc, 17, v212
	s_nop 1
	v_cndmask_b32_e32 v17, 0, v213, vcc
	v_cmp_eq_u32_e32 vcc, 18, v212
	s_nop 1
	v_cndmask_b32_e32 v18, 0, v213, vcc
	v_cmp_eq_u32_e32 vcc, 19, v212
	s_nop 1
	v_cndmask_b32_e32 v19, 0, v213, vcc
	v_cmp_eq_u32_e32 vcc, 20, v212
	s_nop 1
	v_cndmask_b32_e32 v20, 0, v213, vcc
	v_cmp_eq_u32_e32 vcc, 21, v212
	s_nop 1
	v_cndmask_b32_e32 v21, 0, v213, vcc
	v_cmp_eq_u32_e32 vcc, 22, v212
	s_nop 1
	v_cndmask_b32_e32 v22, 0, v213, vcc
	v_cmp_eq_u32_e32 vcc, 23, v212
	s_nop 1
	v_cndmask_b32_e32 v23, 0, v213, vcc
	v_cmp_eq_u32_e32 vcc, 24, v212
	s_nop 1
	v_cndmask_b32_e32 v24, 0, v213, vcc
	v_cmp_eq_u32_e32 vcc, 25, v212
	s_nop 1
	v_cndmask_b32_e32 v25, 0, v213, vcc
	v_cmp_eq_u32_e32 vcc, 26, v212
	s_nop 1
	v_cndmask_b32_e32 v26, 0, v213, vcc
	v_cmp_eq_u32_e32 vcc, 27, v212
	s_nop 1
	v_cndmask_b32_e32 v27, 0, v213, vcc
	v_cmp_eq_u32_e32 vcc, 28, v212
	s_nop 1
	v_cndmask_b32_e32 v28, 0, v213, vcc
	v_cmp_eq_u32_e32 vcc, 29, v212
	s_nop 1
	v_cndmask_b32_e32 v29, 0, v213, vcc
	v_cmp_eq_u32_e32 vcc, 30, v212
	s_nop 1
	v_cndmask_b32_e32 v30, 0, v213, vcc
	v_cmp_eq_u32_e32 vcc, 31, v212
	s_nop 1
	v_cndmask_b32_e32 v31, 0, v213, vcc
	v_cmp_eq_u32_e32 vcc, 32, v212
	s_nop 1
	v_cndmask_b32_e32 v32, 0, v213, vcc
	v_cmp_eq_u32_e32 vcc, 33, v212
	s_nop 1
	v_cndmask_b32_e32 v33, 0, v213, vcc
	v_cmp_eq_u32_e32 vcc, 34, v212
	s_nop 1
	v_cndmask_b32_e32 v34, 0, v213, vcc
	v_cmp_eq_u32_e32 vcc, 35, v212
	s_nop 1
	v_cndmask_b32_e32 v35, 0, v213, vcc
	v_cmp_eq_u32_e32 vcc, 36, v212
	s_nop 1
	v_cndmask_b32_e32 v36, 0, v213, vcc
	v_cmp_eq_u32_e32 vcc, 37, v212
	s_nop 1
	v_cndmask_b32_e32 v37, 0, v213, vcc
	v_cmp_eq_u32_e32 vcc, 38, v212
	s_nop 1
	v_cndmask_b32_e32 v38, 0, v213, vcc
	v_cmp_eq_u32_e32 vcc, 39, v212
	s_nop 1
	v_cndmask_b32_e32 v39, 0, v213, vcc
	v_cmp_eq_u32_e32 vcc, 40, v212
	s_nop 1
	v_cndmask_b32_e32 v40, 0, v213, vcc
	v_cmp_eq_u32_e32 vcc, 41, v212
	s_nop 1
	v_cndmask_b32_e32 v41, 0, v213, vcc
	v_cmp_eq_u32_e32 vcc, 42, v212
	s_nop 1
	v_cndmask_b32_e32 v42, 0, v213, vcc
	v_cmp_eq_u32_e32 vcc, 43, v212
	s_nop 1
	v_cndmask_b32_e32 v43, 0, v213, vcc
	v_cmp_eq_u32_e32 vcc, 44, v212
	s_nop 1
	v_cndmask_b32_e32 v44, 0, v213, vcc
	v_cmp_eq_u32_e32 vcc, 45, v212
	s_nop 1
	v_cndmask_b32_e32 v45, 0, v213, vcc
	v_cmp_eq_u32_e32 vcc, 46, v212
	s_nop 1
	v_cndmask_b32_e32 v46, 0, v213, vcc
	v_cmp_eq_u32_e32 vcc, 47, v212
	s_nop 1
	v_cndmask_b32_e32 v47, 0, v213, vcc
	v_cmp_eq_u32_e32 vcc, 48, v212
	s_nop 1
	v_cndmask_b32_e32 v48, 0, v213, vcc
	v_cmp_eq_u32_e32 vcc, 49, v212
	s_nop 1
	v_cndmask_b32_e32 v49, 0, v213, vcc
	v_cmp_eq_u32_e32 vcc, 50, v212
	s_nop 1
	v_cndmask_b32_e32 v50, 0, v213, vcc
	v_cmp_eq_u32_e32 vcc, 51, v212
	s_nop 1
	v_cndmask_b32_e32 v51, 0, v213, vcc
	v_cmp_eq_u32_e32 vcc, 52, v212
	s_nop 1
	v_cndmask_b32_e32 v52, 0, v213, vcc
	v_cmp_eq_u32_e32 vcc, 53, v212
	s_nop 1
	v_cndmask_b32_e32 v53, 0, v213, vcc
	v_cmp_eq_u32_e32 vcc, 54, v212
	s_nop 1
	v_cndmask_b32_e32 v54, 0, v213, vcc
	v_cmp_eq_u32_e32 vcc, 55, v212
	s_nop 1
	v_cndmask_b32_e32 v55, 0, v213, vcc
	v_cmp_eq_u32_e32 vcc, 56, v212
	s_nop 1
	v_cndmask_b32_e32 v56, 0, v213, vcc
	v_cmp_eq_u32_e32 vcc, 57, v212
	s_nop 1
	v_cndmask_b32_e32 v57, 0, v213, vcc
	v_cmp_eq_u32_e32 vcc, 58, v212
	s_nop 1
	v_cndmask_b32_e32 v58, 0, v213, vcc
	v_cmp_eq_u32_e32 vcc, 59, v212
	s_nop 1
	v_cndmask_b32_e32 v59, 0, v213, vcc
	v_cmp_eq_u32_e32 vcc, 60, v212
	s_nop 1
	v_cndmask_b32_e32 v60, 0, v213, vcc
	v_cmp_eq_u32_e32 vcc, 61, v212
	s_nop 1
	v_cndmask_b32_e32 v61, 0, v213, vcc
	v_cmp_eq_u32_e32 vcc, 62, v212
	s_nop 1
	v_cndmask_b32_e32 v62, 0, v213, vcc
	v_cmp_eq_u32_e32 vcc, 63, v212
	s_nop 1
	v_cndmask_b32_e32 v63, 0, v213, vcc
	s_waitcnt vmcnt(0)
	v_mov_b32_e32 v216, 1.0
	v_mov_b32_e32 v217, 1.0
	v_mov_b32_e32 v218, 1.0
	v_mov_b32_e32 v219, 1.0
	s_movk_i32 s83, 64
	s_branch .Lmy_p1d1_loop_p

;     static __device__ __forceinline__ void dot(const float (&S)[64], const f32x4& a, float (&s)[4]) {
;         if constexpr (K == 0) {
;             asm volatile("v_mul_f32_dpp %0, %4, %8 row_newbcast:%16" DPPM "v_mul_f32_dpp %1, %5, %9 row_newbcast:%16" DPPM "v_mul_f32_dpp %2, %6, %10 row_newbcast:%16" DPPM "v_mul_f32_dpp %3, %7, %11 row_newbcast:%16" DPPM
;                          "v_fmac_f32_dpp %0, %4, %12 row_newbcast:%17" DPPM "v_fmac_f32_dpp %1, %5, %13 row_newbcast:%17" DPPM "v_fmac_f32_dpp %2, %6, %14 row_newbcast:%17" DPPM "v_fmac_f32_dpp %3, %7, %15 row_newbcast:%17" DPPM
;                          : "=&v"(s[0]), "=&v"(s[1]), "=&v"(s[2]), "=&v"(s[3])
;                          : "v"(a[0]), "v"(a[1]), "v"(a[2]), "v"(a[3]), "v"(S[K]), "v"(S[K + 1]), "v"(S[K + 2]), "v"(S[K + 3]), "v"(S[K + 4]), "v"(S[K + 5]), "v"(S[K + 6]), "v"(S[K + 7]), "n"(N0), "n"(N1));
;         } else
;         asm volatile("v_fmac_f32_dpp %0, %4, %8 row_newbcast:%16" DPPM "v_fmac_f32_dpp %1, %5, %9 row_newbcast:%16" DPPM "v_fmac_f32_dpp %2, %6, %10 row_newbcast:%16" DPPM "v_fmac_f32_dpp %3, %7, %11 row_newbcast:%16" DPPM
;                      "v_fmac_f32_dpp %0, %4, %12 row_newbcast:%17" DPPM "v_fmac_f32_dpp %1, %5, %13 row_newbcast:%17" DPPM "v_fmac_f32_dpp %2, %6, %14 row_newbcast:%17" DPPM "v_fmac_f32_dpp %3, %7, %15 row_newbcast:%17" DPPM
;                      : "+v"(s[0]), "+v"(s[1]), "+v"(s[2]), "+v"(s[3])
;                      : "v"(a[0]), "v"(a[1]), "v"(a[2]), "v"(a[3]), "v"(S[K]), "v"(S[K + 1]), "v"(S[K + 2]), "v"(S[K + 3]), "v"(S[K + 4]), "v"(S[K + 5]), "v"(S[K + 6]), "v"(S[K + 7]), "n"(N0), "n"(N1));
;         if constexpr (K + 8 < 64) ScanK<K + 8>::dot(S, a, s);
;     static __device__ __forceinline__ void updP(float (&P)[64], const In1& in, float sa) {
;         float u0, u1, u2, u3;
;         asm volatile("v_mul_f32_dpp %0, %8, %4 row_newbcast:%17" DPPM "v_mul_f32_dpp %1, %9, %5 row_newbcast:%17" DPPM "v_mul_f32_dpp %2, %10, %6 row_newbcast:%17" DPPM "v_mul_f32_dpp %3, %11, %7 row_newbcast:%17" DPPM
;                      "v_fmac_f32_dpp %0, %12, %16 row_newbcast:%17" DPPM "v_fmac_f32_dpp %1, %13, %16 row_newbcast:%17" DPPM "v_fmac_f32_dpp %2, %14, %16 row_newbcast:%17" DPPM "v_fmac_f32_dpp %3, %15, %16 row_newbcast:%17" DPPM
;                      : "=&v"(u0), "=&v"(u1), "=&v"(u2), "=&v"(u3)
.Lmy_p1d1_loop_p:
	s_waitcnt vmcnt(6)
	buffer_load_dwordx4 v[156:159], v204, s[64:67], s72 offen
	buffer_load_dwordx4 v[160:163], v204, s[64:67], s73 offen
	buffer_load_dwordx4 v[164:167], v204, s[64:67], s74 offen
	s_cmp_lt_u32 s80, 255
	s_cselect_b32 s81, 0xfffff000, 0
	s_cselect_b32 s82, 0xfffff800, 0
	s_cselect_b32 s9, 1, 0
	s_add_u32 s80, s80, s9
	s_add_u32 s72, s72, s81
	s_add_u32 s73, s73, s81
	s_add_u32 s74, s74, s81
	v_pk_mul_f32 v[224:225], v[100:101], v[216:217]
	v_pk_mul_f32 v[226:227], v[102:103], v[218:219]
	v_pk_mul_f32 v[216:217], v[216:217], v[96:97]
	v_pk_mul_f32 v[218:219], v[218:219], v[98:99]
	v_pk_mul_f32 v[176:177], v[100:101], v[104:105]
	v_pk_mul_f32 v[178:179], v[102:103], v[106:107]
	v_rcp_f32_e32 v220, v216
	v_rcp_f32_e32 v221, v217
	v_rcp_f32_e32 v222, v218
	v_rcp_f32_e32 v223, v219
	s_nop 0
	v_pk_mul_f32 v[176:177], v[176:177], v[220:221]
	v_pk_mul_f32 v[178:179], v[178:179], v[222:223]
	ds_write_b128 v208, v[176:179]
	ds_read2_b32 v[64:65], v209 offset0:0 offset1:4
	ds_read2_b32 v[66:67], v209 offset0:8 offset1:12
	ds_read2_b32 v[68:69], v209 offset0:16 offset1:20
	ds_read2_b32 v[70:71], v209 offset0:24 offset1:28
	ds_read2_b32 v[72:73], v209 offset0:32 offset1:36
	ds_read2_b32 v[74:75], v209 offset0:40 offset1:44
	ds_read2_b32 v[76:77], v209 offset0:48 offset1:52
	ds_read2_b32 v[78:79], v209 offset0:56 offset1:60
	v_mul_f32_dpp v196, v224, v0 row_newbcast:0 row_mask:0xf bank_mask:0xf
	v_mul_f32_dpp v197, v225, v1 row_newbcast:0 row_mask:0xf bank_mask:0xf
	v_mul_f32_dpp v198, v226, v2 row_newbcast:0 row_mask:0xf bank_mask:0xf
	v_mul_f32_dpp v199, v227, v3 row_newbcast:0 row_mask:0xf bank_mask:0xf
	v_fmac_f32_dpp v196, v224, v4 row_newbcast:1 row_mask:0xf bank_mask:0xf
	v_fmac_f32_dpp v197, v225, v5 row_newbcast:1 row_mask:0xf bank_mask:0xf
	v_fmac_f32_dpp v198, v226, v6 row_newbcast:1 row_mask:0xf bank_mask:0xf
	v_fmac_f32_dpp v199, v227, v7 row_newbcast:1 row_mask:0xf bank_mask:0xf
	v_fmac_f32_dpp v196, v224, v8 row_newbcast:2 row_mask:0xf bank_mask:0xf
	v_fmac_f32_dpp v197, v225, v9 row_newbcast:2 row_mask:0xf bank_mask:0xf
	v_fmac_f32_dpp v198, v226, v10 row_newbcast:2 row_mask:0xf bank_mask:0xf
	v_fmac_f32_dpp v199, v227, v11 row_newbcast:2 row_mask:0xf bank_mask:0xf
	v_fmac_f32_dpp v196, v224, v12 row_newbcast:3 row_mask:0xf bank_mask:0xf
	v_fmac_f32_dpp v197, v225, v13 row_newbcast:3 row_mask:0xf bank_mask:0xf
	v_fmac_f32_dpp v198, v226, v14 row_newbcast:3 row_mask:0xf bank_mask:0xf
	v_fmac_f32_dpp v199, v227, v15 row_newbcast:3 row_mask:0xf bank_mask:0xf
	v_fmac_f32_dpp v196, v224, v16 row_newbcast:4 row_mask:0xf bank_mask:0xf
	v_fmac_f32_dpp v197, v225, v17 row_newbcast:4 row_mask:0xf bank_mask:0xf
	v_fmac_f32_dpp v198, v226, v18 row_newbcast:4 row_mask:0xf bank_mask:0xf
	v_fmac_f32_dpp v199, v227, v19 row_newbcast:4 row_mask:0xf bank_mask:0xf
	v_fmac_f32_dpp v196, v224, v20 row_newbcast:5 row_mask:0xf bank_mask:0xf
	v_fmac_f32_dpp v197, v225, v21 row_newbcast:5 row_mask:0xf bank_mask:0xf
	v_fmac_f32_dpp v198, v226, v22 row_newbcast:5 row_mask:0xf bank_mask:0xf
	v_fmac_f32_dpp v199, v227, v23 row_newbcast:5 row_mask:0xf bank_mask:0xf
	v_fmac_f32_dpp v196, v224, v24 row_newbcast:6 row_mask:0xf bank_mask:0xf
	v_fmac_f32_dpp v197, v225, v25 row_newbcast:6 row_mask:0xf bank_mask:0xf
	v_fmac_f32_dpp v198, v226, v26 row_newbcast:6 row_mask:0xf bank_mask:0xf
	v_fmac_f32_dpp v199, v227, v27 row_newbcast:6 row_mask:0xf bank_mask:0xf
	v_fmac_f32_dpp v196, v224, v28 row_newbcast:7 row_mask:0xf bank_mask:0xf
	v_fmac_f32_dpp v197, v225, v29 row_newbcast:7 row_mask:0xf bank_mask:0xf
	v_fmac_f32_dpp v198, v226, v30 row_newbcast:7 row_mask:0xf bank_mask:0xf
	v_fmac_f32_dpp v199, v227, v31 row_newbcast:7 row_mask:0xf bank_mask:0xf
	v_fmac_f32_dpp v196, v224, v32 row_newbcast:8 row_mask:0xf bank_mask:0xf
	v_fmac_f32_dpp v197, v225, v33 row_newbcast:8 row_mask:0xf bank_mask:0xf
	v_fmac_f32_dpp v198, v226, v34 row_newbcast:8 row_mask:0xf bank_mask:0xf
	v_fmac_f32_dpp v199, v227, v35 row_newbcast:8 row_mask:0xf bank_mask:0xf
	v_fmac_f32_dpp v196, v224, v36 row_newbcast:9 row_mask:0xf bank_mask:0xf
	v_fmac_f32_dpp v197, v225, v37 row_newbcast:9 row_mask:0xf bank_mask:0xf
	v_fmac_f32_dpp v198, v226, v38 row_newbcast:9 row_mask:0xf bank_mask:0xf
	v_fmac_f32_dpp v199, v227, v39 row_newbcast:9 row_mask:0xf bank_mask:0xf
	v_fmac_f32_dpp v196, v224, v40 row_newbcast:10 row_mask:0xf bank_mask:0xf
	v_fmac_f32_dpp v197, v225, v41 row_newbcast:10 row_mask:0xf bank_mask:0xf
	v_fmac_f32_dpp v198, v226, v42 row_newbcast:10 row_mask:0xf bank_mask:0xf
	v_fmac_f32_dpp v199, v227, v43 row_newbcast:10 row_mask:0xf bank_mask:0xf
	v_fmac_f32_dpp v196, v224, v44 row_newbcast:11 row_mask:0xf bank_mask:0xf
	v_fmac_f32_dpp v197, v225, v45 row_newbcast:11 row_mask:0xf bank_mask:0xf
	v_fmac_f32_dpp v198, v226, v46 row_newbcast:11 row_mask:0xf bank_mask:0xf
	v_fmac_f32_dpp v199, v227, v47 row_newbcast:11 row_mask:0xf bank_mask:0xf
	v_fmac_f32_dpp v196, v224, v48 row_newbcast:12 row_mask:0xf bank_mask:0xf
	v_fmac_f32_dpp v197, v225, v49 row_newbcast:12 row_mask:0xf bank_mask:0xf
	v_fmac_f32_dpp v198, v226, v50 row_newbcast:12 row_mask:0xf bank_mask:0xf
	v_fmac_f32_dpp v199, v227, v51 row_newbcast:12 row_mask:0xf bank_mask:0xf
	v_fmac_f32_dpp v196, v224, v52 row_newbcast:13 row_mask:0xf bank_mask:0xf
	v_fmac_f32_dpp v197, v225, v53 row_newbcast:13 row_mask:0xf bank_mask:0xf
	v_fmac_f32_dpp v198, v226, v54 row_newbcast:13 row_mask:0xf bank_mask:0xf
	v_fmac_f32_dpp v199, v227, v55 row_newbcast:13 row_mask:0xf bank_mask:0xf
	v_fmac_f32_dpp v196, v224, v56 row_newbcast:14 row_mask:0xf bank_mask:0xf
	v_fmac_f32_dpp v197, v225, v57 row_newbcast:14 row_mask:0xf bank_mask:0xf
	v_fmac_f32_dpp v198, v226, v58 row_newbcast:14 row_mask:0xf bank_mask:0xf
	v_fmac_f32_dpp v199, v227, v59 row_newbcast:14 row_mask:0xf bank_mask:0xf
	v_fmac_f32_dpp v196, v224, v60 row_newbcast:15 row_mask:0xf bank_mask:0xf
	v_fmac_f32_dpp v197, v225, v61 row_newbcast:15 row_mask:0xf bank_mask:0xf
	v_fmac_f32_dpp v198, v226, v62 row_newbcast:15 row_mask:0xf bank_mask:0xf
	v_fmac_f32_dpp v199, v227, v63 row_newbcast:15 row_mask:0xf bank_mask:0xf
	v_add_f32_e32 v196, v196, v197
	v_add_f32_e32 v198, v198, v199
	v_add_f32_e32 v196, v196, v198
	v_xor_b32_e32 v202, 0x80000000, v196
	s_waitcnt lgkmcnt(0)
; #define SB __builtin_amdgcn_sched_barrier(0)
; #define LD1(set, s) { const int e_ = min((int)(s), LC - 1) * (int)stp; const unsigned s4_ = ob4 + (unsigned)(e_ * 4), s2_ = ob2 + (unsigned)(e_ * 2); set.w = LDX(rW, s4_); set.a = LDX(rA, s4_); set.b = LDX(rB, s4_); \
;             set.kw = __builtin_amdgcn_raw_buffer_load_b64(rK, lo8, s2_, 0); set.v = __builtin_amdgcn_raw_buffer_load_b16(rV, lo2, s2_, 0); }
; #define TOUCH1(set) asm volatile("" :: "v"(set.w), "v"(set.a), "v"(set.b), "v"(set.kw), "v"(set.v))
; #define ST1(set) { DERIVE_BK(set); float sd[4]; ScanK<0>::dot(S, set.a, sd); ScanK<0>::updS(S, set, -((sd[0] + sd[1]) + (sd[2] + sd[3])), __uint_as_float(set.v << 16)); }
; #define LD1(set, s) { const int e_ = min((int)(s), LC - 1) * (int)stp; const unsigned s4_ = ob4 + (unsigned)(e_ * 4); set.w = LDX(rW, s4_); set.a = LDX(rA, s4_); set.b = LDX(rB, s4_); }
; #define TOUCH1(set) asm volatile("" :: "v"(set.w), "v"(set.a), "v"(set.b))
; #define ST1(set) { DERIVE_B(set); float sd[4]; ScanK<0>::dot(S, set.a, sd); ScanK<0>::updP(S, set, -((sd[0] + sd[1]) + (sd[2] + sd[3]))); }
;     static __device__ __forceinline__ void updP(float (&P)[64], const In1& in, float sa) {
;         float u0, u1, u2, u3;
;         asm volatile("v_mul_f32_dpp %0, %8, %4 row_newbcast:%17" DPPM "v_mul_f32_dpp %1, %9, %5 row_newbcast:%17" DPPM "v_mul_f32_dpp %2, %10, %6 row_newbcast:%17" DPPM "v_mul_f32_dpp %3, %11, %7 row_newbcast:%17" DPPM
;                      "v_fmac_f32_dpp %0, %12, %16 row_newbcast:%17" DPPM "v_fmac_f32_dpp %1, %13, %16 row_newbcast:%17" DPPM "v_fmac_f32_dpp %2, %14, %16 row_newbcast:%17" DPPM "v_fmac_f32_dpp %3, %15, %16 row_newbcast:%17" DPPM
;                      : "=&v"(u0), "=&v"(u1), "=&v"(u2), "=&v"(u3)
;                      : "v"(P[K]), "v"(P[K + 1]), "v"(P[K + 2]), "v"(P[K + 3]), "v"(in.w[0]), "v"(in.w[1]), "v"(in.w[2]), "v"(in.w[3]), "v"(in.b[0]), "v"(in.b[1]), "v"(in.b[2]), "v"(in.b[3]), "v"(sa), "n"(N0));
;         P[K] = u0; P[K + 1] = u1; P[K + 2] = u2; P[K + 3] = u3;
;         if constexpr (K + 4 < 64) ScanK<K + 4>::updP(P, in, sa);
;     }
; template <bool MIX> __device__ __forceinline__ void scan_pass1(const Params& p, int d, float* ldsf) {
;     ...
;             In1 i0, i1; LD1(i0, 0);
; #pragma unroll 1
;             for (int s = 0; s < LC; s += 2) { TOUCH1(i0); SB; LD1(i1, s + 1); SB; ST1(i0); TOUCH1(i1); SB; LD1(i0, s + 2); SB; ST1(i1); }
	s_nop 1
	v_mfma_f32_4x4x1_16b_f32 v[0:3], v64, v202, v[0:3]
	v_mfma_f32_4x4x1_16b_f32 v[4:7], v65, v202, v[4:7]
	v_mfma_f32_4x4x1_16b_f32 v[8:11], v66, v202, v[8:11]
	v_mfma_f32_4x4x1_16b_f32 v[12:15], v67, v202, v[12:15]
	v_mfma_f32_4x4x1_16b_f32 v[16:19], v68, v202, v[16:19]
	v_mfma_f32_4x4x1_16b_f32 v[20:23], v69, v202, v[20:23]
	v_mfma_f32_4x4x1_16b_f32 v[24:27], v70, v202, v[24:27]
	v_mfma_f32_4x4x1_16b_f32 v[28:31], v71, v202, v[28:31]
	v_mfma_f32_4x4x1_16b_f32 v[32:35], v72, v202, v[32:35]
	v_mfma_f32_4x4x1_16b_f32 v[36:39], v73, v202, v[36:39]
	v_mfma_f32_4x4x1_16b_f32 v[40:43], v74, v202, v[40:43]
	v_mfma_f32_4x4x1_16b_f32 v[44:47], v75, v202, v[44:47]
	v_mfma_f32_4x4x1_16b_f32 v[48:51], v76, v202, v[48:51]
	v_mfma_f32_4x4x1_16b_f32 v[52:55], v77, v202, v[52:55]
	v_mfma_f32_4x4x1_16b_f32 v[56:59], v78, v202, v[56:59]
	v_mfma_f32_4x4x1_16b_f32 v[60:63], v79, v202, v[60:63]
	s_waitcnt vmcnt(6)
	buffer_load_dwordx4 v[96:99], v204, s[64:67], s72 offen
	buffer_load_dwordx4 v[100:103], v204, s[64:67], s73 offen
	buffer_load_dwordx4 v[104:107], v204, s[64:67], s74 offen
	s_cmp_lt_u32 s80, 255
	s_cselect_b32 s81, 0xfffff000, 0
	s_cselect_b32 s82, 0xfffff800, 0
	s_cselect_b32 s9, 1, 0
	s_add_u32 s80, s80, s9
	s_add_u32 s72, s72, s81
	s_add_u32 s73, s73, s81
	s_add_u32 s74, s74, s81
	v_pk_mul_f32 v[224:225], v[120:121], v[216:217]
	v_pk_mul_f32 v[226:227], v[122:123], v[218:219]
	v_pk_mul_f32 v[216:217], v[216:217], v[116:117]
	v_pk_mul_f32 v[218:219], v[218:219], v[118:119]
	v_pk_mul_f32 v[176:177], v[120:121], v[124:125]
	v_pk_mul_f32 v[178:179], v[122:123], v[126:127]
	v_rcp_f32_e32 v220, v216
	v_rcp_f32_e32 v221, v217
	v_rcp_f32_e32 v222, v218
	v_rcp_f32_e32 v223, v219
	s_nop 0
	v_pk_mul_f32 v[176:177], v[176:177], v[220:221]
	v_pk_mul_f32 v[178:179], v[178:179], v[222:223]
	ds_write_b128 v208, v[176:179]
	ds_read2_b32 v[64:65], v209 offset0:0 offset1:4
	ds_read2_b32 v[66:67], v209 offset0:8 offset1:12
	ds_read2_b32 v[68:69], v209 offset0:16 offset1:20
	ds_read2_b32 v[70:71], v209 offset0:24 offset1:28
	ds_read2_b32 v[72:73], v209 offset0:32 offset1:36
	ds_read2_b32 v[74:75], v209 offset0:40 offset1:44
	ds_read2_b32 v[76:77], v209 offset0:48 offset1:52
	ds_read2_b32 v[78:79], v209 offset0:56 offset1:60
	v_mul_f32_dpp v196, v224, v0 row_newbcast:0 row_mask:0xf bank_mask:0xf
	v_mul_f32_dpp v197, v225, v1 row_newbcast:0 row_mask:0xf bank_mask:0xf
	v_mul_f32_dpp v198, v226, v2 row_newbcast:0 row_mask:0xf bank_mask:0xf
	v_mul_f32_dpp v199, v227, v3 row_newbcast:0 row_mask:0xf bank_mask:0xf
	v_fmac_f32_dpp v196, v224, v4 row_newbcast:1 row_mask:0xf bank_mask:0xf
	v_fmac_f32_dpp v197, v225, v5 row_newbcast:1 row_mask:0xf bank_mask:0xf
	v_fmac_f32_dpp v198, v226, v6 row_newbcast:1 row_mask:0xf bank_mask:0xf
	v_fmac_f32_dpp v199, v227, v7 row_newbcast:1 row_mask:0xf bank_mask:0xf
	v_fmac_f32_dpp v196, v224, v8 row_newbcast:2 row_mask:0xf bank_mask:0xf
	v_fmac_f32_dpp v197, v225, v9 row_newbcast:2 row_mask:0xf bank_mask:0xf
	v_fmac_f32_dpp v198, v226, v10 row_newbcast:2 row_mask:0xf bank_mask:0xf
	v_fmac_f32_dpp v199, v227, v11 row_newbcast:2 row_mask:0xf bank_mask:0xf
	v_fmac_f32_dpp v196, v224, v12 row_newbcast:3 row_mask:0xf bank_mask:0xf
	v_fmac_f32_dpp v197, v225, v13 row_newbcast:3 row_mask:0xf bank_mask:0xf
	v_fmac_f32_dpp v198, v226, v14 row_newbcast:3 row_mask:0xf bank_mask:0xf
	v_fmac_f32_dpp v199, v227, v15 row_newbcast:3 row_mask:0xf bank_mask:0xf
	v_fmac_f32_dpp v196, v224, v16 row_newbcast:4 row_mask:0xf bank_mask:0xf
	v_fmac_f32_dpp v197, v225, v17 row_newbcast:4 row_mask:0xf bank_mask:0xf
	v_fmac_f32_dpp v198, v226, v18 row_newbcast:4 row_mask:0xf bank_mask:0xf
	v_fmac_f32_dpp v199, v227, v19 row_newbcast:4 row_mask:0xf bank_mask:0xf
	v_fmac_f32_dpp v196, v224, v20 row_newbcast:5 row_mask:0xf bank_mask:0xf
	v_fmac_f32_dpp v197, v225, v21 row_newbcast:5 row_mask:0xf bank_mask:0xf
	v_fmac_f32_dpp v198, v226, v22 row_newbcast:5 row_mask:0xf bank_mask:0xf
	v_fmac_f32_dpp v199, v227, v23 row_newbcast:5 row_mask:0xf bank_mask:0xf
	v_fmac_f32_dpp v196, v224, v24 row_newbcast:6 row_mask:0xf bank_mask:0xf
	v_fmac_f32_dpp v197, v225, v25 row_newbcast:6 row_mask:0xf bank_mask:0xf
	v_fmac_f32_dpp v198, v226, v26 row_newbcast:6 row_mask:0xf bank_mask:0xf
	v_fmac_f32_dpp v199, v227, v27 row_newbcast:6 row_mask:0xf bank_mask:0xf
	v_fmac_f32_dpp v196, v224, v28 row_newbcast:7 row_mask:0xf bank_mask:0xf
	v_fmac_f32_dpp v197, v225, v29 row_newbcast:7 row_mask:0xf bank_mask:0xf
	v_fmac_f32_dpp v198, v226, v30 row_newbcast:7 row_mask:0xf bank_mask:0xf
	v_fmac_f32_dpp v199, v227, v31 row_newbcast:7 row_mask:0xf bank_mask:0xf
	v_fmac_f32_dpp v196, v224, v32 row_newbcast:8 row_mask:0xf bank_mask:0xf
	v_fmac_f32_dpp v197, v225, v33 row_newbcast:8 row_mask:0xf bank_mask:0xf
	v_fmac_f32_dpp v198, v226, v34 row_newbcast:8 row_mask:0xf bank_mask:0xf
	v_fmac_f32_dpp v199, v227, v35 row_newbcast:8 row_mask:0xf bank_mask:0xf
	v_fmac_f32_dpp v196, v224, v36 row_newbcast:9 row_mask:0xf bank_mask:0xf
	v_fmac_f32_dpp v197, v225, v37 row_newbcast:9 row_mask:0xf bank_mask:0xf
	v_fmac_f32_dpp v198, v226, v38 row_newbcast:9 row_mask:0xf bank_mask:0xf
	v_fmac_f32_dpp v199, v227, v39 row_newbcast:9 row_mask:0xf bank_mask:0xf
	v_fmac_f32_dpp v196, v224, v40 row_newbcast:10 row_mask:0xf bank_mask:0xf
	v_fmac_f32_dpp v197, v225, v41 row_newbcast:10 row_mask:0xf bank_mask:0xf
	v_fmac_f32_dpp v198, v226, v42 row_newbcast:10 row_mask:0xf bank_mask:0xf
	v_fmac_f32_dpp v199, v227, v43 row_newbcast:10 row_mask:0xf bank_mask:0xf
	v_fmac_f32_dpp v196, v224, v44 row_newbcast:11 row_mask:0xf bank_mask:0xf
	v_fmac_f32_dpp v197, v225, v45 row_newbcast:11 row_mask:0xf bank_mask:0xf
;     static __device__ __forceinline__ void dot(const float (&S)[64], const f32x4& a, float (&s)[4]) {
;         if constexpr (K == 0) {
;             asm volatile("v_mul_f32_dpp %0, %4, %8 row_newbcast:%16" DPPM "v_mul_f32_dpp %1, %5, %9 row_newbcast:%16" DPPM "v_mul_f32_dpp %2, %6, %10 row_newbcast:%16" DPPM "v_mul_f32_dpp %3, %7, %11 row_newbcast:%16" DPPM
;                          "v_fmac_f32_dpp %0, %4, %12 row_newbcast:%17" DPPM "v_fmac_f32_dpp %1, %5, %13 row_newbcast:%17" DPPM "v_fmac_f32_dpp %2, %6, %14 row_newbcast:%17" DPPM "v_fmac_f32_dpp %3, %7, %15 row_newbcast:%17" DPPM
;                          : "=&v"(s[0]), "=&v"(s[1]), "=&v"(s[2]), "=&v"(s[3])
;                          : "v"(a[0]), "v"(a[1]), "v"(a[2]), "v"(a[3]), "v"(S[K]), "v"(S[K + 1]), "v"(S[K + 2]), "v"(S[K + 3]), "v"(S[K + 4]), "v"(S[K + 5]), "v"(S[K + 6]), "v"(S[K + 7]), "n"(N0), "n"(N1));
;         } else
;         asm volatile("v_fmac_f32_dpp %0, %4, %8 row_newbcast:%16" DPPM "v_fmac_f32_dpp %1, %5, %9 row_newbcast:%16" DPPM "v_fmac_f32_dpp %2, %6, %10 row_newbcast:%16" DPPM "v_fmac_f32_dpp %3, %7, %11 row_newbcast:%16" DPPM
;                      "v_fmac_f32_dpp %0, %4, %12 row_newbcast:%17" DPPM "v_fmac_f32_dpp %1, %5, %13 row_newbcast:%17" DPPM "v_fmac_f32_dpp %2, %6, %14 row_newbcast:%17" DPPM "v_fmac_f32_dpp %3, %7, %15 row_newbcast:%17" DPPM
;                      : "+v"(s[0]), "+v"(s[1]), "+v"(s[2]), "+v"(s[3])
;                      : "v"(a[0]), "v"(a[1]), "v"(a[2]), "v"(a[3]), "v"(S[K]), "v"(S[K + 1]), "v"(S[K + 2]), "v"(S[K + 3]), "v"(S[K + 4]), "v"(S[K + 5]), "v"(S[K + 6]), "v"(S[K + 7]), "n"(N0), "n"(N1));
;         if constexpr (K + 8 < 64) ScanK<K + 8>::dot(S, a, s);
;     }
;     static __device__ __forceinline__ void updP(float (&P)[64], const In1& in, float sa) {
;         float u0, u1, u2, u3;
;         asm volatile("v_mul_f32_dpp %0, %8, %4 row_newbcast:%17" DPPM "v_mul_f32_dpp %1, %9, %5 row_newbcast:%17" DPPM "v_mul_f32_dpp %2, %10, %6 row_newbcast:%17" DPPM "v_mul_f32_dpp %3, %11, %7 row_newbcast:%17" DPPM
;                      "v_fmac_f32_dpp %0, %12, %16 row_newbcast:%17" DPPM "v_fmac_f32_dpp %1, %13, %16 row_newbcast:%17" DPPM "v_fmac_f32_dpp %2, %14, %16 row_newbcast:%17" DPPM "v_fmac_f32_dpp %3, %15, %16 row_newbcast:%17" DPPM
;                      : "=&v"(u0), "=&v"(u1), "=&v"(u2), "=&v"(u3)
	v_fmac_f32_dpp v198, v226, v46 row_newbcast:11 row_mask:0xf bank_mask:0xf
	v_fmac_f32_dpp v199, v227, v47 row_newbcast:11 row_mask:0xf bank_mask:0xf
	v_fmac_f32_dpp v196, v224, v48 row_newbcast:12 row_mask:0xf bank_mask:0xf
	v_fmac_f32_dpp v197, v225, v49 row_newbcast:12 row_mask:0xf bank_mask:0xf
	v_fmac_f32_dpp v198, v226, v50 row_newbcast:12 row_mask:0xf bank_mask:0xf
	v_fmac_f32_dpp v199, v227, v51 row_newbcast:12 row_mask:0xf bank_mask:0xf
	v_fmac_f32_dpp v196, v224, v52 row_newbcast:13 row_mask:0xf bank_mask:0xf
	v_fmac_f32_dpp v197, v225, v53 row_newbcast:13 row_mask:0xf bank_mask:0xf
	v_fmac_f32_dpp v198, v226, v54 row_newbcast:13 row_mask:0xf bank_mask:0xf
	v_fmac_f32_dpp v199, v227, v55 row_newbcast:13 row_mask:0xf bank_mask:0xf
	v_fmac_f32_dpp v196, v224, v56 row_newbcast:14 row_mask:0xf bank_mask:0xf
	v_fmac_f32_dpp v197, v225, v57 row_newbcast:14 row_mask:0xf bank_mask:0xf
	v_fmac_f32_dpp v198, v226, v58 row_newbcast:14 row_mask:0xf bank_mask:0xf
	v_fmac_f32_dpp v199, v227, v59 row_newbcast:14 row_mask:0xf bank_mask:0xf
	v_fmac_f32_dpp v196, v224, v60 row_newbcast:15 row_mask:0xf bank_mask:0xf
	v_fmac_f32_dpp v197, v225, v61 row_newbcast:15 row_mask:0xf bank_mask:0xf
	v_fmac_f32_dpp v198, v226, v62 row_newbcast:15 row_mask:0xf bank_mask:0xf
	v_fmac_f32_dpp v199, v227, v63 row_newbcast:15 row_mask:0xf bank_mask:0xf
	v_add_f32_e32 v196, v196, v197
	v_add_f32_e32 v198, v198, v199
	v_add_f32_e32 v196, v196, v198
	v_xor_b32_e32 v202, 0x80000000, v196
	s_waitcnt lgkmcnt(0)
	s_nop 1
	v_mfma_f32_4x4x1_16b_f32 v[0:3], v64, v202, v[0:3]
	v_mfma_f32_4x4x1_16b_f32 v[4:7], v65, v202, v[4:7]
	v_mfma_f32_4x4x1_16b_f32 v[8:11], v66, v202, v[8:11]
	v_mfma_f32_4x4x1_16b_f32 v[12:15], v67, v202, v[12:15]
	v_mfma_f32_4x4x1_16b_f32 v[16:19], v68, v202, v[16:19]
	v_mfma_f32_4x4x1_16b_f32 v[20:23], v69, v202, v[20:23]
	v_mfma_f32_4x4x1_16b_f32 v[24:27], v70, v202, v[24:27]
	v_mfma_f32_4x4x1_16b_f32 v[28:31], v71, v202, v[28:31]
	v_mfma_f32_4x4x1_16b_f32 v[32:35], v72, v202, v[32:35]
	v_mfma_f32_4x4x1_16b_f32 v[36:39], v73, v202, v[36:39]
	v_mfma_f32_4x4x1_16b_f32 v[40:43], v74, v202, v[40:43]
	v_mfma_f32_4x4x1_16b_f32 v[44:47], v75, v202, v[44:47]
	v_mfma_f32_4x4x1_16b_f32 v[48:51], v76, v202, v[48:51]
	v_mfma_f32_4x4x1_16b_f32 v[52:55], v77, v202, v[52:55]
	v_mfma_f32_4x4x1_16b_f32 v[56:59], v78, v202, v[56:59]
	v_mfma_f32_4x4x1_16b_f32 v[60:63], v79, v202, v[60:63]
	s_waitcnt vmcnt(6)
	buffer_load_dwordx4 v[116:119], v204, s[64:67], s72 offen
	buffer_load_dwordx4 v[120:123], v204, s[64:67], s73 offen
	buffer_load_dwordx4 v[124:127], v204, s[64:67], s74 offen
	s_cmp_lt_u32 s80, 255
	s_cselect_b32 s81, 0xfffff000, 0
	s_cselect_b32 s82, 0xfffff800, 0
	s_cselect_b32 s9, 1, 0
	s_add_u32 s80, s80, s9
	s_add_u32 s72, s72, s81
	s_add_u32 s73, s73, s81
	s_add_u32 s74, s74, s81
	v_pk_mul_f32 v[224:225], v[140:141], v[216:217]
	v_pk_mul_f32 v[226:227], v[142:143], v[218:219]
	v_pk_mul_f32 v[216:217], v[216:217], v[136:137]
	v_pk_mul_f32 v[218:219], v[218:219], v[138:139]
	v_pk_mul_f32 v[176:177], v[140:141], v[144:145]
	v_pk_mul_f32 v[178:179], v[142:143], v[146:147]
	v_rcp_f32_e32 v220, v216
	v_rcp_f32_e32 v221, v217
	v_rcp_f32_e32 v222, v218
	v_rcp_f32_e32 v223, v219
	s_nop 0
	v_pk_mul_f32 v[176:177], v[176:177], v[220:221]
	v_pk_mul_f32 v[178:179], v[178:179], v[222:223]
	ds_write_b128 v208, v[176:179]
	ds_read2_b32 v[64:65], v209 offset0:0 offset1:4
	ds_read2_b32 v[66:67], v209 offset0:8 offset1:12
	ds_read2_b32 v[68:69], v209 offset0:16 offset1:20
	ds_read2_b32 v[70:71], v209 offset0:24 offset1:28
	ds_read2_b32 v[72:73], v209 offset0:32 offset1:36
	ds_read2_b32 v[74:75], v209 offset0:40 offset1:44
	ds_read2_b32 v[76:77], v209 offset0:48 offset1:52
	ds_read2_b32 v[78:79], v209 offset0:56 offset1:60
	v_mul_f32_dpp v196, v224, v0 row_newbcast:0 row_mask:0xf bank_mask:0xf
	v_mul_f32_dpp v197, v225, v1 row_newbcast:0 row_mask:0xf bank_mask:0xf
	v_mul_f32_dpp v198, v226, v2 row_newbcast:0 row_mask:0xf bank_mask:0xf
	v_mul_f32_dpp v199, v227, v3 row_newbcast:0 row_mask:0xf bank_mask:0xf
	v_fmac_f32_dpp v196, v224, v4 row_newbcast:1 row_mask:0xf bank_mask:0xf
	v_fmac_f32_dpp v197, v225, v5 row_newbcast:1 row_mask:0xf bank_mask:0xf
	v_fmac_f32_dpp v198, v226, v6 row_newbcast:1 row_mask:0xf bank_mask:0xf
	v_fmac_f32_dpp v199, v227, v7 row_newbcast:1 row_mask:0xf bank_mask:0xf
	v_fmac_f32_dpp v196, v224, v8 row_newbcast:2 row_mask:0xf bank_mask:0xf
	v_fmac_f32_dpp v197, v225, v9 row_newbcast:2 row_mask:0xf bank_mask:0xf
	v_fmac_f32_dpp v198, v226, v10 row_newbcast:2 row_mask:0xf bank_mask:0xf
	v_fmac_f32_dpp v199, v227, v11 row_newbcast:2 row_mask:0xf bank_mask:0xf
	v_fmac_f32_dpp v196, v224, v12 row_newbcast:3 row_mask:0xf bank_mask:0xf
	v_fmac_f32_dpp v197, v225, v13 row_newbcast:3 row_mask:0xf bank_mask:0xf
	v_fmac_f32_dpp v198, v226, v14 row_newbcast:3 row_mask:0xf bank_mask:0xf
	v_fmac_f32_dpp v199, v227, v15 row_newbcast:3 row_mask:0xf bank_mask:0xf
	v_fmac_f32_dpp v196, v224, v16 row_newbcast:4 row_mask:0xf bank_mask:0xf
	v_fmac_f32_dpp v197, v225, v17 row_newbcast:4 row_mask:0xf bank_mask:0xf
	v_fmac_f32_dpp v198, v226, v18 row_newbcast:4 row_mask:0xf bank_mask:0xf
	v_fmac_f32_dpp v199, v227, v19 row_newbcast:4 row_mask:0xf bank_mask:0xf
	v_fmac_f32_dpp v196, v224, v20 row_newbcast:5 row_mask:0xf bank_mask:0xf
	v_fmac_f32_dpp v197, v225, v21 row_newbcast:5 row_mask:0xf bank_mask:0xf
	v_fmac_f32_dpp v198, v226, v22 row_newbcast:5 row_mask:0xf bank_mask:0xf
	v_fmac_f32_dpp v199, v227, v23 row_newbcast:5 row_mask:0xf bank_mask:0xf
	v_fmac_f32_dpp v196, v224, v24 row_newbcast:6 row_mask:0xf bank_mask:0xf
	v_fmac_f32_dpp v197, v225, v25 row_newbcast:6 row_mask:0xf bank_mask:0xf
;     static __device__ __forceinline__ void dot(const float (&S)[64], const f32x4& a, float (&s)[4]) {
;         if constexpr (K == 0) {
;             asm volatile("v_mul_f32_dpp %0, %4, %8 row_newbcast:%16" DPPM "v_mul_f32_dpp %1, %5, %9 row_newbcast:%16" DPPM "v_mul_f32_dpp %2, %6, %10 row_newbcast:%16" DPPM "v_mul_f32_dpp %3, %7, %11 row_newbcast:%16" DPPM
;                          "v_fmac_f32_dpp %0, %4, %12 row_newbcast:%17" DPPM "v_fmac_f32_dpp %1, %5, %13 row_newbcast:%17" DPPM "v_fmac_f32_dpp %2, %6, %14 row_newbcast:%17" DPPM "v_fmac_f32_dpp %3, %7, %15 row_newbcast:%17" DPPM
;                          : "=&v"(s[0]), "=&v"(s[1]), "=&v"(s[2]), "=&v"(s[3])
;                          : "v"(a[0]), "v"(a[1]), "v"(a[2]), "v"(a[3]), "v"(S[K]), "v"(S[K + 1]), "v"(S[K + 2]), "v"(S[K + 3]), "v"(S[K + 4]), "v"(S[K + 5]), "v"(S[K + 6]), "v"(S[K + 7]), "n"(N0), "n"(N1));
;         } else
;         asm volatile("v_fmac_f32_dpp %0, %4, %8 row_newbcast:%16" DPPM "v_fmac_f32_dpp %1, %5, %9 row_newbcast:%16" DPPM "v_fmac_f32_dpp %2, %6, %10 row_newbcast:%16" DPPM "v_fmac_f32_dpp %3, %7, %11 row_newbcast:%16" DPPM
;                      "v_fmac_f32_dpp %0, %4, %12 row_newbcast:%17" DPPM "v_fmac_f32_dpp %1, %5, %13 row_newbcast:%17" DPPM "v_fmac_f32_dpp %2, %6, %14 row_newbcast:%17" DPPM "v_fmac_f32_dpp %3, %7, %15 row_newbcast:%17" DPPM
;                      : "+v"(s[0]), "+v"(s[1]), "+v"(s[2]), "+v"(s[3])
;                      : "v"(a[0]), "v"(a[1]), "v"(a[2]), "v"(a[3]), "v"(S[K]), "v"(S[K + 1]), "v"(S[K + 2]), "v"(S[K + 3]), "v"(S[K + 4]), "v"(S[K + 5]), "v"(S[K + 6]), "v"(S[K + 7]), "n"(N0), "n"(N1));
;         if constexpr (K + 8 < 64) ScanK<K + 8>::dot(S, a, s);
;     }
;     static __device__ __forceinline__ void updP(float (&P)[64], const In1& in, float sa) {
;         float u0, u1, u2, u3;
;         asm volatile("v_mul_f32_dpp %0, %8, %4 row_newbcast:%17" DPPM "v_mul_f32_dpp %1, %9, %5 row_newbcast:%17" DPPM "v_mul_f32_dpp %2, %10, %6 row_newbcast:%17" DPPM "v_mul_f32_dpp %3, %11, %7 row_newbcast:%17" DPPM
;                      "v_fmac_f32_dpp %0, %12, %16 row_newbcast:%17" DPPM "v_fmac_f32_dpp %1, %13, %16 row_newbcast:%17" DPPM "v_fmac_f32_dpp %2, %14, %16 row_newbcast:%17" DPPM "v_fmac_f32_dpp %3, %15, %16 row_newbcast:%17" DPPM
;                      : "=&v"(u0), "=&v"(u1), "=&v"(u2), "=&v"(u3)
	v_fmac_f32_dpp v198, v226, v26 row_newbcast:6 row_mask:0xf bank_mask:0xf
	v_fmac_f32_dpp v199, v227, v27 row_newbcast:6 row_mask:0xf bank_mask:0xf
	v_fmac_f32_dpp v196, v224, v28 row_newbcast:7 row_mask:0xf bank_mask:0xf
	v_fmac_f32_dpp v197, v225, v29 row_newbcast:7 row_mask:0xf bank_mask:0xf
	v_fmac_f32_dpp v198, v226, v30 row_newbcast:7 row_mask:0xf bank_mask:0xf
	v_fmac_f32_dpp v199, v227, v31 row_newbcast:7 row_mask:0xf bank_mask:0xf
	v_fmac_f32_dpp v196, v224, v32 row_newbcast:8 row_mask:0xf bank_mask:0xf
	v_fmac_f32_dpp v197, v225, v33 row_newbcast:8 row_mask:0xf bank_mask:0xf
	v_fmac_f32_dpp v198, v226, v34 row_newbcast:8 row_mask:0xf bank_mask:0xf
	v_fmac_f32_dpp v199, v227, v35 row_newbcast:8 row_mask:0xf bank_mask:0xf
	v_fmac_f32_dpp v196, v224, v36 row_newbcast:9 row_mask:0xf bank_mask:0xf
	v_fmac_f32_dpp v197, v225, v37 row_newbcast:9 row_mask:0xf bank_mask:0xf
	v_fmac_f32_dpp v198, v226, v38 row_newbcast:9 row_mask:0xf bank_mask:0xf
	v_fmac_f32_dpp v199, v227, v39 row_newbcast:9 row_mask:0xf bank_mask:0xf
	v_fmac_f32_dpp v196, v224, v40 row_newbcast:10 row_mask:0xf bank_mask:0xf
	v_fmac_f32_dpp v197, v225, v41 row_newbcast:10 row_mask:0xf bank_mask:0xf
	v_fmac_f32_dpp v198, v226, v42 row_newbcast:10 row_mask:0xf bank_mask:0xf
	v_fmac_f32_dpp v199, v227, v43 row_newbcast:10 row_mask:0xf bank_mask:0xf
	v_fmac_f32_dpp v196, v224, v44 row_newbcast:11 row_mask:0xf bank_mask:0xf
	v_fmac_f32_dpp v197, v225, v45 row_newbcast:11 row_mask:0xf bank_mask:0xf
	v_fmac_f32_dpp v198, v226, v46 row_newbcast:11 row_mask:0xf bank_mask:0xf
	v_fmac_f32_dpp v199, v227, v47 row_newbcast:11 row_mask:0xf bank_mask:0xf
	v_fmac_f32_dpp v196, v224, v48 row_newbcast:12 row_mask:0xf bank_mask:0xf
	v_fmac_f32_dpp v197, v225, v49 row_newbcast:12 row_mask:0xf bank_mask:0xf
	v_fmac_f32_dpp v198, v226, v50 row_newbcast:12 row_mask:0xf bank_mask:0xf
	v_fmac_f32_dpp v199, v227, v51 row_newbcast:12 row_mask:0xf bank_mask:0xf
	v_fmac_f32_dpp v196, v224, v52 row_newbcast:13 row_mask:0xf bank_mask:0xf
	v_fmac_f32_dpp v197, v225, v53 row_newbcast:13 row_mask:0xf bank_mask:0xf
	v_fmac_f32_dpp v198, v226, v54 row_newbcast:13 row_mask:0xf bank_mask:0xf
	v_fmac_f32_dpp v199, v227, v55 row_newbcast:13 row_mask:0xf bank_mask:0xf
	v_fmac_f32_dpp v196, v224, v56 row_newbcast:14 row_mask:0xf bank_mask:0xf
	v_fmac_f32_dpp v197, v225, v57 row_newbcast:14 row_mask:0xf bank_mask:0xf
	v_fmac_f32_dpp v198, v226, v58 row_newbcast:14 row_mask:0xf bank_mask:0xf
	v_fmac_f32_dpp v199, v227, v59 row_newbcast:14 row_mask:0xf bank_mask:0xf
	v_fmac_f32_dpp v196, v224, v60 row_newbcast:15 row_mask:0xf bank_mask:0xf
	v_fmac_f32_dpp v197, v225, v61 row_newbcast:15 row_mask:0xf bank_mask:0xf
	v_fmac_f32_dpp v198, v226, v62 row_newbcast:15 row_mask:0xf bank_mask:0xf
	v_fmac_f32_dpp v199, v227, v63 row_newbcast:15 row_mask:0xf bank_mask:0xf
	v_add_f32_e32 v196, v196, v197
	v_add_f32_e32 v198, v198, v199
	v_add_f32_e32 v196, v196, v198
	v_xor_b32_e32 v202, 0x80000000, v196
	s_waitcnt lgkmcnt(0)
	s_nop 1
	v_mfma_f32_4x4x1_16b_f32 v[0:3], v64, v202, v[0:3]
	v_mfma_f32_4x4x1_16b_f32 v[4:7], v65, v202, v[4:7]
	v_mfma_f32_4x4x1_16b_f32 v[8:11], v66, v202, v[8:11]
	v_mfma_f32_4x4x1_16b_f32 v[12:15], v67, v202, v[12:15]
	v_mfma_f32_4x4x1_16b_f32 v[16:19], v68, v202, v[16:19]
	v_mfma_f32_4x4x1_16b_f32 v[20:23], v69, v202, v[20:23]
	v_mfma_f32_4x4x1_16b_f32 v[24:27], v70, v202, v[24:27]
	v_mfma_f32_4x4x1_16b_f32 v[28:31], v71, v202, v[28:31]
	v_mfma_f32_4x4x1_16b_f32 v[32:35], v72, v202, v[32:35]
	v_mfma_f32_4x4x1_16b_f32 v[36:39], v73, v202, v[36:39]
	v_mfma_f32_4x4x1_16b_f32 v[40:43], v74, v202, v[40:43]
	v_mfma_f32_4x4x1_16b_f32 v[44:47], v75, v202, v[44:47]
	v_mfma_f32_4x4x1_16b_f32 v[48:51], v76, v202, v[48:51]
	v_mfma_f32_4x4x1_16b_f32 v[52:55], v77, v202, v[52:55]
	v_mfma_f32_4x4x1_16b_f32 v[56:59], v78, v202, v[56:59]
	v_mfma_f32_4x4x1_16b_f32 v[60:63], v79, v202, v[60:63]
	s_waitcnt vmcnt(6)
	buffer_load_dwordx4 v[136:139], v204, s[64:67], s72 offen
	buffer_load_dwordx4 v[140:143], v204, s[64:67], s73 offen
	buffer_load_dwordx4 v[144:147], v204, s[64:67], s74 offen
	s_cmp_lt_u32 s80, 255
	s_cselect_b32 s81, 0xfffff000, 0
	s_cselect_b32 s82, 0xfffff800, 0
	s_cselect_b32 s9, 1, 0
	s_add_u32 s80, s80, s9
	s_add_u32 s72, s72, s81
	s_add_u32 s73, s73, s81
	s_add_u32 s74, s74, s81
	v_pk_mul_f32 v[224:225], v[160:161], v[216:217]
	v_pk_mul_f32 v[226:227], v[162:163], v[218:219]
	v_pk_mul_f32 v[216:217], v[216:217], v[156:157]
	v_pk_mul_f32 v[218:219], v[218:219], v[158:159]
	v_pk_mul_f32 v[176:177], v[160:161], v[164:165]
	v_pk_mul_f32 v[178:179], v[162:163], v[166:167]
	v_rcp_f32_e32 v220, v216
	v_rcp_f32_e32 v221, v217
	v_rcp_f32_e32 v222, v218
	v_rcp_f32_e32 v223, v219
	s_nop 0
	v_pk_mul_f32 v[176:177], v[176:177], v[220:221]
	v_pk_mul_f32 v[178:179], v[178:179], v[222:223]
	ds_write_b128 v208, v[176:179]
	ds_read2_b32 v[64:65], v209 offset0:0 offset1:4
	ds_read2_b32 v[66:67], v209 offset0:8 offset1:12
	ds_read2_b32 v[68:69], v209 offset0:16 offset1:20
	ds_read2_b32 v[70:71], v209 offset0:24 offset1:28
	ds_read2_b32 v[72:73], v209 offset0:32 offset1:36
	ds_read2_b32 v[74:75], v209 offset0:40 offset1:44
	ds_read2_b32 v[76:77], v209 offset0:48 offset1:52
	ds_read2_b32 v[78:79], v209 offset0:56 offset1:60
	v_mul_f32_dpp v196, v224, v0 row_newbcast:0 row_mask:0xf bank_mask:0xf
	v_mul_f32_dpp v197, v225, v1 row_newbcast:0 row_mask:0xf bank_mask:0xf
	v_mul_f32_dpp v198, v226, v2 row_newbcast:0 row_mask:0xf bank_mask:0xf
	v_mul_f32_dpp v199, v227, v3 row_newbcast:0 row_mask:0xf bank_mask:0xf
	v_fmac_f32_dpp v196, v224, v4 row_newbcast:1 row_mask:0xf bank_mask:0xf
; #define SB __builtin_amdgcn_sched_barrier(0)
; #define LD1(set, s) { const int e_ = min((int)(s), LC - 1) * (int)stp; const unsigned s4_ = ob4 + (unsigned)(e_ * 4), s2_ = ob2 + (unsigned)(e_ * 2); set.w = LDX(rW, s4_); set.a = LDX(rA, s4_); set.b = LDX(rB, s4_); \
;             set.kw = __builtin_amdgcn_raw_buffer_load_b64(rK, lo8, s2_, 0); set.v = __builtin_amdgcn_raw_buffer_load_b16(rV, lo2, s2_, 0); }
; #define TOUCH1(set) asm volatile("" :: "v"(set.w), "v"(set.a), "v"(set.b), "v"(set.kw), "v"(set.v))
; #define ST1(set) { DERIVE_BK(set); float sd[4]; ScanK<0>::dot(S, set.a, sd); ScanK<0>::updS(S, set, -((sd[0] + sd[1]) + (sd[2] + sd[3])), __uint_as_float(set.v << 16)); }
; #define LD1(set, s) { const int e_ = min((int)(s), LC - 1) * (int)stp; const unsigned s4_ = ob4 + (unsigned)(e_ * 4); set.w = LDX(rW, s4_); set.a = LDX(rA, s4_); set.b = LDX(rB, s4_); }
; #define TOUCH1(set) asm volatile("" :: "v"(set.w), "v"(set.a), "v"(set.b))
; #define ST1(set) { DERIVE_B(set); float sd[4]; ScanK<0>::dot(S, set.a, sd); ScanK<0>::updP(S, set, -((sd[0] + sd[1]) + (sd[2] + sd[3]))); }
;     static __device__ __forceinline__ void updP(float (&P)[64], const In1& in, float sa) {
;         float u0, u1, u2, u3;
;         asm volatile("v_mul_f32_dpp %0, %8, %4 row_newbcast:%17" DPPM "v_mul_f32_dpp %1, %9, %5 row_newbcast:%17" DPPM "v_mul_f32_dpp %2, %10, %6 row_newbcast:%17" DPPM "v_mul_f32_dpp %3, %11, %7 row_newbcast:%17" DPPM
;                      "v_fmac_f32_dpp %0, %12, %16 row_newbcast:%17" DPPM "v_fmac_f32_dpp %1, %13, %16 row_newbcast:%17" DPPM "v_fmac_f32_dpp %2, %14, %16 row_newbcast:%17" DPPM "v_fmac_f32_dpp %3, %15, %16 row_newbcast:%17" DPPM
;                      : "=&v"(u0), "=&v"(u1), "=&v"(u2), "=&v"(u3)
;                      : "v"(P[K]), "v"(P[K + 1]), "v"(P[K + 2]), "v"(P[K + 3]), "v"(in.w[0]), "v"(in.w[1]), "v"(in.w[2]), "v"(in.w[3]), "v"(in.b[0]), "v"(in.b[1]), "v"(in.b[2]), "v"(in.b[3]), "v"(sa), "n"(N0));
;         P[K] = u0; P[K + 1] = u1; P[K + 2] = u2; P[K + 3] = u3;
;         if constexpr (K + 4 < 64) ScanK<K + 4>::updP(P, in, sa);
;     }
; template <bool MIX> __device__ __forceinline__ void scan_pass1(const Params& p, int d, float* ldsf) {
;     ...
;             In1 i0, i1; LD1(i0, 0);
; #pragma unroll 1
;             for (int s = 0; s < LC; s += 2) { TOUCH1(i0); SB; LD1(i1, s + 1); SB; ST1(i0); TOUCH1(i1); SB; LD1(i0, s + 2); SB; ST1(i1); }
	v_fmac_f32_dpp v197, v225, v5 row_newbcast:1 row_mask:0xf bank_mask:0xf
	v_fmac_f32_dpp v198, v226, v6 row_newbcast:1 row_mask:0xf bank_mask:0xf
	v_fmac_f32_dpp v199, v227, v7 row_newbcast:1 row_mask:0xf bank_mask:0xf
	v_fmac_f32_dpp v196, v224, v8 row_newbcast:2 row_mask:0xf bank_mask:0xf
	v_fmac_f32_dpp v197, v225, v9 row_newbcast:2 row_mask:0xf bank_mask:0xf
	v_fmac_f32_dpp v198, v226, v10 row_newbcast:2 row_mask:0xf bank_mask:0xf
	v_fmac_f32_dpp v199, v227, v11 row_newbcast:2 row_mask:0xf bank_mask:0xf
	v_fmac_f32_dpp v196, v224, v12 row_newbcast:3 row_mask:0xf bank_mask:0xf
	v_fmac_f32_dpp v197, v225, v13 row_newbcast:3 row_mask:0xf bank_mask:0xf
	v_fmac_f32_dpp v198, v226, v14 row_newbcast:3 row_mask:0xf bank_mask:0xf
	v_fmac_f32_dpp v199, v227, v15 row_newbcast:3 row_mask:0xf bank_mask:0xf
	v_fmac_f32_dpp v196, v224, v16 row_newbcast:4 row_mask:0xf bank_mask:0xf
	v_fmac_f32_dpp v197, v225, v17 row_newbcast:4 row_mask:0xf bank_mask:0xf
	v_fmac_f32_dpp v198, v226, v18 row_newbcast:4 row_mask:0xf bank_mask:0xf
	v_fmac_f32_dpp v199, v227, v19 row_newbcast:4 row_mask:0xf bank_mask:0xf
	v_fmac_f32_dpp v196, v224, v20 row_newbcast:5 row_mask:0xf bank_mask:0xf
	v_fmac_f32_dpp v197, v225, v21 row_newbcast:5 row_mask:0xf bank_mask:0xf
	v_fmac_f32_dpp v198, v226, v22 row_newbcast:5 row_mask:0xf bank_mask:0xf
	v_fmac_f32_dpp v199, v227, v23 row_newbcast:5 row_mask:0xf bank_mask:0xf
	v_fmac_f32_dpp v196, v224, v24 row_newbcast:6 row_mask:0xf bank_mask:0xf
	v_fmac_f32_dpp v197, v225, v25 row_newbcast:6 row_mask:0xf bank_mask:0xf
	v_fmac_f32_dpp v198, v226, v26 row_newbcast:6 row_mask:0xf bank_mask:0xf
	v_fmac_f32_dpp v199, v227, v27 row_newbcast:6 row_mask:0xf bank_mask:0xf
	v_fmac_f32_dpp v196, v224, v28 row_newbcast:7 row_mask:0xf bank_mask:0xf
	v_fmac_f32_dpp v197, v225, v29 row_newbcast:7 row_mask:0xf bank_mask:0xf
	v_fmac_f32_dpp v198, v226, v30 row_newbcast:7 row_mask:0xf bank_mask:0xf
	v_fmac_f32_dpp v199, v227, v31 row_newbcast:7 row_mask:0xf bank_mask:0xf
	v_fmac_f32_dpp v196, v224, v32 row_newbcast:8 row_mask:0xf bank_mask:0xf
	v_fmac_f32_dpp v197, v225, v33 row_newbcast:8 row_mask:0xf bank_mask:0xf
	v_fmac_f32_dpp v198, v226, v34 row_newbcast:8 row_mask:0xf bank_mask:0xf
	v_fmac_f32_dpp v199, v227, v35 row_newbcast:8 row_mask:0xf bank_mask:0xf
	v_fmac_f32_dpp v196, v224, v36 row_newbcast:9 row_mask:0xf bank_mask:0xf
	v_fmac_f32_dpp v197, v225, v37 row_newbcast:9 row_mask:0xf bank_mask:0xf
	v_fmac_f32_dpp v198, v226, v38 row_newbcast:9 row_mask:0xf bank_mask:0xf
	v_fmac_f32_dpp v199, v227, v39 row_newbcast:9 row_mask:0xf bank_mask:0xf
	v_fmac_f32_dpp v196, v224, v40 row_newbcast:10 row_mask:0xf bank_mask:0xf
	v_fmac_f32_dpp v197, v225, v41 row_newbcast:10 row_mask:0xf bank_mask:0xf
	v_fmac_f32_dpp v198, v226, v42 row_newbcast:10 row_mask:0xf bank_mask:0xf
	v_fmac_f32_dpp v199, v227, v43 row_newbcast:10 row_mask:0xf bank_mask:0xf
	v_fmac_f32_dpp v196, v224, v44 row_newbcast:11 row_mask:0xf bank_mask:0xf
	v_fmac_f32_dpp v197, v225, v45 row_newbcast:11 row_mask:0xf bank_mask:0xf
	v_fmac_f32_dpp v198, v226, v46 row_newbcast:11 row_mask:0xf bank_mask:0xf
	v_fmac_f32_dpp v199, v227, v47 row_newbcast:11 row_mask:0xf bank_mask:0xf
	v_fmac_f32_dpp v196, v224, v48 row_newbcast:12 row_mask:0xf bank_mask:0xf
	v_fmac_f32_dpp v197, v225, v49 row_newbcast:12 row_mask:0xf bank_mask:0xf
	v_fmac_f32_dpp v198, v226, v50 row_newbcast:12 row_mask:0xf bank_mask:0xf
	v_fmac_f32_dpp v199, v227, v51 row_newbcast:12 row_mask:0xf bank_mask:0xf
	v_fmac_f32_dpp v196, v224, v52 row_newbcast:13 row_mask:0xf bank_mask:0xf
	v_fmac_f32_dpp v197, v225, v53 row_newbcast:13 row_mask:0xf bank_mask:0xf
	v_fmac_f32_dpp v198, v226, v54 row_newbcast:13 row_mask:0xf bank_mask:0xf
	v_fmac_f32_dpp v199, v227, v55 row_newbcast:13 row_mask:0xf bank_mask:0xf
	v_fmac_f32_dpp v196, v224, v56 row_newbcast:14 row_mask:0xf bank_mask:0xf
	v_fmac_f32_dpp v197, v225, v57 row_newbcast:14 row_mask:0xf bank_mask:0xf
	v_fmac_f32_dpp v198, v226, v58 row_newbcast:14 row_mask:0xf bank_mask:0xf
	v_fmac_f32_dpp v199, v227, v59 row_newbcast:14 row_mask:0xf bank_mask:0xf
	v_fmac_f32_dpp v196, v224, v60 row_newbcast:15 row_mask:0xf bank_mask:0xf
	v_fmac_f32_dpp v197, v225, v61 row_newbcast:15 row_mask:0xf bank_mask:0xf
	v_fmac_f32_dpp v198, v226, v62 row_newbcast:15 row_mask:0xf bank_mask:0xf
	v_fmac_f32_dpp v199, v227, v63 row_newbcast:15 row_mask:0xf bank_mask:0xf
	v_add_f32_e32 v196, v196, v197
	v_add_f32_e32 v198, v198, v199
	v_add_f32_e32 v196, v196, v198
	v_xor_b32_e32 v202, 0x80000000, v196
	s_waitcnt lgkmcnt(0)
	s_nop 1
	v_mfma_f32_4x4x1_16b_f32 v[0:3], v64, v202, v[0:3]
	v_mfma_f32_4x4x1_16b_f32 v[4:7], v65, v202, v[4:7]
	v_mfma_f32_4x4x1_16b_f32 v[8:11], v66, v202, v[8:11]
	v_mfma_f32_4x4x1_16b_f32 v[12:15], v67, v202, v[12:15]
	v_mfma_f32_4x4x1_16b_f32 v[16:19], v68, v202, v[16:19]
	v_mfma_f32_4x4x1_16b_f32 v[20:23], v69, v202, v[20:23]
	v_mfma_f32_4x4x1_16b_f32 v[24:27], v70, v202, v[24:27]
	v_mfma_f32_4x4x1_16b_f32 v[28:31], v71, v202, v[28:31]
	v_mfma_f32_4x4x1_16b_f32 v[32:35], v72, v202, v[32:35]
	v_mfma_f32_4x4x1_16b_f32 v[36:39], v73, v202, v[36:39]
	v_mfma_f32_4x4x1_16b_f32 v[40:43], v74, v202, v[40:43]
	v_mfma_f32_4x4x1_16b_f32 v[44:47], v75, v202, v[44:47]
	v_mfma_f32_4x4x1_16b_f32 v[48:51], v76, v202, v[48:51]
	v_mfma_f32_4x4x1_16b_f32 v[52:55], v77, v202, v[52:55]
	v_mfma_f32_4x4x1_16b_f32 v[56:59], v78, v202, v[56:59]
	v_mfma_f32_4x4x1_16b_f32 v[60:63], v79, v202, v[60:63]
	s_sub_u32 s83, s83, 1
	s_cmp_eq_u32 s83, 0
	s_cbranch_scc1 .Lmy_p1d1_ldone_p
	s_and_b32 s9, s83, 7
	s_cmp_eq_u32 s9, 0
	s_cbranch_scc1 .Lmy_p1d1_renorm_p
	s_branch .Lmy_p1d1_loop_p

; template <bool MIX> __device__ __forceinline__ void scan_pass1(const Params& p, int d, float* ldsf) {
;     ...
;         float* po = (isP ? PT : SLT) + ((size_t)(bh * NC + c)) * 4096 + lane * 64;
; #pragma unroll
;         for (int i = 0; i < 16; ++i) *(f32x4*)(po + 4 * i) = (f32x4){S[4 * i], S[4 * i + 1], S[4 * i + 2], S[4 * i + 3]};
.Lmy_p1d1_store:
	s_nop 1
	global_store_dwordx4 v210, v[0:3], s[90:91] offset:0
	global_store_dwordx4 v210, v[4:7], s[90:91] offset:16
	global_store_dwordx4 v210, v[8:11], s[90:91] offset:32
	global_store_dwordx4 v210, v[12:15], s[90:91] offset:48
	global_store_dwordx4 v210, v[16:19], s[90:91] offset:64
	global_store_dwordx4 v210, v[20:23], s[90:91] offset:80
	global_store_dwordx4 v210, v[24:27], s[90:91] offset:96
	global_store_dwordx4 v210, v[28:31], s[90:91] offset:112
	global_store_dwordx4 v210, v[32:35], s[90:91] offset:128
	global_store_dwordx4 v210, v[36:39], s[90:91] offset:144
	global_store_dwordx4 v210, v[40:43], s[90:91] offset:160
	global_store_dwordx4 v210, v[44:47], s[90:91] offset:176
	global_store_dwordx4 v210, v[48:51], s[90:91] offset:192
	global_store_dwordx4 v210, v[52:55], s[90:91] offset:208
	global_store_dwordx4 v210, v[56:59], s[90:91] offset:224
	global_store_dwordx4 v210, v[60:63], s[90:91] offset:240
	s_nop 1
	s_lshl_b32 s6, s96, 3
	s_add_i32 s0, s0, s6
	s_branch .Lmy_p1d1_item
